# scan loops trimmed: array bases folded into per-array voffsets with one shared unconditional step offset, transposed LDS pattern layout read with ds_read_b128, fused negate
# speedup vs baseline: 1.0283x; 1.0283x over previous
; #define NEXT_ITEM() (MIX ? (int)__builtin_amdgcn_readfirstlane(lane == 0 ? __hip_atomic_fetch_add(qctr, 1u, __ATOMIC_RELAXED, __HIP_MEMORY_SCOPE_AGENT) : 0u) : item + (int)gridDim.x * 8)
; #define MKR(ptr) __builtin_amdgcn_make_buffer_rsrc((void*)(ptr), 0, 0x7fffffff, 0x00027000)
; #define LD1(set, s) { const int e_ = min((int)(s), LC - 1) * (int)stp; const unsigned s4_ = ob4 + (unsigned)(e_ * 4), s2_ = ob2 + (unsigned)(e_ * 2); set.w = LDX(rW, s4_); set.a = LDX(rA, s4_); set.b = LDX(rB, s4_); \
;             set.kw = __builtin_amdgcn_raw_buffer_load_b64(rK, lo8, s2_, 0); set.v = __builtin_amdgcn_raw_buffer_load_b16(rV, lo2, s2_, 0); }
; #define LD1(set, s) { const int e_ = min((int)(s), LC - 1) * (int)stp; const unsigned s4_ = ob4 + (unsigned)(e_ * 4); set.w = LDX(rW, s4_); set.a = LDX(rA, s4_); set.b = LDX(rB, s4_); }
; template <bool MIX> __device__ __forceinline__ void scan_pass1(const Params& p, int d, float* ldsf) {
;     ...
;     for (int item = MIX ? NEXT_ITEM() : (int)(blockIdx.x * 8 + wid); item < 2 * NS; item = NEXT_ITEM()) {
;         const bool isP = item >= NS; const int idx = isP ? item - NS : item;
;         const int bh = idx / (NC - 1), c = idx - bh * (NC - 1), b = bh >> 4, h = bh & 15;
;         const int t0 = d ? (SEQ - 1 - c * LC) : c * LC;
;         const size_t off0 = ((size_t)(b * SEQ + t0)) * RW + h * 64; const long stp = d ? -(long)RW : (long)RW;
;         const unsigned ob4 = (unsigned)(off0 * 4), ob2 = (unsigned)(off0 * 2);
;         const f32x4 ka4 = *(const f32x4*)(p.k_a + h * 64 + (lane & 15) * 4), c04 = 1.0f - ka4;
;         float S[64]; int ln = lane; asm volatile("" : "+v"(ln));
;     ...
;         const __amdgpu_buffer_rsrc_t rW = MKR(Wd), rA = MKR(A), rB = MKR(Bd), rK = MKR(KB), rV = MKR(V);
;         if (!isP) {
; #pragma unroll
;             for (int i = 0; i < 64; ++i) S[i] = 0.f;
;     ...
;             In1 i0, i1; LD1(i0, 0);
.Lmy_nat_end:
.LBB0_555:
	s_barrier
	s_mov_b64 exec, -1
	s_setprio 0
	v_readfirstlane_b32 s0, v254
	s_nop 3
	s_lshr_b32 s1, s0, 6
	s_lshl_b32 s0, s2, 3
	s_add_i32 s0, s1, s0
	s_mov_b32 s64, s56
	s_and_b32 s65, s57, 0xffff
	s_brev_b32 s66, -2
	s_mov_b32 s67, 0x27000
	s_mov_b32 s68, s54
	s_and_b32 s69, s55, 0xffff
	s_mov_b32 s70, s66
	s_mov_b32 s71, s67
	v_and_b32_e32 v212, 63, v254
	v_and_b32_e32 v213, 15, v254
	v_lshlrev_b32_e32 v204, 4, v213
	v_lshlrev_b32_e32 v205, 3, v213
	v_lshlrev_b32_e32 v206, 1, v212
	v_lshlrev_b32_e32 v207, 2, v212
	v_lshlrev_b32_e32 v210, 8, v212
	s_lshl_b32 s3, s1, 10
	s_add_u32 s3, s3, 0x10000
	v_lshl_add_u32 v208, v213, 2, s3
	v_and_b32_e32 v209, 3, v254
	v_lshl_add_u32 v209, v209, 6, s3
	v_add_u32_e32 v232, 0xb800000, v204
	v_add_u32_e32 v233, 0x24800000, v204
	v_add_u32_e32 v234, 0x35a00000, v204
	v_add_u32_e32 v235, 0x1c800000, v204
	v_add_u32_e32 v236, 0x30800000, v205
	v_add_u32_e32 v237, 0x2c800000, v206
	v_mov_b32_e32 v213, 1.0
	v_mov_b32_e32 v214, 0
	v_mov_b32_e32 v215, 1
	s_mov_b64 exec, 1
	global_atomic_add v214, v214, v215, s[34:35] sc0
	s_mov_b64 exec, -1
	s_waitcnt vmcnt(0)
	s_nop 0
	v_readfirstlane_b32 s0, v214
	s_nop 3
.Lmy_p1d0_item:
	s_cmpk_gt_i32 s0, 0xfbf
	s_cbranch_scc1 .Lmy_p1d0_end
	s_cmpk_gt_i32 s0, 0x7df
	s_cselect_b32 s88, 1, 0
	s_cselect_b32 s6, 0x7e0, 0
	s_sub_u32 s6, s0, s6
	s_mul_i32 s86, s6, 2081
	s_lshr_b32 s86, s86, 17
	s_mul_i32 s7, s86, 63
	s_sub_u32 s85, s6, s7
	s_and_b32 s87, s86, 15
	s_lshr_b32 s6, s86, 4
	s_lshl_b32 s6, s6, 14
	s_lshl_b32 s7, s85, 8
	s_add_u32 s6, s6, s7
	s_lshl_b32 s6, s6, 10
	s_lshl_b32 s7, s87, 6
	s_add_u32 s84, s6, s7
	s_lshl_b32 s6, s84, 2
	s_lshl_b32 s7, s84, 1
	s_mov_b32 s72, s6
	s_mov_b32 s76, s7
	s_lshl_b32 s6, s86, 6
	s_add_u32 s6, s6, s85
	s_lshl_b32 s6, s6, 14
	s_mov_b32 s7, 0x15800000
	s_cmp_eq_u32 s88, 1
	s_cselect_b32 s7, 0x13800000, s7
	s_add_u32 s6, s6, s7
	s_add_u32 s90, s56, s6
	s_addc_u32 s91, s57, 0
	s_cmp_eq_u32 s88, 1
	s_cbranch_scc1 .Lmy_p1d0_pitem
	s_lshl_b32 s8, s87, 8
	s_add_u32 s4, s42, s8
	s_addc_u32 s5, s43, 0
	global_load_dwordx4 v[188:191], v204, s[4:5]
	buffer_load_dwordx4 v[96:99], v232, s[64:67], s72 offen
	buffer_load_dwordx4 v[100:103], v233, s[64:67], s72 offen
	buffer_load_dwordx4 v[104:107], v234, s[64:67], s72 offen
	buffer_load_dwordx2 v[112:113], v236, s[64:67], s76 offen
	buffer_load_ushort v114, v237, s[64:67], s76 offen
	s_add_u32 s72, s72, 0x1000
	s_add_u32 s76, s76, 0x800
	buffer_load_dwordx4 v[116:119], v232, s[64:67], s72 offen
	buffer_load_dwordx4 v[120:123], v233, s[64:67], s72 offen
	buffer_load_dwordx4 v[124:127], v234, s[64:67], s72 offen
	buffer_load_dwordx2 v[132:133], v236, s[64:67], s76 offen
	buffer_load_ushort v134, v237, s[64:67], s76 offen
	s_add_u32 s72, s72, 0x1000
	s_add_u32 s76, s76, 0x800
	buffer_load_dwordx4 v[136:139], v232, s[64:67], s72 offen
	buffer_load_dwordx4 v[140:143], v233, s[64:67], s72 offen
	buffer_load_dwordx4 v[144:147], v234, s[64:67], s72 offen
	buffer_load_dwordx2 v[152:153], v236, s[64:67], s76 offen
	buffer_load_ushort v154, v237, s[64:67], s76 offen
	s_add_u32 s72, s72, 0x1000
	s_add_u32 s76, s76, 0x800
	v_mov_b32_e32 v0, 0
	v_mov_b32_e32 v1, 0
	v_mov_b32_e32 v2, 0
	v_mov_b32_e32 v3, 0
	v_mov_b32_e32 v4, 0
	v_mov_b32_e32 v5, 0
	v_mov_b32_e32 v6, 0
	v_mov_b32_e32 v7, 0
	v_mov_b32_e32 v8, 0
	v_mov_b32_e32 v9, 0
	v_mov_b32_e32 v10, 0
	v_mov_b32_e32 v11, 0
	v_mov_b32_e32 v12, 0
	v_mov_b32_e32 v13, 0
	v_mov_b32_e32 v14, 0
	v_mov_b32_e32 v15, 0
	v_mov_b32_e32 v16, 0
	v_mov_b32_e32 v17, 0
	v_mov_b32_e32 v18, 0
	v_mov_b32_e32 v19, 0
	v_mov_b32_e32 v20, 0
	v_mov_b32_e32 v21, 0
	v_mov_b32_e32 v22, 0
	v_mov_b32_e32 v23, 0
	v_mov_b32_e32 v24, 0
	v_mov_b32_e32 v25, 0
	v_mov_b32_e32 v26, 0
	v_mov_b32_e32 v27, 0
	v_mov_b32_e32 v28, 0
	v_mov_b32_e32 v29, 0
	v_mov_b32_e32 v30, 0
	v_mov_b32_e32 v31, 0
	v_mov_b32_e32 v32, 0
	v_mov_b32_e32 v33, 0
	v_mov_b32_e32 v34, 0
	v_mov_b32_e32 v35, 0
	v_mov_b32_e32 v36, 0
	v_mov_b32_e32 v37, 0
	v_mov_b32_e32 v38, 0
	v_mov_b32_e32 v39, 0
	v_mov_b32_e32 v40, 0
	v_mov_b32_e32 v41, 0
	v_mov_b32_e32 v42, 0
	v_mov_b32_e32 v43, 0
	v_mov_b32_e32 v44, 0
	v_mov_b32_e32 v45, 0
	v_mov_b32_e32 v46, 0
	v_mov_b32_e32 v47, 0
	v_mov_b32_e32 v48, 0
	v_mov_b32_e32 v49, 0
	v_mov_b32_e32 v50, 0
	v_mov_b32_e32 v51, 0
	v_mov_b32_e32 v52, 0
	v_mov_b32_e32 v53, 0
	v_mov_b32_e32 v54, 0
	v_mov_b32_e32 v55, 0
	v_mov_b32_e32 v56, 0
	v_mov_b32_e32 v57, 0
	v_mov_b32_e32 v58, 0
	v_mov_b32_e32 v59, 0
	v_mov_b32_e32 v60, 0
	v_mov_b32_e32 v61, 0
	v_mov_b32_e32 v62, 0
	v_mov_b32_e32 v63, 0
	s_waitcnt vmcnt(0)
	v_sub_f32_e32 v192, 1.0, v188
	v_sub_f32_e32 v193, 1.0, v189
	v_sub_f32_e32 v194, 1.0, v190
	v_sub_f32_e32 v195, 1.0, v191
	v_mov_b32_e32 v216, 1.0
	v_mov_b32_e32 v217, 1.0
	v_mov_b32_e32 v218, 1.0
	v_mov_b32_e32 v219, 1.0
	s_movk_i32 s83, 64
	s_branch .Lmy_p1d0_loop_s

;     static __device__ __forceinline__ void dot(const float (&S)[64], const f32x4& a, float (&s)[4]) {
;         if constexpr (K == 0) {
;             asm volatile("v_mul_f32_dpp %0, %4, %8 row_newbcast:%16" DPPM "v_mul_f32_dpp %1, %5, %9 row_newbcast:%16" DPPM "v_mul_f32_dpp %2, %6, %10 row_newbcast:%16" DPPM "v_mul_f32_dpp %3, %7, %11 row_newbcast:%16" DPPM
;                          "v_fmac_f32_dpp %0, %4, %12 row_newbcast:%17" DPPM "v_fmac_f32_dpp %1, %5, %13 row_newbcast:%17" DPPM "v_fmac_f32_dpp %2, %6, %14 row_newbcast:%17" DPPM "v_fmac_f32_dpp %3, %7, %15 row_newbcast:%17" DPPM
;                          : "=&v"(s[0]), "=&v"(s[1]), "=&v"(s[2]), "=&v"(s[3])
;                          : "v"(a[0]), "v"(a[1]), "v"(a[2]), "v"(a[3]), "v"(S[K]), "v"(S[K + 1]), "v"(S[K + 2]), "v"(S[K + 3]), "v"(S[K + 4]), "v"(S[K + 5]), "v"(S[K + 6]), "v"(S[K + 7]), "n"(N0), "n"(N1));
;         } else
;         asm volatile("v_fmac_f32_dpp %0, %4, %8 row_newbcast:%16" DPPM "v_fmac_f32_dpp %1, %5, %9 row_newbcast:%16" DPPM "v_fmac_f32_dpp %2, %6, %10 row_newbcast:%16" DPPM "v_fmac_f32_dpp %3, %7, %11 row_newbcast:%16" DPPM
;                      "v_fmac_f32_dpp %0, %4, %12 row_newbcast:%17" DPPM "v_fmac_f32_dpp %1, %5, %13 row_newbcast:%17" DPPM "v_fmac_f32_dpp %2, %6, %14 row_newbcast:%17" DPPM "v_fmac_f32_dpp %3, %7, %15 row_newbcast:%17" DPPM
;                      : "+v"(s[0]), "+v"(s[1]), "+v"(s[2]), "+v"(s[3])
;                      : "v"(a[0]), "v"(a[1]), "v"(a[2]), "v"(a[3]), "v"(S[K]), "v"(S[K + 1]), "v"(S[K + 2]), "v"(S[K + 3]), "v"(S[K + 4]), "v"(S[K + 5]), "v"(S[K + 6]), "v"(S[K + 7]), "n"(N0), "n"(N1));
;         if constexpr (K + 8 < 64) ScanK<K + 8>::dot(S, a, s);
;     }
;     static __device__ __forceinline__ void upd(float (&S)[64], const In2& in, float sa, float vv, float& y0, float& y1) {
;         float t0, t1, t2, t3;
;         asm volatile("v_mul_f32_dpp %0, %10, %27 row_newbcast:%28" DPPM "v_mul_f32_dpp %1, %11, %27 row_newbcast:%28" DPPM "v_mul_f32_dpp %2, %12, %27 row_newbcast:%28" DPPM "v_mul_f32_dpp %3, %13, %27 row_newbcast:%28" DPPM
; template <bool MIX> __device__ __forceinline__ void scan_pass1(const Params& p, int d, float* ldsf) {
;     ...
;             In1 i0, i1; LD1(i0, 0);
; #pragma unroll 1
;             for (int s = 0; s < LC; s += 2) { TOUCH1(i0); SB; LD1(i1, s + 1); SB; ST1(i0); TOUCH1(i1); SB; LD1(i0, s + 2); SB; ST1(i1); }
.Lmy_p1d0_loop_s:
	s_waitcnt vmcnt(10)
	buffer_load_dwordx4 v[156:159], v232, s[64:67], s72 offen
	buffer_load_dwordx4 v[160:163], v233, s[64:67], s72 offen
	buffer_load_dwordx4 v[164:167], v234, s[64:67], s72 offen
	buffer_load_dwordx2 v[172:173], v236, s[64:67], s76 offen
	buffer_load_ushort v174, v237, s[64:67], s76 offen
	s_add_u32 s72, s72, 0x1000
	s_add_u32 s76, s76, 0x800
	v_pk_mul_f32 v[224:225], v[100:101], v[216:217]
	v_pk_mul_f32 v[226:227], v[102:103], v[218:219]
	v_pk_mul_f32 v[216:217], v[216:217], v[96:97]
	v_pk_mul_f32 v[218:219], v[218:219], v[98:99]
	v_pk_fma_f32 v[184:185], v[104:105], v[188:189], v[192:193]
	v_pk_fma_f32 v[186:187], v[106:107], v[190:191], v[194:195]
	v_pk_mul_f32 v[176:177], v[100:101], v[104:105]
	v_pk_mul_f32 v[178:179], v[102:103], v[106:107]
	v_rcp_f32_e32 v220, v216
	v_rcp_f32_e32 v221, v217
	v_rcp_f32_e32 v222, v218
	v_rcp_f32_e32 v223, v219
	v_lshlrev_b32_e32 v180, 16, v112
	v_and_b32_e32 v181, 0xffff0000, v112
	v_lshlrev_b32_e32 v182, 16, v113
	v_and_b32_e32 v183, 0xffff0000, v113
	v_pk_mul_f32 v[180:181], v[180:181], v[184:185]
	v_pk_mul_f32 v[182:183], v[182:183], v[186:187]
	v_lshlrev_b32_e32 v203, 16, v114
	v_pk_mul_f32 v[176:177], v[176:177], v[220:221]
	v_pk_mul_f32 v[178:179], v[178:179], v[222:223]
	v_pk_mul_f32 v[180:181], v[180:181], v[220:221]
	v_pk_mul_f32 v[182:183], v[182:183], v[222:223]
	ds_write2_b32 v208, v176, v177 offset0:0 offset1:16
	ds_write2_b32 v208, v178, v179 offset0:32 offset1:48
	ds_write2_b32 v208, v180, v181 offset0:64 offset1:80
	ds_write2_b32 v208, v182, v183 offset0:96 offset1:112
	ds_read_b128 v[64:67], v209 offset:0
	ds_read_b128 v[68:71], v209 offset:16
	ds_read_b128 v[72:75], v209 offset:32
	ds_read_b128 v[76:79], v209 offset:48
	ds_read_b128 v[80:83], v209 offset:256
	ds_read_b128 v[84:87], v209 offset:272
	ds_read_b128 v[88:91], v209 offset:288
	ds_read_b128 v[92:95], v209 offset:304
	v_mul_f32_dpp v196, v224, v0 row_newbcast:0 row_mask:0xf bank_mask:0xf
	v_mul_f32_dpp v197, v225, v1 row_newbcast:0 row_mask:0xf bank_mask:0xf
	v_mul_f32_dpp v198, v226, v2 row_newbcast:0 row_mask:0xf bank_mask:0xf
	v_mul_f32_dpp v199, v227, v3 row_newbcast:0 row_mask:0xf bank_mask:0xf
	v_fmac_f32_dpp v196, v224, v4 row_newbcast:1 row_mask:0xf bank_mask:0xf
	v_fmac_f32_dpp v197, v225, v5 row_newbcast:1 row_mask:0xf bank_mask:0xf
	v_fmac_f32_dpp v198, v226, v6 row_newbcast:1 row_mask:0xf bank_mask:0xf
	v_fmac_f32_dpp v199, v227, v7 row_newbcast:1 row_mask:0xf bank_mask:0xf
	v_fmac_f32_dpp v196, v224, v8 row_newbcast:2 row_mask:0xf bank_mask:0xf
	v_fmac_f32_dpp v197, v225, v9 row_newbcast:2 row_mask:0xf bank_mask:0xf
	v_fmac_f32_dpp v198, v226, v10 row_newbcast:2 row_mask:0xf bank_mask:0xf
	v_fmac_f32_dpp v199, v227, v11 row_newbcast:2 row_mask:0xf bank_mask:0xf
	v_fmac_f32_dpp v196, v224, v12 row_newbcast:3 row_mask:0xf bank_mask:0xf
	v_fmac_f32_dpp v197, v225, v13 row_newbcast:3 row_mask:0xf bank_mask:0xf
	v_fmac_f32_dpp v198, v226, v14 row_newbcast:3 row_mask:0xf bank_mask:0xf
	v_fmac_f32_dpp v199, v227, v15 row_newbcast:3 row_mask:0xf bank_mask:0xf
	v_fmac_f32_dpp v196, v224, v16 row_newbcast:4 row_mask:0xf bank_mask:0xf
	v_fmac_f32_dpp v197, v225, v17 row_newbcast:4 row_mask:0xf bank_mask:0xf
	v_fmac_f32_dpp v198, v226, v18 row_newbcast:4 row_mask:0xf bank_mask:0xf
	v_fmac_f32_dpp v199, v227, v19 row_newbcast:4 row_mask:0xf bank_mask:0xf
	v_fmac_f32_dpp v196, v224, v20 row_newbcast:5 row_mask:0xf bank_mask:0xf
	v_fmac_f32_dpp v197, v225, v21 row_newbcast:5 row_mask:0xf bank_mask:0xf
	v_fmac_f32_dpp v198, v226, v22 row_newbcast:5 row_mask:0xf bank_mask:0xf
	v_fmac_f32_dpp v199, v227, v23 row_newbcast:5 row_mask:0xf bank_mask:0xf
	v_fmac_f32_dpp v196, v224, v24 row_newbcast:6 row_mask:0xf bank_mask:0xf
	v_fmac_f32_dpp v197, v225, v25 row_newbcast:6 row_mask:0xf bank_mask:0xf
	v_fmac_f32_dpp v198, v226, v26 row_newbcast:6 row_mask:0xf bank_mask:0xf
	v_fmac_f32_dpp v199, v227, v27 row_newbcast:6 row_mask:0xf bank_mask:0xf
	v_fmac_f32_dpp v196, v224, v28 row_newbcast:7 row_mask:0xf bank_mask:0xf
	v_fmac_f32_dpp v197, v225, v29 row_newbcast:7 row_mask:0xf bank_mask:0xf
	v_fmac_f32_dpp v198, v226, v30 row_newbcast:7 row_mask:0xf bank_mask:0xf
	v_fmac_f32_dpp v199, v227, v31 row_newbcast:7 row_mask:0xf bank_mask:0xf
	v_fmac_f32_dpp v196, v224, v32 row_newbcast:8 row_mask:0xf bank_mask:0xf
	v_fmac_f32_dpp v197, v225, v33 row_newbcast:8 row_mask:0xf bank_mask:0xf
	v_fmac_f32_dpp v198, v226, v34 row_newbcast:8 row_mask:0xf bank_mask:0xf
	v_fmac_f32_dpp v199, v227, v35 row_newbcast:8 row_mask:0xf bank_mask:0xf
	v_fmac_f32_dpp v196, v224, v36 row_newbcast:9 row_mask:0xf bank_mask:0xf
	v_fmac_f32_dpp v197, v225, v37 row_newbcast:9 row_mask:0xf bank_mask:0xf
	v_fmac_f32_dpp v198, v226, v38 row_newbcast:9 row_mask:0xf bank_mask:0xf
	v_fmac_f32_dpp v199, v227, v39 row_newbcast:9 row_mask:0xf bank_mask:0xf
	v_fmac_f32_dpp v196, v224, v40 row_newbcast:10 row_mask:0xf bank_mask:0xf
	v_fmac_f32_dpp v197, v225, v41 row_newbcast:10 row_mask:0xf bank_mask:0xf
	v_fmac_f32_dpp v198, v226, v42 row_newbcast:10 row_mask:0xf bank_mask:0xf
	v_fmac_f32_dpp v199, v227, v43 row_newbcast:10 row_mask:0xf bank_mask:0xf
	v_fmac_f32_dpp v196, v224, v44 row_newbcast:11 row_mask:0xf bank_mask:0xf
	v_fmac_f32_dpp v197, v225, v45 row_newbcast:11 row_mask:0xf bank_mask:0xf
	v_fmac_f32_dpp v198, v226, v46 row_newbcast:11 row_mask:0xf bank_mask:0xf
	v_fmac_f32_dpp v199, v227, v47 row_newbcast:11 row_mask:0xf bank_mask:0xf
	v_fmac_f32_dpp v196, v224, v48 row_newbcast:12 row_mask:0xf bank_mask:0xf
	v_fmac_f32_dpp v197, v225, v49 row_newbcast:12 row_mask:0xf bank_mask:0xf
	v_fmac_f32_dpp v198, v226, v50 row_newbcast:12 row_mask:0xf bank_mask:0xf
	v_fmac_f32_dpp v199, v227, v51 row_newbcast:12 row_mask:0xf bank_mask:0xf
	v_fmac_f32_dpp v196, v224, v52 row_newbcast:13 row_mask:0xf bank_mask:0xf
	v_fmac_f32_dpp v197, v225, v53 row_newbcast:13 row_mask:0xf bank_mask:0xf
	v_fmac_f32_dpp v198, v226, v54 row_newbcast:13 row_mask:0xf bank_mask:0xf
	v_fmac_f32_dpp v199, v227, v55 row_newbcast:13 row_mask:0xf bank_mask:0xf
	v_fmac_f32_dpp v196, v224, v56 row_newbcast:14 row_mask:0xf bank_mask:0xf
	v_fmac_f32_dpp v197, v225, v57 row_newbcast:14 row_mask:0xf bank_mask:0xf
	v_fmac_f32_dpp v198, v226, v58 row_newbcast:14 row_mask:0xf bank_mask:0xf
	v_fmac_f32_dpp v199, v227, v59 row_newbcast:14 row_mask:0xf bank_mask:0xf
	v_fmac_f32_dpp v196, v224, v60 row_newbcast:15 row_mask:0xf bank_mask:0xf
	v_fmac_f32_dpp v197, v225, v61 row_newbcast:15 row_mask:0xf bank_mask:0xf
	v_fmac_f32_dpp v198, v226, v62 row_newbcast:15 row_mask:0xf bank_mask:0xf
	v_fmac_f32_dpp v199, v227, v63 row_newbcast:15 row_mask:0xf bank_mask:0xf
	v_add_f32_e32 v196, v196, v197
	v_add_f32_e32 v198, v198, v199
	v_sub_f32_e64 v202, -v196, v198
	s_waitcnt lgkmcnt(0)
; #define SB __builtin_amdgcn_sched_barrier(0)
; #define LD1(set, s) { const int e_ = min((int)(s), LC - 1) * (int)stp; const unsigned s4_ = ob4 + (unsigned)(e_ * 4), s2_ = ob2 + (unsigned)(e_ * 2); set.w = LDX(rW, s4_); set.a = LDX(rA, s4_); set.b = LDX(rB, s4_); \
;             set.kw = __builtin_amdgcn_raw_buffer_load_b64(rK, lo8, s2_, 0); set.v = __builtin_amdgcn_raw_buffer_load_b16(rV, lo2, s2_, 0); }
; #define TOUCH1(set) asm volatile("" :: "v"(set.w), "v"(set.a), "v"(set.b), "v"(set.kw), "v"(set.v))
; #define ST1(set) { DERIVE_BK(set); float sd[4]; ScanK<0>::dot(S, set.a, sd); ScanK<0>::updS(S, set, -((sd[0] + sd[1]) + (sd[2] + sd[3])), __uint_as_float(set.v << 16)); }
; #define TOUCH1(set) asm volatile("" :: "v"(set.w), "v"(set.a), "v"(set.b))
;     static __device__ __forceinline__ void updS(float (&S)[64], const In1& in, float sa, float vv) {
;         float t0, t1, t2, t3;
;         asm volatile("v_mul_f32_dpp %0, %8, %21 row_newbcast:%22" DPPM "v_mul_f32_dpp %1, %9, %21 row_newbcast:%22" DPPM "v_mul_f32_dpp %2, %10, %21 row_newbcast:%22" DPPM "v_mul_f32_dpp %3, %11, %21 row_newbcast:%22" DPPM
;                      "v_fmac_f32_dpp %0, %12, %4 row_newbcast:%22" DPPM "v_fmac_f32_dpp %1, %13, %5 row_newbcast:%22" DPPM "v_fmac_f32_dpp %2, %14, %6 row_newbcast:%22" DPPM "v_fmac_f32_dpp %3, %15, %7 row_newbcast:%22" DPPM
;                      "v_fmac_f32_dpp %0, %16, %20 row_newbcast:%22" DPPM "v_fmac_f32_dpp %1, %17, %20 row_newbcast:%22" DPPM "v_fmac_f32_dpp %2, %18, %20 row_newbcast:%22" DPPM "v_fmac_f32_dpp %3, %19, %20 row_newbcast:%22" DPPM
;                      : "=&v"(t0), "=&v"(t1), "=&v"(t2), "=&v"(t3)
;                      : "v"(S[K]), "v"(S[K + 1]), "v"(S[K + 2]), "v"(S[K + 3]), "v"(in.kd[0]), "v"(in.kd[1]), "v"(in.kd[2]), "v"(in.kd[3]), "v"(in.w[0]), "v"(in.w[1]), "v"(in.w[2]), "v"(in.w[3]),
;                        "v"(in.b[0]), "v"(in.b[1]), "v"(in.b[2]), "v"(in.b[3]), "v"(sa), "v"(vv), "n"(N0));
;         S[K] = t0; S[K + 1] = t1; S[K + 2] = t2; S[K + 3] = t3;
;         if constexpr (K + 4 < 64) ScanK<K + 4>::updS(S, in, sa, vv);
;     }
; template <bool MIX> __device__ __forceinline__ void scan_pass1(const Params& p, int d, float* ldsf) {
;     ...
;             In1 i0, i1; LD1(i0, 0);
; #pragma unroll 1
;             for (int s = 0; s < LC; s += 2) { TOUCH1(i0); SB; LD1(i1, s + 1); SB; ST1(i0); TOUCH1(i1); SB; LD1(i0, s + 2); SB; ST1(i1); }
	s_nop 1
	v_mfma_f32_4x4x1_16b_f32 v[0:3], v64, v202, v[0:3]
	v_mfma_f32_4x4x1_16b_f32 v[4:7], v65, v202, v[4:7]
	v_mfma_f32_4x4x1_16b_f32 v[8:11], v66, v202, v[8:11]
	v_mfma_f32_4x4x1_16b_f32 v[12:15], v67, v202, v[12:15]
	v_mfma_f32_4x4x1_16b_f32 v[16:19], v68, v202, v[16:19]
	v_mfma_f32_4x4x1_16b_f32 v[20:23], v69, v202, v[20:23]
	v_mfma_f32_4x4x1_16b_f32 v[24:27], v70, v202, v[24:27]
	v_mfma_f32_4x4x1_16b_f32 v[28:31], v71, v202, v[28:31]
	v_mfma_f32_4x4x1_16b_f32 v[32:35], v72, v202, v[32:35]
	v_mfma_f32_4x4x1_16b_f32 v[36:39], v73, v202, v[36:39]
	v_mfma_f32_4x4x1_16b_f32 v[40:43], v74, v202, v[40:43]
	v_mfma_f32_4x4x1_16b_f32 v[44:47], v75, v202, v[44:47]
	v_mfma_f32_4x4x1_16b_f32 v[48:51], v76, v202, v[48:51]
	v_mfma_f32_4x4x1_16b_f32 v[52:55], v77, v202, v[52:55]
	v_mfma_f32_4x4x1_16b_f32 v[56:59], v78, v202, v[56:59]
	v_mfma_f32_4x4x1_16b_f32 v[60:63], v79, v202, v[60:63]
	v_mfma_f32_4x4x1_16b_f32 v[0:3], v80, v203, v[0:3]
	v_mfma_f32_4x4x1_16b_f32 v[4:7], v81, v203, v[4:7]
	v_mfma_f32_4x4x1_16b_f32 v[8:11], v82, v203, v[8:11]
	v_mfma_f32_4x4x1_16b_f32 v[12:15], v83, v203, v[12:15]
	v_mfma_f32_4x4x1_16b_f32 v[16:19], v84, v203, v[16:19]
	v_mfma_f32_4x4x1_16b_f32 v[20:23], v85, v203, v[20:23]
	v_mfma_f32_4x4x1_16b_f32 v[24:27], v86, v203, v[24:27]
	v_mfma_f32_4x4x1_16b_f32 v[28:31], v87, v203, v[28:31]
	v_mfma_f32_4x4x1_16b_f32 v[32:35], v88, v203, v[32:35]
	v_mfma_f32_4x4x1_16b_f32 v[36:39], v89, v203, v[36:39]
	v_mfma_f32_4x4x1_16b_f32 v[40:43], v90, v203, v[40:43]
	v_mfma_f32_4x4x1_16b_f32 v[44:47], v91, v203, v[44:47]
	v_mfma_f32_4x4x1_16b_f32 v[48:51], v92, v203, v[48:51]
	v_mfma_f32_4x4x1_16b_f32 v[52:55], v93, v203, v[52:55]
	v_mfma_f32_4x4x1_16b_f32 v[56:59], v94, v203, v[56:59]
	v_mfma_f32_4x4x1_16b_f32 v[60:63], v95, v203, v[60:63]
	s_waitcnt vmcnt(10)
	buffer_load_dwordx4 v[96:99], v232, s[64:67], s72 offen
	buffer_load_dwordx4 v[100:103], v233, s[64:67], s72 offen
	buffer_load_dwordx4 v[104:107], v234, s[64:67], s72 offen
	buffer_load_dwordx2 v[112:113], v236, s[64:67], s76 offen
	buffer_load_ushort v114, v237, s[64:67], s76 offen
	s_add_u32 s72, s72, 0x1000
	s_add_u32 s76, s76, 0x800
	v_pk_mul_f32 v[224:225], v[120:121], v[216:217]
	v_pk_mul_f32 v[226:227], v[122:123], v[218:219]
	v_pk_mul_f32 v[216:217], v[216:217], v[116:117]
	v_pk_mul_f32 v[218:219], v[218:219], v[118:119]
	v_pk_fma_f32 v[184:185], v[124:125], v[188:189], v[192:193]
	v_pk_fma_f32 v[186:187], v[126:127], v[190:191], v[194:195]
	v_pk_mul_f32 v[176:177], v[120:121], v[124:125]
	v_pk_mul_f32 v[178:179], v[122:123], v[126:127]
	v_rcp_f32_e32 v220, v216
	v_rcp_f32_e32 v221, v217
	v_rcp_f32_e32 v222, v218
	v_rcp_f32_e32 v223, v219
	v_lshlrev_b32_e32 v180, 16, v132
	v_and_b32_e32 v181, 0xffff0000, v132
	v_lshlrev_b32_e32 v182, 16, v133
	v_and_b32_e32 v183, 0xffff0000, v133
	v_pk_mul_f32 v[180:181], v[180:181], v[184:185]
	v_pk_mul_f32 v[182:183], v[182:183], v[186:187]
	v_lshlrev_b32_e32 v203, 16, v134
	v_pk_mul_f32 v[176:177], v[176:177], v[220:221]
	v_pk_mul_f32 v[178:179], v[178:179], v[222:223]
	v_pk_mul_f32 v[180:181], v[180:181], v[220:221]
	v_pk_mul_f32 v[182:183], v[182:183], v[222:223]
	ds_write2_b32 v208, v176, v177 offset0:0 offset1:16
	ds_write2_b32 v208, v178, v179 offset0:32 offset1:48
	ds_write2_b32 v208, v180, v181 offset0:64 offset1:80
	ds_write2_b32 v208, v182, v183 offset0:96 offset1:112
	ds_read_b128 v[64:67], v209 offset:0
	ds_read_b128 v[68:71], v209 offset:16
	ds_read_b128 v[72:75], v209 offset:32
	ds_read_b128 v[76:79], v209 offset:48
	ds_read_b128 v[80:83], v209 offset:256
	ds_read_b128 v[84:87], v209 offset:272
	ds_read_b128 v[88:91], v209 offset:288
	ds_read_b128 v[92:95], v209 offset:304
	v_mul_f32_dpp v196, v224, v0 row_newbcast:0 row_mask:0xf bank_mask:0xf
	v_mul_f32_dpp v197, v225, v1 row_newbcast:0 row_mask:0xf bank_mask:0xf
	v_mul_f32_dpp v198, v226, v2 row_newbcast:0 row_mask:0xf bank_mask:0xf
	v_mul_f32_dpp v199, v227, v3 row_newbcast:0 row_mask:0xf bank_mask:0xf
	v_fmac_f32_dpp v196, v224, v4 row_newbcast:1 row_mask:0xf bank_mask:0xf
	v_fmac_f32_dpp v197, v225, v5 row_newbcast:1 row_mask:0xf bank_mask:0xf
	v_fmac_f32_dpp v198, v226, v6 row_newbcast:1 row_mask:0xf bank_mask:0xf
	v_fmac_f32_dpp v199, v227, v7 row_newbcast:1 row_mask:0xf bank_mask:0xf
	v_fmac_f32_dpp v196, v224, v8 row_newbcast:2 row_mask:0xf bank_mask:0xf
	v_fmac_f32_dpp v197, v225, v9 row_newbcast:2 row_mask:0xf bank_mask:0xf
	v_fmac_f32_dpp v198, v226, v10 row_newbcast:2 row_mask:0xf bank_mask:0xf
	v_fmac_f32_dpp v199, v227, v11 row_newbcast:2 row_mask:0xf bank_mask:0xf
	v_fmac_f32_dpp v196, v224, v12 row_newbcast:3 row_mask:0xf bank_mask:0xf
	v_fmac_f32_dpp v197, v225, v13 row_newbcast:3 row_mask:0xf bank_mask:0xf
	v_fmac_f32_dpp v198, v226, v14 row_newbcast:3 row_mask:0xf bank_mask:0xf
	v_fmac_f32_dpp v199, v227, v15 row_newbcast:3 row_mask:0xf bank_mask:0xf
	v_fmac_f32_dpp v196, v224, v16 row_newbcast:4 row_mask:0xf bank_mask:0xf
	v_fmac_f32_dpp v197, v225, v17 row_newbcast:4 row_mask:0xf bank_mask:0xf
	v_fmac_f32_dpp v198, v226, v18 row_newbcast:4 row_mask:0xf bank_mask:0xf
	v_fmac_f32_dpp v199, v227, v19 row_newbcast:4 row_mask:0xf bank_mask:0xf
	v_fmac_f32_dpp v196, v224, v20 row_newbcast:5 row_mask:0xf bank_mask:0xf
	v_fmac_f32_dpp v197, v225, v21 row_newbcast:5 row_mask:0xf bank_mask:0xf
	v_fmac_f32_dpp v198, v226, v22 row_newbcast:5 row_mask:0xf bank_mask:0xf
	v_fmac_f32_dpp v199, v227, v23 row_newbcast:5 row_mask:0xf bank_mask:0xf
	v_fmac_f32_dpp v196, v224, v24 row_newbcast:6 row_mask:0xf bank_mask:0xf
	v_fmac_f32_dpp v197, v225, v25 row_newbcast:6 row_mask:0xf bank_mask:0xf
	v_fmac_f32_dpp v198, v226, v26 row_newbcast:6 row_mask:0xf bank_mask:0xf
;     static __device__ __forceinline__ void dot(const float (&S)[64], const f32x4& a, float (&s)[4]) {
;         if constexpr (K == 0) {
;             asm volatile("v_mul_f32_dpp %0, %4, %8 row_newbcast:%16" DPPM "v_mul_f32_dpp %1, %5, %9 row_newbcast:%16" DPPM "v_mul_f32_dpp %2, %6, %10 row_newbcast:%16" DPPM "v_mul_f32_dpp %3, %7, %11 row_newbcast:%16" DPPM
;                          "v_fmac_f32_dpp %0, %4, %12 row_newbcast:%17" DPPM "v_fmac_f32_dpp %1, %5, %13 row_newbcast:%17" DPPM "v_fmac_f32_dpp %2, %6, %14 row_newbcast:%17" DPPM "v_fmac_f32_dpp %3, %7, %15 row_newbcast:%17" DPPM
;                          : "=&v"(s[0]), "=&v"(s[1]), "=&v"(s[2]), "=&v"(s[3])
;                          : "v"(a[0]), "v"(a[1]), "v"(a[2]), "v"(a[3]), "v"(S[K]), "v"(S[K + 1]), "v"(S[K + 2]), "v"(S[K + 3]), "v"(S[K + 4]), "v"(S[K + 5]), "v"(S[K + 6]), "v"(S[K + 7]), "n"(N0), "n"(N1));
;         } else
;         asm volatile("v_fmac_f32_dpp %0, %4, %8 row_newbcast:%16" DPPM "v_fmac_f32_dpp %1, %5, %9 row_newbcast:%16" DPPM "v_fmac_f32_dpp %2, %6, %10 row_newbcast:%16" DPPM "v_fmac_f32_dpp %3, %7, %11 row_newbcast:%16" DPPM
;                      "v_fmac_f32_dpp %0, %4, %12 row_newbcast:%17" DPPM "v_fmac_f32_dpp %1, %5, %13 row_newbcast:%17" DPPM "v_fmac_f32_dpp %2, %6, %14 row_newbcast:%17" DPPM "v_fmac_f32_dpp %3, %7, %15 row_newbcast:%17" DPPM
;                      : "+v"(s[0]), "+v"(s[1]), "+v"(s[2]), "+v"(s[3])
;                      : "v"(a[0]), "v"(a[1]), "v"(a[2]), "v"(a[3]), "v"(S[K]), "v"(S[K + 1]), "v"(S[K + 2]), "v"(S[K + 3]), "v"(S[K + 4]), "v"(S[K + 5]), "v"(S[K + 6]), "v"(S[K + 7]), "n"(N0), "n"(N1));
;         if constexpr (K + 8 < 64) ScanK<K + 8>::dot(S, a, s);
;     }
;     static __device__ __forceinline__ void updS(float (&S)[64], const In1& in, float sa, float vv) {
;         float t0, t1, t2, t3;
;         asm volatile("v_mul_f32_dpp %0, %8, %21 row_newbcast:%22" DPPM "v_mul_f32_dpp %1, %9, %21 row_newbcast:%22" DPPM "v_mul_f32_dpp %2, %10, %21 row_newbcast:%22" DPPM "v_mul_f32_dpp %3, %11, %21 row_newbcast:%22" DPPM
;                      "v_fmac_f32_dpp %0, %12, %4 row_newbcast:%22" DPPM "v_fmac_f32_dpp %1, %13, %5 row_newbcast:%22" DPPM "v_fmac_f32_dpp %2, %14, %6 row_newbcast:%22" DPPM "v_fmac_f32_dpp %3, %15, %7 row_newbcast:%22" DPPM
	v_fmac_f32_dpp v199, v227, v27 row_newbcast:6 row_mask:0xf bank_mask:0xf
	v_fmac_f32_dpp v196, v224, v28 row_newbcast:7 row_mask:0xf bank_mask:0xf
	v_fmac_f32_dpp v197, v225, v29 row_newbcast:7 row_mask:0xf bank_mask:0xf
	v_fmac_f32_dpp v198, v226, v30 row_newbcast:7 row_mask:0xf bank_mask:0xf
	v_fmac_f32_dpp v199, v227, v31 row_newbcast:7 row_mask:0xf bank_mask:0xf
	v_fmac_f32_dpp v196, v224, v32 row_newbcast:8 row_mask:0xf bank_mask:0xf
	v_fmac_f32_dpp v197, v225, v33 row_newbcast:8 row_mask:0xf bank_mask:0xf
	v_fmac_f32_dpp v198, v226, v34 row_newbcast:8 row_mask:0xf bank_mask:0xf
	v_fmac_f32_dpp v199, v227, v35 row_newbcast:8 row_mask:0xf bank_mask:0xf
	v_fmac_f32_dpp v196, v224, v36 row_newbcast:9 row_mask:0xf bank_mask:0xf
	v_fmac_f32_dpp v197, v225, v37 row_newbcast:9 row_mask:0xf bank_mask:0xf
	v_fmac_f32_dpp v198, v226, v38 row_newbcast:9 row_mask:0xf bank_mask:0xf
	v_fmac_f32_dpp v199, v227, v39 row_newbcast:9 row_mask:0xf bank_mask:0xf
	v_fmac_f32_dpp v196, v224, v40 row_newbcast:10 row_mask:0xf bank_mask:0xf
	v_fmac_f32_dpp v197, v225, v41 row_newbcast:10 row_mask:0xf bank_mask:0xf
	v_fmac_f32_dpp v198, v226, v42 row_newbcast:10 row_mask:0xf bank_mask:0xf
	v_fmac_f32_dpp v199, v227, v43 row_newbcast:10 row_mask:0xf bank_mask:0xf
	v_fmac_f32_dpp v196, v224, v44 row_newbcast:11 row_mask:0xf bank_mask:0xf
	v_fmac_f32_dpp v197, v225, v45 row_newbcast:11 row_mask:0xf bank_mask:0xf
	v_fmac_f32_dpp v198, v226, v46 row_newbcast:11 row_mask:0xf bank_mask:0xf
	v_fmac_f32_dpp v199, v227, v47 row_newbcast:11 row_mask:0xf bank_mask:0xf
	v_fmac_f32_dpp v196, v224, v48 row_newbcast:12 row_mask:0xf bank_mask:0xf
	v_fmac_f32_dpp v197, v225, v49 row_newbcast:12 row_mask:0xf bank_mask:0xf
	v_fmac_f32_dpp v198, v226, v50 row_newbcast:12 row_mask:0xf bank_mask:0xf
	v_fmac_f32_dpp v199, v227, v51 row_newbcast:12 row_mask:0xf bank_mask:0xf
	v_fmac_f32_dpp v196, v224, v52 row_newbcast:13 row_mask:0xf bank_mask:0xf
	v_fmac_f32_dpp v197, v225, v53 row_newbcast:13 row_mask:0xf bank_mask:0xf
	v_fmac_f32_dpp v198, v226, v54 row_newbcast:13 row_mask:0xf bank_mask:0xf
	v_fmac_f32_dpp v199, v227, v55 row_newbcast:13 row_mask:0xf bank_mask:0xf
	v_fmac_f32_dpp v196, v224, v56 row_newbcast:14 row_mask:0xf bank_mask:0xf
	v_fmac_f32_dpp v197, v225, v57 row_newbcast:14 row_mask:0xf bank_mask:0xf
	v_fmac_f32_dpp v198, v226, v58 row_newbcast:14 row_mask:0xf bank_mask:0xf
	v_fmac_f32_dpp v199, v227, v59 row_newbcast:14 row_mask:0xf bank_mask:0xf
	v_fmac_f32_dpp v196, v224, v60 row_newbcast:15 row_mask:0xf bank_mask:0xf
	v_fmac_f32_dpp v197, v225, v61 row_newbcast:15 row_mask:0xf bank_mask:0xf
	v_fmac_f32_dpp v198, v226, v62 row_newbcast:15 row_mask:0xf bank_mask:0xf
	v_fmac_f32_dpp v199, v227, v63 row_newbcast:15 row_mask:0xf bank_mask:0xf
	v_add_f32_e32 v196, v196, v197
	v_add_f32_e32 v198, v198, v199
	v_sub_f32_e64 v202, -v196, v198
	s_waitcnt lgkmcnt(0)
	s_nop 1
	v_mfma_f32_4x4x1_16b_f32 v[0:3], v64, v202, v[0:3]
	v_mfma_f32_4x4x1_16b_f32 v[4:7], v65, v202, v[4:7]
	v_mfma_f32_4x4x1_16b_f32 v[8:11], v66, v202, v[8:11]
	v_mfma_f32_4x4x1_16b_f32 v[12:15], v67, v202, v[12:15]
	v_mfma_f32_4x4x1_16b_f32 v[16:19], v68, v202, v[16:19]
	v_mfma_f32_4x4x1_16b_f32 v[20:23], v69, v202, v[20:23]
	v_mfma_f32_4x4x1_16b_f32 v[24:27], v70, v202, v[24:27]
	v_mfma_f32_4x4x1_16b_f32 v[28:31], v71, v202, v[28:31]
	v_mfma_f32_4x4x1_16b_f32 v[32:35], v72, v202, v[32:35]
	v_mfma_f32_4x4x1_16b_f32 v[36:39], v73, v202, v[36:39]
	v_mfma_f32_4x4x1_16b_f32 v[40:43], v74, v202, v[40:43]
	v_mfma_f32_4x4x1_16b_f32 v[44:47], v75, v202, v[44:47]
	v_mfma_f32_4x4x1_16b_f32 v[48:51], v76, v202, v[48:51]
	v_mfma_f32_4x4x1_16b_f32 v[52:55], v77, v202, v[52:55]
	v_mfma_f32_4x4x1_16b_f32 v[56:59], v78, v202, v[56:59]
	v_mfma_f32_4x4x1_16b_f32 v[60:63], v79, v202, v[60:63]
	v_mfma_f32_4x4x1_16b_f32 v[0:3], v80, v203, v[0:3]
	v_mfma_f32_4x4x1_16b_f32 v[4:7], v81, v203, v[4:7]
	v_mfma_f32_4x4x1_16b_f32 v[8:11], v82, v203, v[8:11]
	v_mfma_f32_4x4x1_16b_f32 v[12:15], v83, v203, v[12:15]
	v_mfma_f32_4x4x1_16b_f32 v[16:19], v84, v203, v[16:19]
	v_mfma_f32_4x4x1_16b_f32 v[20:23], v85, v203, v[20:23]
	v_mfma_f32_4x4x1_16b_f32 v[24:27], v86, v203, v[24:27]
	v_mfma_f32_4x4x1_16b_f32 v[28:31], v87, v203, v[28:31]
	v_mfma_f32_4x4x1_16b_f32 v[32:35], v88, v203, v[32:35]
	v_mfma_f32_4x4x1_16b_f32 v[36:39], v89, v203, v[36:39]
	v_mfma_f32_4x4x1_16b_f32 v[40:43], v90, v203, v[40:43]
	v_mfma_f32_4x4x1_16b_f32 v[44:47], v91, v203, v[44:47]
	v_mfma_f32_4x4x1_16b_f32 v[48:51], v92, v203, v[48:51]
	v_mfma_f32_4x4x1_16b_f32 v[52:55], v93, v203, v[52:55]
	v_mfma_f32_4x4x1_16b_f32 v[56:59], v94, v203, v[56:59]
	v_mfma_f32_4x4x1_16b_f32 v[60:63], v95, v203, v[60:63]
	s_waitcnt vmcnt(10)
; #define SB __builtin_amdgcn_sched_barrier(0)
; #define LD1(set, s) { const int e_ = min((int)(s), LC - 1) * (int)stp; const unsigned s4_ = ob4 + (unsigned)(e_ * 4), s2_ = ob2 + (unsigned)(e_ * 2); set.w = LDX(rW, s4_); set.a = LDX(rA, s4_); set.b = LDX(rB, s4_); \
;             set.kw = __builtin_amdgcn_raw_buffer_load_b64(rK, lo8, s2_, 0); set.v = __builtin_amdgcn_raw_buffer_load_b16(rV, lo2, s2_, 0); }
; #define TOUCH1(set) asm volatile("" :: "v"(set.w), "v"(set.a), "v"(set.b), "v"(set.kw), "v"(set.v))
; #define ST1(set) { DERIVE_BK(set); float sd[4]; ScanK<0>::dot(S, set.a, sd); ScanK<0>::updS(S, set, -((sd[0] + sd[1]) + (sd[2] + sd[3])), __uint_as_float(set.v << 16)); }
; #define TOUCH1(set) asm volatile("" :: "v"(set.w), "v"(set.a), "v"(set.b))
;     static __device__ __forceinline__ void updS(float (&S)[64], const In1& in, float sa, float vv) {
;         float t0, t1, t2, t3;
;         asm volatile("v_mul_f32_dpp %0, %8, %21 row_newbcast:%22" DPPM "v_mul_f32_dpp %1, %9, %21 row_newbcast:%22" DPPM "v_mul_f32_dpp %2, %10, %21 row_newbcast:%22" DPPM "v_mul_f32_dpp %3, %11, %21 row_newbcast:%22" DPPM
;                      "v_fmac_f32_dpp %0, %12, %4 row_newbcast:%22" DPPM "v_fmac_f32_dpp %1, %13, %5 row_newbcast:%22" DPPM "v_fmac_f32_dpp %2, %14, %6 row_newbcast:%22" DPPM "v_fmac_f32_dpp %3, %15, %7 row_newbcast:%22" DPPM
;                      "v_fmac_f32_dpp %0, %16, %20 row_newbcast:%22" DPPM "v_fmac_f32_dpp %1, %17, %20 row_newbcast:%22" DPPM "v_fmac_f32_dpp %2, %18, %20 row_newbcast:%22" DPPM "v_fmac_f32_dpp %3, %19, %20 row_newbcast:%22" DPPM
;                      : "=&v"(t0), "=&v"(t1), "=&v"(t2), "=&v"(t3)
;                      : "v"(S[K]), "v"(S[K + 1]), "v"(S[K + 2]), "v"(S[K + 3]), "v"(in.kd[0]), "v"(in.kd[1]), "v"(in.kd[2]), "v"(in.kd[3]), "v"(in.w[0]), "v"(in.w[1]), "v"(in.w[2]), "v"(in.w[3]),
;                        "v"(in.b[0]), "v"(in.b[1]), "v"(in.b[2]), "v"(in.b[3]), "v"(sa), "v"(vv), "n"(N0));
;         S[K] = t0; S[K + 1] = t1; S[K + 2] = t2; S[K + 3] = t3;
;         if constexpr (K + 4 < 64) ScanK<K + 4>::updS(S, in, sa, vv);
;     }
; template <bool MIX> __device__ __forceinline__ void scan_pass1(const Params& p, int d, float* ldsf) {
;     ...
;             In1 i0, i1; LD1(i0, 0);
; #pragma unroll 1
;             for (int s = 0; s < LC; s += 2) { TOUCH1(i0); SB; LD1(i1, s + 1); SB; ST1(i0); TOUCH1(i1); SB; LD1(i0, s + 2); SB; ST1(i1); }
	buffer_load_dwordx4 v[116:119], v232, s[64:67], s72 offen
	buffer_load_dwordx4 v[120:123], v233, s[64:67], s72 offen
	buffer_load_dwordx4 v[124:127], v234, s[64:67], s72 offen
	buffer_load_dwordx2 v[132:133], v236, s[64:67], s76 offen
	buffer_load_ushort v134, v237, s[64:67], s76 offen
	s_add_u32 s72, s72, 0x1000
	s_add_u32 s76, s76, 0x800
	v_pk_mul_f32 v[224:225], v[140:141], v[216:217]
	v_pk_mul_f32 v[226:227], v[142:143], v[218:219]
	v_pk_mul_f32 v[216:217], v[216:217], v[136:137]
	v_pk_mul_f32 v[218:219], v[218:219], v[138:139]
	v_pk_fma_f32 v[184:185], v[144:145], v[188:189], v[192:193]
	v_pk_fma_f32 v[186:187], v[146:147], v[190:191], v[194:195]
	v_pk_mul_f32 v[176:177], v[140:141], v[144:145]
	v_pk_mul_f32 v[178:179], v[142:143], v[146:147]
	v_rcp_f32_e32 v220, v216
	v_rcp_f32_e32 v221, v217
	v_rcp_f32_e32 v222, v218
	v_rcp_f32_e32 v223, v219
	v_lshlrev_b32_e32 v180, 16, v152
	v_and_b32_e32 v181, 0xffff0000, v152
	v_lshlrev_b32_e32 v182, 16, v153
	v_and_b32_e32 v183, 0xffff0000, v153
	v_pk_mul_f32 v[180:181], v[180:181], v[184:185]
	v_pk_mul_f32 v[182:183], v[182:183], v[186:187]
	v_lshlrev_b32_e32 v203, 16, v154
	v_pk_mul_f32 v[176:177], v[176:177], v[220:221]
	v_pk_mul_f32 v[178:179], v[178:179], v[222:223]
	v_pk_mul_f32 v[180:181], v[180:181], v[220:221]
	v_pk_mul_f32 v[182:183], v[182:183], v[222:223]
	ds_write2_b32 v208, v176, v177 offset0:0 offset1:16
	ds_write2_b32 v208, v178, v179 offset0:32 offset1:48
	ds_write2_b32 v208, v180, v181 offset0:64 offset1:80
	ds_write2_b32 v208, v182, v183 offset0:96 offset1:112
	ds_read_b128 v[64:67], v209 offset:0
	ds_read_b128 v[68:71], v209 offset:16
	ds_read_b128 v[72:75], v209 offset:32
	ds_read_b128 v[76:79], v209 offset:48
	ds_read_b128 v[80:83], v209 offset:256
	ds_read_b128 v[84:87], v209 offset:272
	ds_read_b128 v[88:91], v209 offset:288
	ds_read_b128 v[92:95], v209 offset:304
	v_mul_f32_dpp v196, v224, v0 row_newbcast:0 row_mask:0xf bank_mask:0xf
	v_mul_f32_dpp v197, v225, v1 row_newbcast:0 row_mask:0xf bank_mask:0xf
	v_mul_f32_dpp v198, v226, v2 row_newbcast:0 row_mask:0xf bank_mask:0xf
	v_mul_f32_dpp v199, v227, v3 row_newbcast:0 row_mask:0xf bank_mask:0xf
	v_fmac_f32_dpp v196, v224, v4 row_newbcast:1 row_mask:0xf bank_mask:0xf
	v_fmac_f32_dpp v197, v225, v5 row_newbcast:1 row_mask:0xf bank_mask:0xf
	v_fmac_f32_dpp v198, v226, v6 row_newbcast:1 row_mask:0xf bank_mask:0xf
	v_fmac_f32_dpp v199, v227, v7 row_newbcast:1 row_mask:0xf bank_mask:0xf
	v_fmac_f32_dpp v196, v224, v8 row_newbcast:2 row_mask:0xf bank_mask:0xf
	v_fmac_f32_dpp v197, v225, v9 row_newbcast:2 row_mask:0xf bank_mask:0xf
	v_fmac_f32_dpp v198, v226, v10 row_newbcast:2 row_mask:0xf bank_mask:0xf
	v_fmac_f32_dpp v199, v227, v11 row_newbcast:2 row_mask:0xf bank_mask:0xf
	v_fmac_f32_dpp v196, v224, v12 row_newbcast:3 row_mask:0xf bank_mask:0xf
	v_fmac_f32_dpp v197, v225, v13 row_newbcast:3 row_mask:0xf bank_mask:0xf
	v_fmac_f32_dpp v198, v226, v14 row_newbcast:3 row_mask:0xf bank_mask:0xf
	v_fmac_f32_dpp v199, v227, v15 row_newbcast:3 row_mask:0xf bank_mask:0xf
	v_fmac_f32_dpp v196, v224, v16 row_newbcast:4 row_mask:0xf bank_mask:0xf
	v_fmac_f32_dpp v197, v225, v17 row_newbcast:4 row_mask:0xf bank_mask:0xf
	v_fmac_f32_dpp v198, v226, v18 row_newbcast:4 row_mask:0xf bank_mask:0xf
	v_fmac_f32_dpp v199, v227, v19 row_newbcast:4 row_mask:0xf bank_mask:0xf
	v_fmac_f32_dpp v196, v224, v20 row_newbcast:5 row_mask:0xf bank_mask:0xf
	v_fmac_f32_dpp v197, v225, v21 row_newbcast:5 row_mask:0xf bank_mask:0xf
	v_fmac_f32_dpp v198, v226, v22 row_newbcast:5 row_mask:0xf bank_mask:0xf
	v_fmac_f32_dpp v199, v227, v23 row_newbcast:5 row_mask:0xf bank_mask:0xf
	v_fmac_f32_dpp v196, v224, v24 row_newbcast:6 row_mask:0xf bank_mask:0xf
	v_fmac_f32_dpp v197, v225, v25 row_newbcast:6 row_mask:0xf bank_mask:0xf
	v_fmac_f32_dpp v198, v226, v26 row_newbcast:6 row_mask:0xf bank_mask:0xf
	v_fmac_f32_dpp v199, v227, v27 row_newbcast:6 row_mask:0xf bank_mask:0xf
	v_fmac_f32_dpp v196, v224, v28 row_newbcast:7 row_mask:0xf bank_mask:0xf
	v_fmac_f32_dpp v197, v225, v29 row_newbcast:7 row_mask:0xf bank_mask:0xf
	v_fmac_f32_dpp v198, v226, v30 row_newbcast:7 row_mask:0xf bank_mask:0xf
	v_fmac_f32_dpp v199, v227, v31 row_newbcast:7 row_mask:0xf bank_mask:0xf
	v_fmac_f32_dpp v196, v224, v32 row_newbcast:8 row_mask:0xf bank_mask:0xf
	v_fmac_f32_dpp v197, v225, v33 row_newbcast:8 row_mask:0xf bank_mask:0xf
	v_fmac_f32_dpp v198, v226, v34 row_newbcast:8 row_mask:0xf bank_mask:0xf
	v_fmac_f32_dpp v199, v227, v35 row_newbcast:8 row_mask:0xf bank_mask:0xf
	v_fmac_f32_dpp v196, v224, v36 row_newbcast:9 row_mask:0xf bank_mask:0xf
	v_fmac_f32_dpp v197, v225, v37 row_newbcast:9 row_mask:0xf bank_mask:0xf
	v_fmac_f32_dpp v198, v226, v38 row_newbcast:9 row_mask:0xf bank_mask:0xf
	v_fmac_f32_dpp v199, v227, v39 row_newbcast:9 row_mask:0xf bank_mask:0xf
	v_fmac_f32_dpp v196, v224, v40 row_newbcast:10 row_mask:0xf bank_mask:0xf
	v_fmac_f32_dpp v197, v225, v41 row_newbcast:10 row_mask:0xf bank_mask:0xf
	v_fmac_f32_dpp v198, v226, v42 row_newbcast:10 row_mask:0xf bank_mask:0xf
	v_fmac_f32_dpp v199, v227, v43 row_newbcast:10 row_mask:0xf bank_mask:0xf
	v_fmac_f32_dpp v196, v224, v44 row_newbcast:11 row_mask:0xf bank_mask:0xf
	v_fmac_f32_dpp v197, v225, v45 row_newbcast:11 row_mask:0xf bank_mask:0xf
	v_fmac_f32_dpp v198, v226, v46 row_newbcast:11 row_mask:0xf bank_mask:0xf
	v_fmac_f32_dpp v199, v227, v47 row_newbcast:11 row_mask:0xf bank_mask:0xf
	v_fmac_f32_dpp v196, v224, v48 row_newbcast:12 row_mask:0xf bank_mask:0xf
	v_fmac_f32_dpp v197, v225, v49 row_newbcast:12 row_mask:0xf bank_mask:0xf
	v_fmac_f32_dpp v198, v226, v50 row_newbcast:12 row_mask:0xf bank_mask:0xf
	v_fmac_f32_dpp v199, v227, v51 row_newbcast:12 row_mask:0xf bank_mask:0xf
	v_fmac_f32_dpp v196, v224, v52 row_newbcast:13 row_mask:0xf bank_mask:0xf
	v_fmac_f32_dpp v197, v225, v53 row_newbcast:13 row_mask:0xf bank_mask:0xf
	v_fmac_f32_dpp v198, v226, v54 row_newbcast:13 row_mask:0xf bank_mask:0xf
	v_fmac_f32_dpp v199, v227, v55 row_newbcast:13 row_mask:0xf bank_mask:0xf
	v_fmac_f32_dpp v196, v224, v56 row_newbcast:14 row_mask:0xf bank_mask:0xf
	v_fmac_f32_dpp v197, v225, v57 row_newbcast:14 row_mask:0xf bank_mask:0xf
	v_fmac_f32_dpp v198, v226, v58 row_newbcast:14 row_mask:0xf bank_mask:0xf
	v_fmac_f32_dpp v199, v227, v59 row_newbcast:14 row_mask:0xf bank_mask:0xf
	v_fmac_f32_dpp v196, v224, v60 row_newbcast:15 row_mask:0xf bank_mask:0xf
	v_fmac_f32_dpp v197, v225, v61 row_newbcast:15 row_mask:0xf bank_mask:0xf
	v_fmac_f32_dpp v198, v226, v62 row_newbcast:15 row_mask:0xf bank_mask:0xf
	v_fmac_f32_dpp v199, v227, v63 row_newbcast:15 row_mask:0xf bank_mask:0xf
	v_add_f32_e32 v196, v196, v197
	v_add_f32_e32 v198, v198, v199
	v_sub_f32_e64 v202, -v196, v198
	s_waitcnt lgkmcnt(0)
; #define SB __builtin_amdgcn_sched_barrier(0)
; #define LD1(set, s) { const int e_ = min((int)(s), LC - 1) * (int)stp; const unsigned s4_ = ob4 + (unsigned)(e_ * 4), s2_ = ob2 + (unsigned)(e_ * 2); set.w = LDX(rW, s4_); set.a = LDX(rA, s4_); set.b = LDX(rB, s4_); \
;             set.kw = __builtin_amdgcn_raw_buffer_load_b64(rK, lo8, s2_, 0); set.v = __builtin_amdgcn_raw_buffer_load_b16(rV, lo2, s2_, 0); }
; #define TOUCH1(set) asm volatile("" :: "v"(set.w), "v"(set.a), "v"(set.b), "v"(set.kw), "v"(set.v))
; #define ST1(set) { DERIVE_BK(set); float sd[4]; ScanK<0>::dot(S, set.a, sd); ScanK<0>::updS(S, set, -((sd[0] + sd[1]) + (sd[2] + sd[3])), __uint_as_float(set.v << 16)); }
; #define TOUCH1(set) asm volatile("" :: "v"(set.w), "v"(set.a), "v"(set.b))
;     static __device__ __forceinline__ void updS(float (&S)[64], const In1& in, float sa, float vv) {
;         float t0, t1, t2, t3;
;         asm volatile("v_mul_f32_dpp %0, %8, %21 row_newbcast:%22" DPPM "v_mul_f32_dpp %1, %9, %21 row_newbcast:%22" DPPM "v_mul_f32_dpp %2, %10, %21 row_newbcast:%22" DPPM "v_mul_f32_dpp %3, %11, %21 row_newbcast:%22" DPPM
;                      "v_fmac_f32_dpp %0, %12, %4 row_newbcast:%22" DPPM "v_fmac_f32_dpp %1, %13, %5 row_newbcast:%22" DPPM "v_fmac_f32_dpp %2, %14, %6 row_newbcast:%22" DPPM "v_fmac_f32_dpp %3, %15, %7 row_newbcast:%22" DPPM
;                      "v_fmac_f32_dpp %0, %16, %20 row_newbcast:%22" DPPM "v_fmac_f32_dpp %1, %17, %20 row_newbcast:%22" DPPM "v_fmac_f32_dpp %2, %18, %20 row_newbcast:%22" DPPM "v_fmac_f32_dpp %3, %19, %20 row_newbcast:%22" DPPM
;                      : "=&v"(t0), "=&v"(t1), "=&v"(t2), "=&v"(t3)
;                      : "v"(S[K]), "v"(S[K + 1]), "v"(S[K + 2]), "v"(S[K + 3]), "v"(in.kd[0]), "v"(in.kd[1]), "v"(in.kd[2]), "v"(in.kd[3]), "v"(in.w[0]), "v"(in.w[1]), "v"(in.w[2]), "v"(in.w[3]),
;                        "v"(in.b[0]), "v"(in.b[1]), "v"(in.b[2]), "v"(in.b[3]), "v"(sa), "v"(vv), "n"(N0));
;         S[K] = t0; S[K + 1] = t1; S[K + 2] = t2; S[K + 3] = t3;
;         if constexpr (K + 4 < 64) ScanK<K + 4>::updS(S, in, sa, vv);
;     }
; template <bool MIX> __device__ __forceinline__ void scan_pass1(const Params& p, int d, float* ldsf) {
;     ...
;             In1 i0, i1; LD1(i0, 0);
; #pragma unroll 1
;             for (int s = 0; s < LC; s += 2) { TOUCH1(i0); SB; LD1(i1, s + 1); SB; ST1(i0); TOUCH1(i1); SB; LD1(i0, s + 2); SB; ST1(i1); }
	s_nop 1
	v_mfma_f32_4x4x1_16b_f32 v[0:3], v64, v202, v[0:3]
	v_mfma_f32_4x4x1_16b_f32 v[4:7], v65, v202, v[4:7]
	v_mfma_f32_4x4x1_16b_f32 v[8:11], v66, v202, v[8:11]
	v_mfma_f32_4x4x1_16b_f32 v[12:15], v67, v202, v[12:15]
	v_mfma_f32_4x4x1_16b_f32 v[16:19], v68, v202, v[16:19]
	v_mfma_f32_4x4x1_16b_f32 v[20:23], v69, v202, v[20:23]
	v_mfma_f32_4x4x1_16b_f32 v[24:27], v70, v202, v[24:27]
	v_mfma_f32_4x4x1_16b_f32 v[28:31], v71, v202, v[28:31]
	v_mfma_f32_4x4x1_16b_f32 v[32:35], v72, v202, v[32:35]
	v_mfma_f32_4x4x1_16b_f32 v[36:39], v73, v202, v[36:39]
	v_mfma_f32_4x4x1_16b_f32 v[40:43], v74, v202, v[40:43]
	v_mfma_f32_4x4x1_16b_f32 v[44:47], v75, v202, v[44:47]
	v_mfma_f32_4x4x1_16b_f32 v[48:51], v76, v202, v[48:51]
	v_mfma_f32_4x4x1_16b_f32 v[52:55], v77, v202, v[52:55]
	v_mfma_f32_4x4x1_16b_f32 v[56:59], v78, v202, v[56:59]
	v_mfma_f32_4x4x1_16b_f32 v[60:63], v79, v202, v[60:63]
	v_mfma_f32_4x4x1_16b_f32 v[0:3], v80, v203, v[0:3]
	v_mfma_f32_4x4x1_16b_f32 v[4:7], v81, v203, v[4:7]
	v_mfma_f32_4x4x1_16b_f32 v[8:11], v82, v203, v[8:11]
	v_mfma_f32_4x4x1_16b_f32 v[12:15], v83, v203, v[12:15]
	v_mfma_f32_4x4x1_16b_f32 v[16:19], v84, v203, v[16:19]
	v_mfma_f32_4x4x1_16b_f32 v[20:23], v85, v203, v[20:23]
	v_mfma_f32_4x4x1_16b_f32 v[24:27], v86, v203, v[24:27]
	v_mfma_f32_4x4x1_16b_f32 v[28:31], v87, v203, v[28:31]
	v_mfma_f32_4x4x1_16b_f32 v[32:35], v88, v203, v[32:35]
	v_mfma_f32_4x4x1_16b_f32 v[36:39], v89, v203, v[36:39]
	v_mfma_f32_4x4x1_16b_f32 v[40:43], v90, v203, v[40:43]
	v_mfma_f32_4x4x1_16b_f32 v[44:47], v91, v203, v[44:47]
	v_mfma_f32_4x4x1_16b_f32 v[48:51], v92, v203, v[48:51]
	v_mfma_f32_4x4x1_16b_f32 v[52:55], v93, v203, v[52:55]
	v_mfma_f32_4x4x1_16b_f32 v[56:59], v94, v203, v[56:59]
	v_mfma_f32_4x4x1_16b_f32 v[60:63], v95, v203, v[60:63]
	s_waitcnt vmcnt(10)
	buffer_load_dwordx4 v[136:139], v232, s[64:67], s72 offen
	buffer_load_dwordx4 v[140:143], v233, s[64:67], s72 offen
	buffer_load_dwordx4 v[144:147], v234, s[64:67], s72 offen
	buffer_load_dwordx2 v[152:153], v236, s[64:67], s76 offen
	buffer_load_ushort v154, v237, s[64:67], s76 offen
	s_add_u32 s72, s72, 0x1000
	s_add_u32 s76, s76, 0x800
	v_pk_mul_f32 v[224:225], v[160:161], v[216:217]
	v_pk_mul_f32 v[226:227], v[162:163], v[218:219]
	v_pk_mul_f32 v[216:217], v[216:217], v[156:157]
	v_pk_mul_f32 v[218:219], v[218:219], v[158:159]
	v_pk_fma_f32 v[184:185], v[164:165], v[188:189], v[192:193]
	v_pk_fma_f32 v[186:187], v[166:167], v[190:191], v[194:195]
	v_pk_mul_f32 v[176:177], v[160:161], v[164:165]
	v_pk_mul_f32 v[178:179], v[162:163], v[166:167]
	v_rcp_f32_e32 v220, v216
	v_rcp_f32_e32 v221, v217
	v_rcp_f32_e32 v222, v218
	v_rcp_f32_e32 v223, v219
	v_lshlrev_b32_e32 v180, 16, v172
	v_and_b32_e32 v181, 0xffff0000, v172
	v_lshlrev_b32_e32 v182, 16, v173
	v_and_b32_e32 v183, 0xffff0000, v173
	v_pk_mul_f32 v[180:181], v[180:181], v[184:185]
	v_pk_mul_f32 v[182:183], v[182:183], v[186:187]
	v_lshlrev_b32_e32 v203, 16, v174
	v_pk_mul_f32 v[176:177], v[176:177], v[220:221]
	v_pk_mul_f32 v[178:179], v[178:179], v[222:223]
	v_pk_mul_f32 v[180:181], v[180:181], v[220:221]
	v_pk_mul_f32 v[182:183], v[182:183], v[222:223]
	ds_write2_b32 v208, v176, v177 offset0:0 offset1:16
	ds_write2_b32 v208, v178, v179 offset0:32 offset1:48
	ds_write2_b32 v208, v180, v181 offset0:64 offset1:80
	ds_write2_b32 v208, v182, v183 offset0:96 offset1:112
	ds_read_b128 v[64:67], v209 offset:0
	ds_read_b128 v[68:71], v209 offset:16
	ds_read_b128 v[72:75], v209 offset:32
	ds_read_b128 v[76:79], v209 offset:48
	ds_read_b128 v[80:83], v209 offset:256
	ds_read_b128 v[84:87], v209 offset:272
	ds_read_b128 v[88:91], v209 offset:288
	ds_read_b128 v[92:95], v209 offset:304
	v_mul_f32_dpp v196, v224, v0 row_newbcast:0 row_mask:0xf bank_mask:0xf
	v_mul_f32_dpp v197, v225, v1 row_newbcast:0 row_mask:0xf bank_mask:0xf
	v_mul_f32_dpp v198, v226, v2 row_newbcast:0 row_mask:0xf bank_mask:0xf
	v_mul_f32_dpp v199, v227, v3 row_newbcast:0 row_mask:0xf bank_mask:0xf
	v_fmac_f32_dpp v196, v224, v4 row_newbcast:1 row_mask:0xf bank_mask:0xf
	v_fmac_f32_dpp v197, v225, v5 row_newbcast:1 row_mask:0xf bank_mask:0xf
	v_fmac_f32_dpp v198, v226, v6 row_newbcast:1 row_mask:0xf bank_mask:0xf
	v_fmac_f32_dpp v199, v227, v7 row_newbcast:1 row_mask:0xf bank_mask:0xf
	v_fmac_f32_dpp v196, v224, v8 row_newbcast:2 row_mask:0xf bank_mask:0xf
	v_fmac_f32_dpp v197, v225, v9 row_newbcast:2 row_mask:0xf bank_mask:0xf
	v_fmac_f32_dpp v198, v226, v10 row_newbcast:2 row_mask:0xf bank_mask:0xf
	v_fmac_f32_dpp v199, v227, v11 row_newbcast:2 row_mask:0xf bank_mask:0xf
	v_fmac_f32_dpp v196, v224, v12 row_newbcast:3 row_mask:0xf bank_mask:0xf
	v_fmac_f32_dpp v197, v225, v13 row_newbcast:3 row_mask:0xf bank_mask:0xf
	v_fmac_f32_dpp v198, v226, v14 row_newbcast:3 row_mask:0xf bank_mask:0xf
	v_fmac_f32_dpp v199, v227, v15 row_newbcast:3 row_mask:0xf bank_mask:0xf
	v_fmac_f32_dpp v196, v224, v16 row_newbcast:4 row_mask:0xf bank_mask:0xf
	v_fmac_f32_dpp v197, v225, v17 row_newbcast:4 row_mask:0xf bank_mask:0xf
	v_fmac_f32_dpp v198, v226, v18 row_newbcast:4 row_mask:0xf bank_mask:0xf
	v_fmac_f32_dpp v199, v227, v19 row_newbcast:4 row_mask:0xf bank_mask:0xf
	v_fmac_f32_dpp v196, v224, v20 row_newbcast:5 row_mask:0xf bank_mask:0xf
	v_fmac_f32_dpp v197, v225, v21 row_newbcast:5 row_mask:0xf bank_mask:0xf
;     static __device__ __forceinline__ void dot(const float (&S)[64], const f32x4& a, float (&s)[4]) {
;         if constexpr (K == 0) {
;             asm volatile("v_mul_f32_dpp %0, %4, %8 row_newbcast:%16" DPPM "v_mul_f32_dpp %1, %5, %9 row_newbcast:%16" DPPM "v_mul_f32_dpp %2, %6, %10 row_newbcast:%16" DPPM "v_mul_f32_dpp %3, %7, %11 row_newbcast:%16" DPPM
;                          "v_fmac_f32_dpp %0, %4, %12 row_newbcast:%17" DPPM "v_fmac_f32_dpp %1, %5, %13 row_newbcast:%17" DPPM "v_fmac_f32_dpp %2, %6, %14 row_newbcast:%17" DPPM "v_fmac_f32_dpp %3, %7, %15 row_newbcast:%17" DPPM
;                          : "=&v"(s[0]), "=&v"(s[1]), "=&v"(s[2]), "=&v"(s[3])
;                          : "v"(a[0]), "v"(a[1]), "v"(a[2]), "v"(a[3]), "v"(S[K]), "v"(S[K + 1]), "v"(S[K + 2]), "v"(S[K + 3]), "v"(S[K + 4]), "v"(S[K + 5]), "v"(S[K + 6]), "v"(S[K + 7]), "n"(N0), "n"(N1));
;         } else
;         asm volatile("v_fmac_f32_dpp %0, %4, %8 row_newbcast:%16" DPPM "v_fmac_f32_dpp %1, %5, %9 row_newbcast:%16" DPPM "v_fmac_f32_dpp %2, %6, %10 row_newbcast:%16" DPPM "v_fmac_f32_dpp %3, %7, %11 row_newbcast:%16" DPPM
;                      "v_fmac_f32_dpp %0, %4, %12 row_newbcast:%17" DPPM "v_fmac_f32_dpp %1, %5, %13 row_newbcast:%17" DPPM "v_fmac_f32_dpp %2, %6, %14 row_newbcast:%17" DPPM "v_fmac_f32_dpp %3, %7, %15 row_newbcast:%17" DPPM
;                      : "+v"(s[0]), "+v"(s[1]), "+v"(s[2]), "+v"(s[3])
;                      : "v"(a[0]), "v"(a[1]), "v"(a[2]), "v"(a[3]), "v"(S[K]), "v"(S[K + 1]), "v"(S[K + 2]), "v"(S[K + 3]), "v"(S[K + 4]), "v"(S[K + 5]), "v"(S[K + 6]), "v"(S[K + 7]), "n"(N0), "n"(N1));
;         if constexpr (K + 8 < 64) ScanK<K + 8>::dot(S, a, s);
;     }
;     static __device__ __forceinline__ void updS(float (&S)[64], const In1& in, float sa, float vv) {
;         float t0, t1, t2, t3;
;         asm volatile("v_mul_f32_dpp %0, %8, %21 row_newbcast:%22" DPPM "v_mul_f32_dpp %1, %9, %21 row_newbcast:%22" DPPM "v_mul_f32_dpp %2, %10, %21 row_newbcast:%22" DPPM "v_mul_f32_dpp %3, %11, %21 row_newbcast:%22" DPPM
;                      "v_fmac_f32_dpp %0, %12, %4 row_newbcast:%22" DPPM "v_fmac_f32_dpp %1, %13, %5 row_newbcast:%22" DPPM "v_fmac_f32_dpp %2, %14, %6 row_newbcast:%22" DPPM "v_fmac_f32_dpp %3, %15, %7 row_newbcast:%22" DPPM
	v_fmac_f32_dpp v198, v226, v22 row_newbcast:5 row_mask:0xf bank_mask:0xf
	v_fmac_f32_dpp v199, v227, v23 row_newbcast:5 row_mask:0xf bank_mask:0xf
	v_fmac_f32_dpp v196, v224, v24 row_newbcast:6 row_mask:0xf bank_mask:0xf
	v_fmac_f32_dpp v197, v225, v25 row_newbcast:6 row_mask:0xf bank_mask:0xf
	v_fmac_f32_dpp v198, v226, v26 row_newbcast:6 row_mask:0xf bank_mask:0xf
	v_fmac_f32_dpp v199, v227, v27 row_newbcast:6 row_mask:0xf bank_mask:0xf
	v_fmac_f32_dpp v196, v224, v28 row_newbcast:7 row_mask:0xf bank_mask:0xf
	v_fmac_f32_dpp v197, v225, v29 row_newbcast:7 row_mask:0xf bank_mask:0xf
	v_fmac_f32_dpp v198, v226, v30 row_newbcast:7 row_mask:0xf bank_mask:0xf
	v_fmac_f32_dpp v199, v227, v31 row_newbcast:7 row_mask:0xf bank_mask:0xf
	v_fmac_f32_dpp v196, v224, v32 row_newbcast:8 row_mask:0xf bank_mask:0xf
	v_fmac_f32_dpp v197, v225, v33 row_newbcast:8 row_mask:0xf bank_mask:0xf
	v_fmac_f32_dpp v198, v226, v34 row_newbcast:8 row_mask:0xf bank_mask:0xf
	v_fmac_f32_dpp v199, v227, v35 row_newbcast:8 row_mask:0xf bank_mask:0xf
	v_fmac_f32_dpp v196, v224, v36 row_newbcast:9 row_mask:0xf bank_mask:0xf
	v_fmac_f32_dpp v197, v225, v37 row_newbcast:9 row_mask:0xf bank_mask:0xf
	v_fmac_f32_dpp v198, v226, v38 row_newbcast:9 row_mask:0xf bank_mask:0xf
	v_fmac_f32_dpp v199, v227, v39 row_newbcast:9 row_mask:0xf bank_mask:0xf
	v_fmac_f32_dpp v196, v224, v40 row_newbcast:10 row_mask:0xf bank_mask:0xf
	v_fmac_f32_dpp v197, v225, v41 row_newbcast:10 row_mask:0xf bank_mask:0xf
	v_fmac_f32_dpp v198, v226, v42 row_newbcast:10 row_mask:0xf bank_mask:0xf
	v_fmac_f32_dpp v199, v227, v43 row_newbcast:10 row_mask:0xf bank_mask:0xf
	v_fmac_f32_dpp v196, v224, v44 row_newbcast:11 row_mask:0xf bank_mask:0xf
	v_fmac_f32_dpp v197, v225, v45 row_newbcast:11 row_mask:0xf bank_mask:0xf
	v_fmac_f32_dpp v198, v226, v46 row_newbcast:11 row_mask:0xf bank_mask:0xf
	v_fmac_f32_dpp v199, v227, v47 row_newbcast:11 row_mask:0xf bank_mask:0xf
	v_fmac_f32_dpp v196, v224, v48 row_newbcast:12 row_mask:0xf bank_mask:0xf
	v_fmac_f32_dpp v197, v225, v49 row_newbcast:12 row_mask:0xf bank_mask:0xf
	v_fmac_f32_dpp v198, v226, v50 row_newbcast:12 row_mask:0xf bank_mask:0xf
	v_fmac_f32_dpp v199, v227, v51 row_newbcast:12 row_mask:0xf bank_mask:0xf
	v_fmac_f32_dpp v196, v224, v52 row_newbcast:13 row_mask:0xf bank_mask:0xf
	v_fmac_f32_dpp v197, v225, v53 row_newbcast:13 row_mask:0xf bank_mask:0xf
	v_fmac_f32_dpp v198, v226, v54 row_newbcast:13 row_mask:0xf bank_mask:0xf
	v_fmac_f32_dpp v199, v227, v55 row_newbcast:13 row_mask:0xf bank_mask:0xf
	v_fmac_f32_dpp v196, v224, v56 row_newbcast:14 row_mask:0xf bank_mask:0xf
	v_fmac_f32_dpp v197, v225, v57 row_newbcast:14 row_mask:0xf bank_mask:0xf
	v_fmac_f32_dpp v198, v226, v58 row_newbcast:14 row_mask:0xf bank_mask:0xf
	v_fmac_f32_dpp v199, v227, v59 row_newbcast:14 row_mask:0xf bank_mask:0xf
	v_fmac_f32_dpp v196, v224, v60 row_newbcast:15 row_mask:0xf bank_mask:0xf
	v_fmac_f32_dpp v197, v225, v61 row_newbcast:15 row_mask:0xf bank_mask:0xf
	v_fmac_f32_dpp v198, v226, v62 row_newbcast:15 row_mask:0xf bank_mask:0xf
	v_fmac_f32_dpp v199, v227, v63 row_newbcast:15 row_mask:0xf bank_mask:0xf
	v_add_f32_e32 v196, v196, v197
	v_add_f32_e32 v198, v198, v199
	v_sub_f32_e64 v202, -v196, v198
	s_waitcnt lgkmcnt(0)
	s_nop 1
	v_mfma_f32_4x4x1_16b_f32 v[0:3], v64, v202, v[0:3]
	v_mfma_f32_4x4x1_16b_f32 v[4:7], v65, v202, v[4:7]
	v_mfma_f32_4x4x1_16b_f32 v[8:11], v66, v202, v[8:11]
	v_mfma_f32_4x4x1_16b_f32 v[12:15], v67, v202, v[12:15]
	v_mfma_f32_4x4x1_16b_f32 v[16:19], v68, v202, v[16:19]
	v_mfma_f32_4x4x1_16b_f32 v[20:23], v69, v202, v[20:23]
	v_mfma_f32_4x4x1_16b_f32 v[24:27], v70, v202, v[24:27]
	v_mfma_f32_4x4x1_16b_f32 v[28:31], v71, v202, v[28:31]
	v_mfma_f32_4x4x1_16b_f32 v[32:35], v72, v202, v[32:35]
	v_mfma_f32_4x4x1_16b_f32 v[36:39], v73, v202, v[36:39]
	v_mfma_f32_4x4x1_16b_f32 v[40:43], v74, v202, v[40:43]
	v_mfma_f32_4x4x1_16b_f32 v[44:47], v75, v202, v[44:47]
	v_mfma_f32_4x4x1_16b_f32 v[48:51], v76, v202, v[48:51]
	v_mfma_f32_4x4x1_16b_f32 v[52:55], v77, v202, v[52:55]
	v_mfma_f32_4x4x1_16b_f32 v[56:59], v78, v202, v[56:59]
	v_mfma_f32_4x4x1_16b_f32 v[60:63], v79, v202, v[60:63]
	v_mfma_f32_4x4x1_16b_f32 v[0:3], v80, v203, v[0:3]
	v_mfma_f32_4x4x1_16b_f32 v[4:7], v81, v203, v[4:7]
	v_mfma_f32_4x4x1_16b_f32 v[8:11], v82, v203, v[8:11]
	v_mfma_f32_4x4x1_16b_f32 v[12:15], v83, v203, v[12:15]
	v_mfma_f32_4x4x1_16b_f32 v[16:19], v84, v203, v[16:19]
	v_mfma_f32_4x4x1_16b_f32 v[20:23], v85, v203, v[20:23]
	v_mfma_f32_4x4x1_16b_f32 v[24:27], v86, v203, v[24:27]
	v_mfma_f32_4x4x1_16b_f32 v[28:31], v87, v203, v[28:31]
	v_mfma_f32_4x4x1_16b_f32 v[32:35], v88, v203, v[32:35]
	v_mfma_f32_4x4x1_16b_f32 v[36:39], v89, v203, v[36:39]
	v_mfma_f32_4x4x1_16b_f32 v[40:43], v90, v203, v[40:43]
	v_mfma_f32_4x4x1_16b_f32 v[44:47], v91, v203, v[44:47]
	v_mfma_f32_4x4x1_16b_f32 v[48:51], v92, v203, v[48:51]
	v_mfma_f32_4x4x1_16b_f32 v[52:55], v93, v203, v[52:55]
	v_mfma_f32_4x4x1_16b_f32 v[56:59], v94, v203, v[56:59]
	v_mfma_f32_4x4x1_16b_f32 v[60:63], v95, v203, v[60:63]
	s_sub_u32 s83, s83, 1
	s_cmp_eq_u32 s83, 0
	s_cbranch_scc1 .Lmy_p1d0_ldone_s
	s_and_b32 s9, s83, 7
	s_cmp_eq_u32 s9, 0
	s_cbranch_scc1 .Lmy_p1d0_renorm_s
	s_branch .Lmy_p1d0_loop_s

; #define SB __builtin_amdgcn_sched_barrier(0)
; #define LD1(set, s) { const int e_ = min((int)(s), LC - 1) * (int)stp; const unsigned s4_ = ob4 + (unsigned)(e_ * 4), s2_ = ob2 + (unsigned)(e_ * 2); set.w = LDX(rW, s4_); set.a = LDX(rA, s4_); set.b = LDX(rB, s4_); \
;             set.kw = __builtin_amdgcn_raw_buffer_load_b64(rK, lo8, s2_, 0); set.v = __builtin_amdgcn_raw_buffer_load_b16(rV, lo2, s2_, 0); }
; #define TOUCH1(set) asm volatile("" :: "v"(set.w), "v"(set.a), "v"(set.b), "v"(set.kw), "v"(set.v))
; #define ST1(set) { DERIVE_BK(set); float sd[4]; ScanK<0>::dot(S, set.a, sd); ScanK<0>::updS(S, set, -((sd[0] + sd[1]) + (sd[2] + sd[3])), __uint_as_float(set.v << 16)); }
; #define LD1(set, s) { const int e_ = min((int)(s), LC - 1) * (int)stp; const unsigned s4_ = ob4 + (unsigned)(e_ * 4); set.w = LDX(rW, s4_); set.a = LDX(rA, s4_); set.b = LDX(rB, s4_); }
; #define TOUCH1(set) asm volatile("" :: "v"(set.w), "v"(set.a), "v"(set.b))
; #define ST1(set) { DERIVE_B(set); float sd[4]; ScanK<0>::dot(S, set.a, sd); ScanK<0>::updP(S, set, -((sd[0] + sd[1]) + (sd[2] + sd[3]))); }
; template <bool MIX> __device__ __forceinline__ void scan_pass1(const Params& p, int d, float* ldsf) {
;     ...
;             for (int i = 0; i < 64; ++i) S[i] = (ln == i) ? 1.f : 0.f;
;     ...
;             In1 i0, i1; LD1(i0, 0);
; #pragma unroll 1
;             for (int s = 0; s < LC; s += 2) { TOUCH1(i0); SB; LD1(i1, s + 1); SB; ST1(i0); TOUCH1(i1); SB; LD1(i0, s + 2); SB; ST1(i1); }
.Lmy_p1d0_pitem:
	buffer_load_dwordx4 v[96:99], v232, s[64:67], s72 offen
	buffer_load_dwordx4 v[100:103], v233, s[64:67], s72 offen
	buffer_load_dwordx4 v[104:107], v234, s[64:67], s72 offen
	s_add_u32 s72, s72, 0x1000
	buffer_load_dwordx4 v[116:119], v232, s[64:67], s72 offen
	buffer_load_dwordx4 v[120:123], v233, s[64:67], s72 offen
	buffer_load_dwordx4 v[124:127], v234, s[64:67], s72 offen
	s_add_u32 s72, s72, 0x1000
	buffer_load_dwordx4 v[136:139], v232, s[64:67], s72 offen
	buffer_load_dwordx4 v[140:143], v233, s[64:67], s72 offen
	buffer_load_dwordx4 v[144:147], v234, s[64:67], s72 offen
	s_add_u32 s72, s72, 0x1000
	v_cmp_eq_u32_e32 vcc, 0, v212
	s_nop 1
	v_cndmask_b32_e32 v0, 0, v213, vcc
	v_cmp_eq_u32_e32 vcc, 1, v212
	s_nop 1
	v_cndmask_b32_e32 v1, 0, v213, vcc
	v_cmp_eq_u32_e32 vcc, 2, v212
	s_nop 1
	v_cndmask_b32_e32 v2, 0, v213, vcc
	v_cmp_eq_u32_e32 vcc, 3, v212
	s_nop 1
	v_cndmask_b32_e32 v3, 0, v213, vcc
	v_cmp_eq_u32_e32 vcc, 4, v212
	s_nop 1
	v_cndmask_b32_e32 v4, 0, v213, vcc
	v_cmp_eq_u32_e32 vcc, 5, v212
	s_nop 1
	v_cndmask_b32_e32 v5, 0, v213, vcc
	v_cmp_eq_u32_e32 vcc, 6, v212
	s_nop 1
	v_cndmask_b32_e32 v6, 0, v213, vcc
	v_cmp_eq_u32_e32 vcc, 7, v212
	s_nop 1
	v_cndmask_b32_e32 v7, 0, v213, vcc
	v_cmp_eq_u32_e32 vcc, 8, v212
	s_nop 1
	v_cndmask_b32_e32 v8, 0, v213, vcc
	v_cmp_eq_u32_e32 vcc, 9, v212
	s_nop 1
	v_cndmask_b32_e32 v9, 0, v213, vcc
	v_cmp_eq_u32_e32 vcc, 10, v212
	s_nop 1
	v_cndmask_b32_e32 v10, 0, v213, vcc
	v_cmp_eq_u32_e32 vcc, 11, v212
	s_nop 1
	v_cndmask_b32_e32 v11, 0, v213, vcc
	v_cmp_eq_u32_e32 vcc, 12, v212
	s_nop 1
	v_cndmask_b32_e32 v12, 0, v213, vcc
	v_cmp_eq_u32_e32 vcc, 13, v212
	s_nop 1
	v_cndmask_b32_e32 v13, 0, v213, vcc
	v_cmp_eq_u32_e32 vcc, 14, v212
	s_nop 1
	v_cndmask_b32_e32 v14, 0, v213, vcc
	v_cmp_eq_u32_e32 vcc, 15, v212
	s_nop 1
	v_cndmask_b32_e32 v15, 0, v213, vcc
	v_cmp_eq_u32_e32 vcc, 16, v212
	s_nop 1
	v_cndmask_b32_e32 v16, 0, v213, vcc
	v_cmp_eq_u32_e32 vcc, 17, v212
	s_nop 1
	v_cndmask_b32_e32 v17, 0, v213, vcc
	v_cmp_eq_u32_e32 vcc, 18, v212
	s_nop 1
	v_cndmask_b32_e32 v18, 0, v213, vcc
	v_cmp_eq_u32_e32 vcc, 19, v212
	s_nop 1
	v_cndmask_b32_e32 v19, 0, v213, vcc
	v_cmp_eq_u32_e32 vcc, 20, v212
	s_nop 1
	v_cndmask_b32_e32 v20, 0, v213, vcc
	v_cmp_eq_u32_e32 vcc, 21, v212
	s_nop 1
	v_cndmask_b32_e32 v21, 0, v213, vcc
	v_cmp_eq_u32_e32 vcc, 22, v212
	s_nop 1
	v_cndmask_b32_e32 v22, 0, v213, vcc
	v_cmp_eq_u32_e32 vcc, 23, v212
	s_nop 1
	v_cndmask_b32_e32 v23, 0, v213, vcc
	v_cmp_eq_u32_e32 vcc, 24, v212
	s_nop 1
	v_cndmask_b32_e32 v24, 0, v213, vcc
	v_cmp_eq_u32_e32 vcc, 25, v212
	s_nop 1
	v_cndmask_b32_e32 v25, 0, v213, vcc
	v_cmp_eq_u32_e32 vcc, 26, v212
	s_nop 1
	v_cndmask_b32_e32 v26, 0, v213, vcc
	v_cmp_eq_u32_e32 vcc, 27, v212
	s_nop 1
	v_cndmask_b32_e32 v27, 0, v213, vcc
	v_cmp_eq_u32_e32 vcc, 28, v212
	s_nop 1
	v_cndmask_b32_e32 v28, 0, v213, vcc
	v_cmp_eq_u32_e32 vcc, 29, v212
	s_nop 1
	v_cndmask_b32_e32 v29, 0, v213, vcc
	v_cmp_eq_u32_e32 vcc, 30, v212
	s_nop 1
	v_cndmask_b32_e32 v30, 0, v213, vcc
	v_cmp_eq_u32_e32 vcc, 31, v212
	s_nop 1
	v_cndmask_b32_e32 v31, 0, v213, vcc
	v_cmp_eq_u32_e32 vcc, 32, v212
	s_nop 1
	v_cndmask_b32_e32 v32, 0, v213, vcc
	v_cmp_eq_u32_e32 vcc, 33, v212
	s_nop 1
	v_cndmask_b32_e32 v33, 0, v213, vcc
	v_cmp_eq_u32_e32 vcc, 34, v212
	s_nop 1
	v_cndmask_b32_e32 v34, 0, v213, vcc
	v_cmp_eq_u32_e32 vcc, 35, v212
	s_nop 1
	v_cndmask_b32_e32 v35, 0, v213, vcc
	v_cmp_eq_u32_e32 vcc, 36, v212
	s_nop 1
	v_cndmask_b32_e32 v36, 0, v213, vcc
	v_cmp_eq_u32_e32 vcc, 37, v212
	s_nop 1
	v_cndmask_b32_e32 v37, 0, v213, vcc
	v_cmp_eq_u32_e32 vcc, 38, v212
	s_nop 1
	v_cndmask_b32_e32 v38, 0, v213, vcc
	v_cmp_eq_u32_e32 vcc, 39, v212
	s_nop 1
	v_cndmask_b32_e32 v39, 0, v213, vcc
	v_cmp_eq_u32_e32 vcc, 40, v212
	s_nop 1
	v_cndmask_b32_e32 v40, 0, v213, vcc
	v_cmp_eq_u32_e32 vcc, 41, v212
	s_nop 1
	v_cndmask_b32_e32 v41, 0, v213, vcc
	v_cmp_eq_u32_e32 vcc, 42, v212
	s_nop 1
	v_cndmask_b32_e32 v42, 0, v213, vcc
	v_cmp_eq_u32_e32 vcc, 43, v212
	s_nop 1
	v_cndmask_b32_e32 v43, 0, v213, vcc
	v_cmp_eq_u32_e32 vcc, 44, v212
	s_nop 1
	v_cndmask_b32_e32 v44, 0, v213, vcc
	v_cmp_eq_u32_e32 vcc, 45, v212
	s_nop 1
	v_cndmask_b32_e32 v45, 0, v213, vcc
	v_cmp_eq_u32_e32 vcc, 46, v212
	s_nop 1
	v_cndmask_b32_e32 v46, 0, v213, vcc
	v_cmp_eq_u32_e32 vcc, 47, v212
	s_nop 1
	v_cndmask_b32_e32 v47, 0, v213, vcc
	v_cmp_eq_u32_e32 vcc, 48, v212
	s_nop 1
	v_cndmask_b32_e32 v48, 0, v213, vcc
	v_cmp_eq_u32_e32 vcc, 49, v212
	s_nop 1
	v_cndmask_b32_e32 v49, 0, v213, vcc
	v_cmp_eq_u32_e32 vcc, 50, v212
	s_nop 1
	v_cndmask_b32_e32 v50, 0, v213, vcc
	v_cmp_eq_u32_e32 vcc, 51, v212
	s_nop 1
	v_cndmask_b32_e32 v51, 0, v213, vcc
	v_cmp_eq_u32_e32 vcc, 52, v212
	s_nop 1
	v_cndmask_b32_e32 v52, 0, v213, vcc
	v_cmp_eq_u32_e32 vcc, 53, v212
	s_nop 1
	v_cndmask_b32_e32 v53, 0, v213, vcc
	v_cmp_eq_u32_e32 vcc, 54, v212
	s_nop 1
	v_cndmask_b32_e32 v54, 0, v213, vcc
	v_cmp_eq_u32_e32 vcc, 55, v212
	s_nop 1
	v_cndmask_b32_e32 v55, 0, v213, vcc
	v_cmp_eq_u32_e32 vcc, 56, v212
	s_nop 1
	v_cndmask_b32_e32 v56, 0, v213, vcc
	v_cmp_eq_u32_e32 vcc, 57, v212
	s_nop 1
	v_cndmask_b32_e32 v57, 0, v213, vcc
	v_cmp_eq_u32_e32 vcc, 58, v212
	s_nop 1
	v_cndmask_b32_e32 v58, 0, v213, vcc
	v_cmp_eq_u32_e32 vcc, 59, v212
	s_nop 1
	v_cndmask_b32_e32 v59, 0, v213, vcc
	v_cmp_eq_u32_e32 vcc, 60, v212
	s_nop 1
	v_cndmask_b32_e32 v60, 0, v213, vcc
	v_cmp_eq_u32_e32 vcc, 61, v212
	s_nop 1
	v_cndmask_b32_e32 v61, 0, v213, vcc
	v_cmp_eq_u32_e32 vcc, 62, v212
	s_nop 1
	v_cndmask_b32_e32 v62, 0, v213, vcc
	v_cmp_eq_u32_e32 vcc, 63, v212
	s_nop 1
	v_cndmask_b32_e32 v63, 0, v213, vcc
	s_waitcnt vmcnt(0)
	v_mov_b32_e32 v216, 1.0
	v_mov_b32_e32 v217, 1.0
	v_mov_b32_e32 v218, 1.0
	v_mov_b32_e32 v219, 1.0
	s_movk_i32 s83, 64
	s_branch .Lmy_p1d0_loop_p

; #define SB __builtin_amdgcn_sched_barrier(0)
; #define LD1(set, s) { const int e_ = min((int)(s), LC - 1) * (int)stp; const unsigned s4_ = ob4 + (unsigned)(e_ * 4), s2_ = ob2 + (unsigned)(e_ * 2); set.w = LDX(rW, s4_); set.a = LDX(rA, s4_); set.b = LDX(rB, s4_); \
;             set.kw = __builtin_amdgcn_raw_buffer_load_b64(rK, lo8, s2_, 0); set.v = __builtin_amdgcn_raw_buffer_load_b16(rV, lo2, s2_, 0); }
; #define TOUCH1(set) asm volatile("" :: "v"(set.w), "v"(set.a), "v"(set.b), "v"(set.kw), "v"(set.v))
; #define ST1(set) { DERIVE_BK(set); float sd[4]; ScanK<0>::dot(S, set.a, sd); ScanK<0>::updS(S, set, -((sd[0] + sd[1]) + (sd[2] + sd[3])), __uint_as_float(set.v << 16)); }
; #define LD1(set, s) { const int e_ = min((int)(s), LC - 1) * (int)stp; const unsigned s4_ = ob4 + (unsigned)(e_ * 4); set.w = LDX(rW, s4_); set.a = LDX(rA, s4_); set.b = LDX(rB, s4_); }
; #define TOUCH1(set) asm volatile("" :: "v"(set.w), "v"(set.a), "v"(set.b))
;     static __device__ __forceinline__ void updP(float (&P)[64], const In1& in, float sa) {
;         float u0, u1, u2, u3;
;         asm volatile("v_mul_f32_dpp %0, %8, %4 row_newbcast:%17" DPPM "v_mul_f32_dpp %1, %9, %5 row_newbcast:%17" DPPM "v_mul_f32_dpp %2, %10, %6 row_newbcast:%17" DPPM "v_mul_f32_dpp %3, %11, %7 row_newbcast:%17" DPPM
;                      "v_fmac_f32_dpp %0, %12, %16 row_newbcast:%17" DPPM "v_fmac_f32_dpp %1, %13, %16 row_newbcast:%17" DPPM "v_fmac_f32_dpp %2, %14, %16 row_newbcast:%17" DPPM "v_fmac_f32_dpp %3, %15, %16 row_newbcast:%17" DPPM
;                      : "=&v"(u0), "=&v"(u1), "=&v"(u2), "=&v"(u3)
;                      : "v"(P[K]), "v"(P[K + 1]), "v"(P[K + 2]), "v"(P[K + 3]), "v"(in.w[0]), "v"(in.w[1]), "v"(in.w[2]), "v"(in.w[3]), "v"(in.b[0]), "v"(in.b[1]), "v"(in.b[2]), "v"(in.b[3]), "v"(sa), "n"(N0));
;         P[K] = u0; P[K + 1] = u1; P[K + 2] = u2; P[K + 3] = u3;
;         if constexpr (K + 4 < 64) ScanK<K + 4>::updP(P, in, sa);
;     }
; template <bool MIX> __device__ __forceinline__ void scan_pass1(const Params& p, int d, float* ldsf) {
;     ...
;             for (int i = 0; i < 64; ++i) S[i] = (ln == i) ? 1.f : 0.f;
;     ...
;             In1 i0, i1; LD1(i0, 0);
; #pragma unroll 1
;             for (int s = 0; s < LC; s += 2) { TOUCH1(i0); SB; LD1(i1, s + 1); SB; ST1(i0); TOUCH1(i1); SB; LD1(i0, s + 2); SB; ST1(i1); }
.Lmy_p1d0_loop_p:
	s_waitcnt vmcnt(6)
	buffer_load_dwordx4 v[156:159], v232, s[64:67], s72 offen
	buffer_load_dwordx4 v[160:163], v233, s[64:67], s72 offen
	buffer_load_dwordx4 v[164:167], v234, s[64:67], s72 offen
	s_add_u32 s72, s72, 0x1000
	v_pk_mul_f32 v[224:225], v[100:101], v[216:217]
	v_pk_mul_f32 v[226:227], v[102:103], v[218:219]
	v_pk_mul_f32 v[216:217], v[216:217], v[96:97]
	v_pk_mul_f32 v[218:219], v[218:219], v[98:99]
	v_pk_mul_f32 v[176:177], v[100:101], v[104:105]
	v_pk_mul_f32 v[178:179], v[102:103], v[106:107]
	v_rcp_f32_e32 v220, v216
	v_rcp_f32_e32 v221, v217
	v_rcp_f32_e32 v222, v218
	v_rcp_f32_e32 v223, v219
	s_nop 0
	v_pk_mul_f32 v[176:177], v[176:177], v[220:221]
	v_pk_mul_f32 v[178:179], v[178:179], v[222:223]
	ds_write2_b32 v208, v176, v177 offset0:0 offset1:16
	ds_write2_b32 v208, v178, v179 offset0:32 offset1:48
	ds_read_b128 v[64:67], v209 offset:0
	ds_read_b128 v[68:71], v209 offset:16
	ds_read_b128 v[72:75], v209 offset:32
	ds_read_b128 v[76:79], v209 offset:48
	v_mul_f32_dpp v196, v224, v0 row_newbcast:0 row_mask:0xf bank_mask:0xf
	v_mul_f32_dpp v197, v225, v1 row_newbcast:0 row_mask:0xf bank_mask:0xf
	v_mul_f32_dpp v198, v226, v2 row_newbcast:0 row_mask:0xf bank_mask:0xf
	v_mul_f32_dpp v199, v227, v3 row_newbcast:0 row_mask:0xf bank_mask:0xf
	v_fmac_f32_dpp v196, v224, v4 row_newbcast:1 row_mask:0xf bank_mask:0xf
	v_fmac_f32_dpp v197, v225, v5 row_newbcast:1 row_mask:0xf bank_mask:0xf
	v_fmac_f32_dpp v198, v226, v6 row_newbcast:1 row_mask:0xf bank_mask:0xf
	v_fmac_f32_dpp v199, v227, v7 row_newbcast:1 row_mask:0xf bank_mask:0xf
	v_fmac_f32_dpp v196, v224, v8 row_newbcast:2 row_mask:0xf bank_mask:0xf
	v_fmac_f32_dpp v197, v225, v9 row_newbcast:2 row_mask:0xf bank_mask:0xf
	v_fmac_f32_dpp v198, v226, v10 row_newbcast:2 row_mask:0xf bank_mask:0xf
	v_fmac_f32_dpp v199, v227, v11 row_newbcast:2 row_mask:0xf bank_mask:0xf
	v_fmac_f32_dpp v196, v224, v12 row_newbcast:3 row_mask:0xf bank_mask:0xf
	v_fmac_f32_dpp v197, v225, v13 row_newbcast:3 row_mask:0xf bank_mask:0xf
	v_fmac_f32_dpp v198, v226, v14 row_newbcast:3 row_mask:0xf bank_mask:0xf
	v_fmac_f32_dpp v199, v227, v15 row_newbcast:3 row_mask:0xf bank_mask:0xf
	v_fmac_f32_dpp v196, v224, v16 row_newbcast:4 row_mask:0xf bank_mask:0xf
	v_fmac_f32_dpp v197, v225, v17 row_newbcast:4 row_mask:0xf bank_mask:0xf
	v_fmac_f32_dpp v198, v226, v18 row_newbcast:4 row_mask:0xf bank_mask:0xf
	v_fmac_f32_dpp v199, v227, v19 row_newbcast:4 row_mask:0xf bank_mask:0xf
	v_fmac_f32_dpp v196, v224, v20 row_newbcast:5 row_mask:0xf bank_mask:0xf
	v_fmac_f32_dpp v197, v225, v21 row_newbcast:5 row_mask:0xf bank_mask:0xf
	v_fmac_f32_dpp v198, v226, v22 row_newbcast:5 row_mask:0xf bank_mask:0xf
	v_fmac_f32_dpp v199, v227, v23 row_newbcast:5 row_mask:0xf bank_mask:0xf
	v_fmac_f32_dpp v196, v224, v24 row_newbcast:6 row_mask:0xf bank_mask:0xf
	v_fmac_f32_dpp v197, v225, v25 row_newbcast:6 row_mask:0xf bank_mask:0xf
	v_fmac_f32_dpp v198, v226, v26 row_newbcast:6 row_mask:0xf bank_mask:0xf
	v_fmac_f32_dpp v199, v227, v27 row_newbcast:6 row_mask:0xf bank_mask:0xf
	v_fmac_f32_dpp v196, v224, v28 row_newbcast:7 row_mask:0xf bank_mask:0xf
	v_fmac_f32_dpp v197, v225, v29 row_newbcast:7 row_mask:0xf bank_mask:0xf
	v_fmac_f32_dpp v198, v226, v30 row_newbcast:7 row_mask:0xf bank_mask:0xf
	v_fmac_f32_dpp v199, v227, v31 row_newbcast:7 row_mask:0xf bank_mask:0xf
	v_fmac_f32_dpp v196, v224, v32 row_newbcast:8 row_mask:0xf bank_mask:0xf
	v_fmac_f32_dpp v197, v225, v33 row_newbcast:8 row_mask:0xf bank_mask:0xf
	v_fmac_f32_dpp v198, v226, v34 row_newbcast:8 row_mask:0xf bank_mask:0xf
	v_fmac_f32_dpp v199, v227, v35 row_newbcast:8 row_mask:0xf bank_mask:0xf
	v_fmac_f32_dpp v196, v224, v36 row_newbcast:9 row_mask:0xf bank_mask:0xf
	v_fmac_f32_dpp v197, v225, v37 row_newbcast:9 row_mask:0xf bank_mask:0xf
	v_fmac_f32_dpp v198, v226, v38 row_newbcast:9 row_mask:0xf bank_mask:0xf
	v_fmac_f32_dpp v199, v227, v39 row_newbcast:9 row_mask:0xf bank_mask:0xf
	v_fmac_f32_dpp v196, v224, v40 row_newbcast:10 row_mask:0xf bank_mask:0xf
	v_fmac_f32_dpp v197, v225, v41 row_newbcast:10 row_mask:0xf bank_mask:0xf
	v_fmac_f32_dpp v198, v226, v42 row_newbcast:10 row_mask:0xf bank_mask:0xf
	v_fmac_f32_dpp v199, v227, v43 row_newbcast:10 row_mask:0xf bank_mask:0xf
	v_fmac_f32_dpp v196, v224, v44 row_newbcast:11 row_mask:0xf bank_mask:0xf
	v_fmac_f32_dpp v197, v225, v45 row_newbcast:11 row_mask:0xf bank_mask:0xf
	v_fmac_f32_dpp v198, v226, v46 row_newbcast:11 row_mask:0xf bank_mask:0xf
	v_fmac_f32_dpp v199, v227, v47 row_newbcast:11 row_mask:0xf bank_mask:0xf
	v_fmac_f32_dpp v196, v224, v48 row_newbcast:12 row_mask:0xf bank_mask:0xf
	v_fmac_f32_dpp v197, v225, v49 row_newbcast:12 row_mask:0xf bank_mask:0xf
	v_fmac_f32_dpp v198, v226, v50 row_newbcast:12 row_mask:0xf bank_mask:0xf
	v_fmac_f32_dpp v199, v227, v51 row_newbcast:12 row_mask:0xf bank_mask:0xf
	v_fmac_f32_dpp v196, v224, v52 row_newbcast:13 row_mask:0xf bank_mask:0xf
	v_fmac_f32_dpp v197, v225, v53 row_newbcast:13 row_mask:0xf bank_mask:0xf
	v_fmac_f32_dpp v198, v226, v54 row_newbcast:13 row_mask:0xf bank_mask:0xf
	v_fmac_f32_dpp v199, v227, v55 row_newbcast:13 row_mask:0xf bank_mask:0xf
	v_fmac_f32_dpp v196, v224, v56 row_newbcast:14 row_mask:0xf bank_mask:0xf
	v_fmac_f32_dpp v197, v225, v57 row_newbcast:14 row_mask:0xf bank_mask:0xf
	v_fmac_f32_dpp v198, v226, v58 row_newbcast:14 row_mask:0xf bank_mask:0xf
	v_fmac_f32_dpp v199, v227, v59 row_newbcast:14 row_mask:0xf bank_mask:0xf
	v_fmac_f32_dpp v196, v224, v60 row_newbcast:15 row_mask:0xf bank_mask:0xf
	v_fmac_f32_dpp v197, v225, v61 row_newbcast:15 row_mask:0xf bank_mask:0xf
	v_fmac_f32_dpp v198, v226, v62 row_newbcast:15 row_mask:0xf bank_mask:0xf
	v_fmac_f32_dpp v199, v227, v63 row_newbcast:15 row_mask:0xf bank_mask:0xf
	v_add_f32_e32 v196, v196, v197
	v_add_f32_e32 v198, v198, v199
	v_sub_f32_e64 v202, -v196, v198
	s_waitcnt lgkmcnt(0)
; #define SB __builtin_amdgcn_sched_barrier(0)
; #define LD1(set, s) { const int e_ = min((int)(s), LC - 1) * (int)stp; const unsigned s4_ = ob4 + (unsigned)(e_ * 4), s2_ = ob2 + (unsigned)(e_ * 2); set.w = LDX(rW, s4_); set.a = LDX(rA, s4_); set.b = LDX(rB, s4_); \
;             set.kw = __builtin_amdgcn_raw_buffer_load_b64(rK, lo8, s2_, 0); set.v = __builtin_amdgcn_raw_buffer_load_b16(rV, lo2, s2_, 0); }
; #define TOUCH1(set) asm volatile("" :: "v"(set.w), "v"(set.a), "v"(set.b), "v"(set.kw), "v"(set.v))
; #define ST1(set) { DERIVE_BK(set); float sd[4]; ScanK<0>::dot(S, set.a, sd); ScanK<0>::updS(S, set, -((sd[0] + sd[1]) + (sd[2] + sd[3])), __uint_as_float(set.v << 16)); }
; #define LD1(set, s) { const int e_ = min((int)(s), LC - 1) * (int)stp; const unsigned s4_ = ob4 + (unsigned)(e_ * 4); set.w = LDX(rW, s4_); set.a = LDX(rA, s4_); set.b = LDX(rB, s4_); }
; #define TOUCH1(set) asm volatile("" :: "v"(set.w), "v"(set.a), "v"(set.b))
;     static __device__ __forceinline__ void updP(float (&P)[64], const In1& in, float sa) {
;         float u0, u1, u2, u3;
;         asm volatile("v_mul_f32_dpp %0, %8, %4 row_newbcast:%17" DPPM "v_mul_f32_dpp %1, %9, %5 row_newbcast:%17" DPPM "v_mul_f32_dpp %2, %10, %6 row_newbcast:%17" DPPM "v_mul_f32_dpp %3, %11, %7 row_newbcast:%17" DPPM
;                      "v_fmac_f32_dpp %0, %12, %16 row_newbcast:%17" DPPM "v_fmac_f32_dpp %1, %13, %16 row_newbcast:%17" DPPM "v_fmac_f32_dpp %2, %14, %16 row_newbcast:%17" DPPM "v_fmac_f32_dpp %3, %15, %16 row_newbcast:%17" DPPM
;                      : "=&v"(u0), "=&v"(u1), "=&v"(u2), "=&v"(u3)
;                      : "v"(P[K]), "v"(P[K + 1]), "v"(P[K + 2]), "v"(P[K + 3]), "v"(in.w[0]), "v"(in.w[1]), "v"(in.w[2]), "v"(in.w[3]), "v"(in.b[0]), "v"(in.b[1]), "v"(in.b[2]), "v"(in.b[3]), "v"(sa), "n"(N0));
;         P[K] = u0; P[K + 1] = u1; P[K + 2] = u2; P[K + 3] = u3;
;         if constexpr (K + 4 < 64) ScanK<K + 4>::updP(P, in, sa);
;     }
; template <bool MIX> __device__ __forceinline__ void scan_pass1(const Params& p, int d, float* ldsf) {
;     ...
;             for (int i = 0; i < 64; ++i) S[i] = (ln == i) ? 1.f : 0.f;
;     ...
;             In1 i0, i1; LD1(i0, 0);
; #pragma unroll 1
;             for (int s = 0; s < LC; s += 2) { TOUCH1(i0); SB; LD1(i1, s + 1); SB; ST1(i0); TOUCH1(i1); SB; LD1(i0, s + 2); SB; ST1(i1); }
	s_nop 1
	v_mfma_f32_4x4x1_16b_f32 v[0:3], v64, v202, v[0:3]
	v_mfma_f32_4x4x1_16b_f32 v[4:7], v65, v202, v[4:7]
	v_mfma_f32_4x4x1_16b_f32 v[8:11], v66, v202, v[8:11]
	v_mfma_f32_4x4x1_16b_f32 v[12:15], v67, v202, v[12:15]
	v_mfma_f32_4x4x1_16b_f32 v[16:19], v68, v202, v[16:19]
	v_mfma_f32_4x4x1_16b_f32 v[20:23], v69, v202, v[20:23]
	v_mfma_f32_4x4x1_16b_f32 v[24:27], v70, v202, v[24:27]
	v_mfma_f32_4x4x1_16b_f32 v[28:31], v71, v202, v[28:31]
	v_mfma_f32_4x4x1_16b_f32 v[32:35], v72, v202, v[32:35]
	v_mfma_f32_4x4x1_16b_f32 v[36:39], v73, v202, v[36:39]
	v_mfma_f32_4x4x1_16b_f32 v[40:43], v74, v202, v[40:43]
	v_mfma_f32_4x4x1_16b_f32 v[44:47], v75, v202, v[44:47]
	v_mfma_f32_4x4x1_16b_f32 v[48:51], v76, v202, v[48:51]
	v_mfma_f32_4x4x1_16b_f32 v[52:55], v77, v202, v[52:55]
	v_mfma_f32_4x4x1_16b_f32 v[56:59], v78, v202, v[56:59]
	v_mfma_f32_4x4x1_16b_f32 v[60:63], v79, v202, v[60:63]
	s_waitcnt vmcnt(6)
	buffer_load_dwordx4 v[96:99], v232, s[64:67], s72 offen
	buffer_load_dwordx4 v[100:103], v233, s[64:67], s72 offen
	buffer_load_dwordx4 v[104:107], v234, s[64:67], s72 offen
	s_add_u32 s72, s72, 0x1000
	v_pk_mul_f32 v[224:225], v[120:121], v[216:217]
	v_pk_mul_f32 v[226:227], v[122:123], v[218:219]
	v_pk_mul_f32 v[216:217], v[216:217], v[116:117]
	v_pk_mul_f32 v[218:219], v[218:219], v[118:119]
	v_pk_mul_f32 v[176:177], v[120:121], v[124:125]
	v_pk_mul_f32 v[178:179], v[122:123], v[126:127]
	v_rcp_f32_e32 v220, v216
	v_rcp_f32_e32 v221, v217
	v_rcp_f32_e32 v222, v218
	v_rcp_f32_e32 v223, v219
	s_nop 0
	v_pk_mul_f32 v[176:177], v[176:177], v[220:221]
	v_pk_mul_f32 v[178:179], v[178:179], v[222:223]
	ds_write2_b32 v208, v176, v177 offset0:0 offset1:16
	ds_write2_b32 v208, v178, v179 offset0:32 offset1:48
	ds_read_b128 v[64:67], v209 offset:0
	ds_read_b128 v[68:71], v209 offset:16
	ds_read_b128 v[72:75], v209 offset:32
	ds_read_b128 v[76:79], v209 offset:48
	v_mul_f32_dpp v196, v224, v0 row_newbcast:0 row_mask:0xf bank_mask:0xf
	v_mul_f32_dpp v197, v225, v1 row_newbcast:0 row_mask:0xf bank_mask:0xf
	v_mul_f32_dpp v198, v226, v2 row_newbcast:0 row_mask:0xf bank_mask:0xf
	v_mul_f32_dpp v199, v227, v3 row_newbcast:0 row_mask:0xf bank_mask:0xf
	v_fmac_f32_dpp v196, v224, v4 row_newbcast:1 row_mask:0xf bank_mask:0xf
	v_fmac_f32_dpp v197, v225, v5 row_newbcast:1 row_mask:0xf bank_mask:0xf
	v_fmac_f32_dpp v198, v226, v6 row_newbcast:1 row_mask:0xf bank_mask:0xf
	v_fmac_f32_dpp v199, v227, v7 row_newbcast:1 row_mask:0xf bank_mask:0xf
	v_fmac_f32_dpp v196, v224, v8 row_newbcast:2 row_mask:0xf bank_mask:0xf
	v_fmac_f32_dpp v197, v225, v9 row_newbcast:2 row_mask:0xf bank_mask:0xf
	v_fmac_f32_dpp v198, v226, v10 row_newbcast:2 row_mask:0xf bank_mask:0xf
	v_fmac_f32_dpp v199, v227, v11 row_newbcast:2 row_mask:0xf bank_mask:0xf
	v_fmac_f32_dpp v196, v224, v12 row_newbcast:3 row_mask:0xf bank_mask:0xf
	v_fmac_f32_dpp v197, v225, v13 row_newbcast:3 row_mask:0xf bank_mask:0xf
	v_fmac_f32_dpp v198, v226, v14 row_newbcast:3 row_mask:0xf bank_mask:0xf
	v_fmac_f32_dpp v199, v227, v15 row_newbcast:3 row_mask:0xf bank_mask:0xf
	v_fmac_f32_dpp v196, v224, v16 row_newbcast:4 row_mask:0xf bank_mask:0xf
	v_fmac_f32_dpp v197, v225, v17 row_newbcast:4 row_mask:0xf bank_mask:0xf
	v_fmac_f32_dpp v198, v226, v18 row_newbcast:4 row_mask:0xf bank_mask:0xf
	v_fmac_f32_dpp v199, v227, v19 row_newbcast:4 row_mask:0xf bank_mask:0xf
	v_fmac_f32_dpp v196, v224, v20 row_newbcast:5 row_mask:0xf bank_mask:0xf
	v_fmac_f32_dpp v197, v225, v21 row_newbcast:5 row_mask:0xf bank_mask:0xf
	v_fmac_f32_dpp v198, v226, v22 row_newbcast:5 row_mask:0xf bank_mask:0xf
	v_fmac_f32_dpp v199, v227, v23 row_newbcast:5 row_mask:0xf bank_mask:0xf
	v_fmac_f32_dpp v196, v224, v24 row_newbcast:6 row_mask:0xf bank_mask:0xf
	v_fmac_f32_dpp v197, v225, v25 row_newbcast:6 row_mask:0xf bank_mask:0xf
	v_fmac_f32_dpp v198, v226, v26 row_newbcast:6 row_mask:0xf bank_mask:0xf
	v_fmac_f32_dpp v199, v227, v27 row_newbcast:6 row_mask:0xf bank_mask:0xf
	v_fmac_f32_dpp v196, v224, v28 row_newbcast:7 row_mask:0xf bank_mask:0xf
	v_fmac_f32_dpp v197, v225, v29 row_newbcast:7 row_mask:0xf bank_mask:0xf
	v_fmac_f32_dpp v198, v226, v30 row_newbcast:7 row_mask:0xf bank_mask:0xf
	v_fmac_f32_dpp v199, v227, v31 row_newbcast:7 row_mask:0xf bank_mask:0xf
	v_fmac_f32_dpp v196, v224, v32 row_newbcast:8 row_mask:0xf bank_mask:0xf
	v_fmac_f32_dpp v197, v225, v33 row_newbcast:8 row_mask:0xf bank_mask:0xf
	v_fmac_f32_dpp v198, v226, v34 row_newbcast:8 row_mask:0xf bank_mask:0xf
	v_fmac_f32_dpp v199, v227, v35 row_newbcast:8 row_mask:0xf bank_mask:0xf
	v_fmac_f32_dpp v196, v224, v36 row_newbcast:9 row_mask:0xf bank_mask:0xf
	v_fmac_f32_dpp v197, v225, v37 row_newbcast:9 row_mask:0xf bank_mask:0xf
	v_fmac_f32_dpp v198, v226, v38 row_newbcast:9 row_mask:0xf bank_mask:0xf
	v_fmac_f32_dpp v199, v227, v39 row_newbcast:9 row_mask:0xf bank_mask:0xf
	v_fmac_f32_dpp v196, v224, v40 row_newbcast:10 row_mask:0xf bank_mask:0xf
	v_fmac_f32_dpp v197, v225, v41 row_newbcast:10 row_mask:0xf bank_mask:0xf
	v_fmac_f32_dpp v198, v226, v42 row_newbcast:10 row_mask:0xf bank_mask:0xf
	v_fmac_f32_dpp v199, v227, v43 row_newbcast:10 row_mask:0xf bank_mask:0xf
	v_fmac_f32_dpp v196, v224, v44 row_newbcast:11 row_mask:0xf bank_mask:0xf
	v_fmac_f32_dpp v197, v225, v45 row_newbcast:11 row_mask:0xf bank_mask:0xf
	v_fmac_f32_dpp v198, v226, v46 row_newbcast:11 row_mask:0xf bank_mask:0xf
	v_fmac_f32_dpp v199, v227, v47 row_newbcast:11 row_mask:0xf bank_mask:0xf
	v_fmac_f32_dpp v196, v224, v48 row_newbcast:12 row_mask:0xf bank_mask:0xf
	v_fmac_f32_dpp v197, v225, v49 row_newbcast:12 row_mask:0xf bank_mask:0xf
	v_fmac_f32_dpp v198, v226, v50 row_newbcast:12 row_mask:0xf bank_mask:0xf
	v_fmac_f32_dpp v199, v227, v51 row_newbcast:12 row_mask:0xf bank_mask:0xf
	v_fmac_f32_dpp v196, v224, v52 row_newbcast:13 row_mask:0xf bank_mask:0xf
	v_fmac_f32_dpp v197, v225, v53 row_newbcast:13 row_mask:0xf bank_mask:0xf
	v_fmac_f32_dpp v198, v226, v54 row_newbcast:13 row_mask:0xf bank_mask:0xf
	v_fmac_f32_dpp v199, v227, v55 row_newbcast:13 row_mask:0xf bank_mask:0xf
	v_fmac_f32_dpp v196, v224, v56 row_newbcast:14 row_mask:0xf bank_mask:0xf
	v_fmac_f32_dpp v197, v225, v57 row_newbcast:14 row_mask:0xf bank_mask:0xf
	v_fmac_f32_dpp v198, v226, v58 row_newbcast:14 row_mask:0xf bank_mask:0xf
	v_fmac_f32_dpp v199, v227, v59 row_newbcast:14 row_mask:0xf bank_mask:0xf
	v_fmac_f32_dpp v196, v224, v60 row_newbcast:15 row_mask:0xf bank_mask:0xf
	v_fmac_f32_dpp v197, v225, v61 row_newbcast:15 row_mask:0xf bank_mask:0xf
	v_fmac_f32_dpp v198, v226, v62 row_newbcast:15 row_mask:0xf bank_mask:0xf
	v_fmac_f32_dpp v199, v227, v63 row_newbcast:15 row_mask:0xf bank_mask:0xf
	v_add_f32_e32 v196, v196, v197
	v_add_f32_e32 v198, v198, v199
	v_sub_f32_e64 v202, -v196, v198
	s_waitcnt lgkmcnt(0)
; #define SB __builtin_amdgcn_sched_barrier(0)
; #define LD1(set, s) { const int e_ = min((int)(s), LC - 1) * (int)stp; const unsigned s4_ = ob4 + (unsigned)(e_ * 4), s2_ = ob2 + (unsigned)(e_ * 2); set.w = LDX(rW, s4_); set.a = LDX(rA, s4_); set.b = LDX(rB, s4_); \
;             set.kw = __builtin_amdgcn_raw_buffer_load_b64(rK, lo8, s2_, 0); set.v = __builtin_amdgcn_raw_buffer_load_b16(rV, lo2, s2_, 0); }
; #define TOUCH1(set) asm volatile("" :: "v"(set.w), "v"(set.a), "v"(set.b), "v"(set.kw), "v"(set.v))
; #define ST1(set) { DERIVE_BK(set); float sd[4]; ScanK<0>::dot(S, set.a, sd); ScanK<0>::updS(S, set, -((sd[0] + sd[1]) + (sd[2] + sd[3])), __uint_as_float(set.v << 16)); }
; #define LD1(set, s) { const int e_ = min((int)(s), LC - 1) * (int)stp; const unsigned s4_ = ob4 + (unsigned)(e_ * 4); set.w = LDX(rW, s4_); set.a = LDX(rA, s4_); set.b = LDX(rB, s4_); }
; #define TOUCH1(set) asm volatile("" :: "v"(set.w), "v"(set.a), "v"(set.b))
;     static __device__ __forceinline__ void updP(float (&P)[64], const In1& in, float sa) {
;         float u0, u1, u2, u3;
;         asm volatile("v_mul_f32_dpp %0, %8, %4 row_newbcast:%17" DPPM "v_mul_f32_dpp %1, %9, %5 row_newbcast:%17" DPPM "v_mul_f32_dpp %2, %10, %6 row_newbcast:%17" DPPM "v_mul_f32_dpp %3, %11, %7 row_newbcast:%17" DPPM
;                      "v_fmac_f32_dpp %0, %12, %16 row_newbcast:%17" DPPM "v_fmac_f32_dpp %1, %13, %16 row_newbcast:%17" DPPM "v_fmac_f32_dpp %2, %14, %16 row_newbcast:%17" DPPM "v_fmac_f32_dpp %3, %15, %16 row_newbcast:%17" DPPM
;                      : "=&v"(u0), "=&v"(u1), "=&v"(u2), "=&v"(u3)
;                      : "v"(P[K]), "v"(P[K + 1]), "v"(P[K + 2]), "v"(P[K + 3]), "v"(in.w[0]), "v"(in.w[1]), "v"(in.w[2]), "v"(in.w[3]), "v"(in.b[0]), "v"(in.b[1]), "v"(in.b[2]), "v"(in.b[3]), "v"(sa), "n"(N0));
;         P[K] = u0; P[K + 1] = u1; P[K + 2] = u2; P[K + 3] = u3;
;         if constexpr (K + 4 < 64) ScanK<K + 4>::updP(P, in, sa);
;     }
; template <bool MIX> __device__ __forceinline__ void scan_pass1(const Params& p, int d, float* ldsf) {
;     ...
;             for (int i = 0; i < 64; ++i) S[i] = (ln == i) ? 1.f : 0.f;
;     ...
;             In1 i0, i1; LD1(i0, 0);
; #pragma unroll 1
;             for (int s = 0; s < LC; s += 2) { TOUCH1(i0); SB; LD1(i1, s + 1); SB; ST1(i0); TOUCH1(i1); SB; LD1(i0, s + 2); SB; ST1(i1); }
	s_nop 1
	v_mfma_f32_4x4x1_16b_f32 v[0:3], v64, v202, v[0:3]
	v_mfma_f32_4x4x1_16b_f32 v[4:7], v65, v202, v[4:7]
	v_mfma_f32_4x4x1_16b_f32 v[8:11], v66, v202, v[8:11]
	v_mfma_f32_4x4x1_16b_f32 v[12:15], v67, v202, v[12:15]
	v_mfma_f32_4x4x1_16b_f32 v[16:19], v68, v202, v[16:19]
	v_mfma_f32_4x4x1_16b_f32 v[20:23], v69, v202, v[20:23]
	v_mfma_f32_4x4x1_16b_f32 v[24:27], v70, v202, v[24:27]
	v_mfma_f32_4x4x1_16b_f32 v[28:31], v71, v202, v[28:31]
	v_mfma_f32_4x4x1_16b_f32 v[32:35], v72, v202, v[32:35]
	v_mfma_f32_4x4x1_16b_f32 v[36:39], v73, v202, v[36:39]
	v_mfma_f32_4x4x1_16b_f32 v[40:43], v74, v202, v[40:43]
	v_mfma_f32_4x4x1_16b_f32 v[44:47], v75, v202, v[44:47]
	v_mfma_f32_4x4x1_16b_f32 v[48:51], v76, v202, v[48:51]
	v_mfma_f32_4x4x1_16b_f32 v[52:55], v77, v202, v[52:55]
	v_mfma_f32_4x4x1_16b_f32 v[56:59], v78, v202, v[56:59]
	v_mfma_f32_4x4x1_16b_f32 v[60:63], v79, v202, v[60:63]
	s_waitcnt vmcnt(6)
	buffer_load_dwordx4 v[116:119], v232, s[64:67], s72 offen
	buffer_load_dwordx4 v[120:123], v233, s[64:67], s72 offen
	buffer_load_dwordx4 v[124:127], v234, s[64:67], s72 offen
	s_add_u32 s72, s72, 0x1000
	v_pk_mul_f32 v[224:225], v[140:141], v[216:217]
	v_pk_mul_f32 v[226:227], v[142:143], v[218:219]
	v_pk_mul_f32 v[216:217], v[216:217], v[136:137]
	v_pk_mul_f32 v[218:219], v[218:219], v[138:139]
	v_pk_mul_f32 v[176:177], v[140:141], v[144:145]
	v_pk_mul_f32 v[178:179], v[142:143], v[146:147]
	v_rcp_f32_e32 v220, v216
	v_rcp_f32_e32 v221, v217
	v_rcp_f32_e32 v222, v218
	v_rcp_f32_e32 v223, v219
	s_nop 0
	v_pk_mul_f32 v[176:177], v[176:177], v[220:221]
	v_pk_mul_f32 v[178:179], v[178:179], v[222:223]
	ds_write2_b32 v208, v176, v177 offset0:0 offset1:16
	ds_write2_b32 v208, v178, v179 offset0:32 offset1:48
	ds_read_b128 v[64:67], v209 offset:0
	ds_read_b128 v[68:71], v209 offset:16
	ds_read_b128 v[72:75], v209 offset:32
	ds_read_b128 v[76:79], v209 offset:48
	v_mul_f32_dpp v196, v224, v0 row_newbcast:0 row_mask:0xf bank_mask:0xf
	v_mul_f32_dpp v197, v225, v1 row_newbcast:0 row_mask:0xf bank_mask:0xf
	v_mul_f32_dpp v198, v226, v2 row_newbcast:0 row_mask:0xf bank_mask:0xf
	v_mul_f32_dpp v199, v227, v3 row_newbcast:0 row_mask:0xf bank_mask:0xf
	v_fmac_f32_dpp v196, v224, v4 row_newbcast:1 row_mask:0xf bank_mask:0xf
	v_fmac_f32_dpp v197, v225, v5 row_newbcast:1 row_mask:0xf bank_mask:0xf
	v_fmac_f32_dpp v198, v226, v6 row_newbcast:1 row_mask:0xf bank_mask:0xf
	v_fmac_f32_dpp v199, v227, v7 row_newbcast:1 row_mask:0xf bank_mask:0xf
	v_fmac_f32_dpp v196, v224, v8 row_newbcast:2 row_mask:0xf bank_mask:0xf
	v_fmac_f32_dpp v197, v225, v9 row_newbcast:2 row_mask:0xf bank_mask:0xf
	v_fmac_f32_dpp v198, v226, v10 row_newbcast:2 row_mask:0xf bank_mask:0xf
	v_fmac_f32_dpp v199, v227, v11 row_newbcast:2 row_mask:0xf bank_mask:0xf
	v_fmac_f32_dpp v196, v224, v12 row_newbcast:3 row_mask:0xf bank_mask:0xf
	v_fmac_f32_dpp v197, v225, v13 row_newbcast:3 row_mask:0xf bank_mask:0xf
	v_fmac_f32_dpp v198, v226, v14 row_newbcast:3 row_mask:0xf bank_mask:0xf
	v_fmac_f32_dpp v199, v227, v15 row_newbcast:3 row_mask:0xf bank_mask:0xf
	v_fmac_f32_dpp v196, v224, v16 row_newbcast:4 row_mask:0xf bank_mask:0xf
	v_fmac_f32_dpp v197, v225, v17 row_newbcast:4 row_mask:0xf bank_mask:0xf
	v_fmac_f32_dpp v198, v226, v18 row_newbcast:4 row_mask:0xf bank_mask:0xf
	v_fmac_f32_dpp v199, v227, v19 row_newbcast:4 row_mask:0xf bank_mask:0xf
	v_fmac_f32_dpp v196, v224, v20 row_newbcast:5 row_mask:0xf bank_mask:0xf
	v_fmac_f32_dpp v197, v225, v21 row_newbcast:5 row_mask:0xf bank_mask:0xf
	v_fmac_f32_dpp v198, v226, v22 row_newbcast:5 row_mask:0xf bank_mask:0xf
	v_fmac_f32_dpp v199, v227, v23 row_newbcast:5 row_mask:0xf bank_mask:0xf
	v_fmac_f32_dpp v196, v224, v24 row_newbcast:6 row_mask:0xf bank_mask:0xf
	v_fmac_f32_dpp v197, v225, v25 row_newbcast:6 row_mask:0xf bank_mask:0xf
	v_fmac_f32_dpp v198, v226, v26 row_newbcast:6 row_mask:0xf bank_mask:0xf
	v_fmac_f32_dpp v199, v227, v27 row_newbcast:6 row_mask:0xf bank_mask:0xf
	v_fmac_f32_dpp v196, v224, v28 row_newbcast:7 row_mask:0xf bank_mask:0xf
	v_fmac_f32_dpp v197, v225, v29 row_newbcast:7 row_mask:0xf bank_mask:0xf
	v_fmac_f32_dpp v198, v226, v30 row_newbcast:7 row_mask:0xf bank_mask:0xf
	v_fmac_f32_dpp v199, v227, v31 row_newbcast:7 row_mask:0xf bank_mask:0xf
	v_fmac_f32_dpp v196, v224, v32 row_newbcast:8 row_mask:0xf bank_mask:0xf
	v_fmac_f32_dpp v197, v225, v33 row_newbcast:8 row_mask:0xf bank_mask:0xf
	v_fmac_f32_dpp v198, v226, v34 row_newbcast:8 row_mask:0xf bank_mask:0xf
	v_fmac_f32_dpp v199, v227, v35 row_newbcast:8 row_mask:0xf bank_mask:0xf
	v_fmac_f32_dpp v196, v224, v36 row_newbcast:9 row_mask:0xf bank_mask:0xf
	v_fmac_f32_dpp v197, v225, v37 row_newbcast:9 row_mask:0xf bank_mask:0xf
	v_fmac_f32_dpp v198, v226, v38 row_newbcast:9 row_mask:0xf bank_mask:0xf
	v_fmac_f32_dpp v199, v227, v39 row_newbcast:9 row_mask:0xf bank_mask:0xf
	v_fmac_f32_dpp v196, v224, v40 row_newbcast:10 row_mask:0xf bank_mask:0xf
	v_fmac_f32_dpp v197, v225, v41 row_newbcast:10 row_mask:0xf bank_mask:0xf
	v_fmac_f32_dpp v198, v226, v42 row_newbcast:10 row_mask:0xf bank_mask:0xf
	v_fmac_f32_dpp v199, v227, v43 row_newbcast:10 row_mask:0xf bank_mask:0xf
	v_fmac_f32_dpp v196, v224, v44 row_newbcast:11 row_mask:0xf bank_mask:0xf
	v_fmac_f32_dpp v197, v225, v45 row_newbcast:11 row_mask:0xf bank_mask:0xf
	v_fmac_f32_dpp v198, v226, v46 row_newbcast:11 row_mask:0xf bank_mask:0xf
	v_fmac_f32_dpp v199, v227, v47 row_newbcast:11 row_mask:0xf bank_mask:0xf
	v_fmac_f32_dpp v196, v224, v48 row_newbcast:12 row_mask:0xf bank_mask:0xf
	v_fmac_f32_dpp v197, v225, v49 row_newbcast:12 row_mask:0xf bank_mask:0xf
	v_fmac_f32_dpp v198, v226, v50 row_newbcast:12 row_mask:0xf bank_mask:0xf
	v_fmac_f32_dpp v199, v227, v51 row_newbcast:12 row_mask:0xf bank_mask:0xf
	v_fmac_f32_dpp v196, v224, v52 row_newbcast:13 row_mask:0xf bank_mask:0xf
	v_fmac_f32_dpp v197, v225, v53 row_newbcast:13 row_mask:0xf bank_mask:0xf
	v_fmac_f32_dpp v198, v226, v54 row_newbcast:13 row_mask:0xf bank_mask:0xf
	v_fmac_f32_dpp v199, v227, v55 row_newbcast:13 row_mask:0xf bank_mask:0xf
	v_fmac_f32_dpp v196, v224, v56 row_newbcast:14 row_mask:0xf bank_mask:0xf
	v_fmac_f32_dpp v197, v225, v57 row_newbcast:14 row_mask:0xf bank_mask:0xf
	v_fmac_f32_dpp v198, v226, v58 row_newbcast:14 row_mask:0xf bank_mask:0xf
	v_fmac_f32_dpp v199, v227, v59 row_newbcast:14 row_mask:0xf bank_mask:0xf
	v_fmac_f32_dpp v196, v224, v60 row_newbcast:15 row_mask:0xf bank_mask:0xf
	v_fmac_f32_dpp v197, v225, v61 row_newbcast:15 row_mask:0xf bank_mask:0xf
	v_fmac_f32_dpp v198, v226, v62 row_newbcast:15 row_mask:0xf bank_mask:0xf
	v_fmac_f32_dpp v199, v227, v63 row_newbcast:15 row_mask:0xf bank_mask:0xf
	v_add_f32_e32 v196, v196, v197
	v_add_f32_e32 v198, v198, v199
	v_sub_f32_e64 v202, -v196, v198
	s_waitcnt lgkmcnt(0)
; #define SB __builtin_amdgcn_sched_barrier(0)
; #define LD1(set, s) { const int e_ = min((int)(s), LC - 1) * (int)stp; const unsigned s4_ = ob4 + (unsigned)(e_ * 4), s2_ = ob2 + (unsigned)(e_ * 2); set.w = LDX(rW, s4_); set.a = LDX(rA, s4_); set.b = LDX(rB, s4_); \
;             set.kw = __builtin_amdgcn_raw_buffer_load_b64(rK, lo8, s2_, 0); set.v = __builtin_amdgcn_raw_buffer_load_b16(rV, lo2, s2_, 0); }
; #define TOUCH1(set) asm volatile("" :: "v"(set.w), "v"(set.a), "v"(set.b), "v"(set.kw), "v"(set.v))
; #define ST1(set) { DERIVE_BK(set); float sd[4]; ScanK<0>::dot(S, set.a, sd); ScanK<0>::updS(S, set, -((sd[0] + sd[1]) + (sd[2] + sd[3])), __uint_as_float(set.v << 16)); }
; #define LD1(set, s) { const int e_ = min((int)(s), LC - 1) * (int)stp; const unsigned s4_ = ob4 + (unsigned)(e_ * 4); set.w = LDX(rW, s4_); set.a = LDX(rA, s4_); set.b = LDX(rB, s4_); }
; #define TOUCH1(set) asm volatile("" :: "v"(set.w), "v"(set.a), "v"(set.b))
;     static __device__ __forceinline__ void updP(float (&P)[64], const In1& in, float sa) {
;         float u0, u1, u2, u3;
;         asm volatile("v_mul_f32_dpp %0, %8, %4 row_newbcast:%17" DPPM "v_mul_f32_dpp %1, %9, %5 row_newbcast:%17" DPPM "v_mul_f32_dpp %2, %10, %6 row_newbcast:%17" DPPM "v_mul_f32_dpp %3, %11, %7 row_newbcast:%17" DPPM
;                      "v_fmac_f32_dpp %0, %12, %16 row_newbcast:%17" DPPM "v_fmac_f32_dpp %1, %13, %16 row_newbcast:%17" DPPM "v_fmac_f32_dpp %2, %14, %16 row_newbcast:%17" DPPM "v_fmac_f32_dpp %3, %15, %16 row_newbcast:%17" DPPM
;                      : "=&v"(u0), "=&v"(u1), "=&v"(u2), "=&v"(u3)
;                      : "v"(P[K]), "v"(P[K + 1]), "v"(P[K + 2]), "v"(P[K + 3]), "v"(in.w[0]), "v"(in.w[1]), "v"(in.w[2]), "v"(in.w[3]), "v"(in.b[0]), "v"(in.b[1]), "v"(in.b[2]), "v"(in.b[3]), "v"(sa), "n"(N0));
;         P[K] = u0; P[K + 1] = u1; P[K + 2] = u2; P[K + 3] = u3;
;         if constexpr (K + 4 < 64) ScanK<K + 4>::updP(P, in, sa);
;     }
; template <bool MIX> __device__ __forceinline__ void scan_pass1(const Params& p, int d, float* ldsf) {
;     ...
;             for (int i = 0; i < 64; ++i) S[i] = (ln == i) ? 1.f : 0.f;
;     ...
;             In1 i0, i1; LD1(i0, 0);
; #pragma unroll 1
;             for (int s = 0; s < LC; s += 2) { TOUCH1(i0); SB; LD1(i1, s + 1); SB; ST1(i0); TOUCH1(i1); SB; LD1(i0, s + 2); SB; ST1(i1); }
	s_nop 1
	v_mfma_f32_4x4x1_16b_f32 v[0:3], v64, v202, v[0:3]
	v_mfma_f32_4x4x1_16b_f32 v[4:7], v65, v202, v[4:7]
	v_mfma_f32_4x4x1_16b_f32 v[8:11], v66, v202, v[8:11]
	v_mfma_f32_4x4x1_16b_f32 v[12:15], v67, v202, v[12:15]
	v_mfma_f32_4x4x1_16b_f32 v[16:19], v68, v202, v[16:19]
	v_mfma_f32_4x4x1_16b_f32 v[20:23], v69, v202, v[20:23]
	v_mfma_f32_4x4x1_16b_f32 v[24:27], v70, v202, v[24:27]
	v_mfma_f32_4x4x1_16b_f32 v[28:31], v71, v202, v[28:31]
	v_mfma_f32_4x4x1_16b_f32 v[32:35], v72, v202, v[32:35]
	v_mfma_f32_4x4x1_16b_f32 v[36:39], v73, v202, v[36:39]
	v_mfma_f32_4x4x1_16b_f32 v[40:43], v74, v202, v[40:43]
	v_mfma_f32_4x4x1_16b_f32 v[44:47], v75, v202, v[44:47]
	v_mfma_f32_4x4x1_16b_f32 v[48:51], v76, v202, v[48:51]
	v_mfma_f32_4x4x1_16b_f32 v[52:55], v77, v202, v[52:55]
	v_mfma_f32_4x4x1_16b_f32 v[56:59], v78, v202, v[56:59]
	v_mfma_f32_4x4x1_16b_f32 v[60:63], v79, v202, v[60:63]
	s_waitcnt vmcnt(6)
	buffer_load_dwordx4 v[136:139], v232, s[64:67], s72 offen
	buffer_load_dwordx4 v[140:143], v233, s[64:67], s72 offen
	buffer_load_dwordx4 v[144:147], v234, s[64:67], s72 offen
	s_add_u32 s72, s72, 0x1000
	v_pk_mul_f32 v[224:225], v[160:161], v[216:217]
	v_pk_mul_f32 v[226:227], v[162:163], v[218:219]
	v_pk_mul_f32 v[216:217], v[216:217], v[156:157]
	v_pk_mul_f32 v[218:219], v[218:219], v[158:159]
	v_pk_mul_f32 v[176:177], v[160:161], v[164:165]
	v_pk_mul_f32 v[178:179], v[162:163], v[166:167]
	v_rcp_f32_e32 v220, v216
	v_rcp_f32_e32 v221, v217
	v_rcp_f32_e32 v222, v218
	v_rcp_f32_e32 v223, v219
	s_nop 0
	v_pk_mul_f32 v[176:177], v[176:177], v[220:221]
	v_pk_mul_f32 v[178:179], v[178:179], v[222:223]
	ds_write2_b32 v208, v176, v177 offset0:0 offset1:16
	ds_write2_b32 v208, v178, v179 offset0:32 offset1:48
	ds_read_b128 v[64:67], v209 offset:0
	ds_read_b128 v[68:71], v209 offset:16
	ds_read_b128 v[72:75], v209 offset:32
	ds_read_b128 v[76:79], v209 offset:48
	v_mul_f32_dpp v196, v224, v0 row_newbcast:0 row_mask:0xf bank_mask:0xf
	v_mul_f32_dpp v197, v225, v1 row_newbcast:0 row_mask:0xf bank_mask:0xf
	v_mul_f32_dpp v198, v226, v2 row_newbcast:0 row_mask:0xf bank_mask:0xf
	v_mul_f32_dpp v199, v227, v3 row_newbcast:0 row_mask:0xf bank_mask:0xf
	v_fmac_f32_dpp v196, v224, v4 row_newbcast:1 row_mask:0xf bank_mask:0xf
	v_fmac_f32_dpp v197, v225, v5 row_newbcast:1 row_mask:0xf bank_mask:0xf
	v_fmac_f32_dpp v198, v226, v6 row_newbcast:1 row_mask:0xf bank_mask:0xf
	v_fmac_f32_dpp v199, v227, v7 row_newbcast:1 row_mask:0xf bank_mask:0xf
	v_fmac_f32_dpp v196, v224, v8 row_newbcast:2 row_mask:0xf bank_mask:0xf
	v_fmac_f32_dpp v197, v225, v9 row_newbcast:2 row_mask:0xf bank_mask:0xf
	v_fmac_f32_dpp v198, v226, v10 row_newbcast:2 row_mask:0xf bank_mask:0xf
	v_fmac_f32_dpp v199, v227, v11 row_newbcast:2 row_mask:0xf bank_mask:0xf
	v_fmac_f32_dpp v196, v224, v12 row_newbcast:3 row_mask:0xf bank_mask:0xf
	v_fmac_f32_dpp v197, v225, v13 row_newbcast:3 row_mask:0xf bank_mask:0xf
	v_fmac_f32_dpp v198, v226, v14 row_newbcast:3 row_mask:0xf bank_mask:0xf
	v_fmac_f32_dpp v199, v227, v15 row_newbcast:3 row_mask:0xf bank_mask:0xf
	v_fmac_f32_dpp v196, v224, v16 row_newbcast:4 row_mask:0xf bank_mask:0xf
	v_fmac_f32_dpp v197, v225, v17 row_newbcast:4 row_mask:0xf bank_mask:0xf
	v_fmac_f32_dpp v198, v226, v18 row_newbcast:4 row_mask:0xf bank_mask:0xf
	v_fmac_f32_dpp v199, v227, v19 row_newbcast:4 row_mask:0xf bank_mask:0xf
	v_fmac_f32_dpp v196, v224, v20 row_newbcast:5 row_mask:0xf bank_mask:0xf
	v_fmac_f32_dpp v197, v225, v21 row_newbcast:5 row_mask:0xf bank_mask:0xf
	v_fmac_f32_dpp v198, v226, v22 row_newbcast:5 row_mask:0xf bank_mask:0xf
	v_fmac_f32_dpp v199, v227, v23 row_newbcast:5 row_mask:0xf bank_mask:0xf
	v_fmac_f32_dpp v196, v224, v24 row_newbcast:6 row_mask:0xf bank_mask:0xf
	v_fmac_f32_dpp v197, v225, v25 row_newbcast:6 row_mask:0xf bank_mask:0xf
	v_fmac_f32_dpp v198, v226, v26 row_newbcast:6 row_mask:0xf bank_mask:0xf
	v_fmac_f32_dpp v199, v227, v27 row_newbcast:6 row_mask:0xf bank_mask:0xf
	v_fmac_f32_dpp v196, v224, v28 row_newbcast:7 row_mask:0xf bank_mask:0xf
	v_fmac_f32_dpp v197, v225, v29 row_newbcast:7 row_mask:0xf bank_mask:0xf
	v_fmac_f32_dpp v198, v226, v30 row_newbcast:7 row_mask:0xf bank_mask:0xf
	v_fmac_f32_dpp v199, v227, v31 row_newbcast:7 row_mask:0xf bank_mask:0xf
	v_fmac_f32_dpp v196, v224, v32 row_newbcast:8 row_mask:0xf bank_mask:0xf
	v_fmac_f32_dpp v197, v225, v33 row_newbcast:8 row_mask:0xf bank_mask:0xf
	v_fmac_f32_dpp v198, v226, v34 row_newbcast:8 row_mask:0xf bank_mask:0xf
	v_fmac_f32_dpp v199, v227, v35 row_newbcast:8 row_mask:0xf bank_mask:0xf
	v_fmac_f32_dpp v196, v224, v36 row_newbcast:9 row_mask:0xf bank_mask:0xf
	v_fmac_f32_dpp v197, v225, v37 row_newbcast:9 row_mask:0xf bank_mask:0xf
	v_fmac_f32_dpp v198, v226, v38 row_newbcast:9 row_mask:0xf bank_mask:0xf
	v_fmac_f32_dpp v199, v227, v39 row_newbcast:9 row_mask:0xf bank_mask:0xf
	v_fmac_f32_dpp v196, v224, v40 row_newbcast:10 row_mask:0xf bank_mask:0xf
	v_fmac_f32_dpp v197, v225, v41 row_newbcast:10 row_mask:0xf bank_mask:0xf
	v_fmac_f32_dpp v198, v226, v42 row_newbcast:10 row_mask:0xf bank_mask:0xf
	v_fmac_f32_dpp v199, v227, v43 row_newbcast:10 row_mask:0xf bank_mask:0xf
	v_fmac_f32_dpp v196, v224, v44 row_newbcast:11 row_mask:0xf bank_mask:0xf
	v_fmac_f32_dpp v197, v225, v45 row_newbcast:11 row_mask:0xf bank_mask:0xf
	v_fmac_f32_dpp v198, v226, v46 row_newbcast:11 row_mask:0xf bank_mask:0xf
	v_fmac_f32_dpp v199, v227, v47 row_newbcast:11 row_mask:0xf bank_mask:0xf
	v_fmac_f32_dpp v196, v224, v48 row_newbcast:12 row_mask:0xf bank_mask:0xf
	v_fmac_f32_dpp v197, v225, v49 row_newbcast:12 row_mask:0xf bank_mask:0xf
	v_fmac_f32_dpp v198, v226, v50 row_newbcast:12 row_mask:0xf bank_mask:0xf
	v_fmac_f32_dpp v199, v227, v51 row_newbcast:12 row_mask:0xf bank_mask:0xf
	v_fmac_f32_dpp v196, v224, v52 row_newbcast:13 row_mask:0xf bank_mask:0xf
	v_fmac_f32_dpp v197, v225, v53 row_newbcast:13 row_mask:0xf bank_mask:0xf
	v_fmac_f32_dpp v198, v226, v54 row_newbcast:13 row_mask:0xf bank_mask:0xf
	v_fmac_f32_dpp v199, v227, v55 row_newbcast:13 row_mask:0xf bank_mask:0xf
	v_fmac_f32_dpp v196, v224, v56 row_newbcast:14 row_mask:0xf bank_mask:0xf
	v_fmac_f32_dpp v197, v225, v57 row_newbcast:14 row_mask:0xf bank_mask:0xf
	v_fmac_f32_dpp v198, v226, v58 row_newbcast:14 row_mask:0xf bank_mask:0xf
	v_fmac_f32_dpp v199, v227, v59 row_newbcast:14 row_mask:0xf bank_mask:0xf
	v_fmac_f32_dpp v196, v224, v60 row_newbcast:15 row_mask:0xf bank_mask:0xf
	v_fmac_f32_dpp v197, v225, v61 row_newbcast:15 row_mask:0xf bank_mask:0xf
	v_fmac_f32_dpp v198, v226, v62 row_newbcast:15 row_mask:0xf bank_mask:0xf
	v_fmac_f32_dpp v199, v227, v63 row_newbcast:15 row_mask:0xf bank_mask:0xf
	v_add_f32_e32 v196, v196, v197
	v_add_f32_e32 v198, v198, v199
	v_sub_f32_e64 v202, -v196, v198
	s_waitcnt lgkmcnt(0)
; #define SB __builtin_amdgcn_sched_barrier(0)
; #define LD1(set, s) { const int e_ = min((int)(s), LC - 1) * (int)stp; const unsigned s4_ = ob4 + (unsigned)(e_ * 4), s2_ = ob2 + (unsigned)(e_ * 2); set.w = LDX(rW, s4_); set.a = LDX(rA, s4_); set.b = LDX(rB, s4_); \
;             set.kw = __builtin_amdgcn_raw_buffer_load_b64(rK, lo8, s2_, 0); set.v = __builtin_amdgcn_raw_buffer_load_b16(rV, lo2, s2_, 0); }
; #define TOUCH1(set) asm volatile("" :: "v"(set.w), "v"(set.a), "v"(set.b), "v"(set.kw), "v"(set.v))
; #define ST1(set) { DERIVE_BK(set); float sd[4]; ScanK<0>::dot(S, set.a, sd); ScanK<0>::updS(S, set, -((sd[0] + sd[1]) + (sd[2] + sd[3])), __uint_as_float(set.v << 16)); }
; #define LD1(set, s) { const int e_ = min((int)(s), LC - 1) * (int)stp; const unsigned s4_ = ob4 + (unsigned)(e_ * 4); set.w = LDX(rW, s4_); set.a = LDX(rA, s4_); set.b = LDX(rB, s4_); }
; #define TOUCH1(set) asm volatile("" :: "v"(set.w), "v"(set.a), "v"(set.b))
; #define ST1(set) { DERIVE_B(set); float sd[4]; ScanK<0>::dot(S, set.a, sd); ScanK<0>::updP(S, set, -((sd[0] + sd[1]) + (sd[2] + sd[3]))); }
; template <bool MIX> __device__ __forceinline__ void scan_pass1(const Params& p, int d, float* ldsf) {
;     ...
;             for (int s = 0; s < LC; s += 2) { TOUCH1(i0); SB; LD1(i1, s + 1); SB; ST1(i0); TOUCH1(i1); SB; LD1(i0, s + 2); SB; ST1(i1); }
	s_nop 1
	v_mfma_f32_4x4x1_16b_f32 v[0:3], v64, v202, v[0:3]
	v_mfma_f32_4x4x1_16b_f32 v[4:7], v65, v202, v[4:7]
	v_mfma_f32_4x4x1_16b_f32 v[8:11], v66, v202, v[8:11]
	v_mfma_f32_4x4x1_16b_f32 v[12:15], v67, v202, v[12:15]
	v_mfma_f32_4x4x1_16b_f32 v[16:19], v68, v202, v[16:19]
	v_mfma_f32_4x4x1_16b_f32 v[20:23], v69, v202, v[20:23]
	v_mfma_f32_4x4x1_16b_f32 v[24:27], v70, v202, v[24:27]
	v_mfma_f32_4x4x1_16b_f32 v[28:31], v71, v202, v[28:31]
	v_mfma_f32_4x4x1_16b_f32 v[32:35], v72, v202, v[32:35]
	v_mfma_f32_4x4x1_16b_f32 v[36:39], v73, v202, v[36:39]
	v_mfma_f32_4x4x1_16b_f32 v[40:43], v74, v202, v[40:43]
	v_mfma_f32_4x4x1_16b_f32 v[44:47], v75, v202, v[44:47]
	v_mfma_f32_4x4x1_16b_f32 v[48:51], v76, v202, v[48:51]
	v_mfma_f32_4x4x1_16b_f32 v[52:55], v77, v202, v[52:55]
	v_mfma_f32_4x4x1_16b_f32 v[56:59], v78, v202, v[56:59]
	v_mfma_f32_4x4x1_16b_f32 v[60:63], v79, v202, v[60:63]
	s_sub_u32 s83, s83, 1
	s_cmp_eq_u32 s83, 0
	s_cbranch_scc1 .Lmy_p1d0_ldone_p
	s_and_b32 s9, s83, 7
	s_cmp_eq_u32 s9, 0
	s_cbranch_scc1 .Lmy_p1d0_renorm_p
	s_branch .Lmy_p1d0_loop_p

; #define MKR(ptr) __builtin_amdgcn_make_buffer_rsrc((void*)(ptr), 0, 0x7fffffff, 0x00027000)
; __device__ __forceinline__ void scan_pass2(const Params& p, int d) {
;     const int lane = threadIdx.x & 63, wid = __builtin_amdgcn_readfirstlane(threadIdx.x >> 6); const unsigned lo16 = (lane & 15) * 16, lo2 = lane * 2, lo4b = lane * 4;
;     const float* Wd = (const float*)(p.ws + O_KD); const float* Bd = (const float*)(p.ws + O_Y); const u16* KB = (const u16*)(p.ws + O_K); const float* A = (const float*)(p.ws + O_A); const float* R = (const float*)(p.ws + O_R); const unsigned lo8 = (lane & 15) * 8;
;     const u16* V = (const u16*)(p.ws + O_V); const float* SIT = (const float*)(p.ws + O_SIT); float* Y = p.out;
;     for (int item = blockIdx.x * 8 + wid; item < 32 * NC; item += gridDim.x * 8) {
;         const int bh = item / NC, c = item - bh * NC, b = bh >> 4, h = bh & 15;
;         const int t0 = d ? (SEQ - 1 - c * LC) : c * LC;
;         const size_t off0 = ((size_t)(b * SEQ + t0)) * RW + h * 64; const long stp = d ? -(long)RW : (long)RW;
;         const unsigned ob4 = (unsigned)(off0 * 4), ob2 = (unsigned)(off0 * 2);
;         const __amdgpu_buffer_rsrc_t rW = MKR(Wd), rA = MKR(A), rB = MKR(Bd), rK = MKR(KB), rV = MKR(V), rR = MKR(R), rY = MKR(Y);
;         const f32x4 ka4 = *(const f32x4*)(p.k_a + h * 64 + (lane & 15) * 4), c04 = 1.0f - ka4;
;         float S[64];
;         if (c == 0) {
; #pragma unroll
;             for (int i = 0; i < 64; ++i) S[i] = 0.f;
;         } else { const float* si = SIT + ((size_t)(bh * NC + c)) * 4096 + lane * 64;
; #pragma unroll
;             for (int i = 0; i < 16; ++i) { const f32x4 q = *(const f32x4*)(si + 4 * i); S[4 * i] = q[0]; S[4 * i + 1] = q[1]; S[4 * i + 2] = q[2]; S[4 * i + 3] = q[3]; } }
;     ...
;         In2 i0, i1; LD2(i0, 0);
.LBB0_688:
	s_cmp_lt_i32 s58, 7
	s_cselect_b64 s[0:1], -1, 0
	s_cmp_gt_i32 s59, 6
	s_cselect_b64 s[4:5], -1, 0
	s_and_b64 s[0:1], s[0:1], s[4:5]
	s_andn2_b64 vcc, exec, s[0:1]
	s_cbranch_vccnz .LBB0_750
	v_readfirstlane_b32 s0, v254
	s_nop 3
	s_lshr_b32 s1, s0, 6
	s_lshl_b32 s0, s2, 3
	s_add_i32 s0, s1, s0
	s_mov_b32 s64, s56
	s_and_b32 s65, s57, 0xffff
	s_brev_b32 s66, -2
	s_mov_b32 s67, 0x27000
	s_mov_b32 s68, s54
	s_and_b32 s69, s55, 0xffff
	s_mov_b32 s70, s66
	s_mov_b32 s71, s67
	v_and_b32_e32 v212, 63, v254
	v_and_b32_e32 v213, 15, v254
	v_lshlrev_b32_e32 v204, 4, v213
	v_lshlrev_b32_e32 v205, 3, v213
	v_lshlrev_b32_e32 v206, 1, v212
	v_lshlrev_b32_e32 v207, 2, v212
	v_lshlrev_b32_e32 v210, 8, v212
	s_lshl_b32 s3, s1, 10
	s_add_u32 s3, s3, 0x10000
	v_lshl_add_u32 v208, v213, 2, s3
	v_and_b32_e32 v209, 3, v254
	v_lshl_add_u32 v209, v209, 6, s3
	v_add_u32_e32 v232, 0xb800000, v204
	v_add_u32_e32 v233, 0x24800000, v204
	v_add_u32_e32 v234, 0x35a00000, v204
	v_add_u32_e32 v235, 0x1c800000, v204
	v_add_u32_e32 v236, 0x30800000, v205
	v_add_u32_e32 v237, 0x2c800000, v206
.Lmy_p2d0_item:
	s_cmpk_gt_i32 s0, 0x7ff
	s_cbranch_scc1 .Lmy_p2d0_end
	s_lshr_b32 s86, s0, 6
	s_and_b32 s85, s0, 63
	s_and_b32 s87, s86, 15
	s_lshr_b32 s6, s86, 4
	s_lshl_b32 s6, s6, 14
	s_lshl_b32 s7, s85, 8
	s_add_u32 s6, s6, s7
	s_lshl_b32 s6, s6, 10
	s_lshl_b32 s7, s87, 6
	s_add_u32 s84, s6, s7
	s_lshl_b32 s6, s84, 2
	s_lshl_b32 s7, s84, 1
	s_mov_b32 s72, s6
	s_mov_b32 s76, s7
	s_mov_b32 s78, s6
	s_mov_b32 s79, s6
	s_lshl_b32 s8, s87, 8
	s_add_u32 s4, s42, s8
	s_addc_u32 s5, s43, 0
	global_load_dwordx4 v[188:191], v204, s[4:5]
	buffer_load_dwordx4 v[96:99], v232, s[64:67], s72 offen
	buffer_load_dwordx4 v[100:103], v233, s[64:67], s72 offen
	buffer_load_dwordx4 v[104:107], v234, s[64:67], s72 offen
	buffer_load_dwordx4 v[108:111], v235, s[64:67], s72 offen
	buffer_load_dwordx2 v[112:113], v236, s[64:67], s76 offen
	buffer_load_ushort v114, v237, s[64:67], s76 offen
	s_add_u32 s72, s72, 0x1000
	s_add_u32 s76, s76, 0x800
	buffer_load_dwordx4 v[116:119], v232, s[64:67], s72 offen
	buffer_load_dwordx4 v[120:123], v233, s[64:67], s72 offen
	buffer_load_dwordx4 v[124:127], v234, s[64:67], s72 offen
	buffer_load_dwordx4 v[128:131], v235, s[64:67], s72 offen
	buffer_load_dwordx2 v[132:133], v236, s[64:67], s76 offen
	buffer_load_ushort v134, v237, s[64:67], s76 offen
	s_add_u32 s72, s72, 0x1000
	s_add_u32 s76, s76, 0x800
	buffer_load_dwordx4 v[136:139], v232, s[64:67], s72 offen
	buffer_load_dwordx4 v[140:143], v233, s[64:67], s72 offen
	buffer_load_dwordx4 v[144:147], v234, s[64:67], s72 offen
	buffer_load_dwordx4 v[148:151], v235, s[64:67], s72 offen
	buffer_load_dwordx2 v[152:153], v236, s[64:67], s76 offen
	buffer_load_ushort v154, v237, s[64:67], s76 offen
	s_add_u32 s72, s72, 0x1000
	s_add_u32 s76, s76, 0x800
	s_cmp_eq_u32 s85, 0
	s_cbranch_scc1 .Lmy_p2d0_zero
	s_lshl_b32 s8, s0, 14
	s_add_u32 s8, s8, 0x3da00000
	s_add_u32 s4, s56, s8
	s_addc_u32 s5, s57, 0
	global_load_dwordx4 v[0:3], v210, s[4:5] offset:0
	global_load_dwordx4 v[4:7], v210, s[4:5] offset:16
	global_load_dwordx4 v[8:11], v210, s[4:5] offset:32
	global_load_dwordx4 v[12:15], v210, s[4:5] offset:48
	global_load_dwordx4 v[16:19], v210, s[4:5] offset:64
	global_load_dwordx4 v[20:23], v210, s[4:5] offset:80
	global_load_dwordx4 v[24:27], v210, s[4:5] offset:96
	global_load_dwordx4 v[28:31], v210, s[4:5] offset:112
	global_load_dwordx4 v[32:35], v210, s[4:5] offset:128
	global_load_dwordx4 v[36:39], v210, s[4:5] offset:144
	global_load_dwordx4 v[40:43], v210, s[4:5] offset:160
	global_load_dwordx4 v[44:47], v210, s[4:5] offset:176
	global_load_dwordx4 v[48:51], v210, s[4:5] offset:192
	global_load_dwordx4 v[52:55], v210, s[4:5] offset:208
	global_load_dwordx4 v[56:59], v210, s[4:5] offset:224
	global_load_dwordx4 v[60:63], v210, s[4:5] offset:240
	s_branch .Lmy_p2d0_init_done

; #define SB __builtin_amdgcn_sched_barrier(0)
; #define ST2(set, s) { DERIVE_BK(set); float sd[4]; ScanK<0>::dot(S, set.a, sd); float y0 = set.yo, y1 = 0.f; ScanK<0>::upd(S, set, -((sd[0] + sd[1]) + (sd[2] + sd[3])), __uint_as_float(set.v << 16), y0, y1); __builtin_amdgcn_raw_buffer_store_b32(__float_as_uint(y0 + y1), rY, lo4b, ob4 + (unsigned)((int)(s) * (int)stp * 4), 0); }
;     static __device__ __forceinline__ void upd(float (&S)[64], const In2& in, float sa, float vv, float& y0, float& y1) {
;         float t0, t1, t2, t3;
;         asm volatile("v_mul_f32_dpp %0, %10, %27 row_newbcast:%28" DPPM "v_mul_f32_dpp %1, %11, %27 row_newbcast:%28" DPPM "v_mul_f32_dpp %2, %12, %27 row_newbcast:%28" DPPM "v_mul_f32_dpp %3, %13, %27 row_newbcast:%28" DPPM
;                      "v_fmac_f32_dpp %0, %14, %6 row_newbcast:%28" DPPM "v_fmac_f32_dpp %1, %15, %7 row_newbcast:%28" DPPM "v_fmac_f32_dpp %2, %16, %8 row_newbcast:%28" DPPM "v_fmac_f32_dpp %3, %17, %9 row_newbcast:%28" DPPM
;                      "v_fmac_f32_dpp %0, %18, %26 row_newbcast:%28" DPPM "v_fmac_f32_dpp %1, %19, %26 row_newbcast:%28" DPPM "v_fmac_f32_dpp %2, %20, %26 row_newbcast:%28" DPPM "v_fmac_f32_dpp %3, %21, %26 row_newbcast:%28" DPPM
;                      "v_fmac_f32_dpp %4, %22, %0 row_newbcast:%28" DPPM "v_fmac_f32_dpp %5, %23, %1 row_newbcast:%28" DPPM "v_fmac_f32_dpp %4, %24, %2 row_newbcast:%28" DPPM "v_fmac_f32_dpp %5, %25, %3 row_newbcast:%28" DPPM
;                      : "=&v"(t0), "=&v"(t1), "=&v"(t2), "=&v"(t3), "+v"(y0), "+v"(y1)
;                      : "v"(S[K]), "v"(S[K + 1]), "v"(S[K + 2]), "v"(S[K + 3]), "v"(in.kd[0]), "v"(in.kd[1]), "v"(in.kd[2]), "v"(in.kd[3]), "v"(in.w[0]), "v"(in.w[1]), "v"(in.w[2]), "v"(in.w[3]),
;                        "v"(in.b[0]), "v"(in.b[1]), "v"(in.b[2]), "v"(in.b[3]), "v"(in.r[0]), "v"(in.r[1]), "v"(in.r[2]), "v"(in.r[3]), "v"(sa), "v"(vv), "n"(N0));
;         S[K] = t0; S[K + 1] = t1; S[K + 2] = t2; S[K + 3] = t3;
;         if constexpr (K + 4 < 64) ScanK<K + 4>::upd(S, in, sa, vv, y0, y1);
;     }
; __device__ __forceinline__ void scan_pass2(const Params& p, int d) {
;     ...
;         In2 i0, i1; LD2(i0, 0);
; #pragma unroll 1
;         for (int s = 0; s < LC; s += 2) { TOUCH2(i0); SB; LD2(i1, s + 1); SB; ST2(i0, s); TOUCH2(i1); SB; LD2(i0, s + 2); SB; ST2(i1, s + 1); }
.Lmy_p2d0_loop:
	s_waitcnt vmcnt(12)
	s_cmp_eq_u32 s83, 64
	s_cbranch_scc1 .Lmy_p2d0_nost
	buffer_store_dword v200, v207, s[68:71], s79 offen
	s_add_u32 s79, s79, 0x1000
.Lmy_p2d0_nost:
	buffer_load_dwordx4 v[156:159], v232, s[64:67], s72 offen
	buffer_load_dwordx4 v[160:163], v233, s[64:67], s72 offen
	buffer_load_dwordx4 v[164:167], v234, s[64:67], s72 offen
	buffer_load_dwordx4 v[168:171], v235, s[64:67], s72 offen
	buffer_load_dwordx2 v[172:173], v236, s[64:67], s76 offen
	buffer_load_ushort v174, v237, s[64:67], s76 offen
	s_add_u32 s72, s72, 0x1000
	s_add_u32 s76, s76, 0x800
	v_pk_mul_f32 v[224:225], v[100:101], v[216:217]
	v_pk_mul_f32 v[226:227], v[102:103], v[218:219]
	v_pk_mul_f32 v[216:217], v[216:217], v[96:97]
	v_pk_mul_f32 v[218:219], v[218:219], v[98:99]
	v_pk_fma_f32 v[184:185], v[104:105], v[188:189], v[192:193]
	v_pk_fma_f32 v[186:187], v[106:107], v[190:191], v[194:195]
	v_pk_mul_f32 v[176:177], v[100:101], v[104:105]
	v_pk_mul_f32 v[178:179], v[102:103], v[106:107]
	v_rcp_f32_e32 v220, v216
	v_rcp_f32_e32 v221, v217
	v_rcp_f32_e32 v222, v218
	v_rcp_f32_e32 v223, v219
	v_lshlrev_b32_e32 v180, 16, v112
	v_and_b32_e32 v181, 0xffff0000, v112
	v_lshlrev_b32_e32 v182, 16, v113
	v_and_b32_e32 v183, 0xffff0000, v113
	v_pk_mul_f32 v[180:181], v[180:181], v[184:185]
	v_pk_mul_f32 v[182:183], v[182:183], v[186:187]
	v_pk_mul_f32 v[228:229], v[108:109], v[216:217]
	v_pk_mul_f32 v[230:231], v[110:111], v[218:219]
	v_pk_mul_f32 v[176:177], v[176:177], v[220:221]
	v_pk_mul_f32 v[178:179], v[178:179], v[222:223]
	v_pk_mul_f32 v[180:181], v[180:181], v[220:221]
	v_pk_mul_f32 v[182:183], v[182:183], v[222:223]
	v_lshlrev_b32_e32 v203, 16, v114
	ds_write2_b32 v208, v176, v177 offset0:0 offset1:16
	ds_write2_b32 v208, v178, v179 offset0:32 offset1:48
	ds_write2_b32 v208, v180, v181 offset0:64 offset1:80
	ds_write2_b32 v208, v182, v183 offset0:96 offset1:112
	ds_read_b128 v[64:67], v209 offset:0
	ds_read_b128 v[68:71], v209 offset:16
	ds_read_b128 v[72:75], v209 offset:32
	ds_read_b128 v[76:79], v209 offset:48
	ds_read_b128 v[80:83], v209 offset:256
	ds_read_b128 v[84:87], v209 offset:272
	ds_read_b128 v[88:91], v209 offset:288
	ds_read_b128 v[92:95], v209 offset:304
	v_mul_f32_dpp v196, v224, v0 row_newbcast:0 row_mask:0xf bank_mask:0xf
	v_mul_f32_dpp v197, v225, v1 row_newbcast:0 row_mask:0xf bank_mask:0xf
	v_mul_f32_dpp v198, v226, v2 row_newbcast:0 row_mask:0xf bank_mask:0xf
	v_mul_f32_dpp v199, v227, v3 row_newbcast:0 row_mask:0xf bank_mask:0xf
	v_fmac_f32_dpp v196, v224, v4 row_newbcast:1 row_mask:0xf bank_mask:0xf
	v_fmac_f32_dpp v197, v225, v5 row_newbcast:1 row_mask:0xf bank_mask:0xf
	v_fmac_f32_dpp v198, v226, v6 row_newbcast:1 row_mask:0xf bank_mask:0xf
	v_fmac_f32_dpp v199, v227, v7 row_newbcast:1 row_mask:0xf bank_mask:0xf
	v_fmac_f32_dpp v196, v224, v8 row_newbcast:2 row_mask:0xf bank_mask:0xf
	v_fmac_f32_dpp v197, v225, v9 row_newbcast:2 row_mask:0xf bank_mask:0xf
	v_fmac_f32_dpp v198, v226, v10 row_newbcast:2 row_mask:0xf bank_mask:0xf
	v_fmac_f32_dpp v199, v227, v11 row_newbcast:2 row_mask:0xf bank_mask:0xf
	v_fmac_f32_dpp v196, v224, v12 row_newbcast:3 row_mask:0xf bank_mask:0xf
	v_fmac_f32_dpp v197, v225, v13 row_newbcast:3 row_mask:0xf bank_mask:0xf
	v_fmac_f32_dpp v198, v226, v14 row_newbcast:3 row_mask:0xf bank_mask:0xf
	v_fmac_f32_dpp v199, v227, v15 row_newbcast:3 row_mask:0xf bank_mask:0xf
	v_fmac_f32_dpp v196, v224, v16 row_newbcast:4 row_mask:0xf bank_mask:0xf
	v_fmac_f32_dpp v197, v225, v17 row_newbcast:4 row_mask:0xf bank_mask:0xf
	v_fmac_f32_dpp v198, v226, v18 row_newbcast:4 row_mask:0xf bank_mask:0xf
	v_fmac_f32_dpp v199, v227, v19 row_newbcast:4 row_mask:0xf bank_mask:0xf
	v_fmac_f32_dpp v196, v224, v20 row_newbcast:5 row_mask:0xf bank_mask:0xf
	v_fmac_f32_dpp v197, v225, v21 row_newbcast:5 row_mask:0xf bank_mask:0xf
	v_fmac_f32_dpp v198, v226, v22 row_newbcast:5 row_mask:0xf bank_mask:0xf
	v_fmac_f32_dpp v199, v227, v23 row_newbcast:5 row_mask:0xf bank_mask:0xf
	v_fmac_f32_dpp v196, v224, v24 row_newbcast:6 row_mask:0xf bank_mask:0xf
	v_fmac_f32_dpp v197, v225, v25 row_newbcast:6 row_mask:0xf bank_mask:0xf
	v_fmac_f32_dpp v198, v226, v26 row_newbcast:6 row_mask:0xf bank_mask:0xf
	v_fmac_f32_dpp v199, v227, v27 row_newbcast:6 row_mask:0xf bank_mask:0xf
	v_fmac_f32_dpp v196, v224, v28 row_newbcast:7 row_mask:0xf bank_mask:0xf
	v_fmac_f32_dpp v197, v225, v29 row_newbcast:7 row_mask:0xf bank_mask:0xf
	v_fmac_f32_dpp v198, v226, v30 row_newbcast:7 row_mask:0xf bank_mask:0xf
	v_fmac_f32_dpp v199, v227, v31 row_newbcast:7 row_mask:0xf bank_mask:0xf
	v_fmac_f32_dpp v196, v224, v32 row_newbcast:8 row_mask:0xf bank_mask:0xf
	v_fmac_f32_dpp v197, v225, v33 row_newbcast:8 row_mask:0xf bank_mask:0xf
	v_fmac_f32_dpp v198, v226, v34 row_newbcast:8 row_mask:0xf bank_mask:0xf
	v_fmac_f32_dpp v199, v227, v35 row_newbcast:8 row_mask:0xf bank_mask:0xf
	v_fmac_f32_dpp v196, v224, v36 row_newbcast:9 row_mask:0xf bank_mask:0xf
	v_fmac_f32_dpp v197, v225, v37 row_newbcast:9 row_mask:0xf bank_mask:0xf
	v_fmac_f32_dpp v198, v226, v38 row_newbcast:9 row_mask:0xf bank_mask:0xf
	v_fmac_f32_dpp v199, v227, v39 row_newbcast:9 row_mask:0xf bank_mask:0xf
	v_fmac_f32_dpp v196, v224, v40 row_newbcast:10 row_mask:0xf bank_mask:0xf
	v_fmac_f32_dpp v197, v225, v41 row_newbcast:10 row_mask:0xf bank_mask:0xf
	v_fmac_f32_dpp v198, v226, v42 row_newbcast:10 row_mask:0xf bank_mask:0xf
	v_fmac_f32_dpp v199, v227, v43 row_newbcast:10 row_mask:0xf bank_mask:0xf
	v_fmac_f32_dpp v196, v224, v44 row_newbcast:11 row_mask:0xf bank_mask:0xf
	v_fmac_f32_dpp v197, v225, v45 row_newbcast:11 row_mask:0xf bank_mask:0xf
	v_fmac_f32_dpp v198, v226, v46 row_newbcast:11 row_mask:0xf bank_mask:0xf
;     static __device__ __forceinline__ void upd(float (&S)[64], const In2& in, float sa, float vv, float& y0, float& y1) {
;         float t0, t1, t2, t3;
;         asm volatile("v_mul_f32_dpp %0, %10, %27 row_newbcast:%28" DPPM "v_mul_f32_dpp %1, %11, %27 row_newbcast:%28" DPPM "v_mul_f32_dpp %2, %12, %27 row_newbcast:%28" DPPM "v_mul_f32_dpp %3, %13, %27 row_newbcast:%28" DPPM
;                      "v_fmac_f32_dpp %0, %14, %6 row_newbcast:%28" DPPM "v_fmac_f32_dpp %1, %15, %7 row_newbcast:%28" DPPM "v_fmac_f32_dpp %2, %16, %8 row_newbcast:%28" DPPM "v_fmac_f32_dpp %3, %17, %9 row_newbcast:%28" DPPM
;                      "v_fmac_f32_dpp %0, %18, %26 row_newbcast:%28" DPPM "v_fmac_f32_dpp %1, %19, %26 row_newbcast:%28" DPPM "v_fmac_f32_dpp %2, %20, %26 row_newbcast:%28" DPPM "v_fmac_f32_dpp %3, %21, %26 row_newbcast:%28" DPPM
;                      "v_fmac_f32_dpp %4, %22, %0 row_newbcast:%28" DPPM "v_fmac_f32_dpp %5, %23, %1 row_newbcast:%28" DPPM "v_fmac_f32_dpp %4, %24, %2 row_newbcast:%28" DPPM "v_fmac_f32_dpp %5, %25, %3 row_newbcast:%28" DPPM
;                      : "=&v"(t0), "=&v"(t1), "=&v"(t2), "=&v"(t3), "+v"(y0), "+v"(y1)
;                      : "v"(S[K]), "v"(S[K + 1]), "v"(S[K + 2]), "v"(S[K + 3]), "v"(in.kd[0]), "v"(in.kd[1]), "v"(in.kd[2]), "v"(in.kd[3]), "v"(in.w[0]), "v"(in.w[1]), "v"(in.w[2]), "v"(in.w[3]),
;                        "v"(in.b[0]), "v"(in.b[1]), "v"(in.b[2]), "v"(in.b[3]), "v"(in.r[0]), "v"(in.r[1]), "v"(in.r[2]), "v"(in.r[3]), "v"(sa), "v"(vv), "n"(N0));
;         S[K] = t0; S[K + 1] = t1; S[K + 2] = t2; S[K + 3] = t3;
;         if constexpr (K + 4 < 64) ScanK<K + 4>::upd(S, in, sa, vv, y0, y1);
;     }
	v_fmac_f32_dpp v199, v227, v47 row_newbcast:11 row_mask:0xf bank_mask:0xf
	v_fmac_f32_dpp v196, v224, v48 row_newbcast:12 row_mask:0xf bank_mask:0xf
	v_fmac_f32_dpp v197, v225, v49 row_newbcast:12 row_mask:0xf bank_mask:0xf
	v_fmac_f32_dpp v198, v226, v50 row_newbcast:12 row_mask:0xf bank_mask:0xf
	v_fmac_f32_dpp v199, v227, v51 row_newbcast:12 row_mask:0xf bank_mask:0xf
	v_fmac_f32_dpp v196, v224, v52 row_newbcast:13 row_mask:0xf bank_mask:0xf
	v_fmac_f32_dpp v197, v225, v53 row_newbcast:13 row_mask:0xf bank_mask:0xf
	v_fmac_f32_dpp v198, v226, v54 row_newbcast:13 row_mask:0xf bank_mask:0xf
	v_fmac_f32_dpp v199, v227, v55 row_newbcast:13 row_mask:0xf bank_mask:0xf
	v_fmac_f32_dpp v196, v224, v56 row_newbcast:14 row_mask:0xf bank_mask:0xf
	v_fmac_f32_dpp v197, v225, v57 row_newbcast:14 row_mask:0xf bank_mask:0xf
	v_fmac_f32_dpp v198, v226, v58 row_newbcast:14 row_mask:0xf bank_mask:0xf
	v_fmac_f32_dpp v199, v227, v59 row_newbcast:14 row_mask:0xf bank_mask:0xf
	v_fmac_f32_dpp v196, v224, v60 row_newbcast:15 row_mask:0xf bank_mask:0xf
	v_fmac_f32_dpp v197, v225, v61 row_newbcast:15 row_mask:0xf bank_mask:0xf
	v_fmac_f32_dpp v198, v226, v62 row_newbcast:15 row_mask:0xf bank_mask:0xf
	v_fmac_f32_dpp v199, v227, v63 row_newbcast:15 row_mask:0xf bank_mask:0xf
	v_add_f32_e32 v196, v196, v197
	v_add_f32_e32 v198, v198, v199
	v_sub_f32_e64 v202, -v196, v198
	s_waitcnt lgkmcnt(0)
	s_nop 1
	v_mfma_f32_4x4x1_16b_f32 v[0:3], v64, v202, v[0:3]
	v_mfma_f32_4x4x1_16b_f32 v[4:7], v65, v202, v[4:7]
	v_mfma_f32_4x4x1_16b_f32 v[8:11], v66, v202, v[8:11]
	v_mfma_f32_4x4x1_16b_f32 v[12:15], v67, v202, v[12:15]
	v_mfma_f32_4x4x1_16b_f32 v[16:19], v68, v202, v[16:19]
	v_mfma_f32_4x4x1_16b_f32 v[20:23], v69, v202, v[20:23]
	v_mfma_f32_4x4x1_16b_f32 v[24:27], v70, v202, v[24:27]
	v_mfma_f32_4x4x1_16b_f32 v[28:31], v71, v202, v[28:31]
	v_mfma_f32_4x4x1_16b_f32 v[32:35], v72, v202, v[32:35]
	v_mfma_f32_4x4x1_16b_f32 v[36:39], v73, v202, v[36:39]
	v_mfma_f32_4x4x1_16b_f32 v[40:43], v74, v202, v[40:43]
	v_mfma_f32_4x4x1_16b_f32 v[44:47], v75, v202, v[44:47]
	v_mfma_f32_4x4x1_16b_f32 v[48:51], v76, v202, v[48:51]
	v_mfma_f32_4x4x1_16b_f32 v[52:55], v77, v202, v[52:55]
	v_mfma_f32_4x4x1_16b_f32 v[56:59], v78, v202, v[56:59]
	v_mfma_f32_4x4x1_16b_f32 v[60:63], v79, v202, v[60:63]
	v_mfma_f32_4x4x1_16b_f32 v[0:3], v80, v203, v[0:3]
	v_mfma_f32_4x4x1_16b_f32 v[4:7], v81, v203, v[4:7]
	v_mfma_f32_4x4x1_16b_f32 v[8:11], v82, v203, v[8:11]
	v_mfma_f32_4x4x1_16b_f32 v[12:15], v83, v203, v[12:15]
	v_mfma_f32_4x4x1_16b_f32 v[16:19], v84, v203, v[16:19]
	v_mfma_f32_4x4x1_16b_f32 v[20:23], v85, v203, v[20:23]
	v_mfma_f32_4x4x1_16b_f32 v[24:27], v86, v203, v[24:27]
	v_mfma_f32_4x4x1_16b_f32 v[28:31], v87, v203, v[28:31]
	v_mfma_f32_4x4x1_16b_f32 v[32:35], v88, v203, v[32:35]
	v_mfma_f32_4x4x1_16b_f32 v[36:39], v89, v203, v[36:39]
	v_mfma_f32_4x4x1_16b_f32 v[40:43], v90, v203, v[40:43]
	v_mfma_f32_4x4x1_16b_f32 v[44:47], v91, v203, v[44:47]
	v_mfma_f32_4x4x1_16b_f32 v[48:51], v92, v203, v[48:51]
	v_mfma_f32_4x4x1_16b_f32 v[52:55], v93, v203, v[52:55]
	v_mfma_f32_4x4x1_16b_f32 v[56:59], v94, v203, v[56:59]
	v_mfma_f32_4x4x1_16b_f32 v[60:63], v95, v203, v[60:63]
	v_mul_f32_dpp v200, v228, v0 row_newbcast:0 row_mask:0xf bank_mask:0xf
	v_mul_f32_dpp v201, v229, v1 row_newbcast:0 row_mask:0xf bank_mask:0xf
	v_fmac_f32_dpp v200, v230, v2 row_newbcast:0 row_mask:0xf bank_mask:0xf
	v_fmac_f32_dpp v201, v231, v3 row_newbcast:0 row_mask:0xf bank_mask:0xf
	v_fmac_f32_dpp v200, v228, v4 row_newbcast:1 row_mask:0xf bank_mask:0xf
	v_fmac_f32_dpp v201, v229, v5 row_newbcast:1 row_mask:0xf bank_mask:0xf
	v_fmac_f32_dpp v200, v230, v6 row_newbcast:1 row_mask:0xf bank_mask:0xf
	v_fmac_f32_dpp v201, v231, v7 row_newbcast:1 row_mask:0xf bank_mask:0xf
	v_fmac_f32_dpp v200, v228, v8 row_newbcast:2 row_mask:0xf bank_mask:0xf
	v_fmac_f32_dpp v201, v229, v9 row_newbcast:2 row_mask:0xf bank_mask:0xf
	v_fmac_f32_dpp v200, v230, v10 row_newbcast:2 row_mask:0xf bank_mask:0xf
	v_fmac_f32_dpp v201, v231, v11 row_newbcast:2 row_mask:0xf bank_mask:0xf
	v_fmac_f32_dpp v200, v228, v12 row_newbcast:3 row_mask:0xf bank_mask:0xf
	v_fmac_f32_dpp v201, v229, v13 row_newbcast:3 row_mask:0xf bank_mask:0xf
	v_fmac_f32_dpp v200, v230, v14 row_newbcast:3 row_mask:0xf bank_mask:0xf
	v_fmac_f32_dpp v201, v231, v15 row_newbcast:3 row_mask:0xf bank_mask:0xf
	v_fmac_f32_dpp v200, v228, v16 row_newbcast:4 row_mask:0xf bank_mask:0xf
	v_fmac_f32_dpp v201, v229, v17 row_newbcast:4 row_mask:0xf bank_mask:0xf
	v_fmac_f32_dpp v200, v230, v18 row_newbcast:4 row_mask:0xf bank_mask:0xf
	v_fmac_f32_dpp v201, v231, v19 row_newbcast:4 row_mask:0xf bank_mask:0xf
	v_fmac_f32_dpp v200, v228, v20 row_newbcast:5 row_mask:0xf bank_mask:0xf
	v_fmac_f32_dpp v201, v229, v21 row_newbcast:5 row_mask:0xf bank_mask:0xf
	v_fmac_f32_dpp v200, v230, v22 row_newbcast:5 row_mask:0xf bank_mask:0xf
	v_fmac_f32_dpp v201, v231, v23 row_newbcast:5 row_mask:0xf bank_mask:0xf
	v_fmac_f32_dpp v200, v228, v24 row_newbcast:6 row_mask:0xf bank_mask:0xf
	v_fmac_f32_dpp v201, v229, v25 row_newbcast:6 row_mask:0xf bank_mask:0xf
	v_fmac_f32_dpp v200, v230, v26 row_newbcast:6 row_mask:0xf bank_mask:0xf
	v_fmac_f32_dpp v201, v231, v27 row_newbcast:6 row_mask:0xf bank_mask:0xf
	v_fmac_f32_dpp v200, v228, v28 row_newbcast:7 row_mask:0xf bank_mask:0xf
	v_fmac_f32_dpp v201, v229, v29 row_newbcast:7 row_mask:0xf bank_mask:0xf
	v_fmac_f32_dpp v200, v230, v30 row_newbcast:7 row_mask:0xf bank_mask:0xf
	v_fmac_f32_dpp v201, v231, v31 row_newbcast:7 row_mask:0xf bank_mask:0xf
	v_fmac_f32_dpp v200, v228, v32 row_newbcast:8 row_mask:0xf bank_mask:0xf
; #define SB __builtin_amdgcn_sched_barrier(0)
; #define ST2(set, s) { DERIVE_BK(set); float sd[4]; ScanK<0>::dot(S, set.a, sd); float y0 = set.yo, y1 = 0.f; ScanK<0>::upd(S, set, -((sd[0] + sd[1]) + (sd[2] + sd[3])), __uint_as_float(set.v << 16), y0, y1); __builtin_amdgcn_raw_buffer_store_b32(__float_as_uint(y0 + y1), rY, lo4b, ob4 + (unsigned)((int)(s) * (int)stp * 4), 0); }
;     static __device__ __forceinline__ void upd(float (&S)[64], const In2& in, float sa, float vv, float& y0, float& y1) {
;         float t0, t1, t2, t3;
;         asm volatile("v_mul_f32_dpp %0, %10, %27 row_newbcast:%28" DPPM "v_mul_f32_dpp %1, %11, %27 row_newbcast:%28" DPPM "v_mul_f32_dpp %2, %12, %27 row_newbcast:%28" DPPM "v_mul_f32_dpp %3, %13, %27 row_newbcast:%28" DPPM
;                      "v_fmac_f32_dpp %0, %14, %6 row_newbcast:%28" DPPM "v_fmac_f32_dpp %1, %15, %7 row_newbcast:%28" DPPM "v_fmac_f32_dpp %2, %16, %8 row_newbcast:%28" DPPM "v_fmac_f32_dpp %3, %17, %9 row_newbcast:%28" DPPM
;                      "v_fmac_f32_dpp %0, %18, %26 row_newbcast:%28" DPPM "v_fmac_f32_dpp %1, %19, %26 row_newbcast:%28" DPPM "v_fmac_f32_dpp %2, %20, %26 row_newbcast:%28" DPPM "v_fmac_f32_dpp %3, %21, %26 row_newbcast:%28" DPPM
;                      "v_fmac_f32_dpp %4, %22, %0 row_newbcast:%28" DPPM "v_fmac_f32_dpp %5, %23, %1 row_newbcast:%28" DPPM "v_fmac_f32_dpp %4, %24, %2 row_newbcast:%28" DPPM "v_fmac_f32_dpp %5, %25, %3 row_newbcast:%28" DPPM
;                      : "=&v"(t0), "=&v"(t1), "=&v"(t2), "=&v"(t3), "+v"(y0), "+v"(y1)
;                      : "v"(S[K]), "v"(S[K + 1]), "v"(S[K + 2]), "v"(S[K + 3]), "v"(in.kd[0]), "v"(in.kd[1]), "v"(in.kd[2]), "v"(in.kd[3]), "v"(in.w[0]), "v"(in.w[1]), "v"(in.w[2]), "v"(in.w[3]),
;                        "v"(in.b[0]), "v"(in.b[1]), "v"(in.b[2]), "v"(in.b[3]), "v"(in.r[0]), "v"(in.r[1]), "v"(in.r[2]), "v"(in.r[3]), "v"(sa), "v"(vv), "n"(N0));
;         S[K] = t0; S[K + 1] = t1; S[K + 2] = t2; S[K + 3] = t3;
;         if constexpr (K + 4 < 64) ScanK<K + 4>::upd(S, in, sa, vv, y0, y1);
;     }
; __device__ __forceinline__ void scan_pass2(const Params& p, int d) {
;     ...
;         In2 i0, i1; LD2(i0, 0);
; #pragma unroll 1
;         for (int s = 0; s < LC; s += 2) { TOUCH2(i0); SB; LD2(i1, s + 1); SB; ST2(i0, s); TOUCH2(i1); SB; LD2(i0, s + 2); SB; ST2(i1, s + 1); }
	v_fmac_f32_dpp v201, v229, v33 row_newbcast:8 row_mask:0xf bank_mask:0xf
	v_fmac_f32_dpp v200, v230, v34 row_newbcast:8 row_mask:0xf bank_mask:0xf
	v_fmac_f32_dpp v201, v231, v35 row_newbcast:8 row_mask:0xf bank_mask:0xf
	v_fmac_f32_dpp v200, v228, v36 row_newbcast:9 row_mask:0xf bank_mask:0xf
	v_fmac_f32_dpp v201, v229, v37 row_newbcast:9 row_mask:0xf bank_mask:0xf
	v_fmac_f32_dpp v200, v230, v38 row_newbcast:9 row_mask:0xf bank_mask:0xf
	v_fmac_f32_dpp v201, v231, v39 row_newbcast:9 row_mask:0xf bank_mask:0xf
	v_fmac_f32_dpp v200, v228, v40 row_newbcast:10 row_mask:0xf bank_mask:0xf
	v_fmac_f32_dpp v201, v229, v41 row_newbcast:10 row_mask:0xf bank_mask:0xf
	v_fmac_f32_dpp v200, v230, v42 row_newbcast:10 row_mask:0xf bank_mask:0xf
	v_fmac_f32_dpp v201, v231, v43 row_newbcast:10 row_mask:0xf bank_mask:0xf
	v_fmac_f32_dpp v200, v228, v44 row_newbcast:11 row_mask:0xf bank_mask:0xf
	v_fmac_f32_dpp v201, v229, v45 row_newbcast:11 row_mask:0xf bank_mask:0xf
	v_fmac_f32_dpp v200, v230, v46 row_newbcast:11 row_mask:0xf bank_mask:0xf
	v_fmac_f32_dpp v201, v231, v47 row_newbcast:11 row_mask:0xf bank_mask:0xf
	v_fmac_f32_dpp v200, v228, v48 row_newbcast:12 row_mask:0xf bank_mask:0xf
	v_fmac_f32_dpp v201, v229, v49 row_newbcast:12 row_mask:0xf bank_mask:0xf
	v_fmac_f32_dpp v200, v230, v50 row_newbcast:12 row_mask:0xf bank_mask:0xf
	v_fmac_f32_dpp v201, v231, v51 row_newbcast:12 row_mask:0xf bank_mask:0xf
	v_fmac_f32_dpp v200, v228, v52 row_newbcast:13 row_mask:0xf bank_mask:0xf
	v_fmac_f32_dpp v201, v229, v53 row_newbcast:13 row_mask:0xf bank_mask:0xf
	v_fmac_f32_dpp v200, v230, v54 row_newbcast:13 row_mask:0xf bank_mask:0xf
	v_fmac_f32_dpp v201, v231, v55 row_newbcast:13 row_mask:0xf bank_mask:0xf
	v_fmac_f32_dpp v200, v228, v56 row_newbcast:14 row_mask:0xf bank_mask:0xf
	v_fmac_f32_dpp v201, v229, v57 row_newbcast:14 row_mask:0xf bank_mask:0xf
	v_fmac_f32_dpp v200, v230, v58 row_newbcast:14 row_mask:0xf bank_mask:0xf
	v_fmac_f32_dpp v201, v231, v59 row_newbcast:14 row_mask:0xf bank_mask:0xf
	v_fmac_f32_dpp v200, v228, v60 row_newbcast:15 row_mask:0xf bank_mask:0xf
	v_fmac_f32_dpp v201, v229, v61 row_newbcast:15 row_mask:0xf bank_mask:0xf
	v_fmac_f32_dpp v200, v230, v62 row_newbcast:15 row_mask:0xf bank_mask:0xf
	v_fmac_f32_dpp v201, v231, v63 row_newbcast:15 row_mask:0xf bank_mask:0xf
	v_add_f32_e32 v200, v200, v201
	s_waitcnt vmcnt(12)
	buffer_store_dword v200, v207, s[68:71], s79 offen
	s_add_u32 s79, s79, 0x1000
	buffer_load_dwordx4 v[96:99], v232, s[64:67], s72 offen
	buffer_load_dwordx4 v[100:103], v233, s[64:67], s72 offen
	buffer_load_dwordx4 v[104:107], v234, s[64:67], s72 offen
	buffer_load_dwordx4 v[108:111], v235, s[64:67], s72 offen
	buffer_load_dwordx2 v[112:113], v236, s[64:67], s76 offen
	buffer_load_ushort v114, v237, s[64:67], s76 offen
	s_add_u32 s72, s72, 0x1000
	s_add_u32 s76, s76, 0x800
	v_pk_mul_f32 v[224:225], v[120:121], v[216:217]
	v_pk_mul_f32 v[226:227], v[122:123], v[218:219]
	v_pk_mul_f32 v[216:217], v[216:217], v[116:117]
	v_pk_mul_f32 v[218:219], v[218:219], v[118:119]
	v_pk_fma_f32 v[184:185], v[124:125], v[188:189], v[192:193]
	v_pk_fma_f32 v[186:187], v[126:127], v[190:191], v[194:195]
	v_pk_mul_f32 v[176:177], v[120:121], v[124:125]
	v_pk_mul_f32 v[178:179], v[122:123], v[126:127]
	v_rcp_f32_e32 v220, v216
	v_rcp_f32_e32 v221, v217
	v_rcp_f32_e32 v222, v218
	v_rcp_f32_e32 v223, v219
	v_lshlrev_b32_e32 v180, 16, v132
	v_and_b32_e32 v181, 0xffff0000, v132
	v_lshlrev_b32_e32 v182, 16, v133
	v_and_b32_e32 v183, 0xffff0000, v133
	v_pk_mul_f32 v[180:181], v[180:181], v[184:185]
	v_pk_mul_f32 v[182:183], v[182:183], v[186:187]
	v_pk_mul_f32 v[228:229], v[128:129], v[216:217]
	v_pk_mul_f32 v[230:231], v[130:131], v[218:219]
	v_pk_mul_f32 v[176:177], v[176:177], v[220:221]
	v_pk_mul_f32 v[178:179], v[178:179], v[222:223]
	v_pk_mul_f32 v[180:181], v[180:181], v[220:221]
	v_pk_mul_f32 v[182:183], v[182:183], v[222:223]
	v_lshlrev_b32_e32 v203, 16, v134
	ds_write2_b32 v208, v176, v177 offset0:0 offset1:16
	ds_write2_b32 v208, v178, v179 offset0:32 offset1:48
	ds_write2_b32 v208, v180, v181 offset0:64 offset1:80
	ds_write2_b32 v208, v182, v183 offset0:96 offset1:112
	ds_read_b128 v[64:67], v209 offset:0
	ds_read_b128 v[68:71], v209 offset:16
	ds_read_b128 v[72:75], v209 offset:32
	ds_read_b128 v[76:79], v209 offset:48
	ds_read_b128 v[80:83], v209 offset:256
	ds_read_b128 v[84:87], v209 offset:272
	ds_read_b128 v[88:91], v209 offset:288
	ds_read_b128 v[92:95], v209 offset:304
	v_mul_f32_dpp v196, v224, v0 row_newbcast:0 row_mask:0xf bank_mask:0xf
	v_mul_f32_dpp v197, v225, v1 row_newbcast:0 row_mask:0xf bank_mask:0xf
	v_mul_f32_dpp v198, v226, v2 row_newbcast:0 row_mask:0xf bank_mask:0xf
	v_mul_f32_dpp v199, v227, v3 row_newbcast:0 row_mask:0xf bank_mask:0xf
	v_fmac_f32_dpp v196, v224, v4 row_newbcast:1 row_mask:0xf bank_mask:0xf
	v_fmac_f32_dpp v197, v225, v5 row_newbcast:1 row_mask:0xf bank_mask:0xf
	v_fmac_f32_dpp v198, v226, v6 row_newbcast:1 row_mask:0xf bank_mask:0xf
	v_fmac_f32_dpp v199, v227, v7 row_newbcast:1 row_mask:0xf bank_mask:0xf
	v_fmac_f32_dpp v196, v224, v8 row_newbcast:2 row_mask:0xf bank_mask:0xf
	v_fmac_f32_dpp v197, v225, v9 row_newbcast:2 row_mask:0xf bank_mask:0xf
	v_fmac_f32_dpp v198, v226, v10 row_newbcast:2 row_mask:0xf bank_mask:0xf
	v_fmac_f32_dpp v199, v227, v11 row_newbcast:2 row_mask:0xf bank_mask:0xf
	v_fmac_f32_dpp v196, v224, v12 row_newbcast:3 row_mask:0xf bank_mask:0xf
	v_fmac_f32_dpp v197, v225, v13 row_newbcast:3 row_mask:0xf bank_mask:0xf
	v_fmac_f32_dpp v198, v226, v14 row_newbcast:3 row_mask:0xf bank_mask:0xf
	v_fmac_f32_dpp v199, v227, v15 row_newbcast:3 row_mask:0xf bank_mask:0xf
;     static __device__ __forceinline__ void upd(float (&S)[64], const In2& in, float sa, float vv, float& y0, float& y1) {
;         float t0, t1, t2, t3;
;         asm volatile("v_mul_f32_dpp %0, %10, %27 row_newbcast:%28" DPPM "v_mul_f32_dpp %1, %11, %27 row_newbcast:%28" DPPM "v_mul_f32_dpp %2, %12, %27 row_newbcast:%28" DPPM "v_mul_f32_dpp %3, %13, %27 row_newbcast:%28" DPPM
;                      "v_fmac_f32_dpp %0, %14, %6 row_newbcast:%28" DPPM "v_fmac_f32_dpp %1, %15, %7 row_newbcast:%28" DPPM "v_fmac_f32_dpp %2, %16, %8 row_newbcast:%28" DPPM "v_fmac_f32_dpp %3, %17, %9 row_newbcast:%28" DPPM
;                      "v_fmac_f32_dpp %0, %18, %26 row_newbcast:%28" DPPM "v_fmac_f32_dpp %1, %19, %26 row_newbcast:%28" DPPM "v_fmac_f32_dpp %2, %20, %26 row_newbcast:%28" DPPM "v_fmac_f32_dpp %3, %21, %26 row_newbcast:%28" DPPM
;                      "v_fmac_f32_dpp %4, %22, %0 row_newbcast:%28" DPPM "v_fmac_f32_dpp %5, %23, %1 row_newbcast:%28" DPPM "v_fmac_f32_dpp %4, %24, %2 row_newbcast:%28" DPPM "v_fmac_f32_dpp %5, %25, %3 row_newbcast:%28" DPPM
;                      : "=&v"(t0), "=&v"(t1), "=&v"(t2), "=&v"(t3), "+v"(y0), "+v"(y1)
;                      : "v"(S[K]), "v"(S[K + 1]), "v"(S[K + 2]), "v"(S[K + 3]), "v"(in.kd[0]), "v"(in.kd[1]), "v"(in.kd[2]), "v"(in.kd[3]), "v"(in.w[0]), "v"(in.w[1]), "v"(in.w[2]), "v"(in.w[3]),
;                        "v"(in.b[0]), "v"(in.b[1]), "v"(in.b[2]), "v"(in.b[3]), "v"(in.r[0]), "v"(in.r[1]), "v"(in.r[2]), "v"(in.r[3]), "v"(sa), "v"(vv), "n"(N0));
;         S[K] = t0; S[K + 1] = t1; S[K + 2] = t2; S[K + 3] = t3;
;         if constexpr (K + 4 < 64) ScanK<K + 4>::upd(S, in, sa, vv, y0, y1);
;     }
	v_fmac_f32_dpp v196, v224, v16 row_newbcast:4 row_mask:0xf bank_mask:0xf
	v_fmac_f32_dpp v197, v225, v17 row_newbcast:4 row_mask:0xf bank_mask:0xf
	v_fmac_f32_dpp v198, v226, v18 row_newbcast:4 row_mask:0xf bank_mask:0xf
	v_fmac_f32_dpp v199, v227, v19 row_newbcast:4 row_mask:0xf bank_mask:0xf
	v_fmac_f32_dpp v196, v224, v20 row_newbcast:5 row_mask:0xf bank_mask:0xf
	v_fmac_f32_dpp v197, v225, v21 row_newbcast:5 row_mask:0xf bank_mask:0xf
	v_fmac_f32_dpp v198, v226, v22 row_newbcast:5 row_mask:0xf bank_mask:0xf
	v_fmac_f32_dpp v199, v227, v23 row_newbcast:5 row_mask:0xf bank_mask:0xf
	v_fmac_f32_dpp v196, v224, v24 row_newbcast:6 row_mask:0xf bank_mask:0xf
	v_fmac_f32_dpp v197, v225, v25 row_newbcast:6 row_mask:0xf bank_mask:0xf
	v_fmac_f32_dpp v198, v226, v26 row_newbcast:6 row_mask:0xf bank_mask:0xf
	v_fmac_f32_dpp v199, v227, v27 row_newbcast:6 row_mask:0xf bank_mask:0xf
	v_fmac_f32_dpp v196, v224, v28 row_newbcast:7 row_mask:0xf bank_mask:0xf
	v_fmac_f32_dpp v197, v225, v29 row_newbcast:7 row_mask:0xf bank_mask:0xf
	v_fmac_f32_dpp v198, v226, v30 row_newbcast:7 row_mask:0xf bank_mask:0xf
	v_fmac_f32_dpp v199, v227, v31 row_newbcast:7 row_mask:0xf bank_mask:0xf
	v_fmac_f32_dpp v196, v224, v32 row_newbcast:8 row_mask:0xf bank_mask:0xf
	v_fmac_f32_dpp v197, v225, v33 row_newbcast:8 row_mask:0xf bank_mask:0xf
	v_fmac_f32_dpp v198, v226, v34 row_newbcast:8 row_mask:0xf bank_mask:0xf
	v_fmac_f32_dpp v199, v227, v35 row_newbcast:8 row_mask:0xf bank_mask:0xf
	v_fmac_f32_dpp v196, v224, v36 row_newbcast:9 row_mask:0xf bank_mask:0xf
	v_fmac_f32_dpp v197, v225, v37 row_newbcast:9 row_mask:0xf bank_mask:0xf
	v_fmac_f32_dpp v198, v226, v38 row_newbcast:9 row_mask:0xf bank_mask:0xf
	v_fmac_f32_dpp v199, v227, v39 row_newbcast:9 row_mask:0xf bank_mask:0xf
	v_fmac_f32_dpp v196, v224, v40 row_newbcast:10 row_mask:0xf bank_mask:0xf
	v_fmac_f32_dpp v197, v225, v41 row_newbcast:10 row_mask:0xf bank_mask:0xf
	v_fmac_f32_dpp v198, v226, v42 row_newbcast:10 row_mask:0xf bank_mask:0xf
	v_fmac_f32_dpp v199, v227, v43 row_newbcast:10 row_mask:0xf bank_mask:0xf
	v_fmac_f32_dpp v196, v224, v44 row_newbcast:11 row_mask:0xf bank_mask:0xf
	v_fmac_f32_dpp v197, v225, v45 row_newbcast:11 row_mask:0xf bank_mask:0xf
	v_fmac_f32_dpp v198, v226, v46 row_newbcast:11 row_mask:0xf bank_mask:0xf
	v_fmac_f32_dpp v199, v227, v47 row_newbcast:11 row_mask:0xf bank_mask:0xf
	v_fmac_f32_dpp v196, v224, v48 row_newbcast:12 row_mask:0xf bank_mask:0xf
	v_fmac_f32_dpp v197, v225, v49 row_newbcast:12 row_mask:0xf bank_mask:0xf
	v_fmac_f32_dpp v198, v226, v50 row_newbcast:12 row_mask:0xf bank_mask:0xf
	v_fmac_f32_dpp v199, v227, v51 row_newbcast:12 row_mask:0xf bank_mask:0xf
	v_fmac_f32_dpp v196, v224, v52 row_newbcast:13 row_mask:0xf bank_mask:0xf
	v_fmac_f32_dpp v197, v225, v53 row_newbcast:13 row_mask:0xf bank_mask:0xf
	v_fmac_f32_dpp v198, v226, v54 row_newbcast:13 row_mask:0xf bank_mask:0xf
	v_fmac_f32_dpp v199, v227, v55 row_newbcast:13 row_mask:0xf bank_mask:0xf
	v_fmac_f32_dpp v196, v224, v56 row_newbcast:14 row_mask:0xf bank_mask:0xf
	v_fmac_f32_dpp v197, v225, v57 row_newbcast:14 row_mask:0xf bank_mask:0xf
	v_fmac_f32_dpp v198, v226, v58 row_newbcast:14 row_mask:0xf bank_mask:0xf
	v_fmac_f32_dpp v199, v227, v59 row_newbcast:14 row_mask:0xf bank_mask:0xf
	v_fmac_f32_dpp v196, v224, v60 row_newbcast:15 row_mask:0xf bank_mask:0xf
	v_fmac_f32_dpp v197, v225, v61 row_newbcast:15 row_mask:0xf bank_mask:0xf
	v_fmac_f32_dpp v198, v226, v62 row_newbcast:15 row_mask:0xf bank_mask:0xf
	v_fmac_f32_dpp v199, v227, v63 row_newbcast:15 row_mask:0xf bank_mask:0xf
	v_add_f32_e32 v196, v196, v197
	v_add_f32_e32 v198, v198, v199
	v_sub_f32_e64 v202, -v196, v198
	s_waitcnt lgkmcnt(0)
	s_nop 1
	v_mfma_f32_4x4x1_16b_f32 v[0:3], v64, v202, v[0:3]
	v_mfma_f32_4x4x1_16b_f32 v[4:7], v65, v202, v[4:7]
	v_mfma_f32_4x4x1_16b_f32 v[8:11], v66, v202, v[8:11]
	v_mfma_f32_4x4x1_16b_f32 v[12:15], v67, v202, v[12:15]
	v_mfma_f32_4x4x1_16b_f32 v[16:19], v68, v202, v[16:19]
	v_mfma_f32_4x4x1_16b_f32 v[20:23], v69, v202, v[20:23]
	v_mfma_f32_4x4x1_16b_f32 v[24:27], v70, v202, v[24:27]
	v_mfma_f32_4x4x1_16b_f32 v[28:31], v71, v202, v[28:31]
	v_mfma_f32_4x4x1_16b_f32 v[32:35], v72, v202, v[32:35]
	v_mfma_f32_4x4x1_16b_f32 v[36:39], v73, v202, v[36:39]
	v_mfma_f32_4x4x1_16b_f32 v[40:43], v74, v202, v[40:43]
	v_mfma_f32_4x4x1_16b_f32 v[44:47], v75, v202, v[44:47]
	v_mfma_f32_4x4x1_16b_f32 v[48:51], v76, v202, v[48:51]
	v_mfma_f32_4x4x1_16b_f32 v[52:55], v77, v202, v[52:55]
	v_mfma_f32_4x4x1_16b_f32 v[56:59], v78, v202, v[56:59]
	v_mfma_f32_4x4x1_16b_f32 v[60:63], v79, v202, v[60:63]
	v_mfma_f32_4x4x1_16b_f32 v[0:3], v80, v203, v[0:3]
	v_mfma_f32_4x4x1_16b_f32 v[4:7], v81, v203, v[4:7]
	v_mfma_f32_4x4x1_16b_f32 v[8:11], v82, v203, v[8:11]
	v_mfma_f32_4x4x1_16b_f32 v[12:15], v83, v203, v[12:15]
	v_mfma_f32_4x4x1_16b_f32 v[16:19], v84, v203, v[16:19]
	v_mfma_f32_4x4x1_16b_f32 v[20:23], v85, v203, v[20:23]
	v_mfma_f32_4x4x1_16b_f32 v[24:27], v86, v203, v[24:27]
	v_mfma_f32_4x4x1_16b_f32 v[28:31], v87, v203, v[28:31]
	v_mfma_f32_4x4x1_16b_f32 v[32:35], v88, v203, v[32:35]
	v_mfma_f32_4x4x1_16b_f32 v[36:39], v89, v203, v[36:39]
	v_mfma_f32_4x4x1_16b_f32 v[40:43], v90, v203, v[40:43]
	v_mfma_f32_4x4x1_16b_f32 v[44:47], v91, v203, v[44:47]
	v_mfma_f32_4x4x1_16b_f32 v[48:51], v92, v203, v[48:51]
	v_mfma_f32_4x4x1_16b_f32 v[52:55], v93, v203, v[52:55]
	v_mfma_f32_4x4x1_16b_f32 v[56:59], v94, v203, v[56:59]
	v_mfma_f32_4x4x1_16b_f32 v[60:63], v95, v203, v[60:63]
	v_mul_f32_dpp v200, v228, v0 row_newbcast:0 row_mask:0xf bank_mask:0xf
	v_mul_f32_dpp v201, v229, v1 row_newbcast:0 row_mask:0xf bank_mask:0xf
;     static __device__ __forceinline__ void upd(float (&S)[64], const In2& in, float sa, float vv, float& y0, float& y1) {
;         float t0, t1, t2, t3;
;         asm volatile("v_mul_f32_dpp %0, %10, %27 row_newbcast:%28" DPPM "v_mul_f32_dpp %1, %11, %27 row_newbcast:%28" DPPM "v_mul_f32_dpp %2, %12, %27 row_newbcast:%28" DPPM "v_mul_f32_dpp %3, %13, %27 row_newbcast:%28" DPPM
;                      "v_fmac_f32_dpp %0, %14, %6 row_newbcast:%28" DPPM "v_fmac_f32_dpp %1, %15, %7 row_newbcast:%28" DPPM "v_fmac_f32_dpp %2, %16, %8 row_newbcast:%28" DPPM "v_fmac_f32_dpp %3, %17, %9 row_newbcast:%28" DPPM
;                      "v_fmac_f32_dpp %0, %18, %26 row_newbcast:%28" DPPM "v_fmac_f32_dpp %1, %19, %26 row_newbcast:%28" DPPM "v_fmac_f32_dpp %2, %20, %26 row_newbcast:%28" DPPM "v_fmac_f32_dpp %3, %21, %26 row_newbcast:%28" DPPM
;                      "v_fmac_f32_dpp %4, %22, %0 row_newbcast:%28" DPPM "v_fmac_f32_dpp %5, %23, %1 row_newbcast:%28" DPPM "v_fmac_f32_dpp %4, %24, %2 row_newbcast:%28" DPPM "v_fmac_f32_dpp %5, %25, %3 row_newbcast:%28" DPPM
;                      : "=&v"(t0), "=&v"(t1), "=&v"(t2), "=&v"(t3), "+v"(y0), "+v"(y1)
;                      : "v"(S[K]), "v"(S[K + 1]), "v"(S[K + 2]), "v"(S[K + 3]), "v"(in.kd[0]), "v"(in.kd[1]), "v"(in.kd[2]), "v"(in.kd[3]), "v"(in.w[0]), "v"(in.w[1]), "v"(in.w[2]), "v"(in.w[3]),
;                        "v"(in.b[0]), "v"(in.b[1]), "v"(in.b[2]), "v"(in.b[3]), "v"(in.r[0]), "v"(in.r[1]), "v"(in.r[2]), "v"(in.r[3]), "v"(sa), "v"(vv), "n"(N0));
;         S[K] = t0; S[K + 1] = t1; S[K + 2] = t2; S[K + 3] = t3;
;         if constexpr (K + 4 < 64) ScanK<K + 4>::upd(S, in, sa, vv, y0, y1);
;     }
	v_fmac_f32_dpp v200, v230, v2 row_newbcast:0 row_mask:0xf bank_mask:0xf
	v_fmac_f32_dpp v201, v231, v3 row_newbcast:0 row_mask:0xf bank_mask:0xf
	v_fmac_f32_dpp v200, v228, v4 row_newbcast:1 row_mask:0xf bank_mask:0xf
	v_fmac_f32_dpp v201, v229, v5 row_newbcast:1 row_mask:0xf bank_mask:0xf
	v_fmac_f32_dpp v200, v230, v6 row_newbcast:1 row_mask:0xf bank_mask:0xf
	v_fmac_f32_dpp v201, v231, v7 row_newbcast:1 row_mask:0xf bank_mask:0xf
	v_fmac_f32_dpp v200, v228, v8 row_newbcast:2 row_mask:0xf bank_mask:0xf
	v_fmac_f32_dpp v201, v229, v9 row_newbcast:2 row_mask:0xf bank_mask:0xf
	v_fmac_f32_dpp v200, v230, v10 row_newbcast:2 row_mask:0xf bank_mask:0xf
	v_fmac_f32_dpp v201, v231, v11 row_newbcast:2 row_mask:0xf bank_mask:0xf
	v_fmac_f32_dpp v200, v228, v12 row_newbcast:3 row_mask:0xf bank_mask:0xf
	v_fmac_f32_dpp v201, v229, v13 row_newbcast:3 row_mask:0xf bank_mask:0xf
	v_fmac_f32_dpp v200, v230, v14 row_newbcast:3 row_mask:0xf bank_mask:0xf
	v_fmac_f32_dpp v201, v231, v15 row_newbcast:3 row_mask:0xf bank_mask:0xf
	v_fmac_f32_dpp v200, v228, v16 row_newbcast:4 row_mask:0xf bank_mask:0xf
	v_fmac_f32_dpp v201, v229, v17 row_newbcast:4 row_mask:0xf bank_mask:0xf
	v_fmac_f32_dpp v200, v230, v18 row_newbcast:4 row_mask:0xf bank_mask:0xf
	v_fmac_f32_dpp v201, v231, v19 row_newbcast:4 row_mask:0xf bank_mask:0xf
	v_fmac_f32_dpp v200, v228, v20 row_newbcast:5 row_mask:0xf bank_mask:0xf
	v_fmac_f32_dpp v201, v229, v21 row_newbcast:5 row_mask:0xf bank_mask:0xf
	v_fmac_f32_dpp v200, v230, v22 row_newbcast:5 row_mask:0xf bank_mask:0xf
	v_fmac_f32_dpp v201, v231, v23 row_newbcast:5 row_mask:0xf bank_mask:0xf
	v_fmac_f32_dpp v200, v228, v24 row_newbcast:6 row_mask:0xf bank_mask:0xf
	v_fmac_f32_dpp v201, v229, v25 row_newbcast:6 row_mask:0xf bank_mask:0xf
	v_fmac_f32_dpp v200, v230, v26 row_newbcast:6 row_mask:0xf bank_mask:0xf
	v_fmac_f32_dpp v201, v231, v27 row_newbcast:6 row_mask:0xf bank_mask:0xf
	v_fmac_f32_dpp v200, v228, v28 row_newbcast:7 row_mask:0xf bank_mask:0xf
	v_fmac_f32_dpp v201, v229, v29 row_newbcast:7 row_mask:0xf bank_mask:0xf
	v_fmac_f32_dpp v200, v230, v30 row_newbcast:7 row_mask:0xf bank_mask:0xf
	v_fmac_f32_dpp v201, v231, v31 row_newbcast:7 row_mask:0xf bank_mask:0xf
	v_fmac_f32_dpp v200, v228, v32 row_newbcast:8 row_mask:0xf bank_mask:0xf
	v_fmac_f32_dpp v201, v229, v33 row_newbcast:8 row_mask:0xf bank_mask:0xf
	v_fmac_f32_dpp v200, v230, v34 row_newbcast:8 row_mask:0xf bank_mask:0xf
	v_fmac_f32_dpp v201, v231, v35 row_newbcast:8 row_mask:0xf bank_mask:0xf
	v_fmac_f32_dpp v200, v228, v36 row_newbcast:9 row_mask:0xf bank_mask:0xf
	v_fmac_f32_dpp v201, v229, v37 row_newbcast:9 row_mask:0xf bank_mask:0xf
	v_fmac_f32_dpp v200, v230, v38 row_newbcast:9 row_mask:0xf bank_mask:0xf
	v_fmac_f32_dpp v201, v231, v39 row_newbcast:9 row_mask:0xf bank_mask:0xf
	v_fmac_f32_dpp v200, v228, v40 row_newbcast:10 row_mask:0xf bank_mask:0xf
	v_fmac_f32_dpp v201, v229, v41 row_newbcast:10 row_mask:0xf bank_mask:0xf
	v_fmac_f32_dpp v200, v230, v42 row_newbcast:10 row_mask:0xf bank_mask:0xf
	v_fmac_f32_dpp v201, v231, v43 row_newbcast:10 row_mask:0xf bank_mask:0xf
	v_fmac_f32_dpp v200, v228, v44 row_newbcast:11 row_mask:0xf bank_mask:0xf
	v_fmac_f32_dpp v201, v229, v45 row_newbcast:11 row_mask:0xf bank_mask:0xf
	v_fmac_f32_dpp v200, v230, v46 row_newbcast:11 row_mask:0xf bank_mask:0xf
	v_fmac_f32_dpp v201, v231, v47 row_newbcast:11 row_mask:0xf bank_mask:0xf
	v_fmac_f32_dpp v200, v228, v48 row_newbcast:12 row_mask:0xf bank_mask:0xf
	v_fmac_f32_dpp v201, v229, v49 row_newbcast:12 row_mask:0xf bank_mask:0xf
	v_fmac_f32_dpp v200, v230, v50 row_newbcast:12 row_mask:0xf bank_mask:0xf
	v_fmac_f32_dpp v201, v231, v51 row_newbcast:12 row_mask:0xf bank_mask:0xf
	v_fmac_f32_dpp v200, v228, v52 row_newbcast:13 row_mask:0xf bank_mask:0xf
	v_fmac_f32_dpp v201, v229, v53 row_newbcast:13 row_mask:0xf bank_mask:0xf
	v_fmac_f32_dpp v200, v230, v54 row_newbcast:13 row_mask:0xf bank_mask:0xf
	v_fmac_f32_dpp v201, v231, v55 row_newbcast:13 row_mask:0xf bank_mask:0xf
	v_fmac_f32_dpp v200, v228, v56 row_newbcast:14 row_mask:0xf bank_mask:0xf
	v_fmac_f32_dpp v201, v229, v57 row_newbcast:14 row_mask:0xf bank_mask:0xf
	v_fmac_f32_dpp v200, v230, v58 row_newbcast:14 row_mask:0xf bank_mask:0xf
	v_fmac_f32_dpp v201, v231, v59 row_newbcast:14 row_mask:0xf bank_mask:0xf
	v_fmac_f32_dpp v200, v228, v60 row_newbcast:15 row_mask:0xf bank_mask:0xf
	v_fmac_f32_dpp v201, v229, v61 row_newbcast:15 row_mask:0xf bank_mask:0xf
	v_fmac_f32_dpp v200, v230, v62 row_newbcast:15 row_mask:0xf bank_mask:0xf
	v_fmac_f32_dpp v201, v231, v63 row_newbcast:15 row_mask:0xf bank_mask:0xf
	v_add_f32_e32 v200, v200, v201
	s_waitcnt vmcnt(12)
; #define SB __builtin_amdgcn_sched_barrier(0)
; #define ST2(set, s) { DERIVE_BK(set); float sd[4]; ScanK<0>::dot(S, set.a, sd); float y0 = set.yo, y1 = 0.f; ScanK<0>::upd(S, set, -((sd[0] + sd[1]) + (sd[2] + sd[3])), __uint_as_float(set.v << 16), y0, y1); __builtin_amdgcn_raw_buffer_store_b32(__float_as_uint(y0 + y1), rY, lo4b, ob4 + (unsigned)((int)(s) * (int)stp * 4), 0); }
;     static __device__ __forceinline__ void upd(float (&S)[64], const In2& in, float sa, float vv, float& y0, float& y1) {
;         float t0, t1, t2, t3;
;         asm volatile("v_mul_f32_dpp %0, %10, %27 row_newbcast:%28" DPPM "v_mul_f32_dpp %1, %11, %27 row_newbcast:%28" DPPM "v_mul_f32_dpp %2, %12, %27 row_newbcast:%28" DPPM "v_mul_f32_dpp %3, %13, %27 row_newbcast:%28" DPPM
;                      "v_fmac_f32_dpp %0, %14, %6 row_newbcast:%28" DPPM "v_fmac_f32_dpp %1, %15, %7 row_newbcast:%28" DPPM "v_fmac_f32_dpp %2, %16, %8 row_newbcast:%28" DPPM "v_fmac_f32_dpp %3, %17, %9 row_newbcast:%28" DPPM
;                      "v_fmac_f32_dpp %0, %18, %26 row_newbcast:%28" DPPM "v_fmac_f32_dpp %1, %19, %26 row_newbcast:%28" DPPM "v_fmac_f32_dpp %2, %20, %26 row_newbcast:%28" DPPM "v_fmac_f32_dpp %3, %21, %26 row_newbcast:%28" DPPM
;                      "v_fmac_f32_dpp %4, %22, %0 row_newbcast:%28" DPPM "v_fmac_f32_dpp %5, %23, %1 row_newbcast:%28" DPPM "v_fmac_f32_dpp %4, %24, %2 row_newbcast:%28" DPPM "v_fmac_f32_dpp %5, %25, %3 row_newbcast:%28" DPPM
;                      : "=&v"(t0), "=&v"(t1), "=&v"(t2), "=&v"(t3), "+v"(y0), "+v"(y1)
;                      : "v"(S[K]), "v"(S[K + 1]), "v"(S[K + 2]), "v"(S[K + 3]), "v"(in.kd[0]), "v"(in.kd[1]), "v"(in.kd[2]), "v"(in.kd[3]), "v"(in.w[0]), "v"(in.w[1]), "v"(in.w[2]), "v"(in.w[3]),
;                        "v"(in.b[0]), "v"(in.b[1]), "v"(in.b[2]), "v"(in.b[3]), "v"(in.r[0]), "v"(in.r[1]), "v"(in.r[2]), "v"(in.r[3]), "v"(sa), "v"(vv), "n"(N0));
;         S[K] = t0; S[K + 1] = t1; S[K + 2] = t2; S[K + 3] = t3;
;         if constexpr (K + 4 < 64) ScanK<K + 4>::upd(S, in, sa, vv, y0, y1);
;     }
; __device__ __forceinline__ void scan_pass2(const Params& p, int d) {
;     ...
;         In2 i0, i1; LD2(i0, 0);
; #pragma unroll 1
;         for (int s = 0; s < LC; s += 2) { TOUCH2(i0); SB; LD2(i1, s + 1); SB; ST2(i0, s); TOUCH2(i1); SB; LD2(i0, s + 2); SB; ST2(i1, s + 1); }
	buffer_store_dword v200, v207, s[68:71], s79 offen
	s_add_u32 s79, s79, 0x1000
	buffer_load_dwordx4 v[116:119], v232, s[64:67], s72 offen
	buffer_load_dwordx4 v[120:123], v233, s[64:67], s72 offen
	buffer_load_dwordx4 v[124:127], v234, s[64:67], s72 offen
	buffer_load_dwordx4 v[128:131], v235, s[64:67], s72 offen
	buffer_load_dwordx2 v[132:133], v236, s[64:67], s76 offen
	buffer_load_ushort v134, v237, s[64:67], s76 offen
	s_add_u32 s72, s72, 0x1000
	s_add_u32 s76, s76, 0x800
	v_pk_mul_f32 v[224:225], v[140:141], v[216:217]
	v_pk_mul_f32 v[226:227], v[142:143], v[218:219]
	v_pk_mul_f32 v[216:217], v[216:217], v[136:137]
	v_pk_mul_f32 v[218:219], v[218:219], v[138:139]
	v_pk_fma_f32 v[184:185], v[144:145], v[188:189], v[192:193]
	v_pk_fma_f32 v[186:187], v[146:147], v[190:191], v[194:195]
	v_pk_mul_f32 v[176:177], v[140:141], v[144:145]
	v_pk_mul_f32 v[178:179], v[142:143], v[146:147]
	v_rcp_f32_e32 v220, v216
	v_rcp_f32_e32 v221, v217
	v_rcp_f32_e32 v222, v218
	v_rcp_f32_e32 v223, v219
	v_lshlrev_b32_e32 v180, 16, v152
	v_and_b32_e32 v181, 0xffff0000, v152
	v_lshlrev_b32_e32 v182, 16, v153
	v_and_b32_e32 v183, 0xffff0000, v153
	v_pk_mul_f32 v[180:181], v[180:181], v[184:185]
	v_pk_mul_f32 v[182:183], v[182:183], v[186:187]
	v_pk_mul_f32 v[228:229], v[148:149], v[216:217]
	v_pk_mul_f32 v[230:231], v[150:151], v[218:219]
	v_pk_mul_f32 v[176:177], v[176:177], v[220:221]
	v_pk_mul_f32 v[178:179], v[178:179], v[222:223]
	v_pk_mul_f32 v[180:181], v[180:181], v[220:221]
	v_pk_mul_f32 v[182:183], v[182:183], v[222:223]
	v_lshlrev_b32_e32 v203, 16, v154
	ds_write2_b32 v208, v176, v177 offset0:0 offset1:16
	ds_write2_b32 v208, v178, v179 offset0:32 offset1:48
	ds_write2_b32 v208, v180, v181 offset0:64 offset1:80
	ds_write2_b32 v208, v182, v183 offset0:96 offset1:112
	ds_read_b128 v[64:67], v209 offset:0
	ds_read_b128 v[68:71], v209 offset:16
	ds_read_b128 v[72:75], v209 offset:32
	ds_read_b128 v[76:79], v209 offset:48
	ds_read_b128 v[80:83], v209 offset:256
	ds_read_b128 v[84:87], v209 offset:272
	ds_read_b128 v[88:91], v209 offset:288
	ds_read_b128 v[92:95], v209 offset:304
	v_mul_f32_dpp v196, v224, v0 row_newbcast:0 row_mask:0xf bank_mask:0xf
	v_mul_f32_dpp v197, v225, v1 row_newbcast:0 row_mask:0xf bank_mask:0xf
	v_mul_f32_dpp v198, v226, v2 row_newbcast:0 row_mask:0xf bank_mask:0xf
	v_mul_f32_dpp v199, v227, v3 row_newbcast:0 row_mask:0xf bank_mask:0xf
	v_fmac_f32_dpp v196, v224, v4 row_newbcast:1 row_mask:0xf bank_mask:0xf
	v_fmac_f32_dpp v197, v225, v5 row_newbcast:1 row_mask:0xf bank_mask:0xf
	v_fmac_f32_dpp v198, v226, v6 row_newbcast:1 row_mask:0xf bank_mask:0xf
	v_fmac_f32_dpp v199, v227, v7 row_newbcast:1 row_mask:0xf bank_mask:0xf
	v_fmac_f32_dpp v196, v224, v8 row_newbcast:2 row_mask:0xf bank_mask:0xf
	v_fmac_f32_dpp v197, v225, v9 row_newbcast:2 row_mask:0xf bank_mask:0xf
	v_fmac_f32_dpp v198, v226, v10 row_newbcast:2 row_mask:0xf bank_mask:0xf
	v_fmac_f32_dpp v199, v227, v11 row_newbcast:2 row_mask:0xf bank_mask:0xf
	v_fmac_f32_dpp v196, v224, v12 row_newbcast:3 row_mask:0xf bank_mask:0xf
	v_fmac_f32_dpp v197, v225, v13 row_newbcast:3 row_mask:0xf bank_mask:0xf
	v_fmac_f32_dpp v198, v226, v14 row_newbcast:3 row_mask:0xf bank_mask:0xf
	v_fmac_f32_dpp v199, v227, v15 row_newbcast:3 row_mask:0xf bank_mask:0xf
	v_fmac_f32_dpp v196, v224, v16 row_newbcast:4 row_mask:0xf bank_mask:0xf
	v_fmac_f32_dpp v197, v225, v17 row_newbcast:4 row_mask:0xf bank_mask:0xf
	v_fmac_f32_dpp v198, v226, v18 row_newbcast:4 row_mask:0xf bank_mask:0xf
	v_fmac_f32_dpp v199, v227, v19 row_newbcast:4 row_mask:0xf bank_mask:0xf
	v_fmac_f32_dpp v196, v224, v20 row_newbcast:5 row_mask:0xf bank_mask:0xf
	v_fmac_f32_dpp v197, v225, v21 row_newbcast:5 row_mask:0xf bank_mask:0xf
	v_fmac_f32_dpp v198, v226, v22 row_newbcast:5 row_mask:0xf bank_mask:0xf
	v_fmac_f32_dpp v199, v227, v23 row_newbcast:5 row_mask:0xf bank_mask:0xf
	v_fmac_f32_dpp v196, v224, v24 row_newbcast:6 row_mask:0xf bank_mask:0xf
	v_fmac_f32_dpp v197, v225, v25 row_newbcast:6 row_mask:0xf bank_mask:0xf
	v_fmac_f32_dpp v198, v226, v26 row_newbcast:6 row_mask:0xf bank_mask:0xf
	v_fmac_f32_dpp v199, v227, v27 row_newbcast:6 row_mask:0xf bank_mask:0xf
	v_fmac_f32_dpp v196, v224, v28 row_newbcast:7 row_mask:0xf bank_mask:0xf
	v_fmac_f32_dpp v197, v225, v29 row_newbcast:7 row_mask:0xf bank_mask:0xf
	v_fmac_f32_dpp v198, v226, v30 row_newbcast:7 row_mask:0xf bank_mask:0xf
	v_fmac_f32_dpp v199, v227, v31 row_newbcast:7 row_mask:0xf bank_mask:0xf
	v_fmac_f32_dpp v196, v224, v32 row_newbcast:8 row_mask:0xf bank_mask:0xf
	v_fmac_f32_dpp v197, v225, v33 row_newbcast:8 row_mask:0xf bank_mask:0xf
	v_fmac_f32_dpp v198, v226, v34 row_newbcast:8 row_mask:0xf bank_mask:0xf
	v_fmac_f32_dpp v199, v227, v35 row_newbcast:8 row_mask:0xf bank_mask:0xf
	v_fmac_f32_dpp v196, v224, v36 row_newbcast:9 row_mask:0xf bank_mask:0xf
	v_fmac_f32_dpp v197, v225, v37 row_newbcast:9 row_mask:0xf bank_mask:0xf
	v_fmac_f32_dpp v198, v226, v38 row_newbcast:9 row_mask:0xf bank_mask:0xf
	v_fmac_f32_dpp v199, v227, v39 row_newbcast:9 row_mask:0xf bank_mask:0xf
	v_fmac_f32_dpp v196, v224, v40 row_newbcast:10 row_mask:0xf bank_mask:0xf
	v_fmac_f32_dpp v197, v225, v41 row_newbcast:10 row_mask:0xf bank_mask:0xf
	v_fmac_f32_dpp v198, v226, v42 row_newbcast:10 row_mask:0xf bank_mask:0xf
	v_fmac_f32_dpp v199, v227, v43 row_newbcast:10 row_mask:0xf bank_mask:0xf
	v_fmac_f32_dpp v196, v224, v44 row_newbcast:11 row_mask:0xf bank_mask:0xf
	v_fmac_f32_dpp v197, v225, v45 row_newbcast:11 row_mask:0xf bank_mask:0xf
	v_fmac_f32_dpp v198, v226, v46 row_newbcast:11 row_mask:0xf bank_mask:0xf
	v_fmac_f32_dpp v199, v227, v47 row_newbcast:11 row_mask:0xf bank_mask:0xf
	v_fmac_f32_dpp v196, v224, v48 row_newbcast:12 row_mask:0xf bank_mask:0xf
	v_fmac_f32_dpp v197, v225, v49 row_newbcast:12 row_mask:0xf bank_mask:0xf
	v_fmac_f32_dpp v198, v226, v50 row_newbcast:12 row_mask:0xf bank_mask:0xf
	v_fmac_f32_dpp v199, v227, v51 row_newbcast:12 row_mask:0xf bank_mask:0xf
	v_fmac_f32_dpp v196, v224, v52 row_newbcast:13 row_mask:0xf bank_mask:0xf
	v_fmac_f32_dpp v197, v225, v53 row_newbcast:13 row_mask:0xf bank_mask:0xf
	v_fmac_f32_dpp v198, v226, v54 row_newbcast:13 row_mask:0xf bank_mask:0xf
	v_fmac_f32_dpp v199, v227, v55 row_newbcast:13 row_mask:0xf bank_mask:0xf
	v_fmac_f32_dpp v196, v224, v56 row_newbcast:14 row_mask:0xf bank_mask:0xf
	v_fmac_f32_dpp v197, v225, v57 row_newbcast:14 row_mask:0xf bank_mask:0xf
	v_fmac_f32_dpp v198, v226, v58 row_newbcast:14 row_mask:0xf bank_mask:0xf
	v_fmac_f32_dpp v199, v227, v59 row_newbcast:14 row_mask:0xf bank_mask:0xf
	v_fmac_f32_dpp v196, v224, v60 row_newbcast:15 row_mask:0xf bank_mask:0xf
	v_fmac_f32_dpp v197, v225, v61 row_newbcast:15 row_mask:0xf bank_mask:0xf
	v_fmac_f32_dpp v198, v226, v62 row_newbcast:15 row_mask:0xf bank_mask:0xf
	v_fmac_f32_dpp v199, v227, v63 row_newbcast:15 row_mask:0xf bank_mask:0xf
	v_add_f32_e32 v196, v196, v197
	v_add_f32_e32 v198, v198, v199
	v_sub_f32_e64 v202, -v196, v198
	s_waitcnt lgkmcnt(0)
;     static __device__ __forceinline__ void upd(float (&S)[64], const In2& in, float sa, float vv, float& y0, float& y1) {
;         float t0, t1, t2, t3;
;         asm volatile("v_mul_f32_dpp %0, %10, %27 row_newbcast:%28" DPPM "v_mul_f32_dpp %1, %11, %27 row_newbcast:%28" DPPM "v_mul_f32_dpp %2, %12, %27 row_newbcast:%28" DPPM "v_mul_f32_dpp %3, %13, %27 row_newbcast:%28" DPPM
;                      "v_fmac_f32_dpp %0, %14, %6 row_newbcast:%28" DPPM "v_fmac_f32_dpp %1, %15, %7 row_newbcast:%28" DPPM "v_fmac_f32_dpp %2, %16, %8 row_newbcast:%28" DPPM "v_fmac_f32_dpp %3, %17, %9 row_newbcast:%28" DPPM
;                      "v_fmac_f32_dpp %0, %18, %26 row_newbcast:%28" DPPM "v_fmac_f32_dpp %1, %19, %26 row_newbcast:%28" DPPM "v_fmac_f32_dpp %2, %20, %26 row_newbcast:%28" DPPM "v_fmac_f32_dpp %3, %21, %26 row_newbcast:%28" DPPM
;                      "v_fmac_f32_dpp %4, %22, %0 row_newbcast:%28" DPPM "v_fmac_f32_dpp %5, %23, %1 row_newbcast:%28" DPPM "v_fmac_f32_dpp %4, %24, %2 row_newbcast:%28" DPPM "v_fmac_f32_dpp %5, %25, %3 row_newbcast:%28" DPPM
;                      : "=&v"(t0), "=&v"(t1), "=&v"(t2), "=&v"(t3), "+v"(y0), "+v"(y1)
;                      : "v"(S[K]), "v"(S[K + 1]), "v"(S[K + 2]), "v"(S[K + 3]), "v"(in.kd[0]), "v"(in.kd[1]), "v"(in.kd[2]), "v"(in.kd[3]), "v"(in.w[0]), "v"(in.w[1]), "v"(in.w[2]), "v"(in.w[3]),
;                        "v"(in.b[0]), "v"(in.b[1]), "v"(in.b[2]), "v"(in.b[3]), "v"(in.r[0]), "v"(in.r[1]), "v"(in.r[2]), "v"(in.r[3]), "v"(sa), "v"(vv), "n"(N0));
;         S[K] = t0; S[K + 1] = t1; S[K + 2] = t2; S[K + 3] = t3;
;         if constexpr (K + 4 < 64) ScanK<K + 4>::upd(S, in, sa, vv, y0, y1);
;     }
	s_nop 1
	v_mfma_f32_4x4x1_16b_f32 v[0:3], v64, v202, v[0:3]
	v_mfma_f32_4x4x1_16b_f32 v[4:7], v65, v202, v[4:7]
	v_mfma_f32_4x4x1_16b_f32 v[8:11], v66, v202, v[8:11]
	v_mfma_f32_4x4x1_16b_f32 v[12:15], v67, v202, v[12:15]
	v_mfma_f32_4x4x1_16b_f32 v[16:19], v68, v202, v[16:19]
	v_mfma_f32_4x4x1_16b_f32 v[20:23], v69, v202, v[20:23]
	v_mfma_f32_4x4x1_16b_f32 v[24:27], v70, v202, v[24:27]
	v_mfma_f32_4x4x1_16b_f32 v[28:31], v71, v202, v[28:31]
	v_mfma_f32_4x4x1_16b_f32 v[32:35], v72, v202, v[32:35]
	v_mfma_f32_4x4x1_16b_f32 v[36:39], v73, v202, v[36:39]
	v_mfma_f32_4x4x1_16b_f32 v[40:43], v74, v202, v[40:43]
	v_mfma_f32_4x4x1_16b_f32 v[44:47], v75, v202, v[44:47]
	v_mfma_f32_4x4x1_16b_f32 v[48:51], v76, v202, v[48:51]
	v_mfma_f32_4x4x1_16b_f32 v[52:55], v77, v202, v[52:55]
	v_mfma_f32_4x4x1_16b_f32 v[56:59], v78, v202, v[56:59]
	v_mfma_f32_4x4x1_16b_f32 v[60:63], v79, v202, v[60:63]
	v_mfma_f32_4x4x1_16b_f32 v[0:3], v80, v203, v[0:3]
	v_mfma_f32_4x4x1_16b_f32 v[4:7], v81, v203, v[4:7]
	v_mfma_f32_4x4x1_16b_f32 v[8:11], v82, v203, v[8:11]
	v_mfma_f32_4x4x1_16b_f32 v[12:15], v83, v203, v[12:15]
	v_mfma_f32_4x4x1_16b_f32 v[16:19], v84, v203, v[16:19]
	v_mfma_f32_4x4x1_16b_f32 v[20:23], v85, v203, v[20:23]
	v_mfma_f32_4x4x1_16b_f32 v[24:27], v86, v203, v[24:27]
	v_mfma_f32_4x4x1_16b_f32 v[28:31], v87, v203, v[28:31]
	v_mfma_f32_4x4x1_16b_f32 v[32:35], v88, v203, v[32:35]
	v_mfma_f32_4x4x1_16b_f32 v[36:39], v89, v203, v[36:39]
	v_mfma_f32_4x4x1_16b_f32 v[40:43], v90, v203, v[40:43]
	v_mfma_f32_4x4x1_16b_f32 v[44:47], v91, v203, v[44:47]
	v_mfma_f32_4x4x1_16b_f32 v[48:51], v92, v203, v[48:51]
	v_mfma_f32_4x4x1_16b_f32 v[52:55], v93, v203, v[52:55]
	v_mfma_f32_4x4x1_16b_f32 v[56:59], v94, v203, v[56:59]
	v_mfma_f32_4x4x1_16b_f32 v[60:63], v95, v203, v[60:63]
	v_mul_f32_dpp v200, v228, v0 row_newbcast:0 row_mask:0xf bank_mask:0xf
	v_mul_f32_dpp v201, v229, v1 row_newbcast:0 row_mask:0xf bank_mask:0xf
	v_fmac_f32_dpp v200, v230, v2 row_newbcast:0 row_mask:0xf bank_mask:0xf
	v_fmac_f32_dpp v201, v231, v3 row_newbcast:0 row_mask:0xf bank_mask:0xf
	v_fmac_f32_dpp v200, v228, v4 row_newbcast:1 row_mask:0xf bank_mask:0xf
	v_fmac_f32_dpp v201, v229, v5 row_newbcast:1 row_mask:0xf bank_mask:0xf
	v_fmac_f32_dpp v200, v230, v6 row_newbcast:1 row_mask:0xf bank_mask:0xf
	v_fmac_f32_dpp v201, v231, v7 row_newbcast:1 row_mask:0xf bank_mask:0xf
	v_fmac_f32_dpp v200, v228, v8 row_newbcast:2 row_mask:0xf bank_mask:0xf
	v_fmac_f32_dpp v201, v229, v9 row_newbcast:2 row_mask:0xf bank_mask:0xf
	v_fmac_f32_dpp v200, v230, v10 row_newbcast:2 row_mask:0xf bank_mask:0xf
	v_fmac_f32_dpp v201, v231, v11 row_newbcast:2 row_mask:0xf bank_mask:0xf
	v_fmac_f32_dpp v200, v228, v12 row_newbcast:3 row_mask:0xf bank_mask:0xf
	v_fmac_f32_dpp v201, v229, v13 row_newbcast:3 row_mask:0xf bank_mask:0xf
	v_fmac_f32_dpp v200, v230, v14 row_newbcast:3 row_mask:0xf bank_mask:0xf
	v_fmac_f32_dpp v201, v231, v15 row_newbcast:3 row_mask:0xf bank_mask:0xf
	v_fmac_f32_dpp v200, v228, v16 row_newbcast:4 row_mask:0xf bank_mask:0xf
	v_fmac_f32_dpp v201, v229, v17 row_newbcast:4 row_mask:0xf bank_mask:0xf
	v_fmac_f32_dpp v200, v230, v18 row_newbcast:4 row_mask:0xf bank_mask:0xf
	v_fmac_f32_dpp v201, v231, v19 row_newbcast:4 row_mask:0xf bank_mask:0xf
	v_fmac_f32_dpp v200, v228, v20 row_newbcast:5 row_mask:0xf bank_mask:0xf
	v_fmac_f32_dpp v201, v229, v21 row_newbcast:5 row_mask:0xf bank_mask:0xf
	v_fmac_f32_dpp v200, v230, v22 row_newbcast:5 row_mask:0xf bank_mask:0xf
	v_fmac_f32_dpp v201, v231, v23 row_newbcast:5 row_mask:0xf bank_mask:0xf
	v_fmac_f32_dpp v200, v228, v24 row_newbcast:6 row_mask:0xf bank_mask:0xf
	v_fmac_f32_dpp v201, v229, v25 row_newbcast:6 row_mask:0xf bank_mask:0xf
	v_fmac_f32_dpp v200, v230, v26 row_newbcast:6 row_mask:0xf bank_mask:0xf
	v_fmac_f32_dpp v201, v231, v27 row_newbcast:6 row_mask:0xf bank_mask:0xf
	v_fmac_f32_dpp v200, v228, v28 row_newbcast:7 row_mask:0xf bank_mask:0xf
	v_fmac_f32_dpp v201, v229, v29 row_newbcast:7 row_mask:0xf bank_mask:0xf
	v_fmac_f32_dpp v200, v230, v30 row_newbcast:7 row_mask:0xf bank_mask:0xf
	v_fmac_f32_dpp v201, v231, v31 row_newbcast:7 row_mask:0xf bank_mask:0xf
	v_fmac_f32_dpp v200, v228, v32 row_newbcast:8 row_mask:0xf bank_mask:0xf
	v_fmac_f32_dpp v201, v229, v33 row_newbcast:8 row_mask:0xf bank_mask:0xf
	v_fmac_f32_dpp v200, v230, v34 row_newbcast:8 row_mask:0xf bank_mask:0xf
	v_fmac_f32_dpp v201, v231, v35 row_newbcast:8 row_mask:0xf bank_mask:0xf
	v_fmac_f32_dpp v200, v228, v36 row_newbcast:9 row_mask:0xf bank_mask:0xf
	v_fmac_f32_dpp v201, v229, v37 row_newbcast:9 row_mask:0xf bank_mask:0xf
	v_fmac_f32_dpp v200, v230, v38 row_newbcast:9 row_mask:0xf bank_mask:0xf
	v_fmac_f32_dpp v201, v231, v39 row_newbcast:9 row_mask:0xf bank_mask:0xf
	v_fmac_f32_dpp v200, v228, v40 row_newbcast:10 row_mask:0xf bank_mask:0xf
	v_fmac_f32_dpp v201, v229, v41 row_newbcast:10 row_mask:0xf bank_mask:0xf
	v_fmac_f32_dpp v200, v230, v42 row_newbcast:10 row_mask:0xf bank_mask:0xf
	v_fmac_f32_dpp v201, v231, v43 row_newbcast:10 row_mask:0xf bank_mask:0xf
	v_fmac_f32_dpp v200, v228, v44 row_newbcast:11 row_mask:0xf bank_mask:0xf
	v_fmac_f32_dpp v201, v229, v45 row_newbcast:11 row_mask:0xf bank_mask:0xf
	v_fmac_f32_dpp v200, v230, v46 row_newbcast:11 row_mask:0xf bank_mask:0xf
	v_fmac_f32_dpp v201, v231, v47 row_newbcast:11 row_mask:0xf bank_mask:0xf
	v_fmac_f32_dpp v200, v228, v48 row_newbcast:12 row_mask:0xf bank_mask:0xf
	v_fmac_f32_dpp v201, v229, v49 row_newbcast:12 row_mask:0xf bank_mask:0xf
	v_fmac_f32_dpp v200, v230, v50 row_newbcast:12 row_mask:0xf bank_mask:0xf
	v_fmac_f32_dpp v201, v231, v51 row_newbcast:12 row_mask:0xf bank_mask:0xf
	v_fmac_f32_dpp v200, v228, v52 row_newbcast:13 row_mask:0xf bank_mask:0xf
	v_fmac_f32_dpp v201, v229, v53 row_newbcast:13 row_mask:0xf bank_mask:0xf
	v_fmac_f32_dpp v200, v230, v54 row_newbcast:13 row_mask:0xf bank_mask:0xf
	v_fmac_f32_dpp v201, v231, v55 row_newbcast:13 row_mask:0xf bank_mask:0xf
	v_fmac_f32_dpp v200, v228, v56 row_newbcast:14 row_mask:0xf bank_mask:0xf
	v_fmac_f32_dpp v201, v229, v57 row_newbcast:14 row_mask:0xf bank_mask:0xf
	v_fmac_f32_dpp v200, v230, v58 row_newbcast:14 row_mask:0xf bank_mask:0xf
	v_fmac_f32_dpp v201, v231, v59 row_newbcast:14 row_mask:0xf bank_mask:0xf
	v_fmac_f32_dpp v200, v228, v60 row_newbcast:15 row_mask:0xf bank_mask:0xf
	v_fmac_f32_dpp v201, v229, v61 row_newbcast:15 row_mask:0xf bank_mask:0xf
	v_fmac_f32_dpp v200, v230, v62 row_newbcast:15 row_mask:0xf bank_mask:0xf
	v_fmac_f32_dpp v201, v231, v63 row_newbcast:15 row_mask:0xf bank_mask:0xf
	v_add_f32_e32 v200, v200, v201
	s_waitcnt vmcnt(12)
; #define SB __builtin_amdgcn_sched_barrier(0)
; #define ST2(set, s) { DERIVE_BK(set); float sd[4]; ScanK<0>::dot(S, set.a, sd); float y0 = set.yo, y1 = 0.f; ScanK<0>::upd(S, set, -((sd[0] + sd[1]) + (sd[2] + sd[3])), __uint_as_float(set.v << 16), y0, y1); __builtin_amdgcn_raw_buffer_store_b32(__float_as_uint(y0 + y1), rY, lo4b, ob4 + (unsigned)((int)(s) * (int)stp * 4), 0); }
;     static __device__ __forceinline__ void dot(const float (&S)[64], const f32x4& a, float (&s)[4]) {
;         if constexpr (K == 0) {
;             asm volatile("v_mul_f32_dpp %0, %4, %8 row_newbcast:%16" DPPM "v_mul_f32_dpp %1, %5, %9 row_newbcast:%16" DPPM "v_mul_f32_dpp %2, %6, %10 row_newbcast:%16" DPPM "v_mul_f32_dpp %3, %7, %11 row_newbcast:%16" DPPM
;                          "v_fmac_f32_dpp %0, %4, %12 row_newbcast:%17" DPPM "v_fmac_f32_dpp %1, %5, %13 row_newbcast:%17" DPPM "v_fmac_f32_dpp %2, %6, %14 row_newbcast:%17" DPPM "v_fmac_f32_dpp %3, %7, %15 row_newbcast:%17" DPPM
;                          : "=&v"(s[0]), "=&v"(s[1]), "=&v"(s[2]), "=&v"(s[3])
;                          : "v"(a[0]), "v"(a[1]), "v"(a[2]), "v"(a[3]), "v"(S[K]), "v"(S[K + 1]), "v"(S[K + 2]), "v"(S[K + 3]), "v"(S[K + 4]), "v"(S[K + 5]), "v"(S[K + 6]), "v"(S[K + 7]), "n"(N0), "n"(N1));
;         } else
;         asm volatile("v_fmac_f32_dpp %0, %4, %8 row_newbcast:%16" DPPM "v_fmac_f32_dpp %1, %5, %9 row_newbcast:%16" DPPM "v_fmac_f32_dpp %2, %6, %10 row_newbcast:%16" DPPM "v_fmac_f32_dpp %3, %7, %11 row_newbcast:%16" DPPM
;                      "v_fmac_f32_dpp %0, %4, %12 row_newbcast:%17" DPPM "v_fmac_f32_dpp %1, %5, %13 row_newbcast:%17" DPPM "v_fmac_f32_dpp %2, %6, %14 row_newbcast:%17" DPPM "v_fmac_f32_dpp %3, %7, %15 row_newbcast:%17" DPPM
;                      : "+v"(s[0]), "+v"(s[1]), "+v"(s[2]), "+v"(s[3])
;                      : "v"(a[0]), "v"(a[1]), "v"(a[2]), "v"(a[3]), "v"(S[K]), "v"(S[K + 1]), "v"(S[K + 2]), "v"(S[K + 3]), "v"(S[K + 4]), "v"(S[K + 5]), "v"(S[K + 6]), "v"(S[K + 7]), "n"(N0), "n"(N1));
;         if constexpr (K + 8 < 64) ScanK<K + 8>::dot(S, a, s);
; __device__ __forceinline__ void scan_pass2(const Params& p, int d) {
;     ...
;         In2 i0, i1; LD2(i0, 0);
; #pragma unroll 1
;         for (int s = 0; s < LC; s += 2) { TOUCH2(i0); SB; LD2(i1, s + 1); SB; ST2(i0, s); TOUCH2(i1); SB; LD2(i0, s + 2); SB; ST2(i1, s + 1); }
	buffer_store_dword v200, v207, s[68:71], s79 offen
	s_add_u32 s79, s79, 0x1000
	buffer_load_dwordx4 v[136:139], v232, s[64:67], s72 offen
	buffer_load_dwordx4 v[140:143], v233, s[64:67], s72 offen
	buffer_load_dwordx4 v[144:147], v234, s[64:67], s72 offen
	buffer_load_dwordx4 v[148:151], v235, s[64:67], s72 offen
	buffer_load_dwordx2 v[152:153], v236, s[64:67], s76 offen
	buffer_load_ushort v154, v237, s[64:67], s76 offen
	s_add_u32 s72, s72, 0x1000
	s_add_u32 s76, s76, 0x800
	v_pk_mul_f32 v[224:225], v[160:161], v[216:217]
	v_pk_mul_f32 v[226:227], v[162:163], v[218:219]
	v_pk_mul_f32 v[216:217], v[216:217], v[156:157]
	v_pk_mul_f32 v[218:219], v[218:219], v[158:159]
	v_pk_fma_f32 v[184:185], v[164:165], v[188:189], v[192:193]
	v_pk_fma_f32 v[186:187], v[166:167], v[190:191], v[194:195]
	v_pk_mul_f32 v[176:177], v[160:161], v[164:165]
	v_pk_mul_f32 v[178:179], v[162:163], v[166:167]
	v_rcp_f32_e32 v220, v216
	v_rcp_f32_e32 v221, v217
	v_rcp_f32_e32 v222, v218
	v_rcp_f32_e32 v223, v219
	v_lshlrev_b32_e32 v180, 16, v172
	v_and_b32_e32 v181, 0xffff0000, v172
	v_lshlrev_b32_e32 v182, 16, v173
	v_and_b32_e32 v183, 0xffff0000, v173
	v_pk_mul_f32 v[180:181], v[180:181], v[184:185]
	v_pk_mul_f32 v[182:183], v[182:183], v[186:187]
	v_pk_mul_f32 v[228:229], v[168:169], v[216:217]
	v_pk_mul_f32 v[230:231], v[170:171], v[218:219]
	v_pk_mul_f32 v[176:177], v[176:177], v[220:221]
	v_pk_mul_f32 v[178:179], v[178:179], v[222:223]
	v_pk_mul_f32 v[180:181], v[180:181], v[220:221]
	v_pk_mul_f32 v[182:183], v[182:183], v[222:223]
	v_lshlrev_b32_e32 v203, 16, v174
	ds_write2_b32 v208, v176, v177 offset0:0 offset1:16
	ds_write2_b32 v208, v178, v179 offset0:32 offset1:48
	ds_write2_b32 v208, v180, v181 offset0:64 offset1:80
	ds_write2_b32 v208, v182, v183 offset0:96 offset1:112
	ds_read_b128 v[64:67], v209 offset:0
	ds_read_b128 v[68:71], v209 offset:16
	ds_read_b128 v[72:75], v209 offset:32
	ds_read_b128 v[76:79], v209 offset:48
	ds_read_b128 v[80:83], v209 offset:256
	ds_read_b128 v[84:87], v209 offset:272
	ds_read_b128 v[88:91], v209 offset:288
	ds_read_b128 v[92:95], v209 offset:304
	v_mul_f32_dpp v196, v224, v0 row_newbcast:0 row_mask:0xf bank_mask:0xf
	v_mul_f32_dpp v197, v225, v1 row_newbcast:0 row_mask:0xf bank_mask:0xf
	v_mul_f32_dpp v198, v226, v2 row_newbcast:0 row_mask:0xf bank_mask:0xf
	v_mul_f32_dpp v199, v227, v3 row_newbcast:0 row_mask:0xf bank_mask:0xf
	v_fmac_f32_dpp v196, v224, v4 row_newbcast:1 row_mask:0xf bank_mask:0xf
	v_fmac_f32_dpp v197, v225, v5 row_newbcast:1 row_mask:0xf bank_mask:0xf
	v_fmac_f32_dpp v198, v226, v6 row_newbcast:1 row_mask:0xf bank_mask:0xf
	v_fmac_f32_dpp v199, v227, v7 row_newbcast:1 row_mask:0xf bank_mask:0xf
	v_fmac_f32_dpp v196, v224, v8 row_newbcast:2 row_mask:0xf bank_mask:0xf
	v_fmac_f32_dpp v197, v225, v9 row_newbcast:2 row_mask:0xf bank_mask:0xf
	v_fmac_f32_dpp v198, v226, v10 row_newbcast:2 row_mask:0xf bank_mask:0xf
	v_fmac_f32_dpp v199, v227, v11 row_newbcast:2 row_mask:0xf bank_mask:0xf
	v_fmac_f32_dpp v196, v224, v12 row_newbcast:3 row_mask:0xf bank_mask:0xf
	v_fmac_f32_dpp v197, v225, v13 row_newbcast:3 row_mask:0xf bank_mask:0xf
	v_fmac_f32_dpp v198, v226, v14 row_newbcast:3 row_mask:0xf bank_mask:0xf
	v_fmac_f32_dpp v199, v227, v15 row_newbcast:3 row_mask:0xf bank_mask:0xf
	v_fmac_f32_dpp v196, v224, v16 row_newbcast:4 row_mask:0xf bank_mask:0xf
	v_fmac_f32_dpp v197, v225, v17 row_newbcast:4 row_mask:0xf bank_mask:0xf
	v_fmac_f32_dpp v198, v226, v18 row_newbcast:4 row_mask:0xf bank_mask:0xf
	v_fmac_f32_dpp v199, v227, v19 row_newbcast:4 row_mask:0xf bank_mask:0xf
	v_fmac_f32_dpp v196, v224, v20 row_newbcast:5 row_mask:0xf bank_mask:0xf
	v_fmac_f32_dpp v197, v225, v21 row_newbcast:5 row_mask:0xf bank_mask:0xf
	v_fmac_f32_dpp v198, v226, v22 row_newbcast:5 row_mask:0xf bank_mask:0xf
	v_fmac_f32_dpp v199, v227, v23 row_newbcast:5 row_mask:0xf bank_mask:0xf
	v_fmac_f32_dpp v196, v224, v24 row_newbcast:6 row_mask:0xf bank_mask:0xf
	v_fmac_f32_dpp v197, v225, v25 row_newbcast:6 row_mask:0xf bank_mask:0xf
	v_fmac_f32_dpp v198, v226, v26 row_newbcast:6 row_mask:0xf bank_mask:0xf
	v_fmac_f32_dpp v199, v227, v27 row_newbcast:6 row_mask:0xf bank_mask:0xf
	v_fmac_f32_dpp v196, v224, v28 row_newbcast:7 row_mask:0xf bank_mask:0xf
	v_fmac_f32_dpp v197, v225, v29 row_newbcast:7 row_mask:0xf bank_mask:0xf
	v_fmac_f32_dpp v198, v226, v30 row_newbcast:7 row_mask:0xf bank_mask:0xf
	v_fmac_f32_dpp v199, v227, v31 row_newbcast:7 row_mask:0xf bank_mask:0xf
	v_fmac_f32_dpp v196, v224, v32 row_newbcast:8 row_mask:0xf bank_mask:0xf
	v_fmac_f32_dpp v197, v225, v33 row_newbcast:8 row_mask:0xf bank_mask:0xf
	v_fmac_f32_dpp v198, v226, v34 row_newbcast:8 row_mask:0xf bank_mask:0xf
	v_fmac_f32_dpp v199, v227, v35 row_newbcast:8 row_mask:0xf bank_mask:0xf
	v_fmac_f32_dpp v196, v224, v36 row_newbcast:9 row_mask:0xf bank_mask:0xf
	v_fmac_f32_dpp v197, v225, v37 row_newbcast:9 row_mask:0xf bank_mask:0xf
	v_fmac_f32_dpp v198, v226, v38 row_newbcast:9 row_mask:0xf bank_mask:0xf
	v_fmac_f32_dpp v199, v227, v39 row_newbcast:9 row_mask:0xf bank_mask:0xf
	v_fmac_f32_dpp v196, v224, v40 row_newbcast:10 row_mask:0xf bank_mask:0xf
	v_fmac_f32_dpp v197, v225, v41 row_newbcast:10 row_mask:0xf bank_mask:0xf
	v_fmac_f32_dpp v198, v226, v42 row_newbcast:10 row_mask:0xf bank_mask:0xf
	v_fmac_f32_dpp v199, v227, v43 row_newbcast:10 row_mask:0xf bank_mask:0xf
	v_fmac_f32_dpp v196, v224, v44 row_newbcast:11 row_mask:0xf bank_mask:0xf
	v_fmac_f32_dpp v197, v225, v45 row_newbcast:11 row_mask:0xf bank_mask:0xf
	v_fmac_f32_dpp v198, v226, v46 row_newbcast:11 row_mask:0xf bank_mask:0xf
	v_fmac_f32_dpp v199, v227, v47 row_newbcast:11 row_mask:0xf bank_mask:0xf
	v_fmac_f32_dpp v196, v224, v48 row_newbcast:12 row_mask:0xf bank_mask:0xf
	v_fmac_f32_dpp v197, v225, v49 row_newbcast:12 row_mask:0xf bank_mask:0xf
	v_fmac_f32_dpp v198, v226, v50 row_newbcast:12 row_mask:0xf bank_mask:0xf
	v_fmac_f32_dpp v199, v227, v51 row_newbcast:12 row_mask:0xf bank_mask:0xf
	v_fmac_f32_dpp v196, v224, v52 row_newbcast:13 row_mask:0xf bank_mask:0xf
	v_fmac_f32_dpp v197, v225, v53 row_newbcast:13 row_mask:0xf bank_mask:0xf
	v_fmac_f32_dpp v198, v226, v54 row_newbcast:13 row_mask:0xf bank_mask:0xf
	v_fmac_f32_dpp v199, v227, v55 row_newbcast:13 row_mask:0xf bank_mask:0xf
	v_fmac_f32_dpp v196, v224, v56 row_newbcast:14 row_mask:0xf bank_mask:0xf
	v_fmac_f32_dpp v197, v225, v57 row_newbcast:14 row_mask:0xf bank_mask:0xf
	v_fmac_f32_dpp v198, v226, v58 row_newbcast:14 row_mask:0xf bank_mask:0xf
	v_fmac_f32_dpp v199, v227, v59 row_newbcast:14 row_mask:0xf bank_mask:0xf
	v_fmac_f32_dpp v196, v224, v60 row_newbcast:15 row_mask:0xf bank_mask:0xf
	v_fmac_f32_dpp v197, v225, v61 row_newbcast:15 row_mask:0xf bank_mask:0xf
	v_fmac_f32_dpp v198, v226, v62 row_newbcast:15 row_mask:0xf bank_mask:0xf
	v_fmac_f32_dpp v199, v227, v63 row_newbcast:15 row_mask:0xf bank_mask:0xf
	v_add_f32_e32 v196, v196, v197
	v_add_f32_e32 v198, v198, v199
	v_sub_f32_e64 v202, -v196, v198
	s_waitcnt lgkmcnt(0)
; #define SB __builtin_amdgcn_sched_barrier(0)
; #define ST2(set, s) { DERIVE_BK(set); float sd[4]; ScanK<0>::dot(S, set.a, sd); float y0 = set.yo, y1 = 0.f; ScanK<0>::upd(S, set, -((sd[0] + sd[1]) + (sd[2] + sd[3])), __uint_as_float(set.v << 16), y0, y1); __builtin_amdgcn_raw_buffer_store_b32(__float_as_uint(y0 + y1), rY, lo4b, ob4 + (unsigned)((int)(s) * (int)stp * 4), 0); }
;     static __device__ __forceinline__ void upd(float (&S)[64], const In2& in, float sa, float vv, float& y0, float& y1) {
;         float t0, t1, t2, t3;
;         asm volatile("v_mul_f32_dpp %0, %10, %27 row_newbcast:%28" DPPM "v_mul_f32_dpp %1, %11, %27 row_newbcast:%28" DPPM "v_mul_f32_dpp %2, %12, %27 row_newbcast:%28" DPPM "v_mul_f32_dpp %3, %13, %27 row_newbcast:%28" DPPM
;                      "v_fmac_f32_dpp %0, %14, %6 row_newbcast:%28" DPPM "v_fmac_f32_dpp %1, %15, %7 row_newbcast:%28" DPPM "v_fmac_f32_dpp %2, %16, %8 row_newbcast:%28" DPPM "v_fmac_f32_dpp %3, %17, %9 row_newbcast:%28" DPPM
;                      "v_fmac_f32_dpp %0, %18, %26 row_newbcast:%28" DPPM "v_fmac_f32_dpp %1, %19, %26 row_newbcast:%28" DPPM "v_fmac_f32_dpp %2, %20, %26 row_newbcast:%28" DPPM "v_fmac_f32_dpp %3, %21, %26 row_newbcast:%28" DPPM
;                      "v_fmac_f32_dpp %4, %22, %0 row_newbcast:%28" DPPM "v_fmac_f32_dpp %5, %23, %1 row_newbcast:%28" DPPM "v_fmac_f32_dpp %4, %24, %2 row_newbcast:%28" DPPM "v_fmac_f32_dpp %5, %25, %3 row_newbcast:%28" DPPM
;                      : "=&v"(t0), "=&v"(t1), "=&v"(t2), "=&v"(t3), "+v"(y0), "+v"(y1)
;                      : "v"(S[K]), "v"(S[K + 1]), "v"(S[K + 2]), "v"(S[K + 3]), "v"(in.kd[0]), "v"(in.kd[1]), "v"(in.kd[2]), "v"(in.kd[3]), "v"(in.w[0]), "v"(in.w[1]), "v"(in.w[2]), "v"(in.w[3]),
;                        "v"(in.b[0]), "v"(in.b[1]), "v"(in.b[2]), "v"(in.b[3]), "v"(in.r[0]), "v"(in.r[1]), "v"(in.r[2]), "v"(in.r[3]), "v"(sa), "v"(vv), "n"(N0));
;         S[K] = t0; S[K + 1] = t1; S[K + 2] = t2; S[K + 3] = t3;
;         if constexpr (K + 4 < 64) ScanK<K + 4>::upd(S, in, sa, vv, y0, y1);
;     }
; __device__ __forceinline__ void scan_pass2(const Params& p, int d) {
;     ...
;         In2 i0, i1; LD2(i0, 0);
; #pragma unroll 1
;         for (int s = 0; s < LC; s += 2) { TOUCH2(i0); SB; LD2(i1, s + 1); SB; ST2(i0, s); TOUCH2(i1); SB; LD2(i0, s + 2); SB; ST2(i1, s + 1); }
	s_nop 1
	v_mfma_f32_4x4x1_16b_f32 v[0:3], v64, v202, v[0:3]
	v_mfma_f32_4x4x1_16b_f32 v[4:7], v65, v202, v[4:7]
	v_mfma_f32_4x4x1_16b_f32 v[8:11], v66, v202, v[8:11]
	v_mfma_f32_4x4x1_16b_f32 v[12:15], v67, v202, v[12:15]
	v_mfma_f32_4x4x1_16b_f32 v[16:19], v68, v202, v[16:19]
	v_mfma_f32_4x4x1_16b_f32 v[20:23], v69, v202, v[20:23]
	v_mfma_f32_4x4x1_16b_f32 v[24:27], v70, v202, v[24:27]
	v_mfma_f32_4x4x1_16b_f32 v[28:31], v71, v202, v[28:31]
	v_mfma_f32_4x4x1_16b_f32 v[32:35], v72, v202, v[32:35]
	v_mfma_f32_4x4x1_16b_f32 v[36:39], v73, v202, v[36:39]
	v_mfma_f32_4x4x1_16b_f32 v[40:43], v74, v202, v[40:43]
	v_mfma_f32_4x4x1_16b_f32 v[44:47], v75, v202, v[44:47]
	v_mfma_f32_4x4x1_16b_f32 v[48:51], v76, v202, v[48:51]
	v_mfma_f32_4x4x1_16b_f32 v[52:55], v77, v202, v[52:55]
	v_mfma_f32_4x4x1_16b_f32 v[56:59], v78, v202, v[56:59]
	v_mfma_f32_4x4x1_16b_f32 v[60:63], v79, v202, v[60:63]
	v_mfma_f32_4x4x1_16b_f32 v[0:3], v80, v203, v[0:3]
	v_mfma_f32_4x4x1_16b_f32 v[4:7], v81, v203, v[4:7]
	v_mfma_f32_4x4x1_16b_f32 v[8:11], v82, v203, v[8:11]
	v_mfma_f32_4x4x1_16b_f32 v[12:15], v83, v203, v[12:15]
	v_mfma_f32_4x4x1_16b_f32 v[16:19], v84, v203, v[16:19]
	v_mfma_f32_4x4x1_16b_f32 v[20:23], v85, v203, v[20:23]
	v_mfma_f32_4x4x1_16b_f32 v[24:27], v86, v203, v[24:27]
	v_mfma_f32_4x4x1_16b_f32 v[28:31], v87, v203, v[28:31]
	v_mfma_f32_4x4x1_16b_f32 v[32:35], v88, v203, v[32:35]
	v_mfma_f32_4x4x1_16b_f32 v[36:39], v89, v203, v[36:39]
	v_mfma_f32_4x4x1_16b_f32 v[40:43], v90, v203, v[40:43]
	v_mfma_f32_4x4x1_16b_f32 v[44:47], v91, v203, v[44:47]
	v_mfma_f32_4x4x1_16b_f32 v[48:51], v92, v203, v[48:51]
	v_mfma_f32_4x4x1_16b_f32 v[52:55], v93, v203, v[52:55]
	v_mfma_f32_4x4x1_16b_f32 v[56:59], v94, v203, v[56:59]
	v_mfma_f32_4x4x1_16b_f32 v[60:63], v95, v203, v[60:63]
	v_mul_f32_dpp v200, v228, v0 row_newbcast:0 row_mask:0xf bank_mask:0xf
	v_mul_f32_dpp v201, v229, v1 row_newbcast:0 row_mask:0xf bank_mask:0xf
	v_fmac_f32_dpp v200, v230, v2 row_newbcast:0 row_mask:0xf bank_mask:0xf
	v_fmac_f32_dpp v201, v231, v3 row_newbcast:0 row_mask:0xf bank_mask:0xf
	v_fmac_f32_dpp v200, v228, v4 row_newbcast:1 row_mask:0xf bank_mask:0xf
	v_fmac_f32_dpp v201, v229, v5 row_newbcast:1 row_mask:0xf bank_mask:0xf
	v_fmac_f32_dpp v200, v230, v6 row_newbcast:1 row_mask:0xf bank_mask:0xf
	v_fmac_f32_dpp v201, v231, v7 row_newbcast:1 row_mask:0xf bank_mask:0xf
	v_fmac_f32_dpp v200, v228, v8 row_newbcast:2 row_mask:0xf bank_mask:0xf
	v_fmac_f32_dpp v201, v229, v9 row_newbcast:2 row_mask:0xf bank_mask:0xf
	v_fmac_f32_dpp v200, v230, v10 row_newbcast:2 row_mask:0xf bank_mask:0xf
	v_fmac_f32_dpp v201, v231, v11 row_newbcast:2 row_mask:0xf bank_mask:0xf
	v_fmac_f32_dpp v200, v228, v12 row_newbcast:3 row_mask:0xf bank_mask:0xf
	v_fmac_f32_dpp v201, v229, v13 row_newbcast:3 row_mask:0xf bank_mask:0xf
	v_fmac_f32_dpp v200, v230, v14 row_newbcast:3 row_mask:0xf bank_mask:0xf
	v_fmac_f32_dpp v201, v231, v15 row_newbcast:3 row_mask:0xf bank_mask:0xf
	v_fmac_f32_dpp v200, v228, v16 row_newbcast:4 row_mask:0xf bank_mask:0xf
	v_fmac_f32_dpp v201, v229, v17 row_newbcast:4 row_mask:0xf bank_mask:0xf
	v_fmac_f32_dpp v200, v230, v18 row_newbcast:4 row_mask:0xf bank_mask:0xf
	v_fmac_f32_dpp v201, v231, v19 row_newbcast:4 row_mask:0xf bank_mask:0xf
	v_fmac_f32_dpp v200, v228, v20 row_newbcast:5 row_mask:0xf bank_mask:0xf
	v_fmac_f32_dpp v201, v229, v21 row_newbcast:5 row_mask:0xf bank_mask:0xf
	v_fmac_f32_dpp v200, v230, v22 row_newbcast:5 row_mask:0xf bank_mask:0xf
	v_fmac_f32_dpp v201, v231, v23 row_newbcast:5 row_mask:0xf bank_mask:0xf
	v_fmac_f32_dpp v200, v228, v24 row_newbcast:6 row_mask:0xf bank_mask:0xf
	v_fmac_f32_dpp v201, v229, v25 row_newbcast:6 row_mask:0xf bank_mask:0xf
	v_fmac_f32_dpp v200, v230, v26 row_newbcast:6 row_mask:0xf bank_mask:0xf
	v_fmac_f32_dpp v201, v231, v27 row_newbcast:6 row_mask:0xf bank_mask:0xf
	v_fmac_f32_dpp v200, v228, v28 row_newbcast:7 row_mask:0xf bank_mask:0xf
	v_fmac_f32_dpp v201, v229, v29 row_newbcast:7 row_mask:0xf bank_mask:0xf
	v_fmac_f32_dpp v200, v230, v30 row_newbcast:7 row_mask:0xf bank_mask:0xf
	v_fmac_f32_dpp v201, v231, v31 row_newbcast:7 row_mask:0xf bank_mask:0xf
	v_fmac_f32_dpp v200, v228, v32 row_newbcast:8 row_mask:0xf bank_mask:0xf
	v_fmac_f32_dpp v201, v229, v33 row_newbcast:8 row_mask:0xf bank_mask:0xf
	v_fmac_f32_dpp v200, v230, v34 row_newbcast:8 row_mask:0xf bank_mask:0xf
	v_fmac_f32_dpp v201, v231, v35 row_newbcast:8 row_mask:0xf bank_mask:0xf
	v_fmac_f32_dpp v200, v228, v36 row_newbcast:9 row_mask:0xf bank_mask:0xf
	v_fmac_f32_dpp v201, v229, v37 row_newbcast:9 row_mask:0xf bank_mask:0xf
	v_fmac_f32_dpp v200, v230, v38 row_newbcast:9 row_mask:0xf bank_mask:0xf
	v_fmac_f32_dpp v201, v231, v39 row_newbcast:9 row_mask:0xf bank_mask:0xf
	v_fmac_f32_dpp v200, v228, v40 row_newbcast:10 row_mask:0xf bank_mask:0xf
	v_fmac_f32_dpp v201, v229, v41 row_newbcast:10 row_mask:0xf bank_mask:0xf
	v_fmac_f32_dpp v200, v230, v42 row_newbcast:10 row_mask:0xf bank_mask:0xf
	v_fmac_f32_dpp v201, v231, v43 row_newbcast:10 row_mask:0xf bank_mask:0xf
	v_fmac_f32_dpp v200, v228, v44 row_newbcast:11 row_mask:0xf bank_mask:0xf
	v_fmac_f32_dpp v201, v229, v45 row_newbcast:11 row_mask:0xf bank_mask:0xf
	v_fmac_f32_dpp v200, v230, v46 row_newbcast:11 row_mask:0xf bank_mask:0xf
	v_fmac_f32_dpp v201, v231, v47 row_newbcast:11 row_mask:0xf bank_mask:0xf
	v_fmac_f32_dpp v200, v228, v48 row_newbcast:12 row_mask:0xf bank_mask:0xf
	v_fmac_f32_dpp v201, v229, v49 row_newbcast:12 row_mask:0xf bank_mask:0xf
	v_fmac_f32_dpp v200, v230, v50 row_newbcast:12 row_mask:0xf bank_mask:0xf
	v_fmac_f32_dpp v201, v231, v51 row_newbcast:12 row_mask:0xf bank_mask:0xf
	v_fmac_f32_dpp v200, v228, v52 row_newbcast:13 row_mask:0xf bank_mask:0xf
	v_fmac_f32_dpp v201, v229, v53 row_newbcast:13 row_mask:0xf bank_mask:0xf
	v_fmac_f32_dpp v200, v230, v54 row_newbcast:13 row_mask:0xf bank_mask:0xf
	v_fmac_f32_dpp v201, v231, v55 row_newbcast:13 row_mask:0xf bank_mask:0xf
	v_fmac_f32_dpp v200, v228, v56 row_newbcast:14 row_mask:0xf bank_mask:0xf
	v_fmac_f32_dpp v201, v229, v57 row_newbcast:14 row_mask:0xf bank_mask:0xf
	v_fmac_f32_dpp v200, v230, v58 row_newbcast:14 row_mask:0xf bank_mask:0xf
	v_fmac_f32_dpp v201, v231, v59 row_newbcast:14 row_mask:0xf bank_mask:0xf
	v_fmac_f32_dpp v200, v228, v60 row_newbcast:15 row_mask:0xf bank_mask:0xf
	v_fmac_f32_dpp v201, v229, v61 row_newbcast:15 row_mask:0xf bank_mask:0xf
	v_fmac_f32_dpp v200, v230, v62 row_newbcast:15 row_mask:0xf bank_mask:0xf
	v_fmac_f32_dpp v201, v231, v63 row_newbcast:15 row_mask:0xf bank_mask:0xf
	v_add_f32_e32 v200, v200, v201
	s_sub_u32 s83, s83, 1
	s_cmp_eq_u32 s83, 0
	s_cbranch_scc1 .Lmy_p2d0_ldone
	s_and_b32 s9, s83, 7
	s_cmp_eq_u32 s9, 0
	s_cbranch_scc1 .Lmy_p2d0_renorm
	s_branch .Lmy_p2d0_loop

; #define NEXT_ITEM() (MIX ? (int)__builtin_amdgcn_readfirstlane(lane == 0 ? __hip_atomic_fetch_add(qctr, 1u, __ATOMIC_RELAXED, __HIP_MEMORY_SCOPE_AGENT) : 0u) : item + (int)gridDim.x * 8)
; #define SB __builtin_amdgcn_sched_barrier(0)
; #define MKR(ptr) __builtin_amdgcn_make_buffer_rsrc((void*)(ptr), 0, 0x7fffffff, 0x00027000)
; #define TOUCH1(set) asm volatile("" :: "v"(set.w), "v"(set.a), "v"(set.b), "v"(set.kw), "v"(set.v))
; #define TOUCH1(set) asm volatile("" :: "v"(set.w), "v"(set.a), "v"(set.b))
; template <bool MIX> __device__ __forceinline__ void scan_pass1(const Params& p, int d, float* ldsf) {
;     const int lane = threadIdx.x & 63, wid = __builtin_amdgcn_readfirstlane(threadIdx.x >> 6); const unsigned lo16 = (lane & 15) * 16, lo2 = lane * 2;
;     const float* Wd = (const float*)(p.ws + O_KD); const float* Bd = (const float*)(p.ws + O_Y); const u16* KB = (const u16*)(p.ws + O_K); const float* A = (const float*)(p.ws + O_A);
;     const u16* V = (const u16*)(p.ws + O_V); float* PT = (float*)(p.ws + O_PT); float* SLT = (float*)(p.ws + O_SLT); const unsigned lo8 = (lane & 15) * 8;
;     constexpr int NS = 32 * (NC - 1);
;     unsigned* qctr = (unsigned*)(p.ws + O_BAR);
;     if (MIX && wid >= 4) nat_phase(p, ldsf, blockIdx.x * 4 + (wid - 4), gridDim.x * 4);
;     ...
;     for (int item = MIX ? NEXT_ITEM() : (int)(blockIdx.x * 8 + wid); item < 2 * NS; item = NEXT_ITEM()) {
;         const bool isP = item >= NS; const int idx = isP ? item - NS : item;
;         const int bh = idx / (NC - 1), c = idx - bh * (NC - 1), b = bh >> 4, h = bh & 15;
;         const int t0 = d ? (SEQ - 1 - c * LC) : c * LC;
;         const size_t off0 = ((size_t)(b * SEQ + t0)) * RW + h * 64; const long stp = d ? -(long)RW : (long)RW;
;         const unsigned ob4 = (unsigned)(off0 * 4), ob2 = (unsigned)(off0 * 2);
;         const f32x4 ka4 = *(const f32x4*)(p.k_a + h * 64 + (lane & 15) * 4), c04 = 1.0f - ka4;
;         float S[64]; int ln = lane; asm volatile("" : "+v"(ln));
;     ...
;         const __amdgpu_buffer_rsrc_t rW = MKR(Wd), rA = MKR(A), rB = MKR(Bd), rK = MKR(KB), rV = MKR(V);
;         if (!isP) {
; #pragma unroll
;             for (int i = 0; i < 64; ++i) S[i] = 0.f;
;     ...
;             In1 i0, i1; LD1(i0, 0);
; #pragma unroll 1
;             for (int s = 0; s < LC; s += 2) { TOUCH1(i0); SB; LD1(i1, s + 1); SB; ST1(i0); TOUCH1(i1); SB; LD1(i0, s + 2); SB; ST1(i1); }
.LBB0_827:
	s_cmp_lt_i32 s58, 9
	s_cselect_b64 s[0:1], -1, 0
	s_cmp_gt_i32 s59, 8
	s_cselect_b64 s[4:5], -1, 0
	s_and_b64 s[0:1], s[0:1], s[4:5]
	s_andn2_b64 vcc, exec, s[0:1]
	s_cbranch_vccnz .LBB0_893
	s_mov_b64 exec, -1
	v_readfirstlane_b32 s0, v254
	s_nop 3
	s_lshr_b32 s1, s0, 6
	s_lshl_b32 s0, s2, 3
	s_add_i32 s0, s1, s0
	s_mov_b32 s64, s56
	s_and_b32 s65, s57, 0xffff
	s_brev_b32 s66, -2
	s_mov_b32 s67, 0x27000
	s_mov_b32 s68, s54
	s_and_b32 s69, s55, 0xffff
	s_mov_b32 s70, s66
	s_mov_b32 s71, s67
	v_and_b32_e32 v212, 63, v254
	v_and_b32_e32 v213, 15, v254
	v_lshlrev_b32_e32 v204, 4, v213
	v_lshlrev_b32_e32 v205, 3, v213
	v_lshlrev_b32_e32 v206, 1, v212
	v_lshlrev_b32_e32 v207, 2, v212
	v_lshlrev_b32_e32 v210, 8, v212
	s_lshl_b32 s3, s1, 10
	s_add_u32 s3, s3, 0x10000
	v_lshl_add_u32 v208, v213, 2, s3
	v_and_b32_e32 v209, 3, v254
	v_lshl_add_u32 v209, v209, 6, s3
	v_add_u32_e32 v232, 0xb800000, v204
	v_add_u32_e32 v233, 0x24800000, v204
	v_add_u32_e32 v234, 0x35a00000, v204
	v_add_u32_e32 v235, 0x1c800000, v204
	v_add_u32_e32 v236, 0x30800000, v205
	v_add_u32_e32 v237, 0x2c800000, v206
	v_mov_b32_e32 v213, 1.0
.Lmy_p1d1_item:
	s_cmpk_gt_i32 s0, 0xfbf
	s_cbranch_scc1 .Lmy_p1d1_end
	s_cmpk_gt_i32 s0, 0x7df
	s_cselect_b32 s88, 1, 0
	s_cselect_b32 s6, 0x7e0, 0
	s_sub_u32 s6, s0, s6
	s_mul_i32 s86, s6, 2081
	s_lshr_b32 s86, s86, 17
	s_mul_i32 s7, s86, 63
	s_sub_u32 s85, s6, s7
	s_and_b32 s87, s86, 15
	s_lshr_b32 s6, s86, 4
	s_lshl_b32 s6, s6, 14
	s_lshl_b32 s7, s85, 8
	s_sub_u32 s7, 0x3fff, s7
	s_add_u32 s6, s6, s7
	s_lshl_b32 s6, s6, 10
	s_lshl_b32 s7, s87, 6
	s_add_u32 s84, s6, s7
	s_lshl_b32 s6, s84, 2
	s_lshl_b32 s7, s84, 1
	s_mov_b32 s72, s6
	s_mov_b32 s76, s7
	s_lshl_b32 s6, s86, 6
	s_add_u32 s6, s6, s85
	s_lshl_b32 s6, s6, 14
	s_mov_b32 s7, 0x15800000
	s_cmp_eq_u32 s88, 1
	s_cselect_b32 s7, 0x13800000, s7
	s_add_u32 s6, s6, s7
	s_add_u32 s90, s56, s6
	s_addc_u32 s91, s57, 0
	s_cmp_eq_u32 s88, 1
	s_cbranch_scc1 .Lmy_p1d1_pitem
	s_lshl_b32 s8, s87, 8
	s_add_u32 s4, s42, s8
	s_addc_u32 s5, s43, 0
	global_load_dwordx4 v[188:191], v204, s[4:5]
	buffer_load_dwordx4 v[96:99], v232, s[64:67], s72 offen
	buffer_load_dwordx4 v[100:103], v233, s[64:67], s72 offen
	buffer_load_dwordx4 v[104:107], v234, s[64:67], s72 offen
	buffer_load_dwordx2 v[112:113], v236, s[64:67], s76 offen
	buffer_load_ushort v114, v237, s[64:67], s76 offen
	s_add_i32 s72, s72, 0xfffff000
	s_max_i32 s72, s72, 0
	s_add_i32 s76, s76, 0xfffff800
	s_max_i32 s76, s76, 0
	buffer_load_dwordx4 v[116:119], v232, s[64:67], s72 offen
	buffer_load_dwordx4 v[120:123], v233, s[64:67], s72 offen
	buffer_load_dwordx4 v[124:127], v234, s[64:67], s72 offen
	buffer_load_dwordx2 v[132:133], v236, s[64:67], s76 offen
	buffer_load_ushort v134, v237, s[64:67], s76 offen
	s_add_i32 s72, s72, 0xfffff000
	s_max_i32 s72, s72, 0
	s_add_i32 s76, s76, 0xfffff800
	s_max_i32 s76, s76, 0
	buffer_load_dwordx4 v[136:139], v232, s[64:67], s72 offen
	buffer_load_dwordx4 v[140:143], v233, s[64:67], s72 offen
	buffer_load_dwordx4 v[144:147], v234, s[64:67], s72 offen
	buffer_load_dwordx2 v[152:153], v236, s[64:67], s76 offen
	buffer_load_ushort v154, v237, s[64:67], s76 offen
	s_add_i32 s72, s72, 0xfffff000
	s_max_i32 s72, s72, 0
	s_add_i32 s76, s76, 0xfffff800
	s_max_i32 s76, s76, 0
	v_mov_b32_e32 v0, 0
	v_mov_b32_e32 v1, 0
	v_mov_b32_e32 v2, 0
	v_mov_b32_e32 v3, 0
	v_mov_b32_e32 v4, 0
	v_mov_b32_e32 v5, 0
	v_mov_b32_e32 v6, 0
	v_mov_b32_e32 v7, 0
	v_mov_b32_e32 v8, 0
	v_mov_b32_e32 v9, 0
	v_mov_b32_e32 v10, 0
	v_mov_b32_e32 v11, 0
	v_mov_b32_e32 v12, 0
	v_mov_b32_e32 v13, 0
	v_mov_b32_e32 v14, 0
	v_mov_b32_e32 v15, 0
	v_mov_b32_e32 v16, 0
	v_mov_b32_e32 v17, 0
	v_mov_b32_e32 v18, 0
	v_mov_b32_e32 v19, 0
	v_mov_b32_e32 v20, 0
	v_mov_b32_e32 v21, 0
	v_mov_b32_e32 v22, 0
	v_mov_b32_e32 v23, 0
	v_mov_b32_e32 v24, 0
	v_mov_b32_e32 v25, 0
	v_mov_b32_e32 v26, 0
	v_mov_b32_e32 v27, 0
	v_mov_b32_e32 v28, 0
	v_mov_b32_e32 v29, 0
	v_mov_b32_e32 v30, 0
	v_mov_b32_e32 v31, 0
	v_mov_b32_e32 v32, 0
	v_mov_b32_e32 v33, 0
	v_mov_b32_e32 v34, 0
	v_mov_b32_e32 v35, 0
	v_mov_b32_e32 v36, 0
	v_mov_b32_e32 v37, 0
	v_mov_b32_e32 v38, 0
	v_mov_b32_e32 v39, 0
	v_mov_b32_e32 v40, 0
	v_mov_b32_e32 v41, 0
	v_mov_b32_e32 v42, 0
	v_mov_b32_e32 v43, 0
	v_mov_b32_e32 v44, 0
	v_mov_b32_e32 v45, 0
	v_mov_b32_e32 v46, 0
	v_mov_b32_e32 v47, 0
	v_mov_b32_e32 v48, 0
	v_mov_b32_e32 v49, 0
	v_mov_b32_e32 v50, 0
	v_mov_b32_e32 v51, 0
	v_mov_b32_e32 v52, 0
	v_mov_b32_e32 v53, 0
	v_mov_b32_e32 v54, 0
	v_mov_b32_e32 v55, 0
	v_mov_b32_e32 v56, 0
	v_mov_b32_e32 v57, 0
	v_mov_b32_e32 v58, 0
	v_mov_b32_e32 v59, 0
	v_mov_b32_e32 v60, 0
	v_mov_b32_e32 v61, 0
	v_mov_b32_e32 v62, 0
	v_mov_b32_e32 v63, 0
	s_waitcnt vmcnt(0)
	v_sub_f32_e32 v192, 1.0, v188
	v_sub_f32_e32 v193, 1.0, v189
	v_sub_f32_e32 v194, 1.0, v190
	v_sub_f32_e32 v195, 1.0, v191
	v_mov_b32_e32 v216, 1.0
	v_mov_b32_e32 v217, 1.0
	v_mov_b32_e32 v218, 1.0
	v_mov_b32_e32 v219, 1.0
	s_movk_i32 s83, 64
	s_branch .Lmy_p1d1_loop_s

; #define SB __builtin_amdgcn_sched_barrier(0)
; #define TOUCH1(set) asm volatile("" :: "v"(set.w), "v"(set.a), "v"(set.b), "v"(set.kw), "v"(set.v))
; #define ST1(set) { DERIVE_BK(set); float sd[4]; ScanK<0>::dot(S, set.a, sd); ScanK<0>::updS(S, set, -((sd[0] + sd[1]) + (sd[2] + sd[3])), __uint_as_float(set.v << 16)); }
; #define TOUCH1(set) asm volatile("" :: "v"(set.w), "v"(set.a), "v"(set.b))
;     static __device__ __forceinline__ void dot(const float (&S)[64], const f32x4& a, float (&s)[4]) {
;         if constexpr (K == 0) {
;             asm volatile("v_mul_f32_dpp %0, %4, %8 row_newbcast:%16" DPPM "v_mul_f32_dpp %1, %5, %9 row_newbcast:%16" DPPM "v_mul_f32_dpp %2, %6, %10 row_newbcast:%16" DPPM "v_mul_f32_dpp %3, %7, %11 row_newbcast:%16" DPPM
;                          "v_fmac_f32_dpp %0, %4, %12 row_newbcast:%17" DPPM "v_fmac_f32_dpp %1, %5, %13 row_newbcast:%17" DPPM "v_fmac_f32_dpp %2, %6, %14 row_newbcast:%17" DPPM "v_fmac_f32_dpp %3, %7, %15 row_newbcast:%17" DPPM
;                          : "=&v"(s[0]), "=&v"(s[1]), "=&v"(s[2]), "=&v"(s[3])
;                          : "v"(a[0]), "v"(a[1]), "v"(a[2]), "v"(a[3]), "v"(S[K]), "v"(S[K + 1]), "v"(S[K + 2]), "v"(S[K + 3]), "v"(S[K + 4]), "v"(S[K + 5]), "v"(S[K + 6]), "v"(S[K + 7]), "n"(N0), "n"(N1));
;         } else
;         asm volatile("v_fmac_f32_dpp %0, %4, %8 row_newbcast:%16" DPPM "v_fmac_f32_dpp %1, %5, %9 row_newbcast:%16" DPPM "v_fmac_f32_dpp %2, %6, %10 row_newbcast:%16" DPPM "v_fmac_f32_dpp %3, %7, %11 row_newbcast:%16" DPPM
;                      "v_fmac_f32_dpp %0, %4, %12 row_newbcast:%17" DPPM "v_fmac_f32_dpp %1, %5, %13 row_newbcast:%17" DPPM "v_fmac_f32_dpp %2, %6, %14 row_newbcast:%17" DPPM "v_fmac_f32_dpp %3, %7, %15 row_newbcast:%17" DPPM
;                      : "+v"(s[0]), "+v"(s[1]), "+v"(s[2]), "+v"(s[3])
;                      : "v"(a[0]), "v"(a[1]), "v"(a[2]), "v"(a[3]), "v"(S[K]), "v"(S[K + 1]), "v"(S[K + 2]), "v"(S[K + 3]), "v"(S[K + 4]), "v"(S[K + 5]), "v"(S[K + 6]), "v"(S[K + 7]), "n"(N0), "n"(N1));
;         if constexpr (K + 8 < 64) ScanK<K + 8>::dot(S, a, s);
; template <bool MIX> __device__ __forceinline__ void scan_pass1(const Params& p, int d, float* ldsf) {
;     ...
;             In1 i0, i1; LD1(i0, 0);
; #pragma unroll 1
;             for (int s = 0; s < LC; s += 2) { TOUCH1(i0); SB; LD1(i1, s + 1); SB; ST1(i0); TOUCH1(i1); SB; LD1(i0, s + 2); SB; ST1(i1); }
.Lmy_p1d1_loop_s:
	s_waitcnt vmcnt(10)
	buffer_load_dwordx4 v[156:159], v232, s[64:67], s72 offen
	buffer_load_dwordx4 v[160:163], v233, s[64:67], s72 offen
	buffer_load_dwordx4 v[164:167], v234, s[64:67], s72 offen
	buffer_load_dwordx2 v[172:173], v236, s[64:67], s76 offen
	buffer_load_ushort v174, v237, s[64:67], s76 offen
	s_add_i32 s72, s72, 0xfffff000
	s_max_i32 s72, s72, 0
	s_add_i32 s76, s76, 0xfffff800
	s_max_i32 s76, s76, 0
	v_pk_mul_f32 v[224:225], v[100:101], v[216:217]
	v_pk_mul_f32 v[226:227], v[102:103], v[218:219]
	v_pk_mul_f32 v[216:217], v[216:217], v[96:97]
	v_pk_mul_f32 v[218:219], v[218:219], v[98:99]
	v_pk_fma_f32 v[184:185], v[104:105], v[188:189], v[192:193]
	v_pk_fma_f32 v[186:187], v[106:107], v[190:191], v[194:195]
	v_pk_mul_f32 v[176:177], v[100:101], v[104:105]
	v_pk_mul_f32 v[178:179], v[102:103], v[106:107]
	v_rcp_f32_e32 v220, v216
	v_rcp_f32_e32 v221, v217
	v_rcp_f32_e32 v222, v218
	v_rcp_f32_e32 v223, v219
	v_lshlrev_b32_e32 v180, 16, v112
	v_and_b32_e32 v181, 0xffff0000, v112
	v_lshlrev_b32_e32 v182, 16, v113
	v_and_b32_e32 v183, 0xffff0000, v113
	v_pk_mul_f32 v[180:181], v[180:181], v[184:185]
	v_pk_mul_f32 v[182:183], v[182:183], v[186:187]
	v_lshlrev_b32_e32 v203, 16, v114
	v_pk_mul_f32 v[176:177], v[176:177], v[220:221]
	v_pk_mul_f32 v[178:179], v[178:179], v[222:223]
	v_pk_mul_f32 v[180:181], v[180:181], v[220:221]
	v_pk_mul_f32 v[182:183], v[182:183], v[222:223]
	ds_write2_b32 v208, v176, v177 offset0:0 offset1:16
	ds_write2_b32 v208, v178, v179 offset0:32 offset1:48
	ds_write2_b32 v208, v180, v181 offset0:64 offset1:80
	ds_write2_b32 v208, v182, v183 offset0:96 offset1:112
	ds_read_b128 v[64:67], v209 offset:0
	ds_read_b128 v[68:71], v209 offset:16
	ds_read_b128 v[72:75], v209 offset:32
	ds_read_b128 v[76:79], v209 offset:48
	ds_read_b128 v[80:83], v209 offset:256
	ds_read_b128 v[84:87], v209 offset:272
	ds_read_b128 v[88:91], v209 offset:288
	ds_read_b128 v[92:95], v209 offset:304
	v_mul_f32_dpp v196, v224, v0 row_newbcast:0 row_mask:0xf bank_mask:0xf
	v_mul_f32_dpp v197, v225, v1 row_newbcast:0 row_mask:0xf bank_mask:0xf
	v_mul_f32_dpp v198, v226, v2 row_newbcast:0 row_mask:0xf bank_mask:0xf
	v_mul_f32_dpp v199, v227, v3 row_newbcast:0 row_mask:0xf bank_mask:0xf
	v_fmac_f32_dpp v196, v224, v4 row_newbcast:1 row_mask:0xf bank_mask:0xf
	v_fmac_f32_dpp v197, v225, v5 row_newbcast:1 row_mask:0xf bank_mask:0xf
	v_fmac_f32_dpp v198, v226, v6 row_newbcast:1 row_mask:0xf bank_mask:0xf
	v_fmac_f32_dpp v199, v227, v7 row_newbcast:1 row_mask:0xf bank_mask:0xf
	v_fmac_f32_dpp v196, v224, v8 row_newbcast:2 row_mask:0xf bank_mask:0xf
	v_fmac_f32_dpp v197, v225, v9 row_newbcast:2 row_mask:0xf bank_mask:0xf
	v_fmac_f32_dpp v198, v226, v10 row_newbcast:2 row_mask:0xf bank_mask:0xf
	v_fmac_f32_dpp v199, v227, v11 row_newbcast:2 row_mask:0xf bank_mask:0xf
	v_fmac_f32_dpp v196, v224, v12 row_newbcast:3 row_mask:0xf bank_mask:0xf
	v_fmac_f32_dpp v197, v225, v13 row_newbcast:3 row_mask:0xf bank_mask:0xf
	v_fmac_f32_dpp v198, v226, v14 row_newbcast:3 row_mask:0xf bank_mask:0xf
	v_fmac_f32_dpp v199, v227, v15 row_newbcast:3 row_mask:0xf bank_mask:0xf
	v_fmac_f32_dpp v196, v224, v16 row_newbcast:4 row_mask:0xf bank_mask:0xf
	v_fmac_f32_dpp v197, v225, v17 row_newbcast:4 row_mask:0xf bank_mask:0xf
	v_fmac_f32_dpp v198, v226, v18 row_newbcast:4 row_mask:0xf bank_mask:0xf
	v_fmac_f32_dpp v199, v227, v19 row_newbcast:4 row_mask:0xf bank_mask:0xf
	v_fmac_f32_dpp v196, v224, v20 row_newbcast:5 row_mask:0xf bank_mask:0xf
	v_fmac_f32_dpp v197, v225, v21 row_newbcast:5 row_mask:0xf bank_mask:0xf
	v_fmac_f32_dpp v198, v226, v22 row_newbcast:5 row_mask:0xf bank_mask:0xf
	v_fmac_f32_dpp v199, v227, v23 row_newbcast:5 row_mask:0xf bank_mask:0xf
	v_fmac_f32_dpp v196, v224, v24 row_newbcast:6 row_mask:0xf bank_mask:0xf
	v_fmac_f32_dpp v197, v225, v25 row_newbcast:6 row_mask:0xf bank_mask:0xf
	v_fmac_f32_dpp v198, v226, v26 row_newbcast:6 row_mask:0xf bank_mask:0xf
	v_fmac_f32_dpp v199, v227, v27 row_newbcast:6 row_mask:0xf bank_mask:0xf
	v_fmac_f32_dpp v196, v224, v28 row_newbcast:7 row_mask:0xf bank_mask:0xf
	v_fmac_f32_dpp v197, v225, v29 row_newbcast:7 row_mask:0xf bank_mask:0xf
	v_fmac_f32_dpp v198, v226, v30 row_newbcast:7 row_mask:0xf bank_mask:0xf
	v_fmac_f32_dpp v199, v227, v31 row_newbcast:7 row_mask:0xf bank_mask:0xf
	v_fmac_f32_dpp v196, v224, v32 row_newbcast:8 row_mask:0xf bank_mask:0xf
	v_fmac_f32_dpp v197, v225, v33 row_newbcast:8 row_mask:0xf bank_mask:0xf
	v_fmac_f32_dpp v198, v226, v34 row_newbcast:8 row_mask:0xf bank_mask:0xf
	v_fmac_f32_dpp v199, v227, v35 row_newbcast:8 row_mask:0xf bank_mask:0xf
	v_fmac_f32_dpp v196, v224, v36 row_newbcast:9 row_mask:0xf bank_mask:0xf
	v_fmac_f32_dpp v197, v225, v37 row_newbcast:9 row_mask:0xf bank_mask:0xf
	v_fmac_f32_dpp v198, v226, v38 row_newbcast:9 row_mask:0xf bank_mask:0xf
	v_fmac_f32_dpp v199, v227, v39 row_newbcast:9 row_mask:0xf bank_mask:0xf
	v_fmac_f32_dpp v196, v224, v40 row_newbcast:10 row_mask:0xf bank_mask:0xf
	v_fmac_f32_dpp v197, v225, v41 row_newbcast:10 row_mask:0xf bank_mask:0xf
	v_fmac_f32_dpp v198, v226, v42 row_newbcast:10 row_mask:0xf bank_mask:0xf
	v_fmac_f32_dpp v199, v227, v43 row_newbcast:10 row_mask:0xf bank_mask:0xf
	v_fmac_f32_dpp v196, v224, v44 row_newbcast:11 row_mask:0xf bank_mask:0xf
	v_fmac_f32_dpp v197, v225, v45 row_newbcast:11 row_mask:0xf bank_mask:0xf
	v_fmac_f32_dpp v198, v226, v46 row_newbcast:11 row_mask:0xf bank_mask:0xf
	v_fmac_f32_dpp v199, v227, v47 row_newbcast:11 row_mask:0xf bank_mask:0xf
	v_fmac_f32_dpp v196, v224, v48 row_newbcast:12 row_mask:0xf bank_mask:0xf
	v_fmac_f32_dpp v197, v225, v49 row_newbcast:12 row_mask:0xf bank_mask:0xf
	v_fmac_f32_dpp v198, v226, v50 row_newbcast:12 row_mask:0xf bank_mask:0xf
	v_fmac_f32_dpp v199, v227, v51 row_newbcast:12 row_mask:0xf bank_mask:0xf
	v_fmac_f32_dpp v196, v224, v52 row_newbcast:13 row_mask:0xf bank_mask:0xf
	v_fmac_f32_dpp v197, v225, v53 row_newbcast:13 row_mask:0xf bank_mask:0xf
	v_fmac_f32_dpp v198, v226, v54 row_newbcast:13 row_mask:0xf bank_mask:0xf
	v_fmac_f32_dpp v199, v227, v55 row_newbcast:13 row_mask:0xf bank_mask:0xf
	v_fmac_f32_dpp v196, v224, v56 row_newbcast:14 row_mask:0xf bank_mask:0xf
	v_fmac_f32_dpp v197, v225, v57 row_newbcast:14 row_mask:0xf bank_mask:0xf
	v_fmac_f32_dpp v198, v226, v58 row_newbcast:14 row_mask:0xf bank_mask:0xf
	v_fmac_f32_dpp v199, v227, v59 row_newbcast:14 row_mask:0xf bank_mask:0xf
	v_fmac_f32_dpp v196, v224, v60 row_newbcast:15 row_mask:0xf bank_mask:0xf
	v_fmac_f32_dpp v197, v225, v61 row_newbcast:15 row_mask:0xf bank_mask:0xf
	v_fmac_f32_dpp v198, v226, v62 row_newbcast:15 row_mask:0xf bank_mask:0xf
	v_fmac_f32_dpp v199, v227, v63 row_newbcast:15 row_mask:0xf bank_mask:0xf
	v_add_f32_e32 v196, v196, v197
	v_add_f32_e32 v198, v198, v199
	v_sub_f32_e64 v202, -v196, v198
	s_waitcnt lgkmcnt(0)
; #define SB __builtin_amdgcn_sched_barrier(0)
; #define TOUCH1(set) asm volatile("" :: "v"(set.w), "v"(set.a), "v"(set.b), "v"(set.kw), "v"(set.v))
; #define ST1(set) { DERIVE_BK(set); float sd[4]; ScanK<0>::dot(S, set.a, sd); ScanK<0>::updS(S, set, -((sd[0] + sd[1]) + (sd[2] + sd[3])), __uint_as_float(set.v << 16)); }
; #define TOUCH1(set) asm volatile("" :: "v"(set.w), "v"(set.a), "v"(set.b))
;     static __device__ __forceinline__ void dot(const float (&S)[64], const f32x4& a, float (&s)[4]) {
;         if constexpr (K == 0) {
;             asm volatile("v_mul_f32_dpp %0, %4, %8 row_newbcast:%16" DPPM "v_mul_f32_dpp %1, %5, %9 row_newbcast:%16" DPPM "v_mul_f32_dpp %2, %6, %10 row_newbcast:%16" DPPM "v_mul_f32_dpp %3, %7, %11 row_newbcast:%16" DPPM
;                          "v_fmac_f32_dpp %0, %4, %12 row_newbcast:%17" DPPM "v_fmac_f32_dpp %1, %5, %13 row_newbcast:%17" DPPM "v_fmac_f32_dpp %2, %6, %14 row_newbcast:%17" DPPM "v_fmac_f32_dpp %3, %7, %15 row_newbcast:%17" DPPM
;                          : "=&v"(s[0]), "=&v"(s[1]), "=&v"(s[2]), "=&v"(s[3])
;                          : "v"(a[0]), "v"(a[1]), "v"(a[2]), "v"(a[3]), "v"(S[K]), "v"(S[K + 1]), "v"(S[K + 2]), "v"(S[K + 3]), "v"(S[K + 4]), "v"(S[K + 5]), "v"(S[K + 6]), "v"(S[K + 7]), "n"(N0), "n"(N1));
;         } else
;         asm volatile("v_fmac_f32_dpp %0, %4, %8 row_newbcast:%16" DPPM "v_fmac_f32_dpp %1, %5, %9 row_newbcast:%16" DPPM "v_fmac_f32_dpp %2, %6, %10 row_newbcast:%16" DPPM "v_fmac_f32_dpp %3, %7, %11 row_newbcast:%16" DPPM
;                      "v_fmac_f32_dpp %0, %4, %12 row_newbcast:%17" DPPM "v_fmac_f32_dpp %1, %5, %13 row_newbcast:%17" DPPM "v_fmac_f32_dpp %2, %6, %14 row_newbcast:%17" DPPM "v_fmac_f32_dpp %3, %7, %15 row_newbcast:%17" DPPM
;                      : "+v"(s[0]), "+v"(s[1]), "+v"(s[2]), "+v"(s[3])
;                      : "v"(a[0]), "v"(a[1]), "v"(a[2]), "v"(a[3]), "v"(S[K]), "v"(S[K + 1]), "v"(S[K + 2]), "v"(S[K + 3]), "v"(S[K + 4]), "v"(S[K + 5]), "v"(S[K + 6]), "v"(S[K + 7]), "n"(N0), "n"(N1));
;         if constexpr (K + 8 < 64) ScanK<K + 8>::dot(S, a, s);
; template <bool MIX> __device__ __forceinline__ void scan_pass1(const Params& p, int d, float* ldsf) {
;     ...
;             In1 i0, i1; LD1(i0, 0);
; #pragma unroll 1
;             for (int s = 0; s < LC; s += 2) { TOUCH1(i0); SB; LD1(i1, s + 1); SB; ST1(i0); TOUCH1(i1); SB; LD1(i0, s + 2); SB; ST1(i1); }
	s_nop 1
	v_mfma_f32_4x4x1_16b_f32 v[0:3], v64, v202, v[0:3]
	v_mfma_f32_4x4x1_16b_f32 v[4:7], v65, v202, v[4:7]
	v_mfma_f32_4x4x1_16b_f32 v[8:11], v66, v202, v[8:11]
	v_mfma_f32_4x4x1_16b_f32 v[12:15], v67, v202, v[12:15]
	v_mfma_f32_4x4x1_16b_f32 v[16:19], v68, v202, v[16:19]
	v_mfma_f32_4x4x1_16b_f32 v[20:23], v69, v202, v[20:23]
	v_mfma_f32_4x4x1_16b_f32 v[24:27], v70, v202, v[24:27]
	v_mfma_f32_4x4x1_16b_f32 v[28:31], v71, v202, v[28:31]
	v_mfma_f32_4x4x1_16b_f32 v[32:35], v72, v202, v[32:35]
	v_mfma_f32_4x4x1_16b_f32 v[36:39], v73, v202, v[36:39]
	v_mfma_f32_4x4x1_16b_f32 v[40:43], v74, v202, v[40:43]
	v_mfma_f32_4x4x1_16b_f32 v[44:47], v75, v202, v[44:47]
	v_mfma_f32_4x4x1_16b_f32 v[48:51], v76, v202, v[48:51]
	v_mfma_f32_4x4x1_16b_f32 v[52:55], v77, v202, v[52:55]
	v_mfma_f32_4x4x1_16b_f32 v[56:59], v78, v202, v[56:59]
	v_mfma_f32_4x4x1_16b_f32 v[60:63], v79, v202, v[60:63]
	v_mfma_f32_4x4x1_16b_f32 v[0:3], v80, v203, v[0:3]
	v_mfma_f32_4x4x1_16b_f32 v[4:7], v81, v203, v[4:7]
	v_mfma_f32_4x4x1_16b_f32 v[8:11], v82, v203, v[8:11]
	v_mfma_f32_4x4x1_16b_f32 v[12:15], v83, v203, v[12:15]
	v_mfma_f32_4x4x1_16b_f32 v[16:19], v84, v203, v[16:19]
	v_mfma_f32_4x4x1_16b_f32 v[20:23], v85, v203, v[20:23]
	v_mfma_f32_4x4x1_16b_f32 v[24:27], v86, v203, v[24:27]
	v_mfma_f32_4x4x1_16b_f32 v[28:31], v87, v203, v[28:31]
	v_mfma_f32_4x4x1_16b_f32 v[32:35], v88, v203, v[32:35]
	v_mfma_f32_4x4x1_16b_f32 v[36:39], v89, v203, v[36:39]
	v_mfma_f32_4x4x1_16b_f32 v[40:43], v90, v203, v[40:43]
	v_mfma_f32_4x4x1_16b_f32 v[44:47], v91, v203, v[44:47]
	v_mfma_f32_4x4x1_16b_f32 v[48:51], v92, v203, v[48:51]
	v_mfma_f32_4x4x1_16b_f32 v[52:55], v93, v203, v[52:55]
	v_mfma_f32_4x4x1_16b_f32 v[56:59], v94, v203, v[56:59]
	v_mfma_f32_4x4x1_16b_f32 v[60:63], v95, v203, v[60:63]
	s_waitcnt vmcnt(10)
	buffer_load_dwordx4 v[96:99], v232, s[64:67], s72 offen
	buffer_load_dwordx4 v[100:103], v233, s[64:67], s72 offen
	buffer_load_dwordx4 v[104:107], v234, s[64:67], s72 offen
	buffer_load_dwordx2 v[112:113], v236, s[64:67], s76 offen
	buffer_load_ushort v114, v237, s[64:67], s76 offen
	s_add_i32 s72, s72, 0xfffff000
	s_max_i32 s72, s72, 0
	s_add_i32 s76, s76, 0xfffff800
	s_max_i32 s76, s76, 0
	v_pk_mul_f32 v[224:225], v[120:121], v[216:217]
	v_pk_mul_f32 v[226:227], v[122:123], v[218:219]
	v_pk_mul_f32 v[216:217], v[216:217], v[116:117]
	v_pk_mul_f32 v[218:219], v[218:219], v[118:119]
	v_pk_fma_f32 v[184:185], v[124:125], v[188:189], v[192:193]
	v_pk_fma_f32 v[186:187], v[126:127], v[190:191], v[194:195]
	v_pk_mul_f32 v[176:177], v[120:121], v[124:125]
	v_pk_mul_f32 v[178:179], v[122:123], v[126:127]
	v_rcp_f32_e32 v220, v216
	v_rcp_f32_e32 v221, v217
	v_rcp_f32_e32 v222, v218
	v_rcp_f32_e32 v223, v219
	v_lshlrev_b32_e32 v180, 16, v132
	v_and_b32_e32 v181, 0xffff0000, v132
	v_lshlrev_b32_e32 v182, 16, v133
	v_and_b32_e32 v183, 0xffff0000, v133
	v_pk_mul_f32 v[180:181], v[180:181], v[184:185]
	v_pk_mul_f32 v[182:183], v[182:183], v[186:187]
	v_lshlrev_b32_e32 v203, 16, v134
	v_pk_mul_f32 v[176:177], v[176:177], v[220:221]
	v_pk_mul_f32 v[178:179], v[178:179], v[222:223]
	v_pk_mul_f32 v[180:181], v[180:181], v[220:221]
	v_pk_mul_f32 v[182:183], v[182:183], v[222:223]
	ds_write2_b32 v208, v176, v177 offset0:0 offset1:16
	ds_write2_b32 v208, v178, v179 offset0:32 offset1:48
	ds_write2_b32 v208, v180, v181 offset0:64 offset1:80
	ds_write2_b32 v208, v182, v183 offset0:96 offset1:112
	ds_read_b128 v[64:67], v209 offset:0
	ds_read_b128 v[68:71], v209 offset:16
	ds_read_b128 v[72:75], v209 offset:32
	ds_read_b128 v[76:79], v209 offset:48
	ds_read_b128 v[80:83], v209 offset:256
	ds_read_b128 v[84:87], v209 offset:272
	ds_read_b128 v[88:91], v209 offset:288
	ds_read_b128 v[92:95], v209 offset:304
	v_mul_f32_dpp v196, v224, v0 row_newbcast:0 row_mask:0xf bank_mask:0xf
	v_mul_f32_dpp v197, v225, v1 row_newbcast:0 row_mask:0xf bank_mask:0xf
	v_mul_f32_dpp v198, v226, v2 row_newbcast:0 row_mask:0xf bank_mask:0xf
	v_mul_f32_dpp v199, v227, v3 row_newbcast:0 row_mask:0xf bank_mask:0xf
	v_fmac_f32_dpp v196, v224, v4 row_newbcast:1 row_mask:0xf bank_mask:0xf
	v_fmac_f32_dpp v197, v225, v5 row_newbcast:1 row_mask:0xf bank_mask:0xf
	v_fmac_f32_dpp v198, v226, v6 row_newbcast:1 row_mask:0xf bank_mask:0xf
	v_fmac_f32_dpp v199, v227, v7 row_newbcast:1 row_mask:0xf bank_mask:0xf
	v_fmac_f32_dpp v196, v224, v8 row_newbcast:2 row_mask:0xf bank_mask:0xf
	v_fmac_f32_dpp v197, v225, v9 row_newbcast:2 row_mask:0xf bank_mask:0xf
	v_fmac_f32_dpp v198, v226, v10 row_newbcast:2 row_mask:0xf bank_mask:0xf
	v_fmac_f32_dpp v199, v227, v11 row_newbcast:2 row_mask:0xf bank_mask:0xf
	v_fmac_f32_dpp v196, v224, v12 row_newbcast:3 row_mask:0xf bank_mask:0xf
	v_fmac_f32_dpp v197, v225, v13 row_newbcast:3 row_mask:0xf bank_mask:0xf
	v_fmac_f32_dpp v198, v226, v14 row_newbcast:3 row_mask:0xf bank_mask:0xf
	v_fmac_f32_dpp v199, v227, v15 row_newbcast:3 row_mask:0xf bank_mask:0xf
	v_fmac_f32_dpp v196, v224, v16 row_newbcast:4 row_mask:0xf bank_mask:0xf
	v_fmac_f32_dpp v197, v225, v17 row_newbcast:4 row_mask:0xf bank_mask:0xf
	v_fmac_f32_dpp v198, v226, v18 row_newbcast:4 row_mask:0xf bank_mask:0xf
	v_fmac_f32_dpp v199, v227, v19 row_newbcast:4 row_mask:0xf bank_mask:0xf
	v_fmac_f32_dpp v196, v224, v20 row_newbcast:5 row_mask:0xf bank_mask:0xf
	v_fmac_f32_dpp v197, v225, v21 row_newbcast:5 row_mask:0xf bank_mask:0xf
	v_fmac_f32_dpp v198, v226, v22 row_newbcast:5 row_mask:0xf bank_mask:0xf
	v_fmac_f32_dpp v199, v227, v23 row_newbcast:5 row_mask:0xf bank_mask:0xf
	v_fmac_f32_dpp v196, v224, v24 row_newbcast:6 row_mask:0xf bank_mask:0xf
	v_fmac_f32_dpp v197, v225, v25 row_newbcast:6 row_mask:0xf bank_mask:0xf
;     static __device__ __forceinline__ void dot(const float (&S)[64], const f32x4& a, float (&s)[4]) {
;         if constexpr (K == 0) {
;             asm volatile("v_mul_f32_dpp %0, %4, %8 row_newbcast:%16" DPPM "v_mul_f32_dpp %1, %5, %9 row_newbcast:%16" DPPM "v_mul_f32_dpp %2, %6, %10 row_newbcast:%16" DPPM "v_mul_f32_dpp %3, %7, %11 row_newbcast:%16" DPPM
;                          "v_fmac_f32_dpp %0, %4, %12 row_newbcast:%17" DPPM "v_fmac_f32_dpp %1, %5, %13 row_newbcast:%17" DPPM "v_fmac_f32_dpp %2, %6, %14 row_newbcast:%17" DPPM "v_fmac_f32_dpp %3, %7, %15 row_newbcast:%17" DPPM
;                          : "=&v"(s[0]), "=&v"(s[1]), "=&v"(s[2]), "=&v"(s[3])
;                          : "v"(a[0]), "v"(a[1]), "v"(a[2]), "v"(a[3]), "v"(S[K]), "v"(S[K + 1]), "v"(S[K + 2]), "v"(S[K + 3]), "v"(S[K + 4]), "v"(S[K + 5]), "v"(S[K + 6]), "v"(S[K + 7]), "n"(N0), "n"(N1));
;         } else
;         asm volatile("v_fmac_f32_dpp %0, %4, %8 row_newbcast:%16" DPPM "v_fmac_f32_dpp %1, %5, %9 row_newbcast:%16" DPPM "v_fmac_f32_dpp %2, %6, %10 row_newbcast:%16" DPPM "v_fmac_f32_dpp %3, %7, %11 row_newbcast:%16" DPPM
;                      "v_fmac_f32_dpp %0, %4, %12 row_newbcast:%17" DPPM "v_fmac_f32_dpp %1, %5, %13 row_newbcast:%17" DPPM "v_fmac_f32_dpp %2, %6, %14 row_newbcast:%17" DPPM "v_fmac_f32_dpp %3, %7, %15 row_newbcast:%17" DPPM
;                      : "+v"(s[0]), "+v"(s[1]), "+v"(s[2]), "+v"(s[3])
;                      : "v"(a[0]), "v"(a[1]), "v"(a[2]), "v"(a[3]), "v"(S[K]), "v"(S[K + 1]), "v"(S[K + 2]), "v"(S[K + 3]), "v"(S[K + 4]), "v"(S[K + 5]), "v"(S[K + 6]), "v"(S[K + 7]), "n"(N0), "n"(N1));
;         if constexpr (K + 8 < 64) ScanK<K + 8>::dot(S, a, s);
;     }
;     static __device__ __forceinline__ void upd(float (&S)[64], const In2& in, float sa, float vv, float& y0, float& y1) {
;         float t0, t1, t2, t3;
;         asm volatile("v_mul_f32_dpp %0, %10, %27 row_newbcast:%28" DPPM "v_mul_f32_dpp %1, %11, %27 row_newbcast:%28" DPPM "v_mul_f32_dpp %2, %12, %27 row_newbcast:%28" DPPM "v_mul_f32_dpp %3, %13, %27 row_newbcast:%28" DPPM
;                      "v_fmac_f32_dpp %0, %14, %6 row_newbcast:%28" DPPM "v_fmac_f32_dpp %1, %15, %7 row_newbcast:%28" DPPM "v_fmac_f32_dpp %2, %16, %8 row_newbcast:%28" DPPM "v_fmac_f32_dpp %3, %17, %9 row_newbcast:%28" DPPM
	v_fmac_f32_dpp v198, v226, v26 row_newbcast:6 row_mask:0xf bank_mask:0xf
	v_fmac_f32_dpp v199, v227, v27 row_newbcast:6 row_mask:0xf bank_mask:0xf
	v_fmac_f32_dpp v196, v224, v28 row_newbcast:7 row_mask:0xf bank_mask:0xf
	v_fmac_f32_dpp v197, v225, v29 row_newbcast:7 row_mask:0xf bank_mask:0xf
	v_fmac_f32_dpp v198, v226, v30 row_newbcast:7 row_mask:0xf bank_mask:0xf
	v_fmac_f32_dpp v199, v227, v31 row_newbcast:7 row_mask:0xf bank_mask:0xf
	v_fmac_f32_dpp v196, v224, v32 row_newbcast:8 row_mask:0xf bank_mask:0xf
	v_fmac_f32_dpp v197, v225, v33 row_newbcast:8 row_mask:0xf bank_mask:0xf
	v_fmac_f32_dpp v198, v226, v34 row_newbcast:8 row_mask:0xf bank_mask:0xf
	v_fmac_f32_dpp v199, v227, v35 row_newbcast:8 row_mask:0xf bank_mask:0xf
	v_fmac_f32_dpp v196, v224, v36 row_newbcast:9 row_mask:0xf bank_mask:0xf
	v_fmac_f32_dpp v197, v225, v37 row_newbcast:9 row_mask:0xf bank_mask:0xf
	v_fmac_f32_dpp v198, v226, v38 row_newbcast:9 row_mask:0xf bank_mask:0xf
	v_fmac_f32_dpp v199, v227, v39 row_newbcast:9 row_mask:0xf bank_mask:0xf
	v_fmac_f32_dpp v196, v224, v40 row_newbcast:10 row_mask:0xf bank_mask:0xf
	v_fmac_f32_dpp v197, v225, v41 row_newbcast:10 row_mask:0xf bank_mask:0xf
	v_fmac_f32_dpp v198, v226, v42 row_newbcast:10 row_mask:0xf bank_mask:0xf
	v_fmac_f32_dpp v199, v227, v43 row_newbcast:10 row_mask:0xf bank_mask:0xf
	v_fmac_f32_dpp v196, v224, v44 row_newbcast:11 row_mask:0xf bank_mask:0xf
	v_fmac_f32_dpp v197, v225, v45 row_newbcast:11 row_mask:0xf bank_mask:0xf
	v_fmac_f32_dpp v198, v226, v46 row_newbcast:11 row_mask:0xf bank_mask:0xf
	v_fmac_f32_dpp v199, v227, v47 row_newbcast:11 row_mask:0xf bank_mask:0xf
	v_fmac_f32_dpp v196, v224, v48 row_newbcast:12 row_mask:0xf bank_mask:0xf
	v_fmac_f32_dpp v197, v225, v49 row_newbcast:12 row_mask:0xf bank_mask:0xf
	v_fmac_f32_dpp v198, v226, v50 row_newbcast:12 row_mask:0xf bank_mask:0xf
	v_fmac_f32_dpp v199, v227, v51 row_newbcast:12 row_mask:0xf bank_mask:0xf
	v_fmac_f32_dpp v196, v224, v52 row_newbcast:13 row_mask:0xf bank_mask:0xf
	v_fmac_f32_dpp v197, v225, v53 row_newbcast:13 row_mask:0xf bank_mask:0xf
	v_fmac_f32_dpp v198, v226, v54 row_newbcast:13 row_mask:0xf bank_mask:0xf
	v_fmac_f32_dpp v199, v227, v55 row_newbcast:13 row_mask:0xf bank_mask:0xf
	v_fmac_f32_dpp v196, v224, v56 row_newbcast:14 row_mask:0xf bank_mask:0xf
	v_fmac_f32_dpp v197, v225, v57 row_newbcast:14 row_mask:0xf bank_mask:0xf
	v_fmac_f32_dpp v198, v226, v58 row_newbcast:14 row_mask:0xf bank_mask:0xf
	v_fmac_f32_dpp v199, v227, v59 row_newbcast:14 row_mask:0xf bank_mask:0xf
	v_fmac_f32_dpp v196, v224, v60 row_newbcast:15 row_mask:0xf bank_mask:0xf
	v_fmac_f32_dpp v197, v225, v61 row_newbcast:15 row_mask:0xf bank_mask:0xf
	v_fmac_f32_dpp v198, v226, v62 row_newbcast:15 row_mask:0xf bank_mask:0xf
	v_fmac_f32_dpp v199, v227, v63 row_newbcast:15 row_mask:0xf bank_mask:0xf
	v_add_f32_e32 v196, v196, v197
	v_add_f32_e32 v198, v198, v199
	v_sub_f32_e64 v202, -v196, v198
	s_waitcnt lgkmcnt(0)
	s_nop 1
	v_mfma_f32_4x4x1_16b_f32 v[0:3], v64, v202, v[0:3]
	v_mfma_f32_4x4x1_16b_f32 v[4:7], v65, v202, v[4:7]
	v_mfma_f32_4x4x1_16b_f32 v[8:11], v66, v202, v[8:11]
	v_mfma_f32_4x4x1_16b_f32 v[12:15], v67, v202, v[12:15]
	v_mfma_f32_4x4x1_16b_f32 v[16:19], v68, v202, v[16:19]
	v_mfma_f32_4x4x1_16b_f32 v[20:23], v69, v202, v[20:23]
	v_mfma_f32_4x4x1_16b_f32 v[24:27], v70, v202, v[24:27]
	v_mfma_f32_4x4x1_16b_f32 v[28:31], v71, v202, v[28:31]
	v_mfma_f32_4x4x1_16b_f32 v[32:35], v72, v202, v[32:35]
	v_mfma_f32_4x4x1_16b_f32 v[36:39], v73, v202, v[36:39]
	v_mfma_f32_4x4x1_16b_f32 v[40:43], v74, v202, v[40:43]
	v_mfma_f32_4x4x1_16b_f32 v[44:47], v75, v202, v[44:47]
	v_mfma_f32_4x4x1_16b_f32 v[48:51], v76, v202, v[48:51]
	v_mfma_f32_4x4x1_16b_f32 v[52:55], v77, v202, v[52:55]
	v_mfma_f32_4x4x1_16b_f32 v[56:59], v78, v202, v[56:59]
	v_mfma_f32_4x4x1_16b_f32 v[60:63], v79, v202, v[60:63]
	v_mfma_f32_4x4x1_16b_f32 v[0:3], v80, v203, v[0:3]
	v_mfma_f32_4x4x1_16b_f32 v[4:7], v81, v203, v[4:7]
	v_mfma_f32_4x4x1_16b_f32 v[8:11], v82, v203, v[8:11]
	v_mfma_f32_4x4x1_16b_f32 v[12:15], v83, v203, v[12:15]
	v_mfma_f32_4x4x1_16b_f32 v[16:19], v84, v203, v[16:19]
	v_mfma_f32_4x4x1_16b_f32 v[20:23], v85, v203, v[20:23]
	v_mfma_f32_4x4x1_16b_f32 v[24:27], v86, v203, v[24:27]
	v_mfma_f32_4x4x1_16b_f32 v[28:31], v87, v203, v[28:31]
	v_mfma_f32_4x4x1_16b_f32 v[32:35], v88, v203, v[32:35]
	v_mfma_f32_4x4x1_16b_f32 v[36:39], v89, v203, v[36:39]
	v_mfma_f32_4x4x1_16b_f32 v[40:43], v90, v203, v[40:43]
	v_mfma_f32_4x4x1_16b_f32 v[44:47], v91, v203, v[44:47]
	v_mfma_f32_4x4x1_16b_f32 v[48:51], v92, v203, v[48:51]
	v_mfma_f32_4x4x1_16b_f32 v[52:55], v93, v203, v[52:55]
	v_mfma_f32_4x4x1_16b_f32 v[56:59], v94, v203, v[56:59]
	v_mfma_f32_4x4x1_16b_f32 v[60:63], v95, v203, v[60:63]
	s_waitcnt vmcnt(10)
; #define SB __builtin_amdgcn_sched_barrier(0)
; #define TOUCH1(set) asm volatile("" :: "v"(set.w), "v"(set.a), "v"(set.b), "v"(set.kw), "v"(set.v))
; #define ST1(set) { DERIVE_BK(set); float sd[4]; ScanK<0>::dot(S, set.a, sd); ScanK<0>::updS(S, set, -((sd[0] + sd[1]) + (sd[2] + sd[3])), __uint_as_float(set.v << 16)); }
; #define TOUCH1(set) asm volatile("" :: "v"(set.w), "v"(set.a), "v"(set.b))
;     static __device__ __forceinline__ void dot(const float (&S)[64], const f32x4& a, float (&s)[4]) {
;         if constexpr (K == 0) {
;             asm volatile("v_mul_f32_dpp %0, %4, %8 row_newbcast:%16" DPPM "v_mul_f32_dpp %1, %5, %9 row_newbcast:%16" DPPM "v_mul_f32_dpp %2, %6, %10 row_newbcast:%16" DPPM "v_mul_f32_dpp %3, %7, %11 row_newbcast:%16" DPPM
;                          "v_fmac_f32_dpp %0, %4, %12 row_newbcast:%17" DPPM "v_fmac_f32_dpp %1, %5, %13 row_newbcast:%17" DPPM "v_fmac_f32_dpp %2, %6, %14 row_newbcast:%17" DPPM "v_fmac_f32_dpp %3, %7, %15 row_newbcast:%17" DPPM
;                          : "=&v"(s[0]), "=&v"(s[1]), "=&v"(s[2]), "=&v"(s[3])
;                          : "v"(a[0]), "v"(a[1]), "v"(a[2]), "v"(a[3]), "v"(S[K]), "v"(S[K + 1]), "v"(S[K + 2]), "v"(S[K + 3]), "v"(S[K + 4]), "v"(S[K + 5]), "v"(S[K + 6]), "v"(S[K + 7]), "n"(N0), "n"(N1));
;         } else
;         asm volatile("v_fmac_f32_dpp %0, %4, %8 row_newbcast:%16" DPPM "v_fmac_f32_dpp %1, %5, %9 row_newbcast:%16" DPPM "v_fmac_f32_dpp %2, %6, %10 row_newbcast:%16" DPPM "v_fmac_f32_dpp %3, %7, %11 row_newbcast:%16" DPPM
;                      "v_fmac_f32_dpp %0, %4, %12 row_newbcast:%17" DPPM "v_fmac_f32_dpp %1, %5, %13 row_newbcast:%17" DPPM "v_fmac_f32_dpp %2, %6, %14 row_newbcast:%17" DPPM "v_fmac_f32_dpp %3, %7, %15 row_newbcast:%17" DPPM
;                      : "+v"(s[0]), "+v"(s[1]), "+v"(s[2]), "+v"(s[3])
;                      : "v"(a[0]), "v"(a[1]), "v"(a[2]), "v"(a[3]), "v"(S[K]), "v"(S[K + 1]), "v"(S[K + 2]), "v"(S[K + 3]), "v"(S[K + 4]), "v"(S[K + 5]), "v"(S[K + 6]), "v"(S[K + 7]), "n"(N0), "n"(N1));
;         if constexpr (K + 8 < 64) ScanK<K + 8>::dot(S, a, s);
; template <bool MIX> __device__ __forceinline__ void scan_pass1(const Params& p, int d, float* ldsf) {
;     ...
;             In1 i0, i1; LD1(i0, 0);
; #pragma unroll 1
;             for (int s = 0; s < LC; s += 2) { TOUCH1(i0); SB; LD1(i1, s + 1); SB; ST1(i0); TOUCH1(i1); SB; LD1(i0, s + 2); SB; ST1(i1); }
	buffer_load_dwordx4 v[116:119], v232, s[64:67], s72 offen
	buffer_load_dwordx4 v[120:123], v233, s[64:67], s72 offen
	buffer_load_dwordx4 v[124:127], v234, s[64:67], s72 offen
	buffer_load_dwordx2 v[132:133], v236, s[64:67], s76 offen
	buffer_load_ushort v134, v237, s[64:67], s76 offen
	s_add_i32 s72, s72, 0xfffff000
	s_max_i32 s72, s72, 0
	s_add_i32 s76, s76, 0xfffff800
	s_max_i32 s76, s76, 0
	v_pk_mul_f32 v[224:225], v[140:141], v[216:217]
	v_pk_mul_f32 v[226:227], v[142:143], v[218:219]
	v_pk_mul_f32 v[216:217], v[216:217], v[136:137]
	v_pk_mul_f32 v[218:219], v[218:219], v[138:139]
	v_pk_fma_f32 v[184:185], v[144:145], v[188:189], v[192:193]
	v_pk_fma_f32 v[186:187], v[146:147], v[190:191], v[194:195]
	v_pk_mul_f32 v[176:177], v[140:141], v[144:145]
	v_pk_mul_f32 v[178:179], v[142:143], v[146:147]
	v_rcp_f32_e32 v220, v216
	v_rcp_f32_e32 v221, v217
	v_rcp_f32_e32 v222, v218
	v_rcp_f32_e32 v223, v219
	v_lshlrev_b32_e32 v180, 16, v152
	v_and_b32_e32 v181, 0xffff0000, v152
	v_lshlrev_b32_e32 v182, 16, v153
	v_and_b32_e32 v183, 0xffff0000, v153
	v_pk_mul_f32 v[180:181], v[180:181], v[184:185]
	v_pk_mul_f32 v[182:183], v[182:183], v[186:187]
	v_lshlrev_b32_e32 v203, 16, v154
	v_pk_mul_f32 v[176:177], v[176:177], v[220:221]
	v_pk_mul_f32 v[178:179], v[178:179], v[222:223]
	v_pk_mul_f32 v[180:181], v[180:181], v[220:221]
	v_pk_mul_f32 v[182:183], v[182:183], v[222:223]
	ds_write2_b32 v208, v176, v177 offset0:0 offset1:16
	ds_write2_b32 v208, v178, v179 offset0:32 offset1:48
	ds_write2_b32 v208, v180, v181 offset0:64 offset1:80
	ds_write2_b32 v208, v182, v183 offset0:96 offset1:112
	ds_read_b128 v[64:67], v209 offset:0
	ds_read_b128 v[68:71], v209 offset:16
	ds_read_b128 v[72:75], v209 offset:32
	ds_read_b128 v[76:79], v209 offset:48
	ds_read_b128 v[80:83], v209 offset:256
	ds_read_b128 v[84:87], v209 offset:272
	ds_read_b128 v[88:91], v209 offset:288
	ds_read_b128 v[92:95], v209 offset:304
	v_mul_f32_dpp v196, v224, v0 row_newbcast:0 row_mask:0xf bank_mask:0xf
	v_mul_f32_dpp v197, v225, v1 row_newbcast:0 row_mask:0xf bank_mask:0xf
	v_mul_f32_dpp v198, v226, v2 row_newbcast:0 row_mask:0xf bank_mask:0xf
	v_mul_f32_dpp v199, v227, v3 row_newbcast:0 row_mask:0xf bank_mask:0xf
	v_fmac_f32_dpp v196, v224, v4 row_newbcast:1 row_mask:0xf bank_mask:0xf
	v_fmac_f32_dpp v197, v225, v5 row_newbcast:1 row_mask:0xf bank_mask:0xf
	v_fmac_f32_dpp v198, v226, v6 row_newbcast:1 row_mask:0xf bank_mask:0xf
	v_fmac_f32_dpp v199, v227, v7 row_newbcast:1 row_mask:0xf bank_mask:0xf
	v_fmac_f32_dpp v196, v224, v8 row_newbcast:2 row_mask:0xf bank_mask:0xf
	v_fmac_f32_dpp v197, v225, v9 row_newbcast:2 row_mask:0xf bank_mask:0xf
	v_fmac_f32_dpp v198, v226, v10 row_newbcast:2 row_mask:0xf bank_mask:0xf
	v_fmac_f32_dpp v199, v227, v11 row_newbcast:2 row_mask:0xf bank_mask:0xf
	v_fmac_f32_dpp v196, v224, v12 row_newbcast:3 row_mask:0xf bank_mask:0xf
	v_fmac_f32_dpp v197, v225, v13 row_newbcast:3 row_mask:0xf bank_mask:0xf
	v_fmac_f32_dpp v198, v226, v14 row_newbcast:3 row_mask:0xf bank_mask:0xf
	v_fmac_f32_dpp v199, v227, v15 row_newbcast:3 row_mask:0xf bank_mask:0xf
	v_fmac_f32_dpp v196, v224, v16 row_newbcast:4 row_mask:0xf bank_mask:0xf
	v_fmac_f32_dpp v197, v225, v17 row_newbcast:4 row_mask:0xf bank_mask:0xf
	v_fmac_f32_dpp v198, v226, v18 row_newbcast:4 row_mask:0xf bank_mask:0xf
	v_fmac_f32_dpp v199, v227, v19 row_newbcast:4 row_mask:0xf bank_mask:0xf
	v_fmac_f32_dpp v196, v224, v20 row_newbcast:5 row_mask:0xf bank_mask:0xf
	v_fmac_f32_dpp v197, v225, v21 row_newbcast:5 row_mask:0xf bank_mask:0xf
	v_fmac_f32_dpp v198, v226, v22 row_newbcast:5 row_mask:0xf bank_mask:0xf
	v_fmac_f32_dpp v199, v227, v23 row_newbcast:5 row_mask:0xf bank_mask:0xf
	v_fmac_f32_dpp v196, v224, v24 row_newbcast:6 row_mask:0xf bank_mask:0xf
	v_fmac_f32_dpp v197, v225, v25 row_newbcast:6 row_mask:0xf bank_mask:0xf
	v_fmac_f32_dpp v198, v226, v26 row_newbcast:6 row_mask:0xf bank_mask:0xf
	v_fmac_f32_dpp v199, v227, v27 row_newbcast:6 row_mask:0xf bank_mask:0xf
	v_fmac_f32_dpp v196, v224, v28 row_newbcast:7 row_mask:0xf bank_mask:0xf
	v_fmac_f32_dpp v197, v225, v29 row_newbcast:7 row_mask:0xf bank_mask:0xf
	v_fmac_f32_dpp v198, v226, v30 row_newbcast:7 row_mask:0xf bank_mask:0xf
	v_fmac_f32_dpp v199, v227, v31 row_newbcast:7 row_mask:0xf bank_mask:0xf
	v_fmac_f32_dpp v196, v224, v32 row_newbcast:8 row_mask:0xf bank_mask:0xf
	v_fmac_f32_dpp v197, v225, v33 row_newbcast:8 row_mask:0xf bank_mask:0xf
	v_fmac_f32_dpp v198, v226, v34 row_newbcast:8 row_mask:0xf bank_mask:0xf
	v_fmac_f32_dpp v199, v227, v35 row_newbcast:8 row_mask:0xf bank_mask:0xf
	v_fmac_f32_dpp v196, v224, v36 row_newbcast:9 row_mask:0xf bank_mask:0xf
	v_fmac_f32_dpp v197, v225, v37 row_newbcast:9 row_mask:0xf bank_mask:0xf
	v_fmac_f32_dpp v198, v226, v38 row_newbcast:9 row_mask:0xf bank_mask:0xf
	v_fmac_f32_dpp v199, v227, v39 row_newbcast:9 row_mask:0xf bank_mask:0xf
	v_fmac_f32_dpp v196, v224, v40 row_newbcast:10 row_mask:0xf bank_mask:0xf
	v_fmac_f32_dpp v197, v225, v41 row_newbcast:10 row_mask:0xf bank_mask:0xf
	v_fmac_f32_dpp v198, v226, v42 row_newbcast:10 row_mask:0xf bank_mask:0xf
	v_fmac_f32_dpp v199, v227, v43 row_newbcast:10 row_mask:0xf bank_mask:0xf
	v_fmac_f32_dpp v196, v224, v44 row_newbcast:11 row_mask:0xf bank_mask:0xf
	v_fmac_f32_dpp v197, v225, v45 row_newbcast:11 row_mask:0xf bank_mask:0xf
	v_fmac_f32_dpp v198, v226, v46 row_newbcast:11 row_mask:0xf bank_mask:0xf
	v_fmac_f32_dpp v199, v227, v47 row_newbcast:11 row_mask:0xf bank_mask:0xf
	v_fmac_f32_dpp v196, v224, v48 row_newbcast:12 row_mask:0xf bank_mask:0xf
	v_fmac_f32_dpp v197, v225, v49 row_newbcast:12 row_mask:0xf bank_mask:0xf
	v_fmac_f32_dpp v198, v226, v50 row_newbcast:12 row_mask:0xf bank_mask:0xf
	v_fmac_f32_dpp v199, v227, v51 row_newbcast:12 row_mask:0xf bank_mask:0xf
	v_fmac_f32_dpp v196, v224, v52 row_newbcast:13 row_mask:0xf bank_mask:0xf
	v_fmac_f32_dpp v197, v225, v53 row_newbcast:13 row_mask:0xf bank_mask:0xf
	v_fmac_f32_dpp v198, v226, v54 row_newbcast:13 row_mask:0xf bank_mask:0xf
	v_fmac_f32_dpp v199, v227, v55 row_newbcast:13 row_mask:0xf bank_mask:0xf
	v_fmac_f32_dpp v196, v224, v56 row_newbcast:14 row_mask:0xf bank_mask:0xf
	v_fmac_f32_dpp v197, v225, v57 row_newbcast:14 row_mask:0xf bank_mask:0xf
	v_fmac_f32_dpp v198, v226, v58 row_newbcast:14 row_mask:0xf bank_mask:0xf
	v_fmac_f32_dpp v199, v227, v59 row_newbcast:14 row_mask:0xf bank_mask:0xf
	v_fmac_f32_dpp v196, v224, v60 row_newbcast:15 row_mask:0xf bank_mask:0xf
	v_fmac_f32_dpp v197, v225, v61 row_newbcast:15 row_mask:0xf bank_mask:0xf
	v_fmac_f32_dpp v198, v226, v62 row_newbcast:15 row_mask:0xf bank_mask:0xf
	v_fmac_f32_dpp v199, v227, v63 row_newbcast:15 row_mask:0xf bank_mask:0xf
	v_add_f32_e32 v196, v196, v197
	v_add_f32_e32 v198, v198, v199
	v_sub_f32_e64 v202, -v196, v198
	s_waitcnt lgkmcnt(0)
; #define SB __builtin_amdgcn_sched_barrier(0)
; #define TOUCH1(set) asm volatile("" :: "v"(set.w), "v"(set.a), "v"(set.b), "v"(set.kw), "v"(set.v))
; #define ST1(set) { DERIVE_BK(set); float sd[4]; ScanK<0>::dot(S, set.a, sd); ScanK<0>::updS(S, set, -((sd[0] + sd[1]) + (sd[2] + sd[3])), __uint_as_float(set.v << 16)); }
; #define TOUCH1(set) asm volatile("" :: "v"(set.w), "v"(set.a), "v"(set.b))
;     static __device__ __forceinline__ void dot(const float (&S)[64], const f32x4& a, float (&s)[4]) {
;         if constexpr (K == 0) {
;             asm volatile("v_mul_f32_dpp %0, %4, %8 row_newbcast:%16" DPPM "v_mul_f32_dpp %1, %5, %9 row_newbcast:%16" DPPM "v_mul_f32_dpp %2, %6, %10 row_newbcast:%16" DPPM "v_mul_f32_dpp %3, %7, %11 row_newbcast:%16" DPPM
;                          "v_fmac_f32_dpp %0, %4, %12 row_newbcast:%17" DPPM "v_fmac_f32_dpp %1, %5, %13 row_newbcast:%17" DPPM "v_fmac_f32_dpp %2, %6, %14 row_newbcast:%17" DPPM "v_fmac_f32_dpp %3, %7, %15 row_newbcast:%17" DPPM
;                          : "=&v"(s[0]), "=&v"(s[1]), "=&v"(s[2]), "=&v"(s[3])
;                          : "v"(a[0]), "v"(a[1]), "v"(a[2]), "v"(a[3]), "v"(S[K]), "v"(S[K + 1]), "v"(S[K + 2]), "v"(S[K + 3]), "v"(S[K + 4]), "v"(S[K + 5]), "v"(S[K + 6]), "v"(S[K + 7]), "n"(N0), "n"(N1));
;         } else
;         asm volatile("v_fmac_f32_dpp %0, %4, %8 row_newbcast:%16" DPPM "v_fmac_f32_dpp %1, %5, %9 row_newbcast:%16" DPPM "v_fmac_f32_dpp %2, %6, %10 row_newbcast:%16" DPPM "v_fmac_f32_dpp %3, %7, %11 row_newbcast:%16" DPPM
;                      "v_fmac_f32_dpp %0, %4, %12 row_newbcast:%17" DPPM "v_fmac_f32_dpp %1, %5, %13 row_newbcast:%17" DPPM "v_fmac_f32_dpp %2, %6, %14 row_newbcast:%17" DPPM "v_fmac_f32_dpp %3, %7, %15 row_newbcast:%17" DPPM
;                      : "+v"(s[0]), "+v"(s[1]), "+v"(s[2]), "+v"(s[3])
;                      : "v"(a[0]), "v"(a[1]), "v"(a[2]), "v"(a[3]), "v"(S[K]), "v"(S[K + 1]), "v"(S[K + 2]), "v"(S[K + 3]), "v"(S[K + 4]), "v"(S[K + 5]), "v"(S[K + 6]), "v"(S[K + 7]), "n"(N0), "n"(N1));
;         if constexpr (K + 8 < 64) ScanK<K + 8>::dot(S, a, s);
; template <bool MIX> __device__ __forceinline__ void scan_pass1(const Params& p, int d, float* ldsf) {
;     ...
;             In1 i0, i1; LD1(i0, 0);
; #pragma unroll 1
;             for (int s = 0; s < LC; s += 2) { TOUCH1(i0); SB; LD1(i1, s + 1); SB; ST1(i0); TOUCH1(i1); SB; LD1(i0, s + 2); SB; ST1(i1); }
	s_nop 1
	v_mfma_f32_4x4x1_16b_f32 v[0:3], v64, v202, v[0:3]
	v_mfma_f32_4x4x1_16b_f32 v[4:7], v65, v202, v[4:7]
	v_mfma_f32_4x4x1_16b_f32 v[8:11], v66, v202, v[8:11]
	v_mfma_f32_4x4x1_16b_f32 v[12:15], v67, v202, v[12:15]
	v_mfma_f32_4x4x1_16b_f32 v[16:19], v68, v202, v[16:19]
	v_mfma_f32_4x4x1_16b_f32 v[20:23], v69, v202, v[20:23]
	v_mfma_f32_4x4x1_16b_f32 v[24:27], v70, v202, v[24:27]
	v_mfma_f32_4x4x1_16b_f32 v[28:31], v71, v202, v[28:31]
	v_mfma_f32_4x4x1_16b_f32 v[32:35], v72, v202, v[32:35]
	v_mfma_f32_4x4x1_16b_f32 v[36:39], v73, v202, v[36:39]
	v_mfma_f32_4x4x1_16b_f32 v[40:43], v74, v202, v[40:43]
	v_mfma_f32_4x4x1_16b_f32 v[44:47], v75, v202, v[44:47]
	v_mfma_f32_4x4x1_16b_f32 v[48:51], v76, v202, v[48:51]
	v_mfma_f32_4x4x1_16b_f32 v[52:55], v77, v202, v[52:55]
	v_mfma_f32_4x4x1_16b_f32 v[56:59], v78, v202, v[56:59]
	v_mfma_f32_4x4x1_16b_f32 v[60:63], v79, v202, v[60:63]
	v_mfma_f32_4x4x1_16b_f32 v[0:3], v80, v203, v[0:3]
	v_mfma_f32_4x4x1_16b_f32 v[4:7], v81, v203, v[4:7]
	v_mfma_f32_4x4x1_16b_f32 v[8:11], v82, v203, v[8:11]
	v_mfma_f32_4x4x1_16b_f32 v[12:15], v83, v203, v[12:15]
	v_mfma_f32_4x4x1_16b_f32 v[16:19], v84, v203, v[16:19]
	v_mfma_f32_4x4x1_16b_f32 v[20:23], v85, v203, v[20:23]
	v_mfma_f32_4x4x1_16b_f32 v[24:27], v86, v203, v[24:27]
	v_mfma_f32_4x4x1_16b_f32 v[28:31], v87, v203, v[28:31]
	v_mfma_f32_4x4x1_16b_f32 v[32:35], v88, v203, v[32:35]
	v_mfma_f32_4x4x1_16b_f32 v[36:39], v89, v203, v[36:39]
	v_mfma_f32_4x4x1_16b_f32 v[40:43], v90, v203, v[40:43]
	v_mfma_f32_4x4x1_16b_f32 v[44:47], v91, v203, v[44:47]
	v_mfma_f32_4x4x1_16b_f32 v[48:51], v92, v203, v[48:51]
	v_mfma_f32_4x4x1_16b_f32 v[52:55], v93, v203, v[52:55]
	v_mfma_f32_4x4x1_16b_f32 v[56:59], v94, v203, v[56:59]
	v_mfma_f32_4x4x1_16b_f32 v[60:63], v95, v203, v[60:63]
	s_waitcnt vmcnt(10)
	buffer_load_dwordx4 v[136:139], v232, s[64:67], s72 offen
	buffer_load_dwordx4 v[140:143], v233, s[64:67], s72 offen
	buffer_load_dwordx4 v[144:147], v234, s[64:67], s72 offen
	buffer_load_dwordx2 v[152:153], v236, s[64:67], s76 offen
	buffer_load_ushort v154, v237, s[64:67], s76 offen
	s_add_i32 s72, s72, 0xfffff000
	s_max_i32 s72, s72, 0
	s_add_i32 s76, s76, 0xfffff800
	s_max_i32 s76, s76, 0
	v_pk_mul_f32 v[224:225], v[160:161], v[216:217]
	v_pk_mul_f32 v[226:227], v[162:163], v[218:219]
	v_pk_mul_f32 v[216:217], v[216:217], v[156:157]
	v_pk_mul_f32 v[218:219], v[218:219], v[158:159]
	v_pk_fma_f32 v[184:185], v[164:165], v[188:189], v[192:193]
	v_pk_fma_f32 v[186:187], v[166:167], v[190:191], v[194:195]
	v_pk_mul_f32 v[176:177], v[160:161], v[164:165]
	v_pk_mul_f32 v[178:179], v[162:163], v[166:167]
	v_rcp_f32_e32 v220, v216
	v_rcp_f32_e32 v221, v217
	v_rcp_f32_e32 v222, v218
	v_rcp_f32_e32 v223, v219
	v_lshlrev_b32_e32 v180, 16, v172
	v_and_b32_e32 v181, 0xffff0000, v172
	v_lshlrev_b32_e32 v182, 16, v173
	v_and_b32_e32 v183, 0xffff0000, v173
	v_pk_mul_f32 v[180:181], v[180:181], v[184:185]
	v_pk_mul_f32 v[182:183], v[182:183], v[186:187]
	v_lshlrev_b32_e32 v203, 16, v174
	v_pk_mul_f32 v[176:177], v[176:177], v[220:221]
	v_pk_mul_f32 v[178:179], v[178:179], v[222:223]
	v_pk_mul_f32 v[180:181], v[180:181], v[220:221]
	v_pk_mul_f32 v[182:183], v[182:183], v[222:223]
	ds_write2_b32 v208, v176, v177 offset0:0 offset1:16
	ds_write2_b32 v208, v178, v179 offset0:32 offset1:48
	ds_write2_b32 v208, v180, v181 offset0:64 offset1:80
	ds_write2_b32 v208, v182, v183 offset0:96 offset1:112
	ds_read_b128 v[64:67], v209 offset:0
	ds_read_b128 v[68:71], v209 offset:16
	ds_read_b128 v[72:75], v209 offset:32
	ds_read_b128 v[76:79], v209 offset:48
	ds_read_b128 v[80:83], v209 offset:256
	ds_read_b128 v[84:87], v209 offset:272
	ds_read_b128 v[88:91], v209 offset:288
	ds_read_b128 v[92:95], v209 offset:304
	v_mul_f32_dpp v196, v224, v0 row_newbcast:0 row_mask:0xf bank_mask:0xf
	v_mul_f32_dpp v197, v225, v1 row_newbcast:0 row_mask:0xf bank_mask:0xf
	v_mul_f32_dpp v198, v226, v2 row_newbcast:0 row_mask:0xf bank_mask:0xf
	v_mul_f32_dpp v199, v227, v3 row_newbcast:0 row_mask:0xf bank_mask:0xf
	v_fmac_f32_dpp v196, v224, v4 row_newbcast:1 row_mask:0xf bank_mask:0xf
	v_fmac_f32_dpp v197, v225, v5 row_newbcast:1 row_mask:0xf bank_mask:0xf
	v_fmac_f32_dpp v198, v226, v6 row_newbcast:1 row_mask:0xf bank_mask:0xf
	v_fmac_f32_dpp v199, v227, v7 row_newbcast:1 row_mask:0xf bank_mask:0xf
	v_fmac_f32_dpp v196, v224, v8 row_newbcast:2 row_mask:0xf bank_mask:0xf
	v_fmac_f32_dpp v197, v225, v9 row_newbcast:2 row_mask:0xf bank_mask:0xf
	v_fmac_f32_dpp v198, v226, v10 row_newbcast:2 row_mask:0xf bank_mask:0xf
	v_fmac_f32_dpp v199, v227, v11 row_newbcast:2 row_mask:0xf bank_mask:0xf
	v_fmac_f32_dpp v196, v224, v12 row_newbcast:3 row_mask:0xf bank_mask:0xf
	v_fmac_f32_dpp v197, v225, v13 row_newbcast:3 row_mask:0xf bank_mask:0xf
	v_fmac_f32_dpp v198, v226, v14 row_newbcast:3 row_mask:0xf bank_mask:0xf
	v_fmac_f32_dpp v199, v227, v15 row_newbcast:3 row_mask:0xf bank_mask:0xf
	v_fmac_f32_dpp v196, v224, v16 row_newbcast:4 row_mask:0xf bank_mask:0xf
	v_fmac_f32_dpp v197, v225, v17 row_newbcast:4 row_mask:0xf bank_mask:0xf
	v_fmac_f32_dpp v198, v226, v18 row_newbcast:4 row_mask:0xf bank_mask:0xf
	v_fmac_f32_dpp v199, v227, v19 row_newbcast:4 row_mask:0xf bank_mask:0xf
	v_fmac_f32_dpp v196, v224, v20 row_newbcast:5 row_mask:0xf bank_mask:0xf
;     static __device__ __forceinline__ void dot(const float (&S)[64], const f32x4& a, float (&s)[4]) {
;         if constexpr (K == 0) {
;             asm volatile("v_mul_f32_dpp %0, %4, %8 row_newbcast:%16" DPPM "v_mul_f32_dpp %1, %5, %9 row_newbcast:%16" DPPM "v_mul_f32_dpp %2, %6, %10 row_newbcast:%16" DPPM "v_mul_f32_dpp %3, %7, %11 row_newbcast:%16" DPPM
;                          "v_fmac_f32_dpp %0, %4, %12 row_newbcast:%17" DPPM "v_fmac_f32_dpp %1, %5, %13 row_newbcast:%17" DPPM "v_fmac_f32_dpp %2, %6, %14 row_newbcast:%17" DPPM "v_fmac_f32_dpp %3, %7, %15 row_newbcast:%17" DPPM
;                          : "=&v"(s[0]), "=&v"(s[1]), "=&v"(s[2]), "=&v"(s[3])
;                          : "v"(a[0]), "v"(a[1]), "v"(a[2]), "v"(a[3]), "v"(S[K]), "v"(S[K + 1]), "v"(S[K + 2]), "v"(S[K + 3]), "v"(S[K + 4]), "v"(S[K + 5]), "v"(S[K + 6]), "v"(S[K + 7]), "n"(N0), "n"(N1));
;         } else
;         asm volatile("v_fmac_f32_dpp %0, %4, %8 row_newbcast:%16" DPPM "v_fmac_f32_dpp %1, %5, %9 row_newbcast:%16" DPPM "v_fmac_f32_dpp %2, %6, %10 row_newbcast:%16" DPPM "v_fmac_f32_dpp %3, %7, %11 row_newbcast:%16" DPPM
;                      "v_fmac_f32_dpp %0, %4, %12 row_newbcast:%17" DPPM "v_fmac_f32_dpp %1, %5, %13 row_newbcast:%17" DPPM "v_fmac_f32_dpp %2, %6, %14 row_newbcast:%17" DPPM "v_fmac_f32_dpp %3, %7, %15 row_newbcast:%17" DPPM
;                      : "+v"(s[0]), "+v"(s[1]), "+v"(s[2]), "+v"(s[3])
;                      : "v"(a[0]), "v"(a[1]), "v"(a[2]), "v"(a[3]), "v"(S[K]), "v"(S[K + 1]), "v"(S[K + 2]), "v"(S[K + 3]), "v"(S[K + 4]), "v"(S[K + 5]), "v"(S[K + 6]), "v"(S[K + 7]), "n"(N0), "n"(N1));
;         if constexpr (K + 8 < 64) ScanK<K + 8>::dot(S, a, s);
;     }
;     static __device__ __forceinline__ void upd(float (&S)[64], const In2& in, float sa, float vv, float& y0, float& y1) {
;         float t0, t1, t2, t3;
;         asm volatile("v_mul_f32_dpp %0, %10, %27 row_newbcast:%28" DPPM "v_mul_f32_dpp %1, %11, %27 row_newbcast:%28" DPPM "v_mul_f32_dpp %2, %12, %27 row_newbcast:%28" DPPM "v_mul_f32_dpp %3, %13, %27 row_newbcast:%28" DPPM
;                      "v_fmac_f32_dpp %0, %14, %6 row_newbcast:%28" DPPM "v_fmac_f32_dpp %1, %15, %7 row_newbcast:%28" DPPM "v_fmac_f32_dpp %2, %16, %8 row_newbcast:%28" DPPM "v_fmac_f32_dpp %3, %17, %9 row_newbcast:%28" DPPM
	v_fmac_f32_dpp v197, v225, v21 row_newbcast:5 row_mask:0xf bank_mask:0xf
	v_fmac_f32_dpp v198, v226, v22 row_newbcast:5 row_mask:0xf bank_mask:0xf
	v_fmac_f32_dpp v199, v227, v23 row_newbcast:5 row_mask:0xf bank_mask:0xf
	v_fmac_f32_dpp v196, v224, v24 row_newbcast:6 row_mask:0xf bank_mask:0xf
	v_fmac_f32_dpp v197, v225, v25 row_newbcast:6 row_mask:0xf bank_mask:0xf
	v_fmac_f32_dpp v198, v226, v26 row_newbcast:6 row_mask:0xf bank_mask:0xf
	v_fmac_f32_dpp v199, v227, v27 row_newbcast:6 row_mask:0xf bank_mask:0xf
	v_fmac_f32_dpp v196, v224, v28 row_newbcast:7 row_mask:0xf bank_mask:0xf
	v_fmac_f32_dpp v197, v225, v29 row_newbcast:7 row_mask:0xf bank_mask:0xf
	v_fmac_f32_dpp v198, v226, v30 row_newbcast:7 row_mask:0xf bank_mask:0xf
	v_fmac_f32_dpp v199, v227, v31 row_newbcast:7 row_mask:0xf bank_mask:0xf
	v_fmac_f32_dpp v196, v224, v32 row_newbcast:8 row_mask:0xf bank_mask:0xf
	v_fmac_f32_dpp v197, v225, v33 row_newbcast:8 row_mask:0xf bank_mask:0xf
	v_fmac_f32_dpp v198, v226, v34 row_newbcast:8 row_mask:0xf bank_mask:0xf
	v_fmac_f32_dpp v199, v227, v35 row_newbcast:8 row_mask:0xf bank_mask:0xf
	v_fmac_f32_dpp v196, v224, v36 row_newbcast:9 row_mask:0xf bank_mask:0xf
	v_fmac_f32_dpp v197, v225, v37 row_newbcast:9 row_mask:0xf bank_mask:0xf
	v_fmac_f32_dpp v198, v226, v38 row_newbcast:9 row_mask:0xf bank_mask:0xf
	v_fmac_f32_dpp v199, v227, v39 row_newbcast:9 row_mask:0xf bank_mask:0xf
	v_fmac_f32_dpp v196, v224, v40 row_newbcast:10 row_mask:0xf bank_mask:0xf
	v_fmac_f32_dpp v197, v225, v41 row_newbcast:10 row_mask:0xf bank_mask:0xf
	v_fmac_f32_dpp v198, v226, v42 row_newbcast:10 row_mask:0xf bank_mask:0xf
	v_fmac_f32_dpp v199, v227, v43 row_newbcast:10 row_mask:0xf bank_mask:0xf
	v_fmac_f32_dpp v196, v224, v44 row_newbcast:11 row_mask:0xf bank_mask:0xf
	v_fmac_f32_dpp v197, v225, v45 row_newbcast:11 row_mask:0xf bank_mask:0xf
	v_fmac_f32_dpp v198, v226, v46 row_newbcast:11 row_mask:0xf bank_mask:0xf
	v_fmac_f32_dpp v199, v227, v47 row_newbcast:11 row_mask:0xf bank_mask:0xf
	v_fmac_f32_dpp v196, v224, v48 row_newbcast:12 row_mask:0xf bank_mask:0xf
	v_fmac_f32_dpp v197, v225, v49 row_newbcast:12 row_mask:0xf bank_mask:0xf
	v_fmac_f32_dpp v198, v226, v50 row_newbcast:12 row_mask:0xf bank_mask:0xf
	v_fmac_f32_dpp v199, v227, v51 row_newbcast:12 row_mask:0xf bank_mask:0xf
	v_fmac_f32_dpp v196, v224, v52 row_newbcast:13 row_mask:0xf bank_mask:0xf
	v_fmac_f32_dpp v197, v225, v53 row_newbcast:13 row_mask:0xf bank_mask:0xf
	v_fmac_f32_dpp v198, v226, v54 row_newbcast:13 row_mask:0xf bank_mask:0xf
	v_fmac_f32_dpp v199, v227, v55 row_newbcast:13 row_mask:0xf bank_mask:0xf
	v_fmac_f32_dpp v196, v224, v56 row_newbcast:14 row_mask:0xf bank_mask:0xf
	v_fmac_f32_dpp v197, v225, v57 row_newbcast:14 row_mask:0xf bank_mask:0xf
	v_fmac_f32_dpp v198, v226, v58 row_newbcast:14 row_mask:0xf bank_mask:0xf
	v_fmac_f32_dpp v199, v227, v59 row_newbcast:14 row_mask:0xf bank_mask:0xf
	v_fmac_f32_dpp v196, v224, v60 row_newbcast:15 row_mask:0xf bank_mask:0xf
	v_fmac_f32_dpp v197, v225, v61 row_newbcast:15 row_mask:0xf bank_mask:0xf
	v_fmac_f32_dpp v198, v226, v62 row_newbcast:15 row_mask:0xf bank_mask:0xf
	v_fmac_f32_dpp v199, v227, v63 row_newbcast:15 row_mask:0xf bank_mask:0xf
	v_add_f32_e32 v196, v196, v197
	v_add_f32_e32 v198, v198, v199
	v_sub_f32_e64 v202, -v196, v198
	s_waitcnt lgkmcnt(0)
	s_nop 1
	v_mfma_f32_4x4x1_16b_f32 v[0:3], v64, v202, v[0:3]
	v_mfma_f32_4x4x1_16b_f32 v[4:7], v65, v202, v[4:7]
	v_mfma_f32_4x4x1_16b_f32 v[8:11], v66, v202, v[8:11]
	v_mfma_f32_4x4x1_16b_f32 v[12:15], v67, v202, v[12:15]
	v_mfma_f32_4x4x1_16b_f32 v[16:19], v68, v202, v[16:19]
	v_mfma_f32_4x4x1_16b_f32 v[20:23], v69, v202, v[20:23]
	v_mfma_f32_4x4x1_16b_f32 v[24:27], v70, v202, v[24:27]
	v_mfma_f32_4x4x1_16b_f32 v[28:31], v71, v202, v[28:31]
	v_mfma_f32_4x4x1_16b_f32 v[32:35], v72, v202, v[32:35]
	v_mfma_f32_4x4x1_16b_f32 v[36:39], v73, v202, v[36:39]
	v_mfma_f32_4x4x1_16b_f32 v[40:43], v74, v202, v[40:43]
	v_mfma_f32_4x4x1_16b_f32 v[44:47], v75, v202, v[44:47]
	v_mfma_f32_4x4x1_16b_f32 v[48:51], v76, v202, v[48:51]
	v_mfma_f32_4x4x1_16b_f32 v[52:55], v77, v202, v[52:55]
	v_mfma_f32_4x4x1_16b_f32 v[56:59], v78, v202, v[56:59]
	v_mfma_f32_4x4x1_16b_f32 v[60:63], v79, v202, v[60:63]
	v_mfma_f32_4x4x1_16b_f32 v[0:3], v80, v203, v[0:3]
	v_mfma_f32_4x4x1_16b_f32 v[4:7], v81, v203, v[4:7]
	v_mfma_f32_4x4x1_16b_f32 v[8:11], v82, v203, v[8:11]
	v_mfma_f32_4x4x1_16b_f32 v[12:15], v83, v203, v[12:15]
	v_mfma_f32_4x4x1_16b_f32 v[16:19], v84, v203, v[16:19]
	v_mfma_f32_4x4x1_16b_f32 v[20:23], v85, v203, v[20:23]
	v_mfma_f32_4x4x1_16b_f32 v[24:27], v86, v203, v[24:27]
	v_mfma_f32_4x4x1_16b_f32 v[28:31], v87, v203, v[28:31]
	v_mfma_f32_4x4x1_16b_f32 v[32:35], v88, v203, v[32:35]
	v_mfma_f32_4x4x1_16b_f32 v[36:39], v89, v203, v[36:39]
	v_mfma_f32_4x4x1_16b_f32 v[40:43], v90, v203, v[40:43]
	v_mfma_f32_4x4x1_16b_f32 v[44:47], v91, v203, v[44:47]
	v_mfma_f32_4x4x1_16b_f32 v[48:51], v92, v203, v[48:51]
	v_mfma_f32_4x4x1_16b_f32 v[52:55], v93, v203, v[52:55]
	v_mfma_f32_4x4x1_16b_f32 v[56:59], v94, v203, v[56:59]
	v_mfma_f32_4x4x1_16b_f32 v[60:63], v95, v203, v[60:63]
	s_sub_u32 s83, s83, 1
	s_cmp_eq_u32 s83, 0
	s_cbranch_scc1 .Lmy_p1d1_ldone_s
	s_and_b32 s9, s83, 7
	s_cmp_eq_u32 s9, 0
	s_cbranch_scc1 .Lmy_p1d1_renorm_s
	s_branch .Lmy_p1d1_loop_s

; #define SB __builtin_amdgcn_sched_barrier(0)
; #define LD1(set, s) { const int e_ = min((int)(s), LC - 1) * (int)stp; const unsigned s4_ = ob4 + (unsigned)(e_ * 4), s2_ = ob2 + (unsigned)(e_ * 2); set.w = LDX(rW, s4_); set.a = LDX(rA, s4_); set.b = LDX(rB, s4_); \
;             set.kw = __builtin_amdgcn_raw_buffer_load_b64(rK, lo8, s2_, 0); set.v = __builtin_amdgcn_raw_buffer_load_b16(rV, lo2, s2_, 0); }
; #define TOUCH1(set) asm volatile("" :: "v"(set.w), "v"(set.a), "v"(set.b), "v"(set.kw), "v"(set.v))
; #define ST1(set) { DERIVE_BK(set); float sd[4]; ScanK<0>::dot(S, set.a, sd); ScanK<0>::updS(S, set, -((sd[0] + sd[1]) + (sd[2] + sd[3])), __uint_as_float(set.v << 16)); }
; #define LD1(set, s) { const int e_ = min((int)(s), LC - 1) * (int)stp; const unsigned s4_ = ob4 + (unsigned)(e_ * 4); set.w = LDX(rW, s4_); set.a = LDX(rA, s4_); set.b = LDX(rB, s4_); }
; #define TOUCH1(set) asm volatile("" :: "v"(set.w), "v"(set.a), "v"(set.b))
; #define ST1(set) { DERIVE_B(set); float sd[4]; ScanK<0>::dot(S, set.a, sd); ScanK<0>::updP(S, set, -((sd[0] + sd[1]) + (sd[2] + sd[3]))); }
; template <bool MIX> __device__ __forceinline__ void scan_pass1(const Params& p, int d, float* ldsf) {
;     ...
;         } else {
; #pragma unroll
;             for (int i = 0; i < 64; ++i) S[i] = (ln == i) ? 1.f : 0.f;
;     ...
;             In1 i0, i1; LD1(i0, 0);
; #pragma unroll 1
;             for (int s = 0; s < LC; s += 2) { TOUCH1(i0); SB; LD1(i1, s + 1); SB; ST1(i0); TOUCH1(i1); SB; LD1(i0, s + 2); SB; ST1(i1); }
.Lmy_p1d1_pitem:
	buffer_load_dwordx4 v[96:99], v232, s[64:67], s72 offen
	buffer_load_dwordx4 v[100:103], v233, s[64:67], s72 offen
	buffer_load_dwordx4 v[104:107], v234, s[64:67], s72 offen
	s_add_i32 s72, s72, 0xfffff000
	s_max_i32 s72, s72, 0
	buffer_load_dwordx4 v[116:119], v232, s[64:67], s72 offen
	buffer_load_dwordx4 v[120:123], v233, s[64:67], s72 offen
	buffer_load_dwordx4 v[124:127], v234, s[64:67], s72 offen
	s_add_i32 s72, s72, 0xfffff000
	s_max_i32 s72, s72, 0
	buffer_load_dwordx4 v[136:139], v232, s[64:67], s72 offen
	buffer_load_dwordx4 v[140:143], v233, s[64:67], s72 offen
	buffer_load_dwordx4 v[144:147], v234, s[64:67], s72 offen
	s_add_i32 s72, s72, 0xfffff000
	s_max_i32 s72, s72, 0
	v_cmp_eq_u32_e32 vcc, 0, v212
	s_nop 1
	v_cndmask_b32_e32 v0, 0, v213, vcc
	v_cmp_eq_u32_e32 vcc, 1, v212
	s_nop 1
	v_cndmask_b32_e32 v1, 0, v213, vcc
	v_cmp_eq_u32_e32 vcc, 2, v212
	s_nop 1
	v_cndmask_b32_e32 v2, 0, v213, vcc
	v_cmp_eq_u32_e32 vcc, 3, v212
	s_nop 1
	v_cndmask_b32_e32 v3, 0, v213, vcc
	v_cmp_eq_u32_e32 vcc, 4, v212
	s_nop 1
	v_cndmask_b32_e32 v4, 0, v213, vcc
	v_cmp_eq_u32_e32 vcc, 5, v212
	s_nop 1
	v_cndmask_b32_e32 v5, 0, v213, vcc
	v_cmp_eq_u32_e32 vcc, 6, v212
	s_nop 1
	v_cndmask_b32_e32 v6, 0, v213, vcc
	v_cmp_eq_u32_e32 vcc, 7, v212
	s_nop 1
	v_cndmask_b32_e32 v7, 0, v213, vcc
	v_cmp_eq_u32_e32 vcc, 8, v212
	s_nop 1
	v_cndmask_b32_e32 v8, 0, v213, vcc
	v_cmp_eq_u32_e32 vcc, 9, v212
	s_nop 1
	v_cndmask_b32_e32 v9, 0, v213, vcc
	v_cmp_eq_u32_e32 vcc, 10, v212
	s_nop 1
	v_cndmask_b32_e32 v10, 0, v213, vcc
	v_cmp_eq_u32_e32 vcc, 11, v212
	s_nop 1
	v_cndmask_b32_e32 v11, 0, v213, vcc
	v_cmp_eq_u32_e32 vcc, 12, v212
	s_nop 1
	v_cndmask_b32_e32 v12, 0, v213, vcc
	v_cmp_eq_u32_e32 vcc, 13, v212
	s_nop 1
	v_cndmask_b32_e32 v13, 0, v213, vcc
	v_cmp_eq_u32_e32 vcc, 14, v212
	s_nop 1
	v_cndmask_b32_e32 v14, 0, v213, vcc
	v_cmp_eq_u32_e32 vcc, 15, v212
	s_nop 1
	v_cndmask_b32_e32 v15, 0, v213, vcc
	v_cmp_eq_u32_e32 vcc, 16, v212
	s_nop 1
	v_cndmask_b32_e32 v16, 0, v213, vcc
	v_cmp_eq_u32_e32 vcc, 17, v212
	s_nop 1
	v_cndmask_b32_e32 v17, 0, v213, vcc
	v_cmp_eq_u32_e32 vcc, 18, v212
	s_nop 1
	v_cndmask_b32_e32 v18, 0, v213, vcc
	v_cmp_eq_u32_e32 vcc, 19, v212
	s_nop 1
	v_cndmask_b32_e32 v19, 0, v213, vcc
	v_cmp_eq_u32_e32 vcc, 20, v212
	s_nop 1
	v_cndmask_b32_e32 v20, 0, v213, vcc
	v_cmp_eq_u32_e32 vcc, 21, v212
	s_nop 1
	v_cndmask_b32_e32 v21, 0, v213, vcc
	v_cmp_eq_u32_e32 vcc, 22, v212
	s_nop 1
	v_cndmask_b32_e32 v22, 0, v213, vcc
	v_cmp_eq_u32_e32 vcc, 23, v212
	s_nop 1
	v_cndmask_b32_e32 v23, 0, v213, vcc
	v_cmp_eq_u32_e32 vcc, 24, v212
	s_nop 1
	v_cndmask_b32_e32 v24, 0, v213, vcc
	v_cmp_eq_u32_e32 vcc, 25, v212
	s_nop 1
	v_cndmask_b32_e32 v25, 0, v213, vcc
	v_cmp_eq_u32_e32 vcc, 26, v212
	s_nop 1
	v_cndmask_b32_e32 v26, 0, v213, vcc
	v_cmp_eq_u32_e32 vcc, 27, v212
	s_nop 1
	v_cndmask_b32_e32 v27, 0, v213, vcc
	v_cmp_eq_u32_e32 vcc, 28, v212
	s_nop 1
	v_cndmask_b32_e32 v28, 0, v213, vcc
	v_cmp_eq_u32_e32 vcc, 29, v212
	s_nop 1
	v_cndmask_b32_e32 v29, 0, v213, vcc
	v_cmp_eq_u32_e32 vcc, 30, v212
	s_nop 1
	v_cndmask_b32_e32 v30, 0, v213, vcc
	v_cmp_eq_u32_e32 vcc, 31, v212
	s_nop 1
	v_cndmask_b32_e32 v31, 0, v213, vcc
	v_cmp_eq_u32_e32 vcc, 32, v212
	s_nop 1
	v_cndmask_b32_e32 v32, 0, v213, vcc
	v_cmp_eq_u32_e32 vcc, 33, v212
	s_nop 1
	v_cndmask_b32_e32 v33, 0, v213, vcc
	v_cmp_eq_u32_e32 vcc, 34, v212
	s_nop 1
	v_cndmask_b32_e32 v34, 0, v213, vcc
	v_cmp_eq_u32_e32 vcc, 35, v212
	s_nop 1
	v_cndmask_b32_e32 v35, 0, v213, vcc
	v_cmp_eq_u32_e32 vcc, 36, v212
	s_nop 1
	v_cndmask_b32_e32 v36, 0, v213, vcc
	v_cmp_eq_u32_e32 vcc, 37, v212
	s_nop 1
	v_cndmask_b32_e32 v37, 0, v213, vcc
	v_cmp_eq_u32_e32 vcc, 38, v212
	s_nop 1
	v_cndmask_b32_e32 v38, 0, v213, vcc
	v_cmp_eq_u32_e32 vcc, 39, v212
	s_nop 1
	v_cndmask_b32_e32 v39, 0, v213, vcc
	v_cmp_eq_u32_e32 vcc, 40, v212
	s_nop 1
	v_cndmask_b32_e32 v40, 0, v213, vcc
	v_cmp_eq_u32_e32 vcc, 41, v212
	s_nop 1
	v_cndmask_b32_e32 v41, 0, v213, vcc
	v_cmp_eq_u32_e32 vcc, 42, v212
	s_nop 1
	v_cndmask_b32_e32 v42, 0, v213, vcc
	v_cmp_eq_u32_e32 vcc, 43, v212
	s_nop 1
	v_cndmask_b32_e32 v43, 0, v213, vcc
	v_cmp_eq_u32_e32 vcc, 44, v212
	s_nop 1
	v_cndmask_b32_e32 v44, 0, v213, vcc
	v_cmp_eq_u32_e32 vcc, 45, v212
	s_nop 1
	v_cndmask_b32_e32 v45, 0, v213, vcc
	v_cmp_eq_u32_e32 vcc, 46, v212
	s_nop 1
	v_cndmask_b32_e32 v46, 0, v213, vcc
	v_cmp_eq_u32_e32 vcc, 47, v212
	s_nop 1
	v_cndmask_b32_e32 v47, 0, v213, vcc
	v_cmp_eq_u32_e32 vcc, 48, v212
	s_nop 1
	v_cndmask_b32_e32 v48, 0, v213, vcc
	v_cmp_eq_u32_e32 vcc, 49, v212
	s_nop 1
	v_cndmask_b32_e32 v49, 0, v213, vcc
	v_cmp_eq_u32_e32 vcc, 50, v212
	s_nop 1
	v_cndmask_b32_e32 v50, 0, v213, vcc
	v_cmp_eq_u32_e32 vcc, 51, v212
	s_nop 1
	v_cndmask_b32_e32 v51, 0, v213, vcc
	v_cmp_eq_u32_e32 vcc, 52, v212
	s_nop 1
	v_cndmask_b32_e32 v52, 0, v213, vcc
	v_cmp_eq_u32_e32 vcc, 53, v212
	s_nop 1
	v_cndmask_b32_e32 v53, 0, v213, vcc
	v_cmp_eq_u32_e32 vcc, 54, v212
	s_nop 1
	v_cndmask_b32_e32 v54, 0, v213, vcc
	v_cmp_eq_u32_e32 vcc, 55, v212
	s_nop 1
	v_cndmask_b32_e32 v55, 0, v213, vcc
	v_cmp_eq_u32_e32 vcc, 56, v212
	s_nop 1
	v_cndmask_b32_e32 v56, 0, v213, vcc
	v_cmp_eq_u32_e32 vcc, 57, v212
	s_nop 1
	v_cndmask_b32_e32 v57, 0, v213, vcc
	v_cmp_eq_u32_e32 vcc, 58, v212
	s_nop 1
	v_cndmask_b32_e32 v58, 0, v213, vcc
	v_cmp_eq_u32_e32 vcc, 59, v212
	s_nop 1
	v_cndmask_b32_e32 v59, 0, v213, vcc
	v_cmp_eq_u32_e32 vcc, 60, v212
	s_nop 1
	v_cndmask_b32_e32 v60, 0, v213, vcc
	v_cmp_eq_u32_e32 vcc, 61, v212
	s_nop 1
	v_cndmask_b32_e32 v61, 0, v213, vcc
	v_cmp_eq_u32_e32 vcc, 62, v212
	s_nop 1
	v_cndmask_b32_e32 v62, 0, v213, vcc
	v_cmp_eq_u32_e32 vcc, 63, v212
	s_nop 1
	v_cndmask_b32_e32 v63, 0, v213, vcc
	s_waitcnt vmcnt(0)
	v_mov_b32_e32 v216, 1.0
	v_mov_b32_e32 v217, 1.0
	v_mov_b32_e32 v218, 1.0
	v_mov_b32_e32 v219, 1.0
	s_movk_i32 s83, 64
	s_branch .Lmy_p1d1_loop_p

; #define SB __builtin_amdgcn_sched_barrier(0)
; #define TOUCH1(set) asm volatile("" :: "v"(set.w), "v"(set.a), "v"(set.b), "v"(set.kw), "v"(set.v))
; #define ST1(set) { DERIVE_BK(set); float sd[4]; ScanK<0>::dot(S, set.a, sd); ScanK<0>::updS(S, set, -((sd[0] + sd[1]) + (sd[2] + sd[3])), __uint_as_float(set.v << 16)); }
; #define TOUCH1(set) asm volatile("" :: "v"(set.w), "v"(set.a), "v"(set.b))
;     static __device__ __forceinline__ void dot(const float (&S)[64], const f32x4& a, float (&s)[4]) {
;         if constexpr (K == 0) {
;             asm volatile("v_mul_f32_dpp %0, %4, %8 row_newbcast:%16" DPPM "v_mul_f32_dpp %1, %5, %9 row_newbcast:%16" DPPM "v_mul_f32_dpp %2, %6, %10 row_newbcast:%16" DPPM "v_mul_f32_dpp %3, %7, %11 row_newbcast:%16" DPPM
;                          "v_fmac_f32_dpp %0, %4, %12 row_newbcast:%17" DPPM "v_fmac_f32_dpp %1, %5, %13 row_newbcast:%17" DPPM "v_fmac_f32_dpp %2, %6, %14 row_newbcast:%17" DPPM "v_fmac_f32_dpp %3, %7, %15 row_newbcast:%17" DPPM
;                          : "=&v"(s[0]), "=&v"(s[1]), "=&v"(s[2]), "=&v"(s[3])
;                          : "v"(a[0]), "v"(a[1]), "v"(a[2]), "v"(a[3]), "v"(S[K]), "v"(S[K + 1]), "v"(S[K + 2]), "v"(S[K + 3]), "v"(S[K + 4]), "v"(S[K + 5]), "v"(S[K + 6]), "v"(S[K + 7]), "n"(N0), "n"(N1));
;         } else
;         asm volatile("v_fmac_f32_dpp %0, %4, %8 row_newbcast:%16" DPPM "v_fmac_f32_dpp %1, %5, %9 row_newbcast:%16" DPPM "v_fmac_f32_dpp %2, %6, %10 row_newbcast:%16" DPPM "v_fmac_f32_dpp %3, %7, %11 row_newbcast:%16" DPPM
;                      "v_fmac_f32_dpp %0, %4, %12 row_newbcast:%17" DPPM "v_fmac_f32_dpp %1, %5, %13 row_newbcast:%17" DPPM "v_fmac_f32_dpp %2, %6, %14 row_newbcast:%17" DPPM "v_fmac_f32_dpp %3, %7, %15 row_newbcast:%17" DPPM
;                      : "+v"(s[0]), "+v"(s[1]), "+v"(s[2]), "+v"(s[3])
;                      : "v"(a[0]), "v"(a[1]), "v"(a[2]), "v"(a[3]), "v"(S[K]), "v"(S[K + 1]), "v"(S[K + 2]), "v"(S[K + 3]), "v"(S[K + 4]), "v"(S[K + 5]), "v"(S[K + 6]), "v"(S[K + 7]), "n"(N0), "n"(N1));
;         if constexpr (K + 8 < 64) ScanK<K + 8>::dot(S, a, s);
; template <bool MIX> __device__ __forceinline__ void scan_pass1(const Params& p, int d, float* ldsf) {
;     ...
;             In1 i0, i1; LD1(i0, 0);
; #pragma unroll 1
;             for (int s = 0; s < LC; s += 2) { TOUCH1(i0); SB; LD1(i1, s + 1); SB; ST1(i0); TOUCH1(i1); SB; LD1(i0, s + 2); SB; ST1(i1); }
.Lmy_p1d1_loop_p:
	s_waitcnt vmcnt(6)
	buffer_load_dwordx4 v[156:159], v232, s[64:67], s72 offen
	buffer_load_dwordx4 v[160:163], v233, s[64:67], s72 offen
	buffer_load_dwordx4 v[164:167], v234, s[64:67], s72 offen
	s_add_i32 s72, s72, 0xfffff000
	s_max_i32 s72, s72, 0
	v_pk_mul_f32 v[224:225], v[100:101], v[216:217]
	v_pk_mul_f32 v[226:227], v[102:103], v[218:219]
	v_pk_mul_f32 v[216:217], v[216:217], v[96:97]
	v_pk_mul_f32 v[218:219], v[218:219], v[98:99]
	v_pk_mul_f32 v[176:177], v[100:101], v[104:105]
	v_pk_mul_f32 v[178:179], v[102:103], v[106:107]
	v_rcp_f32_e32 v220, v216
	v_rcp_f32_e32 v221, v217
	v_rcp_f32_e32 v222, v218
	v_rcp_f32_e32 v223, v219
	s_nop 0
	v_pk_mul_f32 v[176:177], v[176:177], v[220:221]
	v_pk_mul_f32 v[178:179], v[178:179], v[222:223]
	ds_write2_b32 v208, v176, v177 offset0:0 offset1:16
	ds_write2_b32 v208, v178, v179 offset0:32 offset1:48
	ds_read_b128 v[64:67], v209 offset:0
	ds_read_b128 v[68:71], v209 offset:16
	ds_read_b128 v[72:75], v209 offset:32
	ds_read_b128 v[76:79], v209 offset:48
	v_mul_f32_dpp v196, v224, v0 row_newbcast:0 row_mask:0xf bank_mask:0xf
	v_mul_f32_dpp v197, v225, v1 row_newbcast:0 row_mask:0xf bank_mask:0xf
	v_mul_f32_dpp v198, v226, v2 row_newbcast:0 row_mask:0xf bank_mask:0xf
	v_mul_f32_dpp v199, v227, v3 row_newbcast:0 row_mask:0xf bank_mask:0xf
	v_fmac_f32_dpp v196, v224, v4 row_newbcast:1 row_mask:0xf bank_mask:0xf
	v_fmac_f32_dpp v197, v225, v5 row_newbcast:1 row_mask:0xf bank_mask:0xf
	v_fmac_f32_dpp v198, v226, v6 row_newbcast:1 row_mask:0xf bank_mask:0xf
	v_fmac_f32_dpp v199, v227, v7 row_newbcast:1 row_mask:0xf bank_mask:0xf
	v_fmac_f32_dpp v196, v224, v8 row_newbcast:2 row_mask:0xf bank_mask:0xf
	v_fmac_f32_dpp v197, v225, v9 row_newbcast:2 row_mask:0xf bank_mask:0xf
	v_fmac_f32_dpp v198, v226, v10 row_newbcast:2 row_mask:0xf bank_mask:0xf
	v_fmac_f32_dpp v199, v227, v11 row_newbcast:2 row_mask:0xf bank_mask:0xf
	v_fmac_f32_dpp v196, v224, v12 row_newbcast:3 row_mask:0xf bank_mask:0xf
	v_fmac_f32_dpp v197, v225, v13 row_newbcast:3 row_mask:0xf bank_mask:0xf
	v_fmac_f32_dpp v198, v226, v14 row_newbcast:3 row_mask:0xf bank_mask:0xf
	v_fmac_f32_dpp v199, v227, v15 row_newbcast:3 row_mask:0xf bank_mask:0xf
	v_fmac_f32_dpp v196, v224, v16 row_newbcast:4 row_mask:0xf bank_mask:0xf
	v_fmac_f32_dpp v197, v225, v17 row_newbcast:4 row_mask:0xf bank_mask:0xf
	v_fmac_f32_dpp v198, v226, v18 row_newbcast:4 row_mask:0xf bank_mask:0xf
	v_fmac_f32_dpp v199, v227, v19 row_newbcast:4 row_mask:0xf bank_mask:0xf
	v_fmac_f32_dpp v196, v224, v20 row_newbcast:5 row_mask:0xf bank_mask:0xf
	v_fmac_f32_dpp v197, v225, v21 row_newbcast:5 row_mask:0xf bank_mask:0xf
	v_fmac_f32_dpp v198, v226, v22 row_newbcast:5 row_mask:0xf bank_mask:0xf
	v_fmac_f32_dpp v199, v227, v23 row_newbcast:5 row_mask:0xf bank_mask:0xf
	v_fmac_f32_dpp v196, v224, v24 row_newbcast:6 row_mask:0xf bank_mask:0xf
	v_fmac_f32_dpp v197, v225, v25 row_newbcast:6 row_mask:0xf bank_mask:0xf
	v_fmac_f32_dpp v198, v226, v26 row_newbcast:6 row_mask:0xf bank_mask:0xf
	v_fmac_f32_dpp v199, v227, v27 row_newbcast:6 row_mask:0xf bank_mask:0xf
	v_fmac_f32_dpp v196, v224, v28 row_newbcast:7 row_mask:0xf bank_mask:0xf
	v_fmac_f32_dpp v197, v225, v29 row_newbcast:7 row_mask:0xf bank_mask:0xf
	v_fmac_f32_dpp v198, v226, v30 row_newbcast:7 row_mask:0xf bank_mask:0xf
	v_fmac_f32_dpp v199, v227, v31 row_newbcast:7 row_mask:0xf bank_mask:0xf
	v_fmac_f32_dpp v196, v224, v32 row_newbcast:8 row_mask:0xf bank_mask:0xf
	v_fmac_f32_dpp v197, v225, v33 row_newbcast:8 row_mask:0xf bank_mask:0xf
	v_fmac_f32_dpp v198, v226, v34 row_newbcast:8 row_mask:0xf bank_mask:0xf
	v_fmac_f32_dpp v199, v227, v35 row_newbcast:8 row_mask:0xf bank_mask:0xf
	v_fmac_f32_dpp v196, v224, v36 row_newbcast:9 row_mask:0xf bank_mask:0xf
	v_fmac_f32_dpp v197, v225, v37 row_newbcast:9 row_mask:0xf bank_mask:0xf
	v_fmac_f32_dpp v198, v226, v38 row_newbcast:9 row_mask:0xf bank_mask:0xf
	v_fmac_f32_dpp v199, v227, v39 row_newbcast:9 row_mask:0xf bank_mask:0xf
	v_fmac_f32_dpp v196, v224, v40 row_newbcast:10 row_mask:0xf bank_mask:0xf
	v_fmac_f32_dpp v197, v225, v41 row_newbcast:10 row_mask:0xf bank_mask:0xf
	v_fmac_f32_dpp v198, v226, v42 row_newbcast:10 row_mask:0xf bank_mask:0xf
	v_fmac_f32_dpp v199, v227, v43 row_newbcast:10 row_mask:0xf bank_mask:0xf
	v_fmac_f32_dpp v196, v224, v44 row_newbcast:11 row_mask:0xf bank_mask:0xf
	v_fmac_f32_dpp v197, v225, v45 row_newbcast:11 row_mask:0xf bank_mask:0xf
	v_fmac_f32_dpp v198, v226, v46 row_newbcast:11 row_mask:0xf bank_mask:0xf
	v_fmac_f32_dpp v199, v227, v47 row_newbcast:11 row_mask:0xf bank_mask:0xf
	v_fmac_f32_dpp v196, v224, v48 row_newbcast:12 row_mask:0xf bank_mask:0xf
	v_fmac_f32_dpp v197, v225, v49 row_newbcast:12 row_mask:0xf bank_mask:0xf
	v_fmac_f32_dpp v198, v226, v50 row_newbcast:12 row_mask:0xf bank_mask:0xf
	v_fmac_f32_dpp v199, v227, v51 row_newbcast:12 row_mask:0xf bank_mask:0xf
	v_fmac_f32_dpp v196, v224, v52 row_newbcast:13 row_mask:0xf bank_mask:0xf
	v_fmac_f32_dpp v197, v225, v53 row_newbcast:13 row_mask:0xf bank_mask:0xf
	v_fmac_f32_dpp v198, v226, v54 row_newbcast:13 row_mask:0xf bank_mask:0xf
	v_fmac_f32_dpp v199, v227, v55 row_newbcast:13 row_mask:0xf bank_mask:0xf
	v_fmac_f32_dpp v196, v224, v56 row_newbcast:14 row_mask:0xf bank_mask:0xf
	v_fmac_f32_dpp v197, v225, v57 row_newbcast:14 row_mask:0xf bank_mask:0xf
	v_fmac_f32_dpp v198, v226, v58 row_newbcast:14 row_mask:0xf bank_mask:0xf
	v_fmac_f32_dpp v199, v227, v59 row_newbcast:14 row_mask:0xf bank_mask:0xf
	v_fmac_f32_dpp v196, v224, v60 row_newbcast:15 row_mask:0xf bank_mask:0xf
	v_fmac_f32_dpp v197, v225, v61 row_newbcast:15 row_mask:0xf bank_mask:0xf
	v_fmac_f32_dpp v198, v226, v62 row_newbcast:15 row_mask:0xf bank_mask:0xf
	v_fmac_f32_dpp v199, v227, v63 row_newbcast:15 row_mask:0xf bank_mask:0xf
	v_add_f32_e32 v196, v196, v197
	v_add_f32_e32 v198, v198, v199
	v_sub_f32_e64 v202, -v196, v198
	s_waitcnt lgkmcnt(0)
; #define SB __builtin_amdgcn_sched_barrier(0)
; #define TOUCH1(set) asm volatile("" :: "v"(set.w), "v"(set.a), "v"(set.b), "v"(set.kw), "v"(set.v))
; #define ST1(set) { DERIVE_BK(set); float sd[4]; ScanK<0>::dot(S, set.a, sd); ScanK<0>::updS(S, set, -((sd[0] + sd[1]) + (sd[2] + sd[3])), __uint_as_float(set.v << 16)); }
; #define TOUCH1(set) asm volatile("" :: "v"(set.w), "v"(set.a), "v"(set.b))
;     static __device__ __forceinline__ void dot(const float (&S)[64], const f32x4& a, float (&s)[4]) {
;         if constexpr (K == 0) {
;             asm volatile("v_mul_f32_dpp %0, %4, %8 row_newbcast:%16" DPPM "v_mul_f32_dpp %1, %5, %9 row_newbcast:%16" DPPM "v_mul_f32_dpp %2, %6, %10 row_newbcast:%16" DPPM "v_mul_f32_dpp %3, %7, %11 row_newbcast:%16" DPPM
;                          "v_fmac_f32_dpp %0, %4, %12 row_newbcast:%17" DPPM "v_fmac_f32_dpp %1, %5, %13 row_newbcast:%17" DPPM "v_fmac_f32_dpp %2, %6, %14 row_newbcast:%17" DPPM "v_fmac_f32_dpp %3, %7, %15 row_newbcast:%17" DPPM
;                          : "=&v"(s[0]), "=&v"(s[1]), "=&v"(s[2]), "=&v"(s[3])
;                          : "v"(a[0]), "v"(a[1]), "v"(a[2]), "v"(a[3]), "v"(S[K]), "v"(S[K + 1]), "v"(S[K + 2]), "v"(S[K + 3]), "v"(S[K + 4]), "v"(S[K + 5]), "v"(S[K + 6]), "v"(S[K + 7]), "n"(N0), "n"(N1));
;         } else
;         asm volatile("v_fmac_f32_dpp %0, %4, %8 row_newbcast:%16" DPPM "v_fmac_f32_dpp %1, %5, %9 row_newbcast:%16" DPPM "v_fmac_f32_dpp %2, %6, %10 row_newbcast:%16" DPPM "v_fmac_f32_dpp %3, %7, %11 row_newbcast:%16" DPPM
;                      "v_fmac_f32_dpp %0, %4, %12 row_newbcast:%17" DPPM "v_fmac_f32_dpp %1, %5, %13 row_newbcast:%17" DPPM "v_fmac_f32_dpp %2, %6, %14 row_newbcast:%17" DPPM "v_fmac_f32_dpp %3, %7, %15 row_newbcast:%17" DPPM
;                      : "+v"(s[0]), "+v"(s[1]), "+v"(s[2]), "+v"(s[3])
;                      : "v"(a[0]), "v"(a[1]), "v"(a[2]), "v"(a[3]), "v"(S[K]), "v"(S[K + 1]), "v"(S[K + 2]), "v"(S[K + 3]), "v"(S[K + 4]), "v"(S[K + 5]), "v"(S[K + 6]), "v"(S[K + 7]), "n"(N0), "n"(N1));
;         if constexpr (K + 8 < 64) ScanK<K + 8>::dot(S, a, s);
; template <bool MIX> __device__ __forceinline__ void scan_pass1(const Params& p, int d, float* ldsf) {
;     ...
;             In1 i0, i1; LD1(i0, 0);
; #pragma unroll 1
;             for (int s = 0; s < LC; s += 2) { TOUCH1(i0); SB; LD1(i1, s + 1); SB; ST1(i0); TOUCH1(i1); SB; LD1(i0, s + 2); SB; ST1(i1); }
	s_nop 1
	v_mfma_f32_4x4x1_16b_f32 v[0:3], v64, v202, v[0:3]
	v_mfma_f32_4x4x1_16b_f32 v[4:7], v65, v202, v[4:7]
	v_mfma_f32_4x4x1_16b_f32 v[8:11], v66, v202, v[8:11]
	v_mfma_f32_4x4x1_16b_f32 v[12:15], v67, v202, v[12:15]
	v_mfma_f32_4x4x1_16b_f32 v[16:19], v68, v202, v[16:19]
	v_mfma_f32_4x4x1_16b_f32 v[20:23], v69, v202, v[20:23]
	v_mfma_f32_4x4x1_16b_f32 v[24:27], v70, v202, v[24:27]
	v_mfma_f32_4x4x1_16b_f32 v[28:31], v71, v202, v[28:31]
	v_mfma_f32_4x4x1_16b_f32 v[32:35], v72, v202, v[32:35]
	v_mfma_f32_4x4x1_16b_f32 v[36:39], v73, v202, v[36:39]
	v_mfma_f32_4x4x1_16b_f32 v[40:43], v74, v202, v[40:43]
	v_mfma_f32_4x4x1_16b_f32 v[44:47], v75, v202, v[44:47]
	v_mfma_f32_4x4x1_16b_f32 v[48:51], v76, v202, v[48:51]
	v_mfma_f32_4x4x1_16b_f32 v[52:55], v77, v202, v[52:55]
	v_mfma_f32_4x4x1_16b_f32 v[56:59], v78, v202, v[56:59]
	v_mfma_f32_4x4x1_16b_f32 v[60:63], v79, v202, v[60:63]
	s_waitcnt vmcnt(6)
	buffer_load_dwordx4 v[96:99], v232, s[64:67], s72 offen
	buffer_load_dwordx4 v[100:103], v233, s[64:67], s72 offen
	buffer_load_dwordx4 v[104:107], v234, s[64:67], s72 offen
	s_add_i32 s72, s72, 0xfffff000
	s_max_i32 s72, s72, 0
	v_pk_mul_f32 v[224:225], v[120:121], v[216:217]
	v_pk_mul_f32 v[226:227], v[122:123], v[218:219]
	v_pk_mul_f32 v[216:217], v[216:217], v[116:117]
	v_pk_mul_f32 v[218:219], v[218:219], v[118:119]
	v_pk_mul_f32 v[176:177], v[120:121], v[124:125]
	v_pk_mul_f32 v[178:179], v[122:123], v[126:127]
	v_rcp_f32_e32 v220, v216
	v_rcp_f32_e32 v221, v217
	v_rcp_f32_e32 v222, v218
	v_rcp_f32_e32 v223, v219
	s_nop 0
	v_pk_mul_f32 v[176:177], v[176:177], v[220:221]
	v_pk_mul_f32 v[178:179], v[178:179], v[222:223]
	ds_write2_b32 v208, v176, v177 offset0:0 offset1:16
	ds_write2_b32 v208, v178, v179 offset0:32 offset1:48
	ds_read_b128 v[64:67], v209 offset:0
	ds_read_b128 v[68:71], v209 offset:16
	ds_read_b128 v[72:75], v209 offset:32
	ds_read_b128 v[76:79], v209 offset:48
	v_mul_f32_dpp v196, v224, v0 row_newbcast:0 row_mask:0xf bank_mask:0xf
	v_mul_f32_dpp v197, v225, v1 row_newbcast:0 row_mask:0xf bank_mask:0xf
	v_mul_f32_dpp v198, v226, v2 row_newbcast:0 row_mask:0xf bank_mask:0xf
	v_mul_f32_dpp v199, v227, v3 row_newbcast:0 row_mask:0xf bank_mask:0xf
	v_fmac_f32_dpp v196, v224, v4 row_newbcast:1 row_mask:0xf bank_mask:0xf
	v_fmac_f32_dpp v197, v225, v5 row_newbcast:1 row_mask:0xf bank_mask:0xf
	v_fmac_f32_dpp v198, v226, v6 row_newbcast:1 row_mask:0xf bank_mask:0xf
	v_fmac_f32_dpp v199, v227, v7 row_newbcast:1 row_mask:0xf bank_mask:0xf
	v_fmac_f32_dpp v196, v224, v8 row_newbcast:2 row_mask:0xf bank_mask:0xf
	v_fmac_f32_dpp v197, v225, v9 row_newbcast:2 row_mask:0xf bank_mask:0xf
	v_fmac_f32_dpp v198, v226, v10 row_newbcast:2 row_mask:0xf bank_mask:0xf
	v_fmac_f32_dpp v199, v227, v11 row_newbcast:2 row_mask:0xf bank_mask:0xf
	v_fmac_f32_dpp v196, v224, v12 row_newbcast:3 row_mask:0xf bank_mask:0xf
	v_fmac_f32_dpp v197, v225, v13 row_newbcast:3 row_mask:0xf bank_mask:0xf
	v_fmac_f32_dpp v198, v226, v14 row_newbcast:3 row_mask:0xf bank_mask:0xf
	v_fmac_f32_dpp v199, v227, v15 row_newbcast:3 row_mask:0xf bank_mask:0xf
	v_fmac_f32_dpp v196, v224, v16 row_newbcast:4 row_mask:0xf bank_mask:0xf
	v_fmac_f32_dpp v197, v225, v17 row_newbcast:4 row_mask:0xf bank_mask:0xf
	v_fmac_f32_dpp v198, v226, v18 row_newbcast:4 row_mask:0xf bank_mask:0xf
	v_fmac_f32_dpp v199, v227, v19 row_newbcast:4 row_mask:0xf bank_mask:0xf
	v_fmac_f32_dpp v196, v224, v20 row_newbcast:5 row_mask:0xf bank_mask:0xf
	v_fmac_f32_dpp v197, v225, v21 row_newbcast:5 row_mask:0xf bank_mask:0xf
	v_fmac_f32_dpp v198, v226, v22 row_newbcast:5 row_mask:0xf bank_mask:0xf
	v_fmac_f32_dpp v199, v227, v23 row_newbcast:5 row_mask:0xf bank_mask:0xf
	v_fmac_f32_dpp v196, v224, v24 row_newbcast:6 row_mask:0xf bank_mask:0xf
	v_fmac_f32_dpp v197, v225, v25 row_newbcast:6 row_mask:0xf bank_mask:0xf
	v_fmac_f32_dpp v198, v226, v26 row_newbcast:6 row_mask:0xf bank_mask:0xf
	v_fmac_f32_dpp v199, v227, v27 row_newbcast:6 row_mask:0xf bank_mask:0xf
	v_fmac_f32_dpp v196, v224, v28 row_newbcast:7 row_mask:0xf bank_mask:0xf
	v_fmac_f32_dpp v197, v225, v29 row_newbcast:7 row_mask:0xf bank_mask:0xf
	v_fmac_f32_dpp v198, v226, v30 row_newbcast:7 row_mask:0xf bank_mask:0xf
	v_fmac_f32_dpp v199, v227, v31 row_newbcast:7 row_mask:0xf bank_mask:0xf
	v_fmac_f32_dpp v196, v224, v32 row_newbcast:8 row_mask:0xf bank_mask:0xf
	v_fmac_f32_dpp v197, v225, v33 row_newbcast:8 row_mask:0xf bank_mask:0xf
	v_fmac_f32_dpp v198, v226, v34 row_newbcast:8 row_mask:0xf bank_mask:0xf
	v_fmac_f32_dpp v199, v227, v35 row_newbcast:8 row_mask:0xf bank_mask:0xf
	v_fmac_f32_dpp v196, v224, v36 row_newbcast:9 row_mask:0xf bank_mask:0xf
	v_fmac_f32_dpp v197, v225, v37 row_newbcast:9 row_mask:0xf bank_mask:0xf
	v_fmac_f32_dpp v198, v226, v38 row_newbcast:9 row_mask:0xf bank_mask:0xf
	v_fmac_f32_dpp v199, v227, v39 row_newbcast:9 row_mask:0xf bank_mask:0xf
	v_fmac_f32_dpp v196, v224, v40 row_newbcast:10 row_mask:0xf bank_mask:0xf
	v_fmac_f32_dpp v197, v225, v41 row_newbcast:10 row_mask:0xf bank_mask:0xf
	v_fmac_f32_dpp v198, v226, v42 row_newbcast:10 row_mask:0xf bank_mask:0xf
	v_fmac_f32_dpp v199, v227, v43 row_newbcast:10 row_mask:0xf bank_mask:0xf
	v_fmac_f32_dpp v196, v224, v44 row_newbcast:11 row_mask:0xf bank_mask:0xf
	v_fmac_f32_dpp v197, v225, v45 row_newbcast:11 row_mask:0xf bank_mask:0xf
	v_fmac_f32_dpp v198, v226, v46 row_newbcast:11 row_mask:0xf bank_mask:0xf
	v_fmac_f32_dpp v199, v227, v47 row_newbcast:11 row_mask:0xf bank_mask:0xf
	v_fmac_f32_dpp v196, v224, v48 row_newbcast:12 row_mask:0xf bank_mask:0xf
	v_fmac_f32_dpp v197, v225, v49 row_newbcast:12 row_mask:0xf bank_mask:0xf
	v_fmac_f32_dpp v198, v226, v50 row_newbcast:12 row_mask:0xf bank_mask:0xf
	v_fmac_f32_dpp v199, v227, v51 row_newbcast:12 row_mask:0xf bank_mask:0xf
	v_fmac_f32_dpp v196, v224, v52 row_newbcast:13 row_mask:0xf bank_mask:0xf
	v_fmac_f32_dpp v197, v225, v53 row_newbcast:13 row_mask:0xf bank_mask:0xf
	v_fmac_f32_dpp v198, v226, v54 row_newbcast:13 row_mask:0xf bank_mask:0xf
	v_fmac_f32_dpp v199, v227, v55 row_newbcast:13 row_mask:0xf bank_mask:0xf
	v_fmac_f32_dpp v196, v224, v56 row_newbcast:14 row_mask:0xf bank_mask:0xf
	v_fmac_f32_dpp v197, v225, v57 row_newbcast:14 row_mask:0xf bank_mask:0xf
	v_fmac_f32_dpp v198, v226, v58 row_newbcast:14 row_mask:0xf bank_mask:0xf
	v_fmac_f32_dpp v199, v227, v59 row_newbcast:14 row_mask:0xf bank_mask:0xf
	v_fmac_f32_dpp v196, v224, v60 row_newbcast:15 row_mask:0xf bank_mask:0xf
	v_fmac_f32_dpp v197, v225, v61 row_newbcast:15 row_mask:0xf bank_mask:0xf
	v_fmac_f32_dpp v198, v226, v62 row_newbcast:15 row_mask:0xf bank_mask:0xf
	v_fmac_f32_dpp v199, v227, v63 row_newbcast:15 row_mask:0xf bank_mask:0xf
	v_add_f32_e32 v196, v196, v197
	v_add_f32_e32 v198, v198, v199
	v_sub_f32_e64 v202, -v196, v198
	s_waitcnt lgkmcnt(0)
; #define SB __builtin_amdgcn_sched_barrier(0)
; #define TOUCH1(set) asm volatile("" :: "v"(set.w), "v"(set.a), "v"(set.b), "v"(set.kw), "v"(set.v))
; #define ST1(set) { DERIVE_BK(set); float sd[4]; ScanK<0>::dot(S, set.a, sd); ScanK<0>::updS(S, set, -((sd[0] + sd[1]) + (sd[2] + sd[3])), __uint_as_float(set.v << 16)); }
; #define TOUCH1(set) asm volatile("" :: "v"(set.w), "v"(set.a), "v"(set.b))
;     static __device__ __forceinline__ void dot(const float (&S)[64], const f32x4& a, float (&s)[4]) {
;         if constexpr (K == 0) {
;             asm volatile("v_mul_f32_dpp %0, %4, %8 row_newbcast:%16" DPPM "v_mul_f32_dpp %1, %5, %9 row_newbcast:%16" DPPM "v_mul_f32_dpp %2, %6, %10 row_newbcast:%16" DPPM "v_mul_f32_dpp %3, %7, %11 row_newbcast:%16" DPPM
;                          "v_fmac_f32_dpp %0, %4, %12 row_newbcast:%17" DPPM "v_fmac_f32_dpp %1, %5, %13 row_newbcast:%17" DPPM "v_fmac_f32_dpp %2, %6, %14 row_newbcast:%17" DPPM "v_fmac_f32_dpp %3, %7, %15 row_newbcast:%17" DPPM
;                          : "=&v"(s[0]), "=&v"(s[1]), "=&v"(s[2]), "=&v"(s[3])
;                          : "v"(a[0]), "v"(a[1]), "v"(a[2]), "v"(a[3]), "v"(S[K]), "v"(S[K + 1]), "v"(S[K + 2]), "v"(S[K + 3]), "v"(S[K + 4]), "v"(S[K + 5]), "v"(S[K + 6]), "v"(S[K + 7]), "n"(N0), "n"(N1));
;         } else
;         asm volatile("v_fmac_f32_dpp %0, %4, %8 row_newbcast:%16" DPPM "v_fmac_f32_dpp %1, %5, %9 row_newbcast:%16" DPPM "v_fmac_f32_dpp %2, %6, %10 row_newbcast:%16" DPPM "v_fmac_f32_dpp %3, %7, %11 row_newbcast:%16" DPPM
;                      "v_fmac_f32_dpp %0, %4, %12 row_newbcast:%17" DPPM "v_fmac_f32_dpp %1, %5, %13 row_newbcast:%17" DPPM "v_fmac_f32_dpp %2, %6, %14 row_newbcast:%17" DPPM "v_fmac_f32_dpp %3, %7, %15 row_newbcast:%17" DPPM
;                      : "+v"(s[0]), "+v"(s[1]), "+v"(s[2]), "+v"(s[3])
;                      : "v"(a[0]), "v"(a[1]), "v"(a[2]), "v"(a[3]), "v"(S[K]), "v"(S[K + 1]), "v"(S[K + 2]), "v"(S[K + 3]), "v"(S[K + 4]), "v"(S[K + 5]), "v"(S[K + 6]), "v"(S[K + 7]), "n"(N0), "n"(N1));
;         if constexpr (K + 8 < 64) ScanK<K + 8>::dot(S, a, s);
; template <bool MIX> __device__ __forceinline__ void scan_pass1(const Params& p, int d, float* ldsf) {
;     ...
;             In1 i0, i1; LD1(i0, 0);
; #pragma unroll 1
;             for (int s = 0; s < LC; s += 2) { TOUCH1(i0); SB; LD1(i1, s + 1); SB; ST1(i0); TOUCH1(i1); SB; LD1(i0, s + 2); SB; ST1(i1); }
	s_nop 1
	v_mfma_f32_4x4x1_16b_f32 v[0:3], v64, v202, v[0:3]
	v_mfma_f32_4x4x1_16b_f32 v[4:7], v65, v202, v[4:7]
	v_mfma_f32_4x4x1_16b_f32 v[8:11], v66, v202, v[8:11]
	v_mfma_f32_4x4x1_16b_f32 v[12:15], v67, v202, v[12:15]
	v_mfma_f32_4x4x1_16b_f32 v[16:19], v68, v202, v[16:19]
	v_mfma_f32_4x4x1_16b_f32 v[20:23], v69, v202, v[20:23]
	v_mfma_f32_4x4x1_16b_f32 v[24:27], v70, v202, v[24:27]
	v_mfma_f32_4x4x1_16b_f32 v[28:31], v71, v202, v[28:31]
	v_mfma_f32_4x4x1_16b_f32 v[32:35], v72, v202, v[32:35]
	v_mfma_f32_4x4x1_16b_f32 v[36:39], v73, v202, v[36:39]
	v_mfma_f32_4x4x1_16b_f32 v[40:43], v74, v202, v[40:43]
	v_mfma_f32_4x4x1_16b_f32 v[44:47], v75, v202, v[44:47]
	v_mfma_f32_4x4x1_16b_f32 v[48:51], v76, v202, v[48:51]
	v_mfma_f32_4x4x1_16b_f32 v[52:55], v77, v202, v[52:55]
	v_mfma_f32_4x4x1_16b_f32 v[56:59], v78, v202, v[56:59]
	v_mfma_f32_4x4x1_16b_f32 v[60:63], v79, v202, v[60:63]
	s_waitcnt vmcnt(6)
	buffer_load_dwordx4 v[116:119], v232, s[64:67], s72 offen
	buffer_load_dwordx4 v[120:123], v233, s[64:67], s72 offen
	buffer_load_dwordx4 v[124:127], v234, s[64:67], s72 offen
	s_add_i32 s72, s72, 0xfffff000
	s_max_i32 s72, s72, 0
	v_pk_mul_f32 v[224:225], v[140:141], v[216:217]
	v_pk_mul_f32 v[226:227], v[142:143], v[218:219]
	v_pk_mul_f32 v[216:217], v[216:217], v[136:137]
	v_pk_mul_f32 v[218:219], v[218:219], v[138:139]
	v_pk_mul_f32 v[176:177], v[140:141], v[144:145]
	v_pk_mul_f32 v[178:179], v[142:143], v[146:147]
	v_rcp_f32_e32 v220, v216
	v_rcp_f32_e32 v221, v217
	v_rcp_f32_e32 v222, v218
	v_rcp_f32_e32 v223, v219
	s_nop 0
	v_pk_mul_f32 v[176:177], v[176:177], v[220:221]
	v_pk_mul_f32 v[178:179], v[178:179], v[222:223]
	ds_write2_b32 v208, v176, v177 offset0:0 offset1:16
	ds_write2_b32 v208, v178, v179 offset0:32 offset1:48
	ds_read_b128 v[64:67], v209 offset:0
	ds_read_b128 v[68:71], v209 offset:16
	ds_read_b128 v[72:75], v209 offset:32
	ds_read_b128 v[76:79], v209 offset:48
	v_mul_f32_dpp v196, v224, v0 row_newbcast:0 row_mask:0xf bank_mask:0xf
	v_mul_f32_dpp v197, v225, v1 row_newbcast:0 row_mask:0xf bank_mask:0xf
	v_mul_f32_dpp v198, v226, v2 row_newbcast:0 row_mask:0xf bank_mask:0xf
	v_mul_f32_dpp v199, v227, v3 row_newbcast:0 row_mask:0xf bank_mask:0xf
	v_fmac_f32_dpp v196, v224, v4 row_newbcast:1 row_mask:0xf bank_mask:0xf
	v_fmac_f32_dpp v197, v225, v5 row_newbcast:1 row_mask:0xf bank_mask:0xf
	v_fmac_f32_dpp v198, v226, v6 row_newbcast:1 row_mask:0xf bank_mask:0xf
	v_fmac_f32_dpp v199, v227, v7 row_newbcast:1 row_mask:0xf bank_mask:0xf
	v_fmac_f32_dpp v196, v224, v8 row_newbcast:2 row_mask:0xf bank_mask:0xf
	v_fmac_f32_dpp v197, v225, v9 row_newbcast:2 row_mask:0xf bank_mask:0xf
	v_fmac_f32_dpp v198, v226, v10 row_newbcast:2 row_mask:0xf bank_mask:0xf
	v_fmac_f32_dpp v199, v227, v11 row_newbcast:2 row_mask:0xf bank_mask:0xf
	v_fmac_f32_dpp v196, v224, v12 row_newbcast:3 row_mask:0xf bank_mask:0xf
	v_fmac_f32_dpp v197, v225, v13 row_newbcast:3 row_mask:0xf bank_mask:0xf
	v_fmac_f32_dpp v198, v226, v14 row_newbcast:3 row_mask:0xf bank_mask:0xf
	v_fmac_f32_dpp v199, v227, v15 row_newbcast:3 row_mask:0xf bank_mask:0xf
	v_fmac_f32_dpp v196, v224, v16 row_newbcast:4 row_mask:0xf bank_mask:0xf
	v_fmac_f32_dpp v197, v225, v17 row_newbcast:4 row_mask:0xf bank_mask:0xf
	v_fmac_f32_dpp v198, v226, v18 row_newbcast:4 row_mask:0xf bank_mask:0xf
	v_fmac_f32_dpp v199, v227, v19 row_newbcast:4 row_mask:0xf bank_mask:0xf
	v_fmac_f32_dpp v196, v224, v20 row_newbcast:5 row_mask:0xf bank_mask:0xf
	v_fmac_f32_dpp v197, v225, v21 row_newbcast:5 row_mask:0xf bank_mask:0xf
	v_fmac_f32_dpp v198, v226, v22 row_newbcast:5 row_mask:0xf bank_mask:0xf
	v_fmac_f32_dpp v199, v227, v23 row_newbcast:5 row_mask:0xf bank_mask:0xf
	v_fmac_f32_dpp v196, v224, v24 row_newbcast:6 row_mask:0xf bank_mask:0xf
	v_fmac_f32_dpp v197, v225, v25 row_newbcast:6 row_mask:0xf bank_mask:0xf
	v_fmac_f32_dpp v198, v226, v26 row_newbcast:6 row_mask:0xf bank_mask:0xf
	v_fmac_f32_dpp v199, v227, v27 row_newbcast:6 row_mask:0xf bank_mask:0xf
	v_fmac_f32_dpp v196, v224, v28 row_newbcast:7 row_mask:0xf bank_mask:0xf
	v_fmac_f32_dpp v197, v225, v29 row_newbcast:7 row_mask:0xf bank_mask:0xf
	v_fmac_f32_dpp v198, v226, v30 row_newbcast:7 row_mask:0xf bank_mask:0xf
	v_fmac_f32_dpp v199, v227, v31 row_newbcast:7 row_mask:0xf bank_mask:0xf
	v_fmac_f32_dpp v196, v224, v32 row_newbcast:8 row_mask:0xf bank_mask:0xf
	v_fmac_f32_dpp v197, v225, v33 row_newbcast:8 row_mask:0xf bank_mask:0xf
	v_fmac_f32_dpp v198, v226, v34 row_newbcast:8 row_mask:0xf bank_mask:0xf
	v_fmac_f32_dpp v199, v227, v35 row_newbcast:8 row_mask:0xf bank_mask:0xf
	v_fmac_f32_dpp v196, v224, v36 row_newbcast:9 row_mask:0xf bank_mask:0xf
	v_fmac_f32_dpp v197, v225, v37 row_newbcast:9 row_mask:0xf bank_mask:0xf
	v_fmac_f32_dpp v198, v226, v38 row_newbcast:9 row_mask:0xf bank_mask:0xf
	v_fmac_f32_dpp v199, v227, v39 row_newbcast:9 row_mask:0xf bank_mask:0xf
	v_fmac_f32_dpp v196, v224, v40 row_newbcast:10 row_mask:0xf bank_mask:0xf
	v_fmac_f32_dpp v197, v225, v41 row_newbcast:10 row_mask:0xf bank_mask:0xf
	v_fmac_f32_dpp v198, v226, v42 row_newbcast:10 row_mask:0xf bank_mask:0xf
	v_fmac_f32_dpp v199, v227, v43 row_newbcast:10 row_mask:0xf bank_mask:0xf
	v_fmac_f32_dpp v196, v224, v44 row_newbcast:11 row_mask:0xf bank_mask:0xf
	v_fmac_f32_dpp v197, v225, v45 row_newbcast:11 row_mask:0xf bank_mask:0xf
	v_fmac_f32_dpp v198, v226, v46 row_newbcast:11 row_mask:0xf bank_mask:0xf
	v_fmac_f32_dpp v199, v227, v47 row_newbcast:11 row_mask:0xf bank_mask:0xf
	v_fmac_f32_dpp v196, v224, v48 row_newbcast:12 row_mask:0xf bank_mask:0xf
	v_fmac_f32_dpp v197, v225, v49 row_newbcast:12 row_mask:0xf bank_mask:0xf
	v_fmac_f32_dpp v198, v226, v50 row_newbcast:12 row_mask:0xf bank_mask:0xf
	v_fmac_f32_dpp v199, v227, v51 row_newbcast:12 row_mask:0xf bank_mask:0xf
	v_fmac_f32_dpp v196, v224, v52 row_newbcast:13 row_mask:0xf bank_mask:0xf
	v_fmac_f32_dpp v197, v225, v53 row_newbcast:13 row_mask:0xf bank_mask:0xf
	v_fmac_f32_dpp v198, v226, v54 row_newbcast:13 row_mask:0xf bank_mask:0xf
	v_fmac_f32_dpp v199, v227, v55 row_newbcast:13 row_mask:0xf bank_mask:0xf
	v_fmac_f32_dpp v196, v224, v56 row_newbcast:14 row_mask:0xf bank_mask:0xf
	v_fmac_f32_dpp v197, v225, v57 row_newbcast:14 row_mask:0xf bank_mask:0xf
	v_fmac_f32_dpp v198, v226, v58 row_newbcast:14 row_mask:0xf bank_mask:0xf
	v_fmac_f32_dpp v199, v227, v59 row_newbcast:14 row_mask:0xf bank_mask:0xf
	v_fmac_f32_dpp v196, v224, v60 row_newbcast:15 row_mask:0xf bank_mask:0xf
	v_fmac_f32_dpp v197, v225, v61 row_newbcast:15 row_mask:0xf bank_mask:0xf
	v_fmac_f32_dpp v198, v226, v62 row_newbcast:15 row_mask:0xf bank_mask:0xf
	v_fmac_f32_dpp v199, v227, v63 row_newbcast:15 row_mask:0xf bank_mask:0xf
	v_add_f32_e32 v196, v196, v197
	v_add_f32_e32 v198, v198, v199
	v_sub_f32_e64 v202, -v196, v198
	s_waitcnt lgkmcnt(0)
; #define SB __builtin_amdgcn_sched_barrier(0)
; #define TOUCH1(set) asm volatile("" :: "v"(set.w), "v"(set.a), "v"(set.b), "v"(set.kw), "v"(set.v))
; #define ST1(set) { DERIVE_BK(set); float sd[4]; ScanK<0>::dot(S, set.a, sd); ScanK<0>::updS(S, set, -((sd[0] + sd[1]) + (sd[2] + sd[3])), __uint_as_float(set.v << 16)); }
; #define TOUCH1(set) asm volatile("" :: "v"(set.w), "v"(set.a), "v"(set.b))
;     static __device__ __forceinline__ void dot(const float (&S)[64], const f32x4& a, float (&s)[4]) {
;         if constexpr (K == 0) {
;             asm volatile("v_mul_f32_dpp %0, %4, %8 row_newbcast:%16" DPPM "v_mul_f32_dpp %1, %5, %9 row_newbcast:%16" DPPM "v_mul_f32_dpp %2, %6, %10 row_newbcast:%16" DPPM "v_mul_f32_dpp %3, %7, %11 row_newbcast:%16" DPPM
;                          "v_fmac_f32_dpp %0, %4, %12 row_newbcast:%17" DPPM "v_fmac_f32_dpp %1, %5, %13 row_newbcast:%17" DPPM "v_fmac_f32_dpp %2, %6, %14 row_newbcast:%17" DPPM "v_fmac_f32_dpp %3, %7, %15 row_newbcast:%17" DPPM
;                          : "=&v"(s[0]), "=&v"(s[1]), "=&v"(s[2]), "=&v"(s[3])
;                          : "v"(a[0]), "v"(a[1]), "v"(a[2]), "v"(a[3]), "v"(S[K]), "v"(S[K + 1]), "v"(S[K + 2]), "v"(S[K + 3]), "v"(S[K + 4]), "v"(S[K + 5]), "v"(S[K + 6]), "v"(S[K + 7]), "n"(N0), "n"(N1));
;         } else
;         asm volatile("v_fmac_f32_dpp %0, %4, %8 row_newbcast:%16" DPPM "v_fmac_f32_dpp %1, %5, %9 row_newbcast:%16" DPPM "v_fmac_f32_dpp %2, %6, %10 row_newbcast:%16" DPPM "v_fmac_f32_dpp %3, %7, %11 row_newbcast:%16" DPPM
;                      "v_fmac_f32_dpp %0, %4, %12 row_newbcast:%17" DPPM "v_fmac_f32_dpp %1, %5, %13 row_newbcast:%17" DPPM "v_fmac_f32_dpp %2, %6, %14 row_newbcast:%17" DPPM "v_fmac_f32_dpp %3, %7, %15 row_newbcast:%17" DPPM
;                      : "+v"(s[0]), "+v"(s[1]), "+v"(s[2]), "+v"(s[3])
;                      : "v"(a[0]), "v"(a[1]), "v"(a[2]), "v"(a[3]), "v"(S[K]), "v"(S[K + 1]), "v"(S[K + 2]), "v"(S[K + 3]), "v"(S[K + 4]), "v"(S[K + 5]), "v"(S[K + 6]), "v"(S[K + 7]), "n"(N0), "n"(N1));
;         if constexpr (K + 8 < 64) ScanK<K + 8>::dot(S, a, s);
; template <bool MIX> __device__ __forceinline__ void scan_pass1(const Params& p, int d, float* ldsf) {
;     ...
;             In1 i0, i1; LD1(i0, 0);
; #pragma unroll 1
;             for (int s = 0; s < LC; s += 2) { TOUCH1(i0); SB; LD1(i1, s + 1); SB; ST1(i0); TOUCH1(i1); SB; LD1(i0, s + 2); SB; ST1(i1); }
	s_nop 1
	v_mfma_f32_4x4x1_16b_f32 v[0:3], v64, v202, v[0:3]
	v_mfma_f32_4x4x1_16b_f32 v[4:7], v65, v202, v[4:7]
	v_mfma_f32_4x4x1_16b_f32 v[8:11], v66, v202, v[8:11]
	v_mfma_f32_4x4x1_16b_f32 v[12:15], v67, v202, v[12:15]
	v_mfma_f32_4x4x1_16b_f32 v[16:19], v68, v202, v[16:19]
	v_mfma_f32_4x4x1_16b_f32 v[20:23], v69, v202, v[20:23]
	v_mfma_f32_4x4x1_16b_f32 v[24:27], v70, v202, v[24:27]
	v_mfma_f32_4x4x1_16b_f32 v[28:31], v71, v202, v[28:31]
	v_mfma_f32_4x4x1_16b_f32 v[32:35], v72, v202, v[32:35]
	v_mfma_f32_4x4x1_16b_f32 v[36:39], v73, v202, v[36:39]
	v_mfma_f32_4x4x1_16b_f32 v[40:43], v74, v202, v[40:43]
	v_mfma_f32_4x4x1_16b_f32 v[44:47], v75, v202, v[44:47]
	v_mfma_f32_4x4x1_16b_f32 v[48:51], v76, v202, v[48:51]
	v_mfma_f32_4x4x1_16b_f32 v[52:55], v77, v202, v[52:55]
	v_mfma_f32_4x4x1_16b_f32 v[56:59], v78, v202, v[56:59]
	v_mfma_f32_4x4x1_16b_f32 v[60:63], v79, v202, v[60:63]
	s_waitcnt vmcnt(6)
	buffer_load_dwordx4 v[136:139], v232, s[64:67], s72 offen
	buffer_load_dwordx4 v[140:143], v233, s[64:67], s72 offen
	buffer_load_dwordx4 v[144:147], v234, s[64:67], s72 offen
	s_add_i32 s72, s72, 0xfffff000
	s_max_i32 s72, s72, 0
	v_pk_mul_f32 v[224:225], v[160:161], v[216:217]
	v_pk_mul_f32 v[226:227], v[162:163], v[218:219]
	v_pk_mul_f32 v[216:217], v[216:217], v[156:157]
	v_pk_mul_f32 v[218:219], v[218:219], v[158:159]
	v_pk_mul_f32 v[176:177], v[160:161], v[164:165]
	v_pk_mul_f32 v[178:179], v[162:163], v[166:167]
	v_rcp_f32_e32 v220, v216
	v_rcp_f32_e32 v221, v217
	v_rcp_f32_e32 v222, v218
	v_rcp_f32_e32 v223, v219
	s_nop 0
	v_pk_mul_f32 v[176:177], v[176:177], v[220:221]
	v_pk_mul_f32 v[178:179], v[178:179], v[222:223]
	ds_write2_b32 v208, v176, v177 offset0:0 offset1:16
	ds_write2_b32 v208, v178, v179 offset0:32 offset1:48
	ds_read_b128 v[64:67], v209 offset:0
	ds_read_b128 v[68:71], v209 offset:16
	ds_read_b128 v[72:75], v209 offset:32
	ds_read_b128 v[76:79], v209 offset:48
	v_mul_f32_dpp v196, v224, v0 row_newbcast:0 row_mask:0xf bank_mask:0xf
	v_mul_f32_dpp v197, v225, v1 row_newbcast:0 row_mask:0xf bank_mask:0xf
	v_mul_f32_dpp v198, v226, v2 row_newbcast:0 row_mask:0xf bank_mask:0xf
	v_mul_f32_dpp v199, v227, v3 row_newbcast:0 row_mask:0xf bank_mask:0xf
	v_fmac_f32_dpp v196, v224, v4 row_newbcast:1 row_mask:0xf bank_mask:0xf
	v_fmac_f32_dpp v197, v225, v5 row_newbcast:1 row_mask:0xf bank_mask:0xf
	v_fmac_f32_dpp v198, v226, v6 row_newbcast:1 row_mask:0xf bank_mask:0xf
	v_fmac_f32_dpp v199, v227, v7 row_newbcast:1 row_mask:0xf bank_mask:0xf
	v_fmac_f32_dpp v196, v224, v8 row_newbcast:2 row_mask:0xf bank_mask:0xf
	v_fmac_f32_dpp v197, v225, v9 row_newbcast:2 row_mask:0xf bank_mask:0xf
	v_fmac_f32_dpp v198, v226, v10 row_newbcast:2 row_mask:0xf bank_mask:0xf
	v_fmac_f32_dpp v199, v227, v11 row_newbcast:2 row_mask:0xf bank_mask:0xf
	v_fmac_f32_dpp v196, v224, v12 row_newbcast:3 row_mask:0xf bank_mask:0xf
	v_fmac_f32_dpp v197, v225, v13 row_newbcast:3 row_mask:0xf bank_mask:0xf
	v_fmac_f32_dpp v198, v226, v14 row_newbcast:3 row_mask:0xf bank_mask:0xf
	v_fmac_f32_dpp v199, v227, v15 row_newbcast:3 row_mask:0xf bank_mask:0xf
	v_fmac_f32_dpp v196, v224, v16 row_newbcast:4 row_mask:0xf bank_mask:0xf
	v_fmac_f32_dpp v197, v225, v17 row_newbcast:4 row_mask:0xf bank_mask:0xf
	v_fmac_f32_dpp v198, v226, v18 row_newbcast:4 row_mask:0xf bank_mask:0xf
	v_fmac_f32_dpp v199, v227, v19 row_newbcast:4 row_mask:0xf bank_mask:0xf
	v_fmac_f32_dpp v196, v224, v20 row_newbcast:5 row_mask:0xf bank_mask:0xf
	v_fmac_f32_dpp v197, v225, v21 row_newbcast:5 row_mask:0xf bank_mask:0xf
	v_fmac_f32_dpp v198, v226, v22 row_newbcast:5 row_mask:0xf bank_mask:0xf
	v_fmac_f32_dpp v199, v227, v23 row_newbcast:5 row_mask:0xf bank_mask:0xf
	v_fmac_f32_dpp v196, v224, v24 row_newbcast:6 row_mask:0xf bank_mask:0xf
	v_fmac_f32_dpp v197, v225, v25 row_newbcast:6 row_mask:0xf bank_mask:0xf
	v_fmac_f32_dpp v198, v226, v26 row_newbcast:6 row_mask:0xf bank_mask:0xf
	v_fmac_f32_dpp v199, v227, v27 row_newbcast:6 row_mask:0xf bank_mask:0xf
	v_fmac_f32_dpp v196, v224, v28 row_newbcast:7 row_mask:0xf bank_mask:0xf
	v_fmac_f32_dpp v197, v225, v29 row_newbcast:7 row_mask:0xf bank_mask:0xf
	v_fmac_f32_dpp v198, v226, v30 row_newbcast:7 row_mask:0xf bank_mask:0xf
	v_fmac_f32_dpp v199, v227, v31 row_newbcast:7 row_mask:0xf bank_mask:0xf
	v_fmac_f32_dpp v196, v224, v32 row_newbcast:8 row_mask:0xf bank_mask:0xf
	v_fmac_f32_dpp v197, v225, v33 row_newbcast:8 row_mask:0xf bank_mask:0xf
	v_fmac_f32_dpp v198, v226, v34 row_newbcast:8 row_mask:0xf bank_mask:0xf
	v_fmac_f32_dpp v199, v227, v35 row_newbcast:8 row_mask:0xf bank_mask:0xf
	v_fmac_f32_dpp v196, v224, v36 row_newbcast:9 row_mask:0xf bank_mask:0xf
	v_fmac_f32_dpp v197, v225, v37 row_newbcast:9 row_mask:0xf bank_mask:0xf
	v_fmac_f32_dpp v198, v226, v38 row_newbcast:9 row_mask:0xf bank_mask:0xf
	v_fmac_f32_dpp v199, v227, v39 row_newbcast:9 row_mask:0xf bank_mask:0xf
	v_fmac_f32_dpp v196, v224, v40 row_newbcast:10 row_mask:0xf bank_mask:0xf
	v_fmac_f32_dpp v197, v225, v41 row_newbcast:10 row_mask:0xf bank_mask:0xf
	v_fmac_f32_dpp v198, v226, v42 row_newbcast:10 row_mask:0xf bank_mask:0xf
	v_fmac_f32_dpp v199, v227, v43 row_newbcast:10 row_mask:0xf bank_mask:0xf
	v_fmac_f32_dpp v196, v224, v44 row_newbcast:11 row_mask:0xf bank_mask:0xf
	v_fmac_f32_dpp v197, v225, v45 row_newbcast:11 row_mask:0xf bank_mask:0xf
	v_fmac_f32_dpp v198, v226, v46 row_newbcast:11 row_mask:0xf bank_mask:0xf
	v_fmac_f32_dpp v199, v227, v47 row_newbcast:11 row_mask:0xf bank_mask:0xf
	v_fmac_f32_dpp v196, v224, v48 row_newbcast:12 row_mask:0xf bank_mask:0xf
	v_fmac_f32_dpp v197, v225, v49 row_newbcast:12 row_mask:0xf bank_mask:0xf
	v_fmac_f32_dpp v198, v226, v50 row_newbcast:12 row_mask:0xf bank_mask:0xf
	v_fmac_f32_dpp v199, v227, v51 row_newbcast:12 row_mask:0xf bank_mask:0xf
	v_fmac_f32_dpp v196, v224, v52 row_newbcast:13 row_mask:0xf bank_mask:0xf
	v_fmac_f32_dpp v197, v225, v53 row_newbcast:13 row_mask:0xf bank_mask:0xf
	v_fmac_f32_dpp v198, v226, v54 row_newbcast:13 row_mask:0xf bank_mask:0xf
	v_fmac_f32_dpp v199, v227, v55 row_newbcast:13 row_mask:0xf bank_mask:0xf
	v_fmac_f32_dpp v196, v224, v56 row_newbcast:14 row_mask:0xf bank_mask:0xf
	v_fmac_f32_dpp v197, v225, v57 row_newbcast:14 row_mask:0xf bank_mask:0xf
	v_fmac_f32_dpp v198, v226, v58 row_newbcast:14 row_mask:0xf bank_mask:0xf
	v_fmac_f32_dpp v199, v227, v59 row_newbcast:14 row_mask:0xf bank_mask:0xf
	v_fmac_f32_dpp v196, v224, v60 row_newbcast:15 row_mask:0xf bank_mask:0xf
	v_fmac_f32_dpp v197, v225, v61 row_newbcast:15 row_mask:0xf bank_mask:0xf
	v_fmac_f32_dpp v198, v226, v62 row_newbcast:15 row_mask:0xf bank_mask:0xf
	v_fmac_f32_dpp v199, v227, v63 row_newbcast:15 row_mask:0xf bank_mask:0xf
	v_add_f32_e32 v196, v196, v197
	v_add_f32_e32 v198, v198, v199
	v_sub_f32_e64 v202, -v196, v198
	s_waitcnt lgkmcnt(0)
; #define SB __builtin_amdgcn_sched_barrier(0)
; #define LD1(set, s) { const int e_ = min((int)(s), LC - 1) * (int)stp; const unsigned s4_ = ob4 + (unsigned)(e_ * 4), s2_ = ob2 + (unsigned)(e_ * 2); set.w = LDX(rW, s4_); set.a = LDX(rA, s4_); set.b = LDX(rB, s4_); \
;             set.kw = __builtin_amdgcn_raw_buffer_load_b64(rK, lo8, s2_, 0); set.v = __builtin_amdgcn_raw_buffer_load_b16(rV, lo2, s2_, 0); }
; #define TOUCH1(set) asm volatile("" :: "v"(set.w), "v"(set.a), "v"(set.b), "v"(set.kw), "v"(set.v))
; #define ST1(set) { DERIVE_BK(set); float sd[4]; ScanK<0>::dot(S, set.a, sd); ScanK<0>::updS(S, set, -((sd[0] + sd[1]) + (sd[2] + sd[3])), __uint_as_float(set.v << 16)); }
; #define LD1(set, s) { const int e_ = min((int)(s), LC - 1) * (int)stp; const unsigned s4_ = ob4 + (unsigned)(e_ * 4); set.w = LDX(rW, s4_); set.a = LDX(rA, s4_); set.b = LDX(rB, s4_); }
; #define TOUCH1(set) asm volatile("" :: "v"(set.w), "v"(set.a), "v"(set.b))
; #define ST1(set) { DERIVE_B(set); float sd[4]; ScanK<0>::dot(S, set.a, sd); ScanK<0>::updP(S, set, -((sd[0] + sd[1]) + (sd[2] + sd[3]))); }
;     static __device__ __forceinline__ void updP(float (&P)[64], const In1& in, float sa) {
;         float u0, u1, u2, u3;
;         asm volatile("v_mul_f32_dpp %0, %8, %4 row_newbcast:%17" DPPM "v_mul_f32_dpp %1, %9, %5 row_newbcast:%17" DPPM "v_mul_f32_dpp %2, %10, %6 row_newbcast:%17" DPPM "v_mul_f32_dpp %3, %11, %7 row_newbcast:%17" DPPM
;                      "v_fmac_f32_dpp %0, %12, %16 row_newbcast:%17" DPPM "v_fmac_f32_dpp %1, %13, %16 row_newbcast:%17" DPPM "v_fmac_f32_dpp %2, %14, %16 row_newbcast:%17" DPPM "v_fmac_f32_dpp %3, %15, %16 row_newbcast:%17" DPPM
;                      : "=&v"(u0), "=&v"(u1), "=&v"(u2), "=&v"(u3)
;                      : "v"(P[K]), "v"(P[K + 1]), "v"(P[K + 2]), "v"(P[K + 3]), "v"(in.w[0]), "v"(in.w[1]), "v"(in.w[2]), "v"(in.w[3]), "v"(in.b[0]), "v"(in.b[1]), "v"(in.b[2]), "v"(in.b[3]), "v"(sa), "n"(N0));
;         P[K] = u0; P[K + 1] = u1; P[K + 2] = u2; P[K + 3] = u3;
;         if constexpr (K + 4 < 64) ScanK<K + 4>::updP(P, in, sa);
;     }
; template <bool MIX> __device__ __forceinline__ void scan_pass1(const Params& p, int d, float* ldsf) {
;     ...
;             In1 i0, i1; LD1(i0, 0);
; #pragma unroll 1
;             for (int s = 0; s < LC; s += 2) { TOUCH1(i0); SB; LD1(i1, s + 1); SB; ST1(i0); TOUCH1(i1); SB; LD1(i0, s + 2); SB; ST1(i1); }
	s_nop 1
	v_mfma_f32_4x4x1_16b_f32 v[0:3], v64, v202, v[0:3]
	v_mfma_f32_4x4x1_16b_f32 v[4:7], v65, v202, v[4:7]
	v_mfma_f32_4x4x1_16b_f32 v[8:11], v66, v202, v[8:11]
	v_mfma_f32_4x4x1_16b_f32 v[12:15], v67, v202, v[12:15]
	v_mfma_f32_4x4x1_16b_f32 v[16:19], v68, v202, v[16:19]
	v_mfma_f32_4x4x1_16b_f32 v[20:23], v69, v202, v[20:23]
	v_mfma_f32_4x4x1_16b_f32 v[24:27], v70, v202, v[24:27]
	v_mfma_f32_4x4x1_16b_f32 v[28:31], v71, v202, v[28:31]
	v_mfma_f32_4x4x1_16b_f32 v[32:35], v72, v202, v[32:35]
	v_mfma_f32_4x4x1_16b_f32 v[36:39], v73, v202, v[36:39]
	v_mfma_f32_4x4x1_16b_f32 v[40:43], v74, v202, v[40:43]
	v_mfma_f32_4x4x1_16b_f32 v[44:47], v75, v202, v[44:47]
	v_mfma_f32_4x4x1_16b_f32 v[48:51], v76, v202, v[48:51]
	v_mfma_f32_4x4x1_16b_f32 v[52:55], v77, v202, v[52:55]
	v_mfma_f32_4x4x1_16b_f32 v[56:59], v78, v202, v[56:59]
	v_mfma_f32_4x4x1_16b_f32 v[60:63], v79, v202, v[60:63]
	s_sub_u32 s83, s83, 1
	s_cmp_eq_u32 s83, 0
	s_cbranch_scc1 .Lmy_p1d1_ldone_p
	s_and_b32 s9, s83, 7
	s_cmp_eq_u32 s9, 0
	s_cbranch_scc1 .Lmy_p1d1_renorm_p
	s_branch .Lmy_p1d1_loop_p

; #define MKR(ptr) __builtin_amdgcn_make_buffer_rsrc((void*)(ptr), 0, 0x7fffffff, 0x00027000)
; __device__ __forceinline__ void scan_pass2(const Params& p, int d) {
;     const int lane = threadIdx.x & 63, wid = __builtin_amdgcn_readfirstlane(threadIdx.x >> 6); const unsigned lo16 = (lane & 15) * 16, lo2 = lane * 2, lo4b = lane * 4;
;     const float* Wd = (const float*)(p.ws + O_KD); const float* Bd = (const float*)(p.ws + O_Y); const u16* KB = (const u16*)(p.ws + O_K); const float* A = (const float*)(p.ws + O_A); const float* R = (const float*)(p.ws + O_R); const unsigned lo8 = (lane & 15) * 8;
;     const u16* V = (const u16*)(p.ws + O_V); const float* SIT = (const float*)(p.ws + O_SIT); float* Y = p.out;
;     for (int item = blockIdx.x * 8 + wid; item < 32 * NC; item += gridDim.x * 8) {
;         const int bh = item / NC, c = item - bh * NC, b = bh >> 4, h = bh & 15;
;         const int t0 = d ? (SEQ - 1 - c * LC) : c * LC;
;         const size_t off0 = ((size_t)(b * SEQ + t0)) * RW + h * 64; const long stp = d ? -(long)RW : (long)RW;
;         const unsigned ob4 = (unsigned)(off0 * 4), ob2 = (unsigned)(off0 * 2);
;         const __amdgpu_buffer_rsrc_t rW = MKR(Wd), rA = MKR(A), rB = MKR(Bd), rK = MKR(KB), rV = MKR(V), rR = MKR(R), rY = MKR(Y);
;         const f32x4 ka4 = *(const f32x4*)(p.k_a + h * 64 + (lane & 15) * 4), c04 = 1.0f - ka4;
;         float S[64];
;         if (c == 0) {
; #pragma unroll
;             for (int i = 0; i < 64; ++i) S[i] = 0.f;
;         } else { const float* si = SIT + ((size_t)(bh * NC + c)) * 4096 + lane * 64;
; #pragma unroll
;             for (int i = 0; i < 16; ++i) { const f32x4 q = *(const f32x4*)(si + 4 * i); S[4 * i] = q[0]; S[4 * i + 1] = q[1]; S[4 * i + 2] = q[2]; S[4 * i + 3] = q[3]; } }
;     ...
;         In2 i0, i1; LD2(i0, 0);
.LBB0_953:
	s_cmp_lt_i32 s58, 11
	s_cselect_b64 s[0:1], -1, 0
	s_cmp_gt_i32 s59, 10
	s_cselect_b64 s[4:5], -1, 0
	s_and_b64 s[0:1], s[0:1], s[4:5]
	s_andn2_b64 vcc, exec, s[0:1]
	s_cbranch_vccnz .LBB0_1015
	v_readfirstlane_b32 s0, v254
	s_nop 3
	s_lshr_b32 s1, s0, 6
	s_lshl_b32 s0, s2, 3
	s_add_i32 s0, s1, s0
	s_mov_b32 s64, s56
	s_and_b32 s65, s57, 0xffff
	s_brev_b32 s66, -2
	s_mov_b32 s67, 0x27000
	s_mov_b32 s68, s54
	s_and_b32 s69, s55, 0xffff
	s_mov_b32 s70, s66
	s_mov_b32 s71, s67
	v_and_b32_e32 v212, 63, v254
	v_and_b32_e32 v213, 15, v254
	v_lshlrev_b32_e32 v204, 4, v213
	v_lshlrev_b32_e32 v205, 3, v213
	v_lshlrev_b32_e32 v206, 1, v212
	v_lshlrev_b32_e32 v207, 2, v212
	v_lshlrev_b32_e32 v210, 8, v212
	s_lshl_b32 s3, s1, 10
	s_add_u32 s3, s3, 0x10000
	v_lshl_add_u32 v208, v213, 2, s3
	v_and_b32_e32 v209, 3, v254
	v_lshl_add_u32 v209, v209, 6, s3
	v_add_u32_e32 v232, 0xb800000, v204
	v_add_u32_e32 v233, 0x24800000, v204
	v_add_u32_e32 v234, 0x35a00000, v204
	v_add_u32_e32 v235, 0x1c800000, v204
	v_add_u32_e32 v236, 0x30800000, v205
	v_add_u32_e32 v237, 0x2c800000, v206
.Lmy_p2d1_item:
	s_cmpk_gt_i32 s0, 0x7ff
	s_cbranch_scc1 .Lmy_p2d1_end
	s_lshr_b32 s86, s0, 6
	s_and_b32 s85, s0, 63
	s_and_b32 s87, s86, 15
	s_lshr_b32 s6, s86, 4
	s_lshl_b32 s6, s6, 14
	s_lshl_b32 s7, s85, 8
	s_sub_u32 s7, 0x3fff, s7
	s_add_u32 s6, s6, s7
	s_lshl_b32 s6, s6, 10
	s_lshl_b32 s7, s87, 6
	s_add_u32 s84, s6, s7
	s_lshl_b32 s6, s84, 2
	s_lshl_b32 s7, s84, 1
	s_mov_b32 s72, s6
	s_mov_b32 s76, s7
	s_mov_b32 s78, s6
	s_mov_b32 s79, s6
	s_lshl_b32 s8, s87, 8
	s_add_u32 s4, s42, s8
	s_addc_u32 s5, s43, 0
	global_load_dwordx4 v[188:191], v204, s[4:5]
	buffer_load_dwordx4 v[96:99], v232, s[64:67], s72 offen
	buffer_load_dwordx4 v[100:103], v233, s[64:67], s72 offen
	buffer_load_dwordx4 v[104:107], v234, s[64:67], s72 offen
	buffer_load_dwordx4 v[108:111], v235, s[64:67], s72 offen
	buffer_load_dwordx2 v[112:113], v236, s[64:67], s76 offen
	buffer_load_ushort v114, v237, s[64:67], s76 offen
	buffer_load_dword v115, v207, s[68:71], s78 offen
	s_add_i32 s72, s72, 0xfffff000
	s_max_i32 s72, s72, 0
	s_add_i32 s76, s76, 0xfffff800
	s_max_i32 s76, s76, 0
	s_add_i32 s78, s78, 0xfffff000
	s_max_i32 s78, s78, 0
	buffer_load_dwordx4 v[116:119], v232, s[64:67], s72 offen
	buffer_load_dwordx4 v[120:123], v233, s[64:67], s72 offen
	buffer_load_dwordx4 v[124:127], v234, s[64:67], s72 offen
	buffer_load_dwordx4 v[128:131], v235, s[64:67], s72 offen
	buffer_load_dwordx2 v[132:133], v236, s[64:67], s76 offen
	buffer_load_ushort v134, v237, s[64:67], s76 offen
	buffer_load_dword v135, v207, s[68:71], s78 offen
	s_add_i32 s72, s72, 0xfffff000
	s_max_i32 s72, s72, 0
	s_add_i32 s76, s76, 0xfffff800
	s_max_i32 s76, s76, 0
	s_add_i32 s78, s78, 0xfffff000
	s_max_i32 s78, s78, 0
	buffer_load_dwordx4 v[136:139], v232, s[64:67], s72 offen
	buffer_load_dwordx4 v[140:143], v233, s[64:67], s72 offen
	buffer_load_dwordx4 v[144:147], v234, s[64:67], s72 offen
	buffer_load_dwordx4 v[148:151], v235, s[64:67], s72 offen
	buffer_load_dwordx2 v[152:153], v236, s[64:67], s76 offen
	buffer_load_ushort v154, v237, s[64:67], s76 offen
	buffer_load_dword v155, v207, s[68:71], s78 offen
	s_add_i32 s72, s72, 0xfffff000
	s_max_i32 s72, s72, 0
	s_add_i32 s76, s76, 0xfffff800
	s_max_i32 s76, s76, 0
	s_add_i32 s78, s78, 0xfffff000
	s_max_i32 s78, s78, 0
	s_cmp_eq_u32 s85, 0
	s_cbranch_scc1 .Lmy_p2d1_zero
	s_lshl_b32 s8, s0, 14
	s_add_u32 s8, s8, 0x3da00000
	s_add_u32 s4, s56, s8
	s_addc_u32 s5, s57, 0
	global_load_dwordx4 v[0:3], v210, s[4:5] offset:0
	global_load_dwordx4 v[4:7], v210, s[4:5] offset:16
	global_load_dwordx4 v[8:11], v210, s[4:5] offset:32
	global_load_dwordx4 v[12:15], v210, s[4:5] offset:48
	global_load_dwordx4 v[16:19], v210, s[4:5] offset:64
	global_load_dwordx4 v[20:23], v210, s[4:5] offset:80
	global_load_dwordx4 v[24:27], v210, s[4:5] offset:96
	global_load_dwordx4 v[28:31], v210, s[4:5] offset:112
	global_load_dwordx4 v[32:35], v210, s[4:5] offset:128
	global_load_dwordx4 v[36:39], v210, s[4:5] offset:144
	global_load_dwordx4 v[40:43], v210, s[4:5] offset:160
	global_load_dwordx4 v[44:47], v210, s[4:5] offset:176
	global_load_dwordx4 v[48:51], v210, s[4:5] offset:192
	global_load_dwordx4 v[52:55], v210, s[4:5] offset:208
	global_load_dwordx4 v[56:59], v210, s[4:5] offset:224
	global_load_dwordx4 v[60:63], v210, s[4:5] offset:240
	s_branch .Lmy_p2d1_init_done

; #define SB __builtin_amdgcn_sched_barrier(0)
; #define ST2(set, s) { DERIVE_BK(set); float sd[4]; ScanK<0>::dot(S, set.a, sd); float y0 = set.yo, y1 = 0.f; ScanK<0>::upd(S, set, -((sd[0] + sd[1]) + (sd[2] + sd[3])), __uint_as_float(set.v << 16), y0, y1); __builtin_amdgcn_raw_buffer_store_b32(__float_as_uint(y0 + y1), rY, lo4b, ob4 + (unsigned)((int)(s) * (int)stp * 4), 0); }
;     static __device__ __forceinline__ void dot(const float (&S)[64], const f32x4& a, float (&s)[4]) {
;         if constexpr (K == 0) {
;             asm volatile("v_mul_f32_dpp %0, %4, %8 row_newbcast:%16" DPPM "v_mul_f32_dpp %1, %5, %9 row_newbcast:%16" DPPM "v_mul_f32_dpp %2, %6, %10 row_newbcast:%16" DPPM "v_mul_f32_dpp %3, %7, %11 row_newbcast:%16" DPPM
;                          "v_fmac_f32_dpp %0, %4, %12 row_newbcast:%17" DPPM "v_fmac_f32_dpp %1, %5, %13 row_newbcast:%17" DPPM "v_fmac_f32_dpp %2, %6, %14 row_newbcast:%17" DPPM "v_fmac_f32_dpp %3, %7, %15 row_newbcast:%17" DPPM
;                          : "=&v"(s[0]), "=&v"(s[1]), "=&v"(s[2]), "=&v"(s[3])
;                          : "v"(a[0]), "v"(a[1]), "v"(a[2]), "v"(a[3]), "v"(S[K]), "v"(S[K + 1]), "v"(S[K + 2]), "v"(S[K + 3]), "v"(S[K + 4]), "v"(S[K + 5]), "v"(S[K + 6]), "v"(S[K + 7]), "n"(N0), "n"(N1));
;         } else
;         asm volatile("v_fmac_f32_dpp %0, %4, %8 row_newbcast:%16" DPPM "v_fmac_f32_dpp %1, %5, %9 row_newbcast:%16" DPPM "v_fmac_f32_dpp %2, %6, %10 row_newbcast:%16" DPPM "v_fmac_f32_dpp %3, %7, %11 row_newbcast:%16" DPPM
;                      "v_fmac_f32_dpp %0, %4, %12 row_newbcast:%17" DPPM "v_fmac_f32_dpp %1, %5, %13 row_newbcast:%17" DPPM "v_fmac_f32_dpp %2, %6, %14 row_newbcast:%17" DPPM "v_fmac_f32_dpp %3, %7, %15 row_newbcast:%17" DPPM
;                      : "+v"(s[0]), "+v"(s[1]), "+v"(s[2]), "+v"(s[3])
;                      : "v"(a[0]), "v"(a[1]), "v"(a[2]), "v"(a[3]), "v"(S[K]), "v"(S[K + 1]), "v"(S[K + 2]), "v"(S[K + 3]), "v"(S[K + 4]), "v"(S[K + 5]), "v"(S[K + 6]), "v"(S[K + 7]), "n"(N0), "n"(N1));
;         if constexpr (K + 8 < 64) ScanK<K + 8>::dot(S, a, s);
; __device__ __forceinline__ void scan_pass2(const Params& p, int d) {
;     ...
;         In2 i0, i1; LD2(i0, 0);
; #pragma unroll 1
;         for (int s = 0; s < LC; s += 2) { TOUCH2(i0); SB; LD2(i1, s + 1); SB; ST2(i0, s); TOUCH2(i1); SB; LD2(i0, s + 2); SB; ST2(i1, s + 1); }
.Lmy_p2d1_loop:
	s_waitcnt vmcnt(14)
	s_cmp_eq_u32 s83, 64
	s_cbranch_scc1 .Lmy_p2d1_nost
	buffer_store_dword v200, v207, s[68:71], s79 offen
	s_add_u32 s79, s79, 0xfffff000
.Lmy_p2d1_nost:
	buffer_load_dwordx4 v[156:159], v232, s[64:67], s72 offen
	buffer_load_dwordx4 v[160:163], v233, s[64:67], s72 offen
	buffer_load_dwordx4 v[164:167], v234, s[64:67], s72 offen
	buffer_load_dwordx4 v[168:171], v235, s[64:67], s72 offen
	buffer_load_dwordx2 v[172:173], v236, s[64:67], s76 offen
	buffer_load_ushort v174, v237, s[64:67], s76 offen
	buffer_load_dword v175, v207, s[68:71], s78 offen
	s_add_i32 s72, s72, 0xfffff000
	s_max_i32 s72, s72, 0
	s_add_i32 s76, s76, 0xfffff800
	s_max_i32 s76, s76, 0
	s_add_i32 s78, s78, 0xfffff000
	s_max_i32 s78, s78, 0
	v_pk_mul_f32 v[224:225], v[100:101], v[216:217]
	v_pk_mul_f32 v[226:227], v[102:103], v[218:219]
	v_pk_mul_f32 v[216:217], v[216:217], v[96:97]
	v_pk_mul_f32 v[218:219], v[218:219], v[98:99]
	v_pk_fma_f32 v[184:185], v[104:105], v[188:189], v[192:193]
	v_pk_fma_f32 v[186:187], v[106:107], v[190:191], v[194:195]
	v_pk_mul_f32 v[176:177], v[100:101], v[104:105]
	v_pk_mul_f32 v[178:179], v[102:103], v[106:107]
	v_rcp_f32_e32 v220, v216
	v_rcp_f32_e32 v221, v217
	v_rcp_f32_e32 v222, v218
	v_rcp_f32_e32 v223, v219
	v_lshlrev_b32_e32 v180, 16, v112
	v_and_b32_e32 v181, 0xffff0000, v112
	v_lshlrev_b32_e32 v182, 16, v113
	v_and_b32_e32 v183, 0xffff0000, v113
	v_pk_mul_f32 v[180:181], v[180:181], v[184:185]
	v_pk_mul_f32 v[182:183], v[182:183], v[186:187]
	v_pk_mul_f32 v[228:229], v[108:109], v[216:217]
	v_pk_mul_f32 v[230:231], v[110:111], v[218:219]
	v_pk_mul_f32 v[176:177], v[176:177], v[220:221]
	v_pk_mul_f32 v[178:179], v[178:179], v[222:223]
	v_pk_mul_f32 v[180:181], v[180:181], v[220:221]
	v_pk_mul_f32 v[182:183], v[182:183], v[222:223]
	v_lshlrev_b32_e32 v203, 16, v114
	ds_write2_b32 v208, v176, v177 offset0:0 offset1:16
	ds_write2_b32 v208, v178, v179 offset0:32 offset1:48
	ds_write2_b32 v208, v180, v181 offset0:64 offset1:80
	ds_write2_b32 v208, v182, v183 offset0:96 offset1:112
	ds_read_b128 v[64:67], v209 offset:0
	ds_read_b128 v[68:71], v209 offset:16
	ds_read_b128 v[72:75], v209 offset:32
	ds_read_b128 v[76:79], v209 offset:48
	ds_read_b128 v[80:83], v209 offset:256
	ds_read_b128 v[84:87], v209 offset:272
	ds_read_b128 v[88:91], v209 offset:288
	ds_read_b128 v[92:95], v209 offset:304
	v_mul_f32_dpp v196, v224, v0 row_newbcast:0 row_mask:0xf bank_mask:0xf
	v_mul_f32_dpp v197, v225, v1 row_newbcast:0 row_mask:0xf bank_mask:0xf
	v_mul_f32_dpp v198, v226, v2 row_newbcast:0 row_mask:0xf bank_mask:0xf
	v_mul_f32_dpp v199, v227, v3 row_newbcast:0 row_mask:0xf bank_mask:0xf
	v_fmac_f32_dpp v196, v224, v4 row_newbcast:1 row_mask:0xf bank_mask:0xf
	v_fmac_f32_dpp v197, v225, v5 row_newbcast:1 row_mask:0xf bank_mask:0xf
	v_fmac_f32_dpp v198, v226, v6 row_newbcast:1 row_mask:0xf bank_mask:0xf
	v_fmac_f32_dpp v199, v227, v7 row_newbcast:1 row_mask:0xf bank_mask:0xf
	v_fmac_f32_dpp v196, v224, v8 row_newbcast:2 row_mask:0xf bank_mask:0xf
	v_fmac_f32_dpp v197, v225, v9 row_newbcast:2 row_mask:0xf bank_mask:0xf
	v_fmac_f32_dpp v198, v226, v10 row_newbcast:2 row_mask:0xf bank_mask:0xf
	v_fmac_f32_dpp v199, v227, v11 row_newbcast:2 row_mask:0xf bank_mask:0xf
	v_fmac_f32_dpp v196, v224, v12 row_newbcast:3 row_mask:0xf bank_mask:0xf
	v_fmac_f32_dpp v197, v225, v13 row_newbcast:3 row_mask:0xf bank_mask:0xf
	v_fmac_f32_dpp v198, v226, v14 row_newbcast:3 row_mask:0xf bank_mask:0xf
	v_fmac_f32_dpp v199, v227, v15 row_newbcast:3 row_mask:0xf bank_mask:0xf
	v_fmac_f32_dpp v196, v224, v16 row_newbcast:4 row_mask:0xf bank_mask:0xf
	v_fmac_f32_dpp v197, v225, v17 row_newbcast:4 row_mask:0xf bank_mask:0xf
	v_fmac_f32_dpp v198, v226, v18 row_newbcast:4 row_mask:0xf bank_mask:0xf
	v_fmac_f32_dpp v199, v227, v19 row_newbcast:4 row_mask:0xf bank_mask:0xf
	v_fmac_f32_dpp v196, v224, v20 row_newbcast:5 row_mask:0xf bank_mask:0xf
	v_fmac_f32_dpp v197, v225, v21 row_newbcast:5 row_mask:0xf bank_mask:0xf
	v_fmac_f32_dpp v198, v226, v22 row_newbcast:5 row_mask:0xf bank_mask:0xf
	v_fmac_f32_dpp v199, v227, v23 row_newbcast:5 row_mask:0xf bank_mask:0xf
	v_fmac_f32_dpp v196, v224, v24 row_newbcast:6 row_mask:0xf bank_mask:0xf
	v_fmac_f32_dpp v197, v225, v25 row_newbcast:6 row_mask:0xf bank_mask:0xf
	v_fmac_f32_dpp v198, v226, v26 row_newbcast:6 row_mask:0xf bank_mask:0xf
	v_fmac_f32_dpp v199, v227, v27 row_newbcast:6 row_mask:0xf bank_mask:0xf
	v_fmac_f32_dpp v196, v224, v28 row_newbcast:7 row_mask:0xf bank_mask:0xf
	v_fmac_f32_dpp v197, v225, v29 row_newbcast:7 row_mask:0xf bank_mask:0xf
	v_fmac_f32_dpp v198, v226, v30 row_newbcast:7 row_mask:0xf bank_mask:0xf
	v_fmac_f32_dpp v199, v227, v31 row_newbcast:7 row_mask:0xf bank_mask:0xf
	v_fmac_f32_dpp v196, v224, v32 row_newbcast:8 row_mask:0xf bank_mask:0xf
	v_fmac_f32_dpp v197, v225, v33 row_newbcast:8 row_mask:0xf bank_mask:0xf
	v_fmac_f32_dpp v198, v226, v34 row_newbcast:8 row_mask:0xf bank_mask:0xf
	v_fmac_f32_dpp v199, v227, v35 row_newbcast:8 row_mask:0xf bank_mask:0xf
	v_fmac_f32_dpp v196, v224, v36 row_newbcast:9 row_mask:0xf bank_mask:0xf
	v_fmac_f32_dpp v197, v225, v37 row_newbcast:9 row_mask:0xf bank_mask:0xf
	v_fmac_f32_dpp v198, v226, v38 row_newbcast:9 row_mask:0xf bank_mask:0xf
	v_fmac_f32_dpp v199, v227, v39 row_newbcast:9 row_mask:0xf bank_mask:0xf
	v_fmac_f32_dpp v196, v224, v40 row_newbcast:10 row_mask:0xf bank_mask:0xf
	v_fmac_f32_dpp v197, v225, v41 row_newbcast:10 row_mask:0xf bank_mask:0xf
	v_fmac_f32_dpp v198, v226, v42 row_newbcast:10 row_mask:0xf bank_mask:0xf
	v_fmac_f32_dpp v199, v227, v43 row_newbcast:10 row_mask:0xf bank_mask:0xf
;     static __device__ __forceinline__ void dot(const float (&S)[64], const f32x4& a, float (&s)[4]) {
;         if constexpr (K == 0) {
;             asm volatile("v_mul_f32_dpp %0, %4, %8 row_newbcast:%16" DPPM "v_mul_f32_dpp %1, %5, %9 row_newbcast:%16" DPPM "v_mul_f32_dpp %2, %6, %10 row_newbcast:%16" DPPM "v_mul_f32_dpp %3, %7, %11 row_newbcast:%16" DPPM
;                          "v_fmac_f32_dpp %0, %4, %12 row_newbcast:%17" DPPM "v_fmac_f32_dpp %1, %5, %13 row_newbcast:%17" DPPM "v_fmac_f32_dpp %2, %6, %14 row_newbcast:%17" DPPM "v_fmac_f32_dpp %3, %7, %15 row_newbcast:%17" DPPM
;                          : "=&v"(s[0]), "=&v"(s[1]), "=&v"(s[2]), "=&v"(s[3])
;                          : "v"(a[0]), "v"(a[1]), "v"(a[2]), "v"(a[3]), "v"(S[K]), "v"(S[K + 1]), "v"(S[K + 2]), "v"(S[K + 3]), "v"(S[K + 4]), "v"(S[K + 5]), "v"(S[K + 6]), "v"(S[K + 7]), "n"(N0), "n"(N1));
;         } else
;         asm volatile("v_fmac_f32_dpp %0, %4, %8 row_newbcast:%16" DPPM "v_fmac_f32_dpp %1, %5, %9 row_newbcast:%16" DPPM "v_fmac_f32_dpp %2, %6, %10 row_newbcast:%16" DPPM "v_fmac_f32_dpp %3, %7, %11 row_newbcast:%16" DPPM
;                      "v_fmac_f32_dpp %0, %4, %12 row_newbcast:%17" DPPM "v_fmac_f32_dpp %1, %5, %13 row_newbcast:%17" DPPM "v_fmac_f32_dpp %2, %6, %14 row_newbcast:%17" DPPM "v_fmac_f32_dpp %3, %7, %15 row_newbcast:%17" DPPM
;                      : "+v"(s[0]), "+v"(s[1]), "+v"(s[2]), "+v"(s[3])
;                      : "v"(a[0]), "v"(a[1]), "v"(a[2]), "v"(a[3]), "v"(S[K]), "v"(S[K + 1]), "v"(S[K + 2]), "v"(S[K + 3]), "v"(S[K + 4]), "v"(S[K + 5]), "v"(S[K + 6]), "v"(S[K + 7]), "n"(N0), "n"(N1));
;         if constexpr (K + 8 < 64) ScanK<K + 8>::dot(S, a, s);
;     }
;     static __device__ __forceinline__ void upd(float (&S)[64], const In2& in, float sa, float vv, float& y0, float& y1) {
;         float t0, t1, t2, t3;
;         asm volatile("v_mul_f32_dpp %0, %10, %27 row_newbcast:%28" DPPM "v_mul_f32_dpp %1, %11, %27 row_newbcast:%28" DPPM "v_mul_f32_dpp %2, %12, %27 row_newbcast:%28" DPPM "v_mul_f32_dpp %3, %13, %27 row_newbcast:%28" DPPM
;                      "v_fmac_f32_dpp %0, %14, %6 row_newbcast:%28" DPPM "v_fmac_f32_dpp %1, %15, %7 row_newbcast:%28" DPPM "v_fmac_f32_dpp %2, %16, %8 row_newbcast:%28" DPPM "v_fmac_f32_dpp %3, %17, %9 row_newbcast:%28" DPPM
	v_fmac_f32_dpp v196, v224, v44 row_newbcast:11 row_mask:0xf bank_mask:0xf
	v_fmac_f32_dpp v197, v225, v45 row_newbcast:11 row_mask:0xf bank_mask:0xf
	v_fmac_f32_dpp v198, v226, v46 row_newbcast:11 row_mask:0xf bank_mask:0xf
	v_fmac_f32_dpp v199, v227, v47 row_newbcast:11 row_mask:0xf bank_mask:0xf
	v_fmac_f32_dpp v196, v224, v48 row_newbcast:12 row_mask:0xf bank_mask:0xf
	v_fmac_f32_dpp v197, v225, v49 row_newbcast:12 row_mask:0xf bank_mask:0xf
	v_fmac_f32_dpp v198, v226, v50 row_newbcast:12 row_mask:0xf bank_mask:0xf
	v_fmac_f32_dpp v199, v227, v51 row_newbcast:12 row_mask:0xf bank_mask:0xf
	v_fmac_f32_dpp v196, v224, v52 row_newbcast:13 row_mask:0xf bank_mask:0xf
	v_fmac_f32_dpp v197, v225, v53 row_newbcast:13 row_mask:0xf bank_mask:0xf
	v_fmac_f32_dpp v198, v226, v54 row_newbcast:13 row_mask:0xf bank_mask:0xf
	v_fmac_f32_dpp v199, v227, v55 row_newbcast:13 row_mask:0xf bank_mask:0xf
	v_fmac_f32_dpp v196, v224, v56 row_newbcast:14 row_mask:0xf bank_mask:0xf
	v_fmac_f32_dpp v197, v225, v57 row_newbcast:14 row_mask:0xf bank_mask:0xf
	v_fmac_f32_dpp v198, v226, v58 row_newbcast:14 row_mask:0xf bank_mask:0xf
	v_fmac_f32_dpp v199, v227, v59 row_newbcast:14 row_mask:0xf bank_mask:0xf
	v_fmac_f32_dpp v196, v224, v60 row_newbcast:15 row_mask:0xf bank_mask:0xf
	v_fmac_f32_dpp v197, v225, v61 row_newbcast:15 row_mask:0xf bank_mask:0xf
	v_fmac_f32_dpp v198, v226, v62 row_newbcast:15 row_mask:0xf bank_mask:0xf
	v_fmac_f32_dpp v199, v227, v63 row_newbcast:15 row_mask:0xf bank_mask:0xf
	v_add_f32_e32 v196, v196, v197
	v_add_f32_e32 v198, v198, v199
	v_sub_f32_e64 v202, -v196, v198
	s_waitcnt lgkmcnt(0)
	s_nop 1
	v_mfma_f32_4x4x1_16b_f32 v[0:3], v64, v202, v[0:3]
	v_mfma_f32_4x4x1_16b_f32 v[4:7], v65, v202, v[4:7]
	v_mfma_f32_4x4x1_16b_f32 v[8:11], v66, v202, v[8:11]
	v_mfma_f32_4x4x1_16b_f32 v[12:15], v67, v202, v[12:15]
	v_mfma_f32_4x4x1_16b_f32 v[16:19], v68, v202, v[16:19]
	v_mfma_f32_4x4x1_16b_f32 v[20:23], v69, v202, v[20:23]
	v_mfma_f32_4x4x1_16b_f32 v[24:27], v70, v202, v[24:27]
	v_mfma_f32_4x4x1_16b_f32 v[28:31], v71, v202, v[28:31]
	v_mfma_f32_4x4x1_16b_f32 v[32:35], v72, v202, v[32:35]
	v_mfma_f32_4x4x1_16b_f32 v[36:39], v73, v202, v[36:39]
	v_mfma_f32_4x4x1_16b_f32 v[40:43], v74, v202, v[40:43]
	v_mfma_f32_4x4x1_16b_f32 v[44:47], v75, v202, v[44:47]
	v_mfma_f32_4x4x1_16b_f32 v[48:51], v76, v202, v[48:51]
	v_mfma_f32_4x4x1_16b_f32 v[52:55], v77, v202, v[52:55]
	v_mfma_f32_4x4x1_16b_f32 v[56:59], v78, v202, v[56:59]
	v_mfma_f32_4x4x1_16b_f32 v[60:63], v79, v202, v[60:63]
	v_mfma_f32_4x4x1_16b_f32 v[0:3], v80, v203, v[0:3]
	v_mfma_f32_4x4x1_16b_f32 v[4:7], v81, v203, v[4:7]
	v_mfma_f32_4x4x1_16b_f32 v[8:11], v82, v203, v[8:11]
	v_mfma_f32_4x4x1_16b_f32 v[12:15], v83, v203, v[12:15]
	v_mfma_f32_4x4x1_16b_f32 v[16:19], v84, v203, v[16:19]
	v_mfma_f32_4x4x1_16b_f32 v[20:23], v85, v203, v[20:23]
	v_mfma_f32_4x4x1_16b_f32 v[24:27], v86, v203, v[24:27]
	v_mfma_f32_4x4x1_16b_f32 v[28:31], v87, v203, v[28:31]
	v_mfma_f32_4x4x1_16b_f32 v[32:35], v88, v203, v[32:35]
	v_mfma_f32_4x4x1_16b_f32 v[36:39], v89, v203, v[36:39]
	v_mfma_f32_4x4x1_16b_f32 v[40:43], v90, v203, v[40:43]
	v_mfma_f32_4x4x1_16b_f32 v[44:47], v91, v203, v[44:47]
	v_mfma_f32_4x4x1_16b_f32 v[48:51], v92, v203, v[48:51]
	v_mfma_f32_4x4x1_16b_f32 v[52:55], v93, v203, v[52:55]
	v_mfma_f32_4x4x1_16b_f32 v[56:59], v94, v203, v[56:59]
	v_mfma_f32_4x4x1_16b_f32 v[60:63], v95, v203, v[60:63]
	v_fmac_f32_dpp v115, v228, v0 row_newbcast:0 row_mask:0xf bank_mask:0xf
	v_mul_f32_dpp v201, v229, v1 row_newbcast:0 row_mask:0xf bank_mask:0xf
	v_fmac_f32_dpp v115, v230, v2 row_newbcast:0 row_mask:0xf bank_mask:0xf
	v_fmac_f32_dpp v201, v231, v3 row_newbcast:0 row_mask:0xf bank_mask:0xf
	v_fmac_f32_dpp v115, v228, v4 row_newbcast:1 row_mask:0xf bank_mask:0xf
	v_fmac_f32_dpp v201, v229, v5 row_newbcast:1 row_mask:0xf bank_mask:0xf
	v_fmac_f32_dpp v115, v230, v6 row_newbcast:1 row_mask:0xf bank_mask:0xf
	v_fmac_f32_dpp v201, v231, v7 row_newbcast:1 row_mask:0xf bank_mask:0xf
	v_fmac_f32_dpp v115, v228, v8 row_newbcast:2 row_mask:0xf bank_mask:0xf
	v_fmac_f32_dpp v201, v229, v9 row_newbcast:2 row_mask:0xf bank_mask:0xf
	v_fmac_f32_dpp v115, v230, v10 row_newbcast:2 row_mask:0xf bank_mask:0xf
	v_fmac_f32_dpp v201, v231, v11 row_newbcast:2 row_mask:0xf bank_mask:0xf
	v_fmac_f32_dpp v115, v228, v12 row_newbcast:3 row_mask:0xf bank_mask:0xf
	v_fmac_f32_dpp v201, v229, v13 row_newbcast:3 row_mask:0xf bank_mask:0xf
	v_fmac_f32_dpp v115, v230, v14 row_newbcast:3 row_mask:0xf bank_mask:0xf
	v_fmac_f32_dpp v201, v231, v15 row_newbcast:3 row_mask:0xf bank_mask:0xf
	v_fmac_f32_dpp v115, v228, v16 row_newbcast:4 row_mask:0xf bank_mask:0xf
	v_fmac_f32_dpp v201, v229, v17 row_newbcast:4 row_mask:0xf bank_mask:0xf
	v_fmac_f32_dpp v115, v230, v18 row_newbcast:4 row_mask:0xf bank_mask:0xf
	v_fmac_f32_dpp v201, v231, v19 row_newbcast:4 row_mask:0xf bank_mask:0xf
	v_fmac_f32_dpp v115, v228, v20 row_newbcast:5 row_mask:0xf bank_mask:0xf
	v_fmac_f32_dpp v201, v229, v21 row_newbcast:5 row_mask:0xf bank_mask:0xf
	v_fmac_f32_dpp v115, v230, v22 row_newbcast:5 row_mask:0xf bank_mask:0xf
	v_fmac_f32_dpp v201, v231, v23 row_newbcast:5 row_mask:0xf bank_mask:0xf
	v_fmac_f32_dpp v115, v228, v24 row_newbcast:6 row_mask:0xf bank_mask:0xf
	v_fmac_f32_dpp v201, v229, v25 row_newbcast:6 row_mask:0xf bank_mask:0xf
	v_fmac_f32_dpp v115, v230, v26 row_newbcast:6 row_mask:0xf bank_mask:0xf
	v_fmac_f32_dpp v201, v231, v27 row_newbcast:6 row_mask:0xf bank_mask:0xf
	v_fmac_f32_dpp v115, v228, v28 row_newbcast:7 row_mask:0xf bank_mask:0xf
	v_fmac_f32_dpp v201, v229, v29 row_newbcast:7 row_mask:0xf bank_mask:0xf
; #define SB __builtin_amdgcn_sched_barrier(0)
; #define ST2(set, s) { DERIVE_BK(set); float sd[4]; ScanK<0>::dot(S, set.a, sd); float y0 = set.yo, y1 = 0.f; ScanK<0>::upd(S, set, -((sd[0] + sd[1]) + (sd[2] + sd[3])), __uint_as_float(set.v << 16), y0, y1); __builtin_amdgcn_raw_buffer_store_b32(__float_as_uint(y0 + y1), rY, lo4b, ob4 + (unsigned)((int)(s) * (int)stp * 4), 0); }
; #define TOUCH2(set) asm volatile("" :: "v"(set.w), "v"(set.a), "v"(set.b), "v"(set.kw), "v"(set.r), "v"(set.v), "v"(set.yo))
; __device__ __forceinline__ void scan_pass2(const Params& p, int d) {
;     ...
;         In2 i0, i1; LD2(i0, 0);
; #pragma unroll 1
;         for (int s = 0; s < LC; s += 2) { TOUCH2(i0); SB; LD2(i1, s + 1); SB; ST2(i0, s); TOUCH2(i1); SB; LD2(i0, s + 2); SB; ST2(i1, s + 1); }
	v_fmac_f32_dpp v115, v230, v30 row_newbcast:7 row_mask:0xf bank_mask:0xf
	v_fmac_f32_dpp v201, v231, v31 row_newbcast:7 row_mask:0xf bank_mask:0xf
	v_fmac_f32_dpp v115, v228, v32 row_newbcast:8 row_mask:0xf bank_mask:0xf
	v_fmac_f32_dpp v201, v229, v33 row_newbcast:8 row_mask:0xf bank_mask:0xf
	v_fmac_f32_dpp v115, v230, v34 row_newbcast:8 row_mask:0xf bank_mask:0xf
	v_fmac_f32_dpp v201, v231, v35 row_newbcast:8 row_mask:0xf bank_mask:0xf
	v_fmac_f32_dpp v115, v228, v36 row_newbcast:9 row_mask:0xf bank_mask:0xf
	v_fmac_f32_dpp v201, v229, v37 row_newbcast:9 row_mask:0xf bank_mask:0xf
	v_fmac_f32_dpp v115, v230, v38 row_newbcast:9 row_mask:0xf bank_mask:0xf
	v_fmac_f32_dpp v201, v231, v39 row_newbcast:9 row_mask:0xf bank_mask:0xf
	v_fmac_f32_dpp v115, v228, v40 row_newbcast:10 row_mask:0xf bank_mask:0xf
	v_fmac_f32_dpp v201, v229, v41 row_newbcast:10 row_mask:0xf bank_mask:0xf
	v_fmac_f32_dpp v115, v230, v42 row_newbcast:10 row_mask:0xf bank_mask:0xf
	v_fmac_f32_dpp v201, v231, v43 row_newbcast:10 row_mask:0xf bank_mask:0xf
	v_fmac_f32_dpp v115, v228, v44 row_newbcast:11 row_mask:0xf bank_mask:0xf
	v_fmac_f32_dpp v201, v229, v45 row_newbcast:11 row_mask:0xf bank_mask:0xf
	v_fmac_f32_dpp v115, v230, v46 row_newbcast:11 row_mask:0xf bank_mask:0xf
	v_fmac_f32_dpp v201, v231, v47 row_newbcast:11 row_mask:0xf bank_mask:0xf
	v_fmac_f32_dpp v115, v228, v48 row_newbcast:12 row_mask:0xf bank_mask:0xf
	v_fmac_f32_dpp v201, v229, v49 row_newbcast:12 row_mask:0xf bank_mask:0xf
	v_fmac_f32_dpp v115, v230, v50 row_newbcast:12 row_mask:0xf bank_mask:0xf
	v_fmac_f32_dpp v201, v231, v51 row_newbcast:12 row_mask:0xf bank_mask:0xf
	v_fmac_f32_dpp v115, v228, v52 row_newbcast:13 row_mask:0xf bank_mask:0xf
	v_fmac_f32_dpp v201, v229, v53 row_newbcast:13 row_mask:0xf bank_mask:0xf
	v_fmac_f32_dpp v115, v230, v54 row_newbcast:13 row_mask:0xf bank_mask:0xf
	v_fmac_f32_dpp v201, v231, v55 row_newbcast:13 row_mask:0xf bank_mask:0xf
	v_fmac_f32_dpp v115, v228, v56 row_newbcast:14 row_mask:0xf bank_mask:0xf
	v_fmac_f32_dpp v201, v229, v57 row_newbcast:14 row_mask:0xf bank_mask:0xf
	v_fmac_f32_dpp v115, v230, v58 row_newbcast:14 row_mask:0xf bank_mask:0xf
	v_fmac_f32_dpp v201, v231, v59 row_newbcast:14 row_mask:0xf bank_mask:0xf
	v_fmac_f32_dpp v115, v228, v60 row_newbcast:15 row_mask:0xf bank_mask:0xf
	v_fmac_f32_dpp v201, v229, v61 row_newbcast:15 row_mask:0xf bank_mask:0xf
	v_fmac_f32_dpp v115, v230, v62 row_newbcast:15 row_mask:0xf bank_mask:0xf
	v_fmac_f32_dpp v201, v231, v63 row_newbcast:15 row_mask:0xf bank_mask:0xf
	v_add_f32_e32 v200, v115, v201
	s_waitcnt vmcnt(14)
	buffer_store_dword v200, v207, s[68:71], s79 offen
	s_add_u32 s79, s79, 0xfffff000
	buffer_load_dwordx4 v[96:99], v232, s[64:67], s72 offen
	buffer_load_dwordx4 v[100:103], v233, s[64:67], s72 offen
	buffer_load_dwordx4 v[104:107], v234, s[64:67], s72 offen
	buffer_load_dwordx4 v[108:111], v235, s[64:67], s72 offen
	buffer_load_dwordx2 v[112:113], v236, s[64:67], s76 offen
	buffer_load_ushort v114, v237, s[64:67], s76 offen
	buffer_load_dword v115, v207, s[68:71], s78 offen
	s_add_i32 s72, s72, 0xfffff000
	s_max_i32 s72, s72, 0
	s_add_i32 s76, s76, 0xfffff800
	s_max_i32 s76, s76, 0
	s_add_i32 s78, s78, 0xfffff000
	s_max_i32 s78, s78, 0
	v_pk_mul_f32 v[224:225], v[120:121], v[216:217]
	v_pk_mul_f32 v[226:227], v[122:123], v[218:219]
	v_pk_mul_f32 v[216:217], v[216:217], v[116:117]
	v_pk_mul_f32 v[218:219], v[218:219], v[118:119]
	v_pk_fma_f32 v[184:185], v[124:125], v[188:189], v[192:193]
	v_pk_fma_f32 v[186:187], v[126:127], v[190:191], v[194:195]
	v_pk_mul_f32 v[176:177], v[120:121], v[124:125]
	v_pk_mul_f32 v[178:179], v[122:123], v[126:127]
	v_rcp_f32_e32 v220, v216
	v_rcp_f32_e32 v221, v217
	v_rcp_f32_e32 v222, v218
	v_rcp_f32_e32 v223, v219
	v_lshlrev_b32_e32 v180, 16, v132
	v_and_b32_e32 v181, 0xffff0000, v132
	v_lshlrev_b32_e32 v182, 16, v133
	v_and_b32_e32 v183, 0xffff0000, v133
	v_pk_mul_f32 v[180:181], v[180:181], v[184:185]
	v_pk_mul_f32 v[182:183], v[182:183], v[186:187]
	v_pk_mul_f32 v[228:229], v[128:129], v[216:217]
	v_pk_mul_f32 v[230:231], v[130:131], v[218:219]
	v_pk_mul_f32 v[176:177], v[176:177], v[220:221]
	v_pk_mul_f32 v[178:179], v[178:179], v[222:223]
	v_pk_mul_f32 v[180:181], v[180:181], v[220:221]
	v_pk_mul_f32 v[182:183], v[182:183], v[222:223]
	v_lshlrev_b32_e32 v203, 16, v134
	ds_write2_b32 v208, v176, v177 offset0:0 offset1:16
	ds_write2_b32 v208, v178, v179 offset0:32 offset1:48
	ds_write2_b32 v208, v180, v181 offset0:64 offset1:80
	ds_write2_b32 v208, v182, v183 offset0:96 offset1:112
	ds_read_b128 v[64:67], v209 offset:0
	ds_read_b128 v[68:71], v209 offset:16
	ds_read_b128 v[72:75], v209 offset:32
	ds_read_b128 v[76:79], v209 offset:48
	ds_read_b128 v[80:83], v209 offset:256
	ds_read_b128 v[84:87], v209 offset:272
	ds_read_b128 v[88:91], v209 offset:288
	ds_read_b128 v[92:95], v209 offset:304
	v_mul_f32_dpp v196, v224, v0 row_newbcast:0 row_mask:0xf bank_mask:0xf
	v_mul_f32_dpp v197, v225, v1 row_newbcast:0 row_mask:0xf bank_mask:0xf
	v_mul_f32_dpp v198, v226, v2 row_newbcast:0 row_mask:0xf bank_mask:0xf
	v_mul_f32_dpp v199, v227, v3 row_newbcast:0 row_mask:0xf bank_mask:0xf
	v_fmac_f32_dpp v196, v224, v4 row_newbcast:1 row_mask:0xf bank_mask:0xf
	v_fmac_f32_dpp v197, v225, v5 row_newbcast:1 row_mask:0xf bank_mask:0xf
	v_fmac_f32_dpp v198, v226, v6 row_newbcast:1 row_mask:0xf bank_mask:0xf
	v_fmac_f32_dpp v199, v227, v7 row_newbcast:1 row_mask:0xf bank_mask:0xf
	v_fmac_f32_dpp v196, v224, v8 row_newbcast:2 row_mask:0xf bank_mask:0xf
	v_fmac_f32_dpp v197, v225, v9 row_newbcast:2 row_mask:0xf bank_mask:0xf
	v_fmac_f32_dpp v198, v226, v10 row_newbcast:2 row_mask:0xf bank_mask:0xf
;     static __device__ __forceinline__ void dot(const float (&S)[64], const f32x4& a, float (&s)[4]) {
;         if constexpr (K == 0) {
;             asm volatile("v_mul_f32_dpp %0, %4, %8 row_newbcast:%16" DPPM "v_mul_f32_dpp %1, %5, %9 row_newbcast:%16" DPPM "v_mul_f32_dpp %2, %6, %10 row_newbcast:%16" DPPM "v_mul_f32_dpp %3, %7, %11 row_newbcast:%16" DPPM
;                          "v_fmac_f32_dpp %0, %4, %12 row_newbcast:%17" DPPM "v_fmac_f32_dpp %1, %5, %13 row_newbcast:%17" DPPM "v_fmac_f32_dpp %2, %6, %14 row_newbcast:%17" DPPM "v_fmac_f32_dpp %3, %7, %15 row_newbcast:%17" DPPM
;                          : "=&v"(s[0]), "=&v"(s[1]), "=&v"(s[2]), "=&v"(s[3])
;                          : "v"(a[0]), "v"(a[1]), "v"(a[2]), "v"(a[3]), "v"(S[K]), "v"(S[K + 1]), "v"(S[K + 2]), "v"(S[K + 3]), "v"(S[K + 4]), "v"(S[K + 5]), "v"(S[K + 6]), "v"(S[K + 7]), "n"(N0), "n"(N1));
;         } else
;         asm volatile("v_fmac_f32_dpp %0, %4, %8 row_newbcast:%16" DPPM "v_fmac_f32_dpp %1, %5, %9 row_newbcast:%16" DPPM "v_fmac_f32_dpp %2, %6, %10 row_newbcast:%16" DPPM "v_fmac_f32_dpp %3, %7, %11 row_newbcast:%16" DPPM
;                      "v_fmac_f32_dpp %0, %4, %12 row_newbcast:%17" DPPM "v_fmac_f32_dpp %1, %5, %13 row_newbcast:%17" DPPM "v_fmac_f32_dpp %2, %6, %14 row_newbcast:%17" DPPM "v_fmac_f32_dpp %3, %7, %15 row_newbcast:%17" DPPM
;                      : "+v"(s[0]), "+v"(s[1]), "+v"(s[2]), "+v"(s[3])
;                      : "v"(a[0]), "v"(a[1]), "v"(a[2]), "v"(a[3]), "v"(S[K]), "v"(S[K + 1]), "v"(S[K + 2]), "v"(S[K + 3]), "v"(S[K + 4]), "v"(S[K + 5]), "v"(S[K + 6]), "v"(S[K + 7]), "n"(N0), "n"(N1));
;         if constexpr (K + 8 < 64) ScanK<K + 8>::dot(S, a, s);
;     }
;     static __device__ __forceinline__ void upd(float (&S)[64], const In2& in, float sa, float vv, float& y0, float& y1) {
;         float t0, t1, t2, t3;
;         asm volatile("v_mul_f32_dpp %0, %10, %27 row_newbcast:%28" DPPM "v_mul_f32_dpp %1, %11, %27 row_newbcast:%28" DPPM "v_mul_f32_dpp %2, %12, %27 row_newbcast:%28" DPPM "v_mul_f32_dpp %3, %13, %27 row_newbcast:%28" DPPM
;                      "v_fmac_f32_dpp %0, %14, %6 row_newbcast:%28" DPPM "v_fmac_f32_dpp %1, %15, %7 row_newbcast:%28" DPPM "v_fmac_f32_dpp %2, %16, %8 row_newbcast:%28" DPPM "v_fmac_f32_dpp %3, %17, %9 row_newbcast:%28" DPPM
	v_fmac_f32_dpp v199, v227, v11 row_newbcast:2 row_mask:0xf bank_mask:0xf
	v_fmac_f32_dpp v196, v224, v12 row_newbcast:3 row_mask:0xf bank_mask:0xf
	v_fmac_f32_dpp v197, v225, v13 row_newbcast:3 row_mask:0xf bank_mask:0xf
	v_fmac_f32_dpp v198, v226, v14 row_newbcast:3 row_mask:0xf bank_mask:0xf
	v_fmac_f32_dpp v199, v227, v15 row_newbcast:3 row_mask:0xf bank_mask:0xf
	v_fmac_f32_dpp v196, v224, v16 row_newbcast:4 row_mask:0xf bank_mask:0xf
	v_fmac_f32_dpp v197, v225, v17 row_newbcast:4 row_mask:0xf bank_mask:0xf
	v_fmac_f32_dpp v198, v226, v18 row_newbcast:4 row_mask:0xf bank_mask:0xf
	v_fmac_f32_dpp v199, v227, v19 row_newbcast:4 row_mask:0xf bank_mask:0xf
	v_fmac_f32_dpp v196, v224, v20 row_newbcast:5 row_mask:0xf bank_mask:0xf
	v_fmac_f32_dpp v197, v225, v21 row_newbcast:5 row_mask:0xf bank_mask:0xf
	v_fmac_f32_dpp v198, v226, v22 row_newbcast:5 row_mask:0xf bank_mask:0xf
	v_fmac_f32_dpp v199, v227, v23 row_newbcast:5 row_mask:0xf bank_mask:0xf
	v_fmac_f32_dpp v196, v224, v24 row_newbcast:6 row_mask:0xf bank_mask:0xf
	v_fmac_f32_dpp v197, v225, v25 row_newbcast:6 row_mask:0xf bank_mask:0xf
	v_fmac_f32_dpp v198, v226, v26 row_newbcast:6 row_mask:0xf bank_mask:0xf
	v_fmac_f32_dpp v199, v227, v27 row_newbcast:6 row_mask:0xf bank_mask:0xf
	v_fmac_f32_dpp v196, v224, v28 row_newbcast:7 row_mask:0xf bank_mask:0xf
	v_fmac_f32_dpp v197, v225, v29 row_newbcast:7 row_mask:0xf bank_mask:0xf
	v_fmac_f32_dpp v198, v226, v30 row_newbcast:7 row_mask:0xf bank_mask:0xf
	v_fmac_f32_dpp v199, v227, v31 row_newbcast:7 row_mask:0xf bank_mask:0xf
	v_fmac_f32_dpp v196, v224, v32 row_newbcast:8 row_mask:0xf bank_mask:0xf
	v_fmac_f32_dpp v197, v225, v33 row_newbcast:8 row_mask:0xf bank_mask:0xf
	v_fmac_f32_dpp v198, v226, v34 row_newbcast:8 row_mask:0xf bank_mask:0xf
	v_fmac_f32_dpp v199, v227, v35 row_newbcast:8 row_mask:0xf bank_mask:0xf
	v_fmac_f32_dpp v196, v224, v36 row_newbcast:9 row_mask:0xf bank_mask:0xf
	v_fmac_f32_dpp v197, v225, v37 row_newbcast:9 row_mask:0xf bank_mask:0xf
	v_fmac_f32_dpp v198, v226, v38 row_newbcast:9 row_mask:0xf bank_mask:0xf
	v_fmac_f32_dpp v199, v227, v39 row_newbcast:9 row_mask:0xf bank_mask:0xf
	v_fmac_f32_dpp v196, v224, v40 row_newbcast:10 row_mask:0xf bank_mask:0xf
	v_fmac_f32_dpp v197, v225, v41 row_newbcast:10 row_mask:0xf bank_mask:0xf
	v_fmac_f32_dpp v198, v226, v42 row_newbcast:10 row_mask:0xf bank_mask:0xf
	v_fmac_f32_dpp v199, v227, v43 row_newbcast:10 row_mask:0xf bank_mask:0xf
	v_fmac_f32_dpp v196, v224, v44 row_newbcast:11 row_mask:0xf bank_mask:0xf
	v_fmac_f32_dpp v197, v225, v45 row_newbcast:11 row_mask:0xf bank_mask:0xf
	v_fmac_f32_dpp v198, v226, v46 row_newbcast:11 row_mask:0xf bank_mask:0xf
	v_fmac_f32_dpp v199, v227, v47 row_newbcast:11 row_mask:0xf bank_mask:0xf
	v_fmac_f32_dpp v196, v224, v48 row_newbcast:12 row_mask:0xf bank_mask:0xf
	v_fmac_f32_dpp v197, v225, v49 row_newbcast:12 row_mask:0xf bank_mask:0xf
	v_fmac_f32_dpp v198, v226, v50 row_newbcast:12 row_mask:0xf bank_mask:0xf
	v_fmac_f32_dpp v199, v227, v51 row_newbcast:12 row_mask:0xf bank_mask:0xf
	v_fmac_f32_dpp v196, v224, v52 row_newbcast:13 row_mask:0xf bank_mask:0xf
	v_fmac_f32_dpp v197, v225, v53 row_newbcast:13 row_mask:0xf bank_mask:0xf
	v_fmac_f32_dpp v198, v226, v54 row_newbcast:13 row_mask:0xf bank_mask:0xf
	v_fmac_f32_dpp v199, v227, v55 row_newbcast:13 row_mask:0xf bank_mask:0xf
	v_fmac_f32_dpp v196, v224, v56 row_newbcast:14 row_mask:0xf bank_mask:0xf
	v_fmac_f32_dpp v197, v225, v57 row_newbcast:14 row_mask:0xf bank_mask:0xf
	v_fmac_f32_dpp v198, v226, v58 row_newbcast:14 row_mask:0xf bank_mask:0xf
	v_fmac_f32_dpp v199, v227, v59 row_newbcast:14 row_mask:0xf bank_mask:0xf
	v_fmac_f32_dpp v196, v224, v60 row_newbcast:15 row_mask:0xf bank_mask:0xf
	v_fmac_f32_dpp v197, v225, v61 row_newbcast:15 row_mask:0xf bank_mask:0xf
	v_fmac_f32_dpp v198, v226, v62 row_newbcast:15 row_mask:0xf bank_mask:0xf
	v_fmac_f32_dpp v199, v227, v63 row_newbcast:15 row_mask:0xf bank_mask:0xf
	v_add_f32_e32 v196, v196, v197
	v_add_f32_e32 v198, v198, v199
	v_sub_f32_e64 v202, -v196, v198
	s_waitcnt lgkmcnt(0)
	s_nop 1
	v_mfma_f32_4x4x1_16b_f32 v[0:3], v64, v202, v[0:3]
	v_mfma_f32_4x4x1_16b_f32 v[4:7], v65, v202, v[4:7]
	v_mfma_f32_4x4x1_16b_f32 v[8:11], v66, v202, v[8:11]
	v_mfma_f32_4x4x1_16b_f32 v[12:15], v67, v202, v[12:15]
	v_mfma_f32_4x4x1_16b_f32 v[16:19], v68, v202, v[16:19]
	v_mfma_f32_4x4x1_16b_f32 v[20:23], v69, v202, v[20:23]
	v_mfma_f32_4x4x1_16b_f32 v[24:27], v70, v202, v[24:27]
	v_mfma_f32_4x4x1_16b_f32 v[28:31], v71, v202, v[28:31]
	v_mfma_f32_4x4x1_16b_f32 v[32:35], v72, v202, v[32:35]
	v_mfma_f32_4x4x1_16b_f32 v[36:39], v73, v202, v[36:39]
	v_mfma_f32_4x4x1_16b_f32 v[40:43], v74, v202, v[40:43]
	v_mfma_f32_4x4x1_16b_f32 v[44:47], v75, v202, v[44:47]
	v_mfma_f32_4x4x1_16b_f32 v[48:51], v76, v202, v[48:51]
	v_mfma_f32_4x4x1_16b_f32 v[52:55], v77, v202, v[52:55]
	v_mfma_f32_4x4x1_16b_f32 v[56:59], v78, v202, v[56:59]
	v_mfma_f32_4x4x1_16b_f32 v[60:63], v79, v202, v[60:63]
	v_mfma_f32_4x4x1_16b_f32 v[0:3], v80, v203, v[0:3]
	v_mfma_f32_4x4x1_16b_f32 v[4:7], v81, v203, v[4:7]
	v_mfma_f32_4x4x1_16b_f32 v[8:11], v82, v203, v[8:11]
	v_mfma_f32_4x4x1_16b_f32 v[12:15], v83, v203, v[12:15]
	v_mfma_f32_4x4x1_16b_f32 v[16:19], v84, v203, v[16:19]
	v_mfma_f32_4x4x1_16b_f32 v[20:23], v85, v203, v[20:23]
	v_mfma_f32_4x4x1_16b_f32 v[24:27], v86, v203, v[24:27]
	v_mfma_f32_4x4x1_16b_f32 v[28:31], v87, v203, v[28:31]
	v_mfma_f32_4x4x1_16b_f32 v[32:35], v88, v203, v[32:35]
	v_mfma_f32_4x4x1_16b_f32 v[36:39], v89, v203, v[36:39]
	v_mfma_f32_4x4x1_16b_f32 v[40:43], v90, v203, v[40:43]
	v_mfma_f32_4x4x1_16b_f32 v[44:47], v91, v203, v[44:47]
;     static __device__ __forceinline__ void upd(float (&S)[64], const In2& in, float sa, float vv, float& y0, float& y1) {
;         float t0, t1, t2, t3;
;         asm volatile("v_mul_f32_dpp %0, %10, %27 row_newbcast:%28" DPPM "v_mul_f32_dpp %1, %11, %27 row_newbcast:%28" DPPM "v_mul_f32_dpp %2, %12, %27 row_newbcast:%28" DPPM "v_mul_f32_dpp %3, %13, %27 row_newbcast:%28" DPPM
;                      "v_fmac_f32_dpp %0, %14, %6 row_newbcast:%28" DPPM "v_fmac_f32_dpp %1, %15, %7 row_newbcast:%28" DPPM "v_fmac_f32_dpp %2, %16, %8 row_newbcast:%28" DPPM "v_fmac_f32_dpp %3, %17, %9 row_newbcast:%28" DPPM
;                      "v_fmac_f32_dpp %0, %18, %26 row_newbcast:%28" DPPM "v_fmac_f32_dpp %1, %19, %26 row_newbcast:%28" DPPM "v_fmac_f32_dpp %2, %20, %26 row_newbcast:%28" DPPM "v_fmac_f32_dpp %3, %21, %26 row_newbcast:%28" DPPM
;                      "v_fmac_f32_dpp %4, %22, %0 row_newbcast:%28" DPPM "v_fmac_f32_dpp %5, %23, %1 row_newbcast:%28" DPPM "v_fmac_f32_dpp %4, %24, %2 row_newbcast:%28" DPPM "v_fmac_f32_dpp %5, %25, %3 row_newbcast:%28" DPPM
;                      : "=&v"(t0), "=&v"(t1), "=&v"(t2), "=&v"(t3), "+v"(y0), "+v"(y1)
;                      : "v"(S[K]), "v"(S[K + 1]), "v"(S[K + 2]), "v"(S[K + 3]), "v"(in.kd[0]), "v"(in.kd[1]), "v"(in.kd[2]), "v"(in.kd[3]), "v"(in.w[0]), "v"(in.w[1]), "v"(in.w[2]), "v"(in.w[3]),
;                        "v"(in.b[0]), "v"(in.b[1]), "v"(in.b[2]), "v"(in.b[3]), "v"(in.r[0]), "v"(in.r[1]), "v"(in.r[2]), "v"(in.r[3]), "v"(sa), "v"(vv), "n"(N0));
;         S[K] = t0; S[K + 1] = t1; S[K + 2] = t2; S[K + 3] = t3;
;         if constexpr (K + 4 < 64) ScanK<K + 4>::upd(S, in, sa, vv, y0, y1);
;     }
	v_mfma_f32_4x4x1_16b_f32 v[48:51], v92, v203, v[48:51]
	v_mfma_f32_4x4x1_16b_f32 v[52:55], v93, v203, v[52:55]
	v_mfma_f32_4x4x1_16b_f32 v[56:59], v94, v203, v[56:59]
	v_mfma_f32_4x4x1_16b_f32 v[60:63], v95, v203, v[60:63]
	v_fmac_f32_dpp v135, v228, v0 row_newbcast:0 row_mask:0xf bank_mask:0xf
	v_mul_f32_dpp v201, v229, v1 row_newbcast:0 row_mask:0xf bank_mask:0xf
	v_fmac_f32_dpp v135, v230, v2 row_newbcast:0 row_mask:0xf bank_mask:0xf
	v_fmac_f32_dpp v201, v231, v3 row_newbcast:0 row_mask:0xf bank_mask:0xf
	v_fmac_f32_dpp v135, v228, v4 row_newbcast:1 row_mask:0xf bank_mask:0xf
	v_fmac_f32_dpp v201, v229, v5 row_newbcast:1 row_mask:0xf bank_mask:0xf
	v_fmac_f32_dpp v135, v230, v6 row_newbcast:1 row_mask:0xf bank_mask:0xf
	v_fmac_f32_dpp v201, v231, v7 row_newbcast:1 row_mask:0xf bank_mask:0xf
	v_fmac_f32_dpp v135, v228, v8 row_newbcast:2 row_mask:0xf bank_mask:0xf
	v_fmac_f32_dpp v201, v229, v9 row_newbcast:2 row_mask:0xf bank_mask:0xf
	v_fmac_f32_dpp v135, v230, v10 row_newbcast:2 row_mask:0xf bank_mask:0xf
	v_fmac_f32_dpp v201, v231, v11 row_newbcast:2 row_mask:0xf bank_mask:0xf
	v_fmac_f32_dpp v135, v228, v12 row_newbcast:3 row_mask:0xf bank_mask:0xf
	v_fmac_f32_dpp v201, v229, v13 row_newbcast:3 row_mask:0xf bank_mask:0xf
	v_fmac_f32_dpp v135, v230, v14 row_newbcast:3 row_mask:0xf bank_mask:0xf
	v_fmac_f32_dpp v201, v231, v15 row_newbcast:3 row_mask:0xf bank_mask:0xf
	v_fmac_f32_dpp v135, v228, v16 row_newbcast:4 row_mask:0xf bank_mask:0xf
	v_fmac_f32_dpp v201, v229, v17 row_newbcast:4 row_mask:0xf bank_mask:0xf
	v_fmac_f32_dpp v135, v230, v18 row_newbcast:4 row_mask:0xf bank_mask:0xf
	v_fmac_f32_dpp v201, v231, v19 row_newbcast:4 row_mask:0xf bank_mask:0xf
	v_fmac_f32_dpp v135, v228, v20 row_newbcast:5 row_mask:0xf bank_mask:0xf
	v_fmac_f32_dpp v201, v229, v21 row_newbcast:5 row_mask:0xf bank_mask:0xf
	v_fmac_f32_dpp v135, v230, v22 row_newbcast:5 row_mask:0xf bank_mask:0xf
	v_fmac_f32_dpp v201, v231, v23 row_newbcast:5 row_mask:0xf bank_mask:0xf
	v_fmac_f32_dpp v135, v228, v24 row_newbcast:6 row_mask:0xf bank_mask:0xf
	v_fmac_f32_dpp v201, v229, v25 row_newbcast:6 row_mask:0xf bank_mask:0xf
	v_fmac_f32_dpp v135, v230, v26 row_newbcast:6 row_mask:0xf bank_mask:0xf
	v_fmac_f32_dpp v201, v231, v27 row_newbcast:6 row_mask:0xf bank_mask:0xf
	v_fmac_f32_dpp v135, v228, v28 row_newbcast:7 row_mask:0xf bank_mask:0xf
	v_fmac_f32_dpp v201, v229, v29 row_newbcast:7 row_mask:0xf bank_mask:0xf
	v_fmac_f32_dpp v135, v230, v30 row_newbcast:7 row_mask:0xf bank_mask:0xf
	v_fmac_f32_dpp v201, v231, v31 row_newbcast:7 row_mask:0xf bank_mask:0xf
	v_fmac_f32_dpp v135, v228, v32 row_newbcast:8 row_mask:0xf bank_mask:0xf
	v_fmac_f32_dpp v201, v229, v33 row_newbcast:8 row_mask:0xf bank_mask:0xf
	v_fmac_f32_dpp v135, v230, v34 row_newbcast:8 row_mask:0xf bank_mask:0xf
	v_fmac_f32_dpp v201, v231, v35 row_newbcast:8 row_mask:0xf bank_mask:0xf
	v_fmac_f32_dpp v135, v228, v36 row_newbcast:9 row_mask:0xf bank_mask:0xf
	v_fmac_f32_dpp v201, v229, v37 row_newbcast:9 row_mask:0xf bank_mask:0xf
	v_fmac_f32_dpp v135, v230, v38 row_newbcast:9 row_mask:0xf bank_mask:0xf
	v_fmac_f32_dpp v201, v231, v39 row_newbcast:9 row_mask:0xf bank_mask:0xf
	v_fmac_f32_dpp v135, v228, v40 row_newbcast:10 row_mask:0xf bank_mask:0xf
	v_fmac_f32_dpp v201, v229, v41 row_newbcast:10 row_mask:0xf bank_mask:0xf
	v_fmac_f32_dpp v135, v230, v42 row_newbcast:10 row_mask:0xf bank_mask:0xf
	v_fmac_f32_dpp v201, v231, v43 row_newbcast:10 row_mask:0xf bank_mask:0xf
	v_fmac_f32_dpp v135, v228, v44 row_newbcast:11 row_mask:0xf bank_mask:0xf
	v_fmac_f32_dpp v201, v229, v45 row_newbcast:11 row_mask:0xf bank_mask:0xf
	v_fmac_f32_dpp v135, v230, v46 row_newbcast:11 row_mask:0xf bank_mask:0xf
	v_fmac_f32_dpp v201, v231, v47 row_newbcast:11 row_mask:0xf bank_mask:0xf
	v_fmac_f32_dpp v135, v228, v48 row_newbcast:12 row_mask:0xf bank_mask:0xf
	v_fmac_f32_dpp v201, v229, v49 row_newbcast:12 row_mask:0xf bank_mask:0xf
	v_fmac_f32_dpp v135, v230, v50 row_newbcast:12 row_mask:0xf bank_mask:0xf
	v_fmac_f32_dpp v201, v231, v51 row_newbcast:12 row_mask:0xf bank_mask:0xf
	v_fmac_f32_dpp v135, v228, v52 row_newbcast:13 row_mask:0xf bank_mask:0xf
	v_fmac_f32_dpp v201, v229, v53 row_newbcast:13 row_mask:0xf bank_mask:0xf
	v_fmac_f32_dpp v135, v230, v54 row_newbcast:13 row_mask:0xf bank_mask:0xf
	v_fmac_f32_dpp v201, v231, v55 row_newbcast:13 row_mask:0xf bank_mask:0xf
	v_fmac_f32_dpp v135, v228, v56 row_newbcast:14 row_mask:0xf bank_mask:0xf
	v_fmac_f32_dpp v201, v229, v57 row_newbcast:14 row_mask:0xf bank_mask:0xf
	v_fmac_f32_dpp v135, v230, v58 row_newbcast:14 row_mask:0xf bank_mask:0xf
	v_fmac_f32_dpp v201, v231, v59 row_newbcast:14 row_mask:0xf bank_mask:0xf
	v_fmac_f32_dpp v135, v228, v60 row_newbcast:15 row_mask:0xf bank_mask:0xf
	v_fmac_f32_dpp v201, v229, v61 row_newbcast:15 row_mask:0xf bank_mask:0xf
	v_fmac_f32_dpp v135, v230, v62 row_newbcast:15 row_mask:0xf bank_mask:0xf
	v_fmac_f32_dpp v201, v231, v63 row_newbcast:15 row_mask:0xf bank_mask:0xf
	v_add_f32_e32 v200, v135, v201
	s_waitcnt vmcnt(14)
; #define SB __builtin_amdgcn_sched_barrier(0)
; #define ST2(set, s) { DERIVE_BK(set); float sd[4]; ScanK<0>::dot(S, set.a, sd); float y0 = set.yo, y1 = 0.f; ScanK<0>::upd(S, set, -((sd[0] + sd[1]) + (sd[2] + sd[3])), __uint_as_float(set.v << 16), y0, y1); __builtin_amdgcn_raw_buffer_store_b32(__float_as_uint(y0 + y1), rY, lo4b, ob4 + (unsigned)((int)(s) * (int)stp * 4), 0); }
; #define TOUCH2(set) asm volatile("" :: "v"(set.w), "v"(set.a), "v"(set.b), "v"(set.kw), "v"(set.r), "v"(set.v), "v"(set.yo))
; __device__ __forceinline__ void scan_pass2(const Params& p, int d) {
;     ...
;         In2 i0, i1; LD2(i0, 0);
; #pragma unroll 1
;         for (int s = 0; s < LC; s += 2) { TOUCH2(i0); SB; LD2(i1, s + 1); SB; ST2(i0, s); TOUCH2(i1); SB; LD2(i0, s + 2); SB; ST2(i1, s + 1); }
	buffer_store_dword v200, v207, s[68:71], s79 offen
	s_add_u32 s79, s79, 0xfffff000
	buffer_load_dwordx4 v[116:119], v232, s[64:67], s72 offen
	buffer_load_dwordx4 v[120:123], v233, s[64:67], s72 offen
	buffer_load_dwordx4 v[124:127], v234, s[64:67], s72 offen
	buffer_load_dwordx4 v[128:131], v235, s[64:67], s72 offen
	buffer_load_dwordx2 v[132:133], v236, s[64:67], s76 offen
	buffer_load_ushort v134, v237, s[64:67], s76 offen
	buffer_load_dword v135, v207, s[68:71], s78 offen
	s_add_i32 s72, s72, 0xfffff000
	s_max_i32 s72, s72, 0
	s_add_i32 s76, s76, 0xfffff800
	s_max_i32 s76, s76, 0
	s_add_i32 s78, s78, 0xfffff000
	s_max_i32 s78, s78, 0
	v_pk_mul_f32 v[224:225], v[140:141], v[216:217]
	v_pk_mul_f32 v[226:227], v[142:143], v[218:219]
	v_pk_mul_f32 v[216:217], v[216:217], v[136:137]
	v_pk_mul_f32 v[218:219], v[218:219], v[138:139]
	v_pk_fma_f32 v[184:185], v[144:145], v[188:189], v[192:193]
	v_pk_fma_f32 v[186:187], v[146:147], v[190:191], v[194:195]
	v_pk_mul_f32 v[176:177], v[140:141], v[144:145]
	v_pk_mul_f32 v[178:179], v[142:143], v[146:147]
	v_rcp_f32_e32 v220, v216
	v_rcp_f32_e32 v221, v217
	v_rcp_f32_e32 v222, v218
	v_rcp_f32_e32 v223, v219
	v_lshlrev_b32_e32 v180, 16, v152
	v_and_b32_e32 v181, 0xffff0000, v152
	v_lshlrev_b32_e32 v182, 16, v153
	v_and_b32_e32 v183, 0xffff0000, v153
	v_pk_mul_f32 v[180:181], v[180:181], v[184:185]
	v_pk_mul_f32 v[182:183], v[182:183], v[186:187]
	v_pk_mul_f32 v[228:229], v[148:149], v[216:217]
	v_pk_mul_f32 v[230:231], v[150:151], v[218:219]
	v_pk_mul_f32 v[176:177], v[176:177], v[220:221]
	v_pk_mul_f32 v[178:179], v[178:179], v[222:223]
	v_pk_mul_f32 v[180:181], v[180:181], v[220:221]
	v_pk_mul_f32 v[182:183], v[182:183], v[222:223]
	v_lshlrev_b32_e32 v203, 16, v154
	ds_write2_b32 v208, v176, v177 offset0:0 offset1:16
	ds_write2_b32 v208, v178, v179 offset0:32 offset1:48
	ds_write2_b32 v208, v180, v181 offset0:64 offset1:80
	ds_write2_b32 v208, v182, v183 offset0:96 offset1:112
	ds_read_b128 v[64:67], v209 offset:0
	ds_read_b128 v[68:71], v209 offset:16
	ds_read_b128 v[72:75], v209 offset:32
	ds_read_b128 v[76:79], v209 offset:48
	ds_read_b128 v[80:83], v209 offset:256
	ds_read_b128 v[84:87], v209 offset:272
	ds_read_b128 v[88:91], v209 offset:288
	ds_read_b128 v[92:95], v209 offset:304
	v_mul_f32_dpp v196, v224, v0 row_newbcast:0 row_mask:0xf bank_mask:0xf
	v_mul_f32_dpp v197, v225, v1 row_newbcast:0 row_mask:0xf bank_mask:0xf
	v_mul_f32_dpp v198, v226, v2 row_newbcast:0 row_mask:0xf bank_mask:0xf
	v_mul_f32_dpp v199, v227, v3 row_newbcast:0 row_mask:0xf bank_mask:0xf
	v_fmac_f32_dpp v196, v224, v4 row_newbcast:1 row_mask:0xf bank_mask:0xf
	v_fmac_f32_dpp v197, v225, v5 row_newbcast:1 row_mask:0xf bank_mask:0xf
	v_fmac_f32_dpp v198, v226, v6 row_newbcast:1 row_mask:0xf bank_mask:0xf
	v_fmac_f32_dpp v199, v227, v7 row_newbcast:1 row_mask:0xf bank_mask:0xf
	v_fmac_f32_dpp v196, v224, v8 row_newbcast:2 row_mask:0xf bank_mask:0xf
	v_fmac_f32_dpp v197, v225, v9 row_newbcast:2 row_mask:0xf bank_mask:0xf
	v_fmac_f32_dpp v198, v226, v10 row_newbcast:2 row_mask:0xf bank_mask:0xf
	v_fmac_f32_dpp v199, v227, v11 row_newbcast:2 row_mask:0xf bank_mask:0xf
	v_fmac_f32_dpp v196, v224, v12 row_newbcast:3 row_mask:0xf bank_mask:0xf
	v_fmac_f32_dpp v197, v225, v13 row_newbcast:3 row_mask:0xf bank_mask:0xf
	v_fmac_f32_dpp v198, v226, v14 row_newbcast:3 row_mask:0xf bank_mask:0xf
	v_fmac_f32_dpp v199, v227, v15 row_newbcast:3 row_mask:0xf bank_mask:0xf
	v_fmac_f32_dpp v196, v224, v16 row_newbcast:4 row_mask:0xf bank_mask:0xf
	v_fmac_f32_dpp v197, v225, v17 row_newbcast:4 row_mask:0xf bank_mask:0xf
	v_fmac_f32_dpp v198, v226, v18 row_newbcast:4 row_mask:0xf bank_mask:0xf
	v_fmac_f32_dpp v199, v227, v19 row_newbcast:4 row_mask:0xf bank_mask:0xf
	v_fmac_f32_dpp v196, v224, v20 row_newbcast:5 row_mask:0xf bank_mask:0xf
	v_fmac_f32_dpp v197, v225, v21 row_newbcast:5 row_mask:0xf bank_mask:0xf
	v_fmac_f32_dpp v198, v226, v22 row_newbcast:5 row_mask:0xf bank_mask:0xf
	v_fmac_f32_dpp v199, v227, v23 row_newbcast:5 row_mask:0xf bank_mask:0xf
	v_fmac_f32_dpp v196, v224, v24 row_newbcast:6 row_mask:0xf bank_mask:0xf
	v_fmac_f32_dpp v197, v225, v25 row_newbcast:6 row_mask:0xf bank_mask:0xf
	v_fmac_f32_dpp v198, v226, v26 row_newbcast:6 row_mask:0xf bank_mask:0xf
	v_fmac_f32_dpp v199, v227, v27 row_newbcast:6 row_mask:0xf bank_mask:0xf
	v_fmac_f32_dpp v196, v224, v28 row_newbcast:7 row_mask:0xf bank_mask:0xf
	v_fmac_f32_dpp v197, v225, v29 row_newbcast:7 row_mask:0xf bank_mask:0xf
	v_fmac_f32_dpp v198, v226, v30 row_newbcast:7 row_mask:0xf bank_mask:0xf
	v_fmac_f32_dpp v199, v227, v31 row_newbcast:7 row_mask:0xf bank_mask:0xf
	v_fmac_f32_dpp v196, v224, v32 row_newbcast:8 row_mask:0xf bank_mask:0xf
	v_fmac_f32_dpp v197, v225, v33 row_newbcast:8 row_mask:0xf bank_mask:0xf
	v_fmac_f32_dpp v198, v226, v34 row_newbcast:8 row_mask:0xf bank_mask:0xf
	v_fmac_f32_dpp v199, v227, v35 row_newbcast:8 row_mask:0xf bank_mask:0xf
	v_fmac_f32_dpp v196, v224, v36 row_newbcast:9 row_mask:0xf bank_mask:0xf
	v_fmac_f32_dpp v197, v225, v37 row_newbcast:9 row_mask:0xf bank_mask:0xf
	v_fmac_f32_dpp v198, v226, v38 row_newbcast:9 row_mask:0xf bank_mask:0xf
	v_fmac_f32_dpp v199, v227, v39 row_newbcast:9 row_mask:0xf bank_mask:0xf
	v_fmac_f32_dpp v196, v224, v40 row_newbcast:10 row_mask:0xf bank_mask:0xf
	v_fmac_f32_dpp v197, v225, v41 row_newbcast:10 row_mask:0xf bank_mask:0xf
	v_fmac_f32_dpp v198, v226, v42 row_newbcast:10 row_mask:0xf bank_mask:0xf
	v_fmac_f32_dpp v199, v227, v43 row_newbcast:10 row_mask:0xf bank_mask:0xf
	v_fmac_f32_dpp v196, v224, v44 row_newbcast:11 row_mask:0xf bank_mask:0xf
	v_fmac_f32_dpp v197, v225, v45 row_newbcast:11 row_mask:0xf bank_mask:0xf
;     static __device__ __forceinline__ void dot(const float (&S)[64], const f32x4& a, float (&s)[4]) {
;         if constexpr (K == 0) {
;             asm volatile("v_mul_f32_dpp %0, %4, %8 row_newbcast:%16" DPPM "v_mul_f32_dpp %1, %5, %9 row_newbcast:%16" DPPM "v_mul_f32_dpp %2, %6, %10 row_newbcast:%16" DPPM "v_mul_f32_dpp %3, %7, %11 row_newbcast:%16" DPPM
;                          "v_fmac_f32_dpp %0, %4, %12 row_newbcast:%17" DPPM "v_fmac_f32_dpp %1, %5, %13 row_newbcast:%17" DPPM "v_fmac_f32_dpp %2, %6, %14 row_newbcast:%17" DPPM "v_fmac_f32_dpp %3, %7, %15 row_newbcast:%17" DPPM
;                          : "=&v"(s[0]), "=&v"(s[1]), "=&v"(s[2]), "=&v"(s[3])
;                          : "v"(a[0]), "v"(a[1]), "v"(a[2]), "v"(a[3]), "v"(S[K]), "v"(S[K + 1]), "v"(S[K + 2]), "v"(S[K + 3]), "v"(S[K + 4]), "v"(S[K + 5]), "v"(S[K + 6]), "v"(S[K + 7]), "n"(N0), "n"(N1));
;         } else
;         asm volatile("v_fmac_f32_dpp %0, %4, %8 row_newbcast:%16" DPPM "v_fmac_f32_dpp %1, %5, %9 row_newbcast:%16" DPPM "v_fmac_f32_dpp %2, %6, %10 row_newbcast:%16" DPPM "v_fmac_f32_dpp %3, %7, %11 row_newbcast:%16" DPPM
;                      "v_fmac_f32_dpp %0, %4, %12 row_newbcast:%17" DPPM "v_fmac_f32_dpp %1, %5, %13 row_newbcast:%17" DPPM "v_fmac_f32_dpp %2, %6, %14 row_newbcast:%17" DPPM "v_fmac_f32_dpp %3, %7, %15 row_newbcast:%17" DPPM
;                      : "+v"(s[0]), "+v"(s[1]), "+v"(s[2]), "+v"(s[3])
;                      : "v"(a[0]), "v"(a[1]), "v"(a[2]), "v"(a[3]), "v"(S[K]), "v"(S[K + 1]), "v"(S[K + 2]), "v"(S[K + 3]), "v"(S[K + 4]), "v"(S[K + 5]), "v"(S[K + 6]), "v"(S[K + 7]), "n"(N0), "n"(N1));
;         if constexpr (K + 8 < 64) ScanK<K + 8>::dot(S, a, s);
;     }
;     static __device__ __forceinline__ void upd(float (&S)[64], const In2& in, float sa, float vv, float& y0, float& y1) {
;         float t0, t1, t2, t3;
;         asm volatile("v_mul_f32_dpp %0, %10, %27 row_newbcast:%28" DPPM "v_mul_f32_dpp %1, %11, %27 row_newbcast:%28" DPPM "v_mul_f32_dpp %2, %12, %27 row_newbcast:%28" DPPM "v_mul_f32_dpp %3, %13, %27 row_newbcast:%28" DPPM
;                      "v_fmac_f32_dpp %0, %14, %6 row_newbcast:%28" DPPM "v_fmac_f32_dpp %1, %15, %7 row_newbcast:%28" DPPM "v_fmac_f32_dpp %2, %16, %8 row_newbcast:%28" DPPM "v_fmac_f32_dpp %3, %17, %9 row_newbcast:%28" DPPM
	v_fmac_f32_dpp v198, v226, v46 row_newbcast:11 row_mask:0xf bank_mask:0xf
	v_fmac_f32_dpp v199, v227, v47 row_newbcast:11 row_mask:0xf bank_mask:0xf
	v_fmac_f32_dpp v196, v224, v48 row_newbcast:12 row_mask:0xf bank_mask:0xf
	v_fmac_f32_dpp v197, v225, v49 row_newbcast:12 row_mask:0xf bank_mask:0xf
	v_fmac_f32_dpp v198, v226, v50 row_newbcast:12 row_mask:0xf bank_mask:0xf
	v_fmac_f32_dpp v199, v227, v51 row_newbcast:12 row_mask:0xf bank_mask:0xf
	v_fmac_f32_dpp v196, v224, v52 row_newbcast:13 row_mask:0xf bank_mask:0xf
	v_fmac_f32_dpp v197, v225, v53 row_newbcast:13 row_mask:0xf bank_mask:0xf
	v_fmac_f32_dpp v198, v226, v54 row_newbcast:13 row_mask:0xf bank_mask:0xf
	v_fmac_f32_dpp v199, v227, v55 row_newbcast:13 row_mask:0xf bank_mask:0xf
	v_fmac_f32_dpp v196, v224, v56 row_newbcast:14 row_mask:0xf bank_mask:0xf
	v_fmac_f32_dpp v197, v225, v57 row_newbcast:14 row_mask:0xf bank_mask:0xf
	v_fmac_f32_dpp v198, v226, v58 row_newbcast:14 row_mask:0xf bank_mask:0xf
	v_fmac_f32_dpp v199, v227, v59 row_newbcast:14 row_mask:0xf bank_mask:0xf
	v_fmac_f32_dpp v196, v224, v60 row_newbcast:15 row_mask:0xf bank_mask:0xf
	v_fmac_f32_dpp v197, v225, v61 row_newbcast:15 row_mask:0xf bank_mask:0xf
	v_fmac_f32_dpp v198, v226, v62 row_newbcast:15 row_mask:0xf bank_mask:0xf
	v_fmac_f32_dpp v199, v227, v63 row_newbcast:15 row_mask:0xf bank_mask:0xf
	v_add_f32_e32 v196, v196, v197
	v_add_f32_e32 v198, v198, v199
	v_sub_f32_e64 v202, -v196, v198
	s_waitcnt lgkmcnt(0)
	s_nop 1
	v_mfma_f32_4x4x1_16b_f32 v[0:3], v64, v202, v[0:3]
	v_mfma_f32_4x4x1_16b_f32 v[4:7], v65, v202, v[4:7]
	v_mfma_f32_4x4x1_16b_f32 v[8:11], v66, v202, v[8:11]
	v_mfma_f32_4x4x1_16b_f32 v[12:15], v67, v202, v[12:15]
	v_mfma_f32_4x4x1_16b_f32 v[16:19], v68, v202, v[16:19]
	v_mfma_f32_4x4x1_16b_f32 v[20:23], v69, v202, v[20:23]
	v_mfma_f32_4x4x1_16b_f32 v[24:27], v70, v202, v[24:27]
	v_mfma_f32_4x4x1_16b_f32 v[28:31], v71, v202, v[28:31]
	v_mfma_f32_4x4x1_16b_f32 v[32:35], v72, v202, v[32:35]
	v_mfma_f32_4x4x1_16b_f32 v[36:39], v73, v202, v[36:39]
	v_mfma_f32_4x4x1_16b_f32 v[40:43], v74, v202, v[40:43]
	v_mfma_f32_4x4x1_16b_f32 v[44:47], v75, v202, v[44:47]
	v_mfma_f32_4x4x1_16b_f32 v[48:51], v76, v202, v[48:51]
	v_mfma_f32_4x4x1_16b_f32 v[52:55], v77, v202, v[52:55]
	v_mfma_f32_4x4x1_16b_f32 v[56:59], v78, v202, v[56:59]
	v_mfma_f32_4x4x1_16b_f32 v[60:63], v79, v202, v[60:63]
	v_mfma_f32_4x4x1_16b_f32 v[0:3], v80, v203, v[0:3]
	v_mfma_f32_4x4x1_16b_f32 v[4:7], v81, v203, v[4:7]
	v_mfma_f32_4x4x1_16b_f32 v[8:11], v82, v203, v[8:11]
	v_mfma_f32_4x4x1_16b_f32 v[12:15], v83, v203, v[12:15]
	v_mfma_f32_4x4x1_16b_f32 v[16:19], v84, v203, v[16:19]
	v_mfma_f32_4x4x1_16b_f32 v[20:23], v85, v203, v[20:23]
	v_mfma_f32_4x4x1_16b_f32 v[24:27], v86, v203, v[24:27]
	v_mfma_f32_4x4x1_16b_f32 v[28:31], v87, v203, v[28:31]
	v_mfma_f32_4x4x1_16b_f32 v[32:35], v88, v203, v[32:35]
	v_mfma_f32_4x4x1_16b_f32 v[36:39], v89, v203, v[36:39]
	v_mfma_f32_4x4x1_16b_f32 v[40:43], v90, v203, v[40:43]
	v_mfma_f32_4x4x1_16b_f32 v[44:47], v91, v203, v[44:47]
	v_mfma_f32_4x4x1_16b_f32 v[48:51], v92, v203, v[48:51]
	v_mfma_f32_4x4x1_16b_f32 v[52:55], v93, v203, v[52:55]
	v_mfma_f32_4x4x1_16b_f32 v[56:59], v94, v203, v[56:59]
	v_mfma_f32_4x4x1_16b_f32 v[60:63], v95, v203, v[60:63]
	v_fmac_f32_dpp v155, v228, v0 row_newbcast:0 row_mask:0xf bank_mask:0xf
	v_mul_f32_dpp v201, v229, v1 row_newbcast:0 row_mask:0xf bank_mask:0xf
	v_fmac_f32_dpp v155, v230, v2 row_newbcast:0 row_mask:0xf bank_mask:0xf
	v_fmac_f32_dpp v201, v231, v3 row_newbcast:0 row_mask:0xf bank_mask:0xf
	v_fmac_f32_dpp v155, v228, v4 row_newbcast:1 row_mask:0xf bank_mask:0xf
	v_fmac_f32_dpp v201, v229, v5 row_newbcast:1 row_mask:0xf bank_mask:0xf
	v_fmac_f32_dpp v155, v230, v6 row_newbcast:1 row_mask:0xf bank_mask:0xf
	v_fmac_f32_dpp v201, v231, v7 row_newbcast:1 row_mask:0xf bank_mask:0xf
	v_fmac_f32_dpp v155, v228, v8 row_newbcast:2 row_mask:0xf bank_mask:0xf
	v_fmac_f32_dpp v201, v229, v9 row_newbcast:2 row_mask:0xf bank_mask:0xf
	v_fmac_f32_dpp v155, v230, v10 row_newbcast:2 row_mask:0xf bank_mask:0xf
	v_fmac_f32_dpp v201, v231, v11 row_newbcast:2 row_mask:0xf bank_mask:0xf
	v_fmac_f32_dpp v155, v228, v12 row_newbcast:3 row_mask:0xf bank_mask:0xf
	v_fmac_f32_dpp v201, v229, v13 row_newbcast:3 row_mask:0xf bank_mask:0xf
	v_fmac_f32_dpp v155, v230, v14 row_newbcast:3 row_mask:0xf bank_mask:0xf
	v_fmac_f32_dpp v201, v231, v15 row_newbcast:3 row_mask:0xf bank_mask:0xf
	v_fmac_f32_dpp v155, v228, v16 row_newbcast:4 row_mask:0xf bank_mask:0xf
	v_fmac_f32_dpp v201, v229, v17 row_newbcast:4 row_mask:0xf bank_mask:0xf
	v_fmac_f32_dpp v155, v230, v18 row_newbcast:4 row_mask:0xf bank_mask:0xf
	v_fmac_f32_dpp v201, v231, v19 row_newbcast:4 row_mask:0xf bank_mask:0xf
	v_fmac_f32_dpp v155, v228, v20 row_newbcast:5 row_mask:0xf bank_mask:0xf
	v_fmac_f32_dpp v201, v229, v21 row_newbcast:5 row_mask:0xf bank_mask:0xf
	v_fmac_f32_dpp v155, v230, v22 row_newbcast:5 row_mask:0xf bank_mask:0xf
	v_fmac_f32_dpp v201, v231, v23 row_newbcast:5 row_mask:0xf bank_mask:0xf
	v_fmac_f32_dpp v155, v228, v24 row_newbcast:6 row_mask:0xf bank_mask:0xf
	v_fmac_f32_dpp v201, v229, v25 row_newbcast:6 row_mask:0xf bank_mask:0xf
	v_fmac_f32_dpp v155, v230, v26 row_newbcast:6 row_mask:0xf bank_mask:0xf
	v_fmac_f32_dpp v201, v231, v27 row_newbcast:6 row_mask:0xf bank_mask:0xf
	v_fmac_f32_dpp v155, v228, v28 row_newbcast:7 row_mask:0xf bank_mask:0xf
	v_fmac_f32_dpp v201, v229, v29 row_newbcast:7 row_mask:0xf bank_mask:0xf
	v_fmac_f32_dpp v155, v230, v30 row_newbcast:7 row_mask:0xf bank_mask:0xf
	v_fmac_f32_dpp v201, v231, v31 row_newbcast:7 row_mask:0xf bank_mask:0xf
; #define SB __builtin_amdgcn_sched_barrier(0)
; #define ST2(set, s) { DERIVE_BK(set); float sd[4]; ScanK<0>::dot(S, set.a, sd); float y0 = set.yo, y1 = 0.f; ScanK<0>::upd(S, set, -((sd[0] + sd[1]) + (sd[2] + sd[3])), __uint_as_float(set.v << 16), y0, y1); __builtin_amdgcn_raw_buffer_store_b32(__float_as_uint(y0 + y1), rY, lo4b, ob4 + (unsigned)((int)(s) * (int)stp * 4), 0); }
; #define TOUCH2(set) asm volatile("" :: "v"(set.w), "v"(set.a), "v"(set.b), "v"(set.kw), "v"(set.r), "v"(set.v), "v"(set.yo))
; __device__ __forceinline__ void scan_pass2(const Params& p, int d) {
;     ...
;         In2 i0, i1; LD2(i0, 0);
; #pragma unroll 1
;         for (int s = 0; s < LC; s += 2) { TOUCH2(i0); SB; LD2(i1, s + 1); SB; ST2(i0, s); TOUCH2(i1); SB; LD2(i0, s + 2); SB; ST2(i1, s + 1); }
	v_fmac_f32_dpp v155, v228, v32 row_newbcast:8 row_mask:0xf bank_mask:0xf
	v_fmac_f32_dpp v201, v229, v33 row_newbcast:8 row_mask:0xf bank_mask:0xf
	v_fmac_f32_dpp v155, v230, v34 row_newbcast:8 row_mask:0xf bank_mask:0xf
	v_fmac_f32_dpp v201, v231, v35 row_newbcast:8 row_mask:0xf bank_mask:0xf
	v_fmac_f32_dpp v155, v228, v36 row_newbcast:9 row_mask:0xf bank_mask:0xf
	v_fmac_f32_dpp v201, v229, v37 row_newbcast:9 row_mask:0xf bank_mask:0xf
	v_fmac_f32_dpp v155, v230, v38 row_newbcast:9 row_mask:0xf bank_mask:0xf
	v_fmac_f32_dpp v201, v231, v39 row_newbcast:9 row_mask:0xf bank_mask:0xf
	v_fmac_f32_dpp v155, v228, v40 row_newbcast:10 row_mask:0xf bank_mask:0xf
	v_fmac_f32_dpp v201, v229, v41 row_newbcast:10 row_mask:0xf bank_mask:0xf
	v_fmac_f32_dpp v155, v230, v42 row_newbcast:10 row_mask:0xf bank_mask:0xf
	v_fmac_f32_dpp v201, v231, v43 row_newbcast:10 row_mask:0xf bank_mask:0xf
	v_fmac_f32_dpp v155, v228, v44 row_newbcast:11 row_mask:0xf bank_mask:0xf
	v_fmac_f32_dpp v201, v229, v45 row_newbcast:11 row_mask:0xf bank_mask:0xf
	v_fmac_f32_dpp v155, v230, v46 row_newbcast:11 row_mask:0xf bank_mask:0xf
	v_fmac_f32_dpp v201, v231, v47 row_newbcast:11 row_mask:0xf bank_mask:0xf
	v_fmac_f32_dpp v155, v228, v48 row_newbcast:12 row_mask:0xf bank_mask:0xf
	v_fmac_f32_dpp v201, v229, v49 row_newbcast:12 row_mask:0xf bank_mask:0xf
	v_fmac_f32_dpp v155, v230, v50 row_newbcast:12 row_mask:0xf bank_mask:0xf
	v_fmac_f32_dpp v201, v231, v51 row_newbcast:12 row_mask:0xf bank_mask:0xf
	v_fmac_f32_dpp v155, v228, v52 row_newbcast:13 row_mask:0xf bank_mask:0xf
	v_fmac_f32_dpp v201, v229, v53 row_newbcast:13 row_mask:0xf bank_mask:0xf
	v_fmac_f32_dpp v155, v230, v54 row_newbcast:13 row_mask:0xf bank_mask:0xf
	v_fmac_f32_dpp v201, v231, v55 row_newbcast:13 row_mask:0xf bank_mask:0xf
	v_fmac_f32_dpp v155, v228, v56 row_newbcast:14 row_mask:0xf bank_mask:0xf
	v_fmac_f32_dpp v201, v229, v57 row_newbcast:14 row_mask:0xf bank_mask:0xf
	v_fmac_f32_dpp v155, v230, v58 row_newbcast:14 row_mask:0xf bank_mask:0xf
	v_fmac_f32_dpp v201, v231, v59 row_newbcast:14 row_mask:0xf bank_mask:0xf
	v_fmac_f32_dpp v155, v228, v60 row_newbcast:15 row_mask:0xf bank_mask:0xf
	v_fmac_f32_dpp v201, v229, v61 row_newbcast:15 row_mask:0xf bank_mask:0xf
	v_fmac_f32_dpp v155, v230, v62 row_newbcast:15 row_mask:0xf bank_mask:0xf
	v_fmac_f32_dpp v201, v231, v63 row_newbcast:15 row_mask:0xf bank_mask:0xf
	v_add_f32_e32 v200, v155, v201
	s_waitcnt vmcnt(14)
	buffer_store_dword v200, v207, s[68:71], s79 offen
	s_add_u32 s79, s79, 0xfffff000
	buffer_load_dwordx4 v[136:139], v232, s[64:67], s72 offen
	buffer_load_dwordx4 v[140:143], v233, s[64:67], s72 offen
	buffer_load_dwordx4 v[144:147], v234, s[64:67], s72 offen
	buffer_load_dwordx4 v[148:151], v235, s[64:67], s72 offen
	buffer_load_dwordx2 v[152:153], v236, s[64:67], s76 offen
	buffer_load_ushort v154, v237, s[64:67], s76 offen
	buffer_load_dword v155, v207, s[68:71], s78 offen
	s_add_i32 s72, s72, 0xfffff000
	s_max_i32 s72, s72, 0
	s_add_i32 s76, s76, 0xfffff800
	s_max_i32 s76, s76, 0
	s_add_i32 s78, s78, 0xfffff000
	s_max_i32 s78, s78, 0
	v_pk_mul_f32 v[224:225], v[160:161], v[216:217]
	v_pk_mul_f32 v[226:227], v[162:163], v[218:219]
	v_pk_mul_f32 v[216:217], v[216:217], v[156:157]
	v_pk_mul_f32 v[218:219], v[218:219], v[158:159]
	v_pk_fma_f32 v[184:185], v[164:165], v[188:189], v[192:193]
	v_pk_fma_f32 v[186:187], v[166:167], v[190:191], v[194:195]
	v_pk_mul_f32 v[176:177], v[160:161], v[164:165]
	v_pk_mul_f32 v[178:179], v[162:163], v[166:167]
	v_rcp_f32_e32 v220, v216
	v_rcp_f32_e32 v221, v217
	v_rcp_f32_e32 v222, v218
	v_rcp_f32_e32 v223, v219
	v_lshlrev_b32_e32 v180, 16, v172
	v_and_b32_e32 v181, 0xffff0000, v172
	v_lshlrev_b32_e32 v182, 16, v173
	v_and_b32_e32 v183, 0xffff0000, v173
	v_pk_mul_f32 v[180:181], v[180:181], v[184:185]
	v_pk_mul_f32 v[182:183], v[182:183], v[186:187]
	v_pk_mul_f32 v[228:229], v[168:169], v[216:217]
	v_pk_mul_f32 v[230:231], v[170:171], v[218:219]
	v_pk_mul_f32 v[176:177], v[176:177], v[220:221]
	v_pk_mul_f32 v[178:179], v[178:179], v[222:223]
	v_pk_mul_f32 v[180:181], v[180:181], v[220:221]
	v_pk_mul_f32 v[182:183], v[182:183], v[222:223]
	v_lshlrev_b32_e32 v203, 16, v174
	ds_write2_b32 v208, v176, v177 offset0:0 offset1:16
	ds_write2_b32 v208, v178, v179 offset0:32 offset1:48
	ds_write2_b32 v208, v180, v181 offset0:64 offset1:80
	ds_write2_b32 v208, v182, v183 offset0:96 offset1:112
	ds_read_b128 v[64:67], v209 offset:0
	ds_read_b128 v[68:71], v209 offset:16
	ds_read_b128 v[72:75], v209 offset:32
	ds_read_b128 v[76:79], v209 offset:48
	ds_read_b128 v[80:83], v209 offset:256
	ds_read_b128 v[84:87], v209 offset:272
	ds_read_b128 v[88:91], v209 offset:288
	ds_read_b128 v[92:95], v209 offset:304
	v_mul_f32_dpp v196, v224, v0 row_newbcast:0 row_mask:0xf bank_mask:0xf
	v_mul_f32_dpp v197, v225, v1 row_newbcast:0 row_mask:0xf bank_mask:0xf
	v_mul_f32_dpp v198, v226, v2 row_newbcast:0 row_mask:0xf bank_mask:0xf
	v_mul_f32_dpp v199, v227, v3 row_newbcast:0 row_mask:0xf bank_mask:0xf
	v_fmac_f32_dpp v196, v224, v4 row_newbcast:1 row_mask:0xf bank_mask:0xf
	v_fmac_f32_dpp v197, v225, v5 row_newbcast:1 row_mask:0xf bank_mask:0xf
	v_fmac_f32_dpp v198, v226, v6 row_newbcast:1 row_mask:0xf bank_mask:0xf
	v_fmac_f32_dpp v199, v227, v7 row_newbcast:1 row_mask:0xf bank_mask:0xf
	v_fmac_f32_dpp v196, v224, v8 row_newbcast:2 row_mask:0xf bank_mask:0xf
	v_fmac_f32_dpp v197, v225, v9 row_newbcast:2 row_mask:0xf bank_mask:0xf
	v_fmac_f32_dpp v198, v226, v10 row_newbcast:2 row_mask:0xf bank_mask:0xf
	v_fmac_f32_dpp v199, v227, v11 row_newbcast:2 row_mask:0xf bank_mask:0xf
	v_fmac_f32_dpp v196, v224, v12 row_newbcast:3 row_mask:0xf bank_mask:0xf
;     static __device__ __forceinline__ void dot(const float (&S)[64], const f32x4& a, float (&s)[4]) {
;         if constexpr (K == 0) {
;             asm volatile("v_mul_f32_dpp %0, %4, %8 row_newbcast:%16" DPPM "v_mul_f32_dpp %1, %5, %9 row_newbcast:%16" DPPM "v_mul_f32_dpp %2, %6, %10 row_newbcast:%16" DPPM "v_mul_f32_dpp %3, %7, %11 row_newbcast:%16" DPPM
;                          "v_fmac_f32_dpp %0, %4, %12 row_newbcast:%17" DPPM "v_fmac_f32_dpp %1, %5, %13 row_newbcast:%17" DPPM "v_fmac_f32_dpp %2, %6, %14 row_newbcast:%17" DPPM "v_fmac_f32_dpp %3, %7, %15 row_newbcast:%17" DPPM
;                          : "=&v"(s[0]), "=&v"(s[1]), "=&v"(s[2]), "=&v"(s[3])
;                          : "v"(a[0]), "v"(a[1]), "v"(a[2]), "v"(a[3]), "v"(S[K]), "v"(S[K + 1]), "v"(S[K + 2]), "v"(S[K + 3]), "v"(S[K + 4]), "v"(S[K + 5]), "v"(S[K + 6]), "v"(S[K + 7]), "n"(N0), "n"(N1));
;         } else
;         asm volatile("v_fmac_f32_dpp %0, %4, %8 row_newbcast:%16" DPPM "v_fmac_f32_dpp %1, %5, %9 row_newbcast:%16" DPPM "v_fmac_f32_dpp %2, %6, %10 row_newbcast:%16" DPPM "v_fmac_f32_dpp %3, %7, %11 row_newbcast:%16" DPPM
;                      "v_fmac_f32_dpp %0, %4, %12 row_newbcast:%17" DPPM "v_fmac_f32_dpp %1, %5, %13 row_newbcast:%17" DPPM "v_fmac_f32_dpp %2, %6, %14 row_newbcast:%17" DPPM "v_fmac_f32_dpp %3, %7, %15 row_newbcast:%17" DPPM
;                      : "+v"(s[0]), "+v"(s[1]), "+v"(s[2]), "+v"(s[3])
;                      : "v"(a[0]), "v"(a[1]), "v"(a[2]), "v"(a[3]), "v"(S[K]), "v"(S[K + 1]), "v"(S[K + 2]), "v"(S[K + 3]), "v"(S[K + 4]), "v"(S[K + 5]), "v"(S[K + 6]), "v"(S[K + 7]), "n"(N0), "n"(N1));
;         if constexpr (K + 8 < 64) ScanK<K + 8>::dot(S, a, s);
;     }
;     static __device__ __forceinline__ void upd(float (&S)[64], const In2& in, float sa, float vv, float& y0, float& y1) {
;         float t0, t1, t2, t3;
;         asm volatile("v_mul_f32_dpp %0, %10, %27 row_newbcast:%28" DPPM "v_mul_f32_dpp %1, %11, %27 row_newbcast:%28" DPPM "v_mul_f32_dpp %2, %12, %27 row_newbcast:%28" DPPM "v_mul_f32_dpp %3, %13, %27 row_newbcast:%28" DPPM
;                      "v_fmac_f32_dpp %0, %14, %6 row_newbcast:%28" DPPM "v_fmac_f32_dpp %1, %15, %7 row_newbcast:%28" DPPM "v_fmac_f32_dpp %2, %16, %8 row_newbcast:%28" DPPM "v_fmac_f32_dpp %3, %17, %9 row_newbcast:%28" DPPM
	v_fmac_f32_dpp v197, v225, v13 row_newbcast:3 row_mask:0xf bank_mask:0xf
	v_fmac_f32_dpp v198, v226, v14 row_newbcast:3 row_mask:0xf bank_mask:0xf
	v_fmac_f32_dpp v199, v227, v15 row_newbcast:3 row_mask:0xf bank_mask:0xf
	v_fmac_f32_dpp v196, v224, v16 row_newbcast:4 row_mask:0xf bank_mask:0xf
	v_fmac_f32_dpp v197, v225, v17 row_newbcast:4 row_mask:0xf bank_mask:0xf
	v_fmac_f32_dpp v198, v226, v18 row_newbcast:4 row_mask:0xf bank_mask:0xf
	v_fmac_f32_dpp v199, v227, v19 row_newbcast:4 row_mask:0xf bank_mask:0xf
	v_fmac_f32_dpp v196, v224, v20 row_newbcast:5 row_mask:0xf bank_mask:0xf
	v_fmac_f32_dpp v197, v225, v21 row_newbcast:5 row_mask:0xf bank_mask:0xf
	v_fmac_f32_dpp v198, v226, v22 row_newbcast:5 row_mask:0xf bank_mask:0xf
	v_fmac_f32_dpp v199, v227, v23 row_newbcast:5 row_mask:0xf bank_mask:0xf
	v_fmac_f32_dpp v196, v224, v24 row_newbcast:6 row_mask:0xf bank_mask:0xf
	v_fmac_f32_dpp v197, v225, v25 row_newbcast:6 row_mask:0xf bank_mask:0xf
	v_fmac_f32_dpp v198, v226, v26 row_newbcast:6 row_mask:0xf bank_mask:0xf
	v_fmac_f32_dpp v199, v227, v27 row_newbcast:6 row_mask:0xf bank_mask:0xf
	v_fmac_f32_dpp v196, v224, v28 row_newbcast:7 row_mask:0xf bank_mask:0xf
	v_fmac_f32_dpp v197, v225, v29 row_newbcast:7 row_mask:0xf bank_mask:0xf
	v_fmac_f32_dpp v198, v226, v30 row_newbcast:7 row_mask:0xf bank_mask:0xf
	v_fmac_f32_dpp v199, v227, v31 row_newbcast:7 row_mask:0xf bank_mask:0xf
	v_fmac_f32_dpp v196, v224, v32 row_newbcast:8 row_mask:0xf bank_mask:0xf
	v_fmac_f32_dpp v197, v225, v33 row_newbcast:8 row_mask:0xf bank_mask:0xf
	v_fmac_f32_dpp v198, v226, v34 row_newbcast:8 row_mask:0xf bank_mask:0xf
	v_fmac_f32_dpp v199, v227, v35 row_newbcast:8 row_mask:0xf bank_mask:0xf
	v_fmac_f32_dpp v196, v224, v36 row_newbcast:9 row_mask:0xf bank_mask:0xf
	v_fmac_f32_dpp v197, v225, v37 row_newbcast:9 row_mask:0xf bank_mask:0xf
	v_fmac_f32_dpp v198, v226, v38 row_newbcast:9 row_mask:0xf bank_mask:0xf
	v_fmac_f32_dpp v199, v227, v39 row_newbcast:9 row_mask:0xf bank_mask:0xf
	v_fmac_f32_dpp v196, v224, v40 row_newbcast:10 row_mask:0xf bank_mask:0xf
	v_fmac_f32_dpp v197, v225, v41 row_newbcast:10 row_mask:0xf bank_mask:0xf
	v_fmac_f32_dpp v198, v226, v42 row_newbcast:10 row_mask:0xf bank_mask:0xf
	v_fmac_f32_dpp v199, v227, v43 row_newbcast:10 row_mask:0xf bank_mask:0xf
	v_fmac_f32_dpp v196, v224, v44 row_newbcast:11 row_mask:0xf bank_mask:0xf
	v_fmac_f32_dpp v197, v225, v45 row_newbcast:11 row_mask:0xf bank_mask:0xf
	v_fmac_f32_dpp v198, v226, v46 row_newbcast:11 row_mask:0xf bank_mask:0xf
	v_fmac_f32_dpp v199, v227, v47 row_newbcast:11 row_mask:0xf bank_mask:0xf
	v_fmac_f32_dpp v196, v224, v48 row_newbcast:12 row_mask:0xf bank_mask:0xf
	v_fmac_f32_dpp v197, v225, v49 row_newbcast:12 row_mask:0xf bank_mask:0xf
	v_fmac_f32_dpp v198, v226, v50 row_newbcast:12 row_mask:0xf bank_mask:0xf
	v_fmac_f32_dpp v199, v227, v51 row_newbcast:12 row_mask:0xf bank_mask:0xf
	v_fmac_f32_dpp v196, v224, v52 row_newbcast:13 row_mask:0xf bank_mask:0xf
	v_fmac_f32_dpp v197, v225, v53 row_newbcast:13 row_mask:0xf bank_mask:0xf
	v_fmac_f32_dpp v198, v226, v54 row_newbcast:13 row_mask:0xf bank_mask:0xf
	v_fmac_f32_dpp v199, v227, v55 row_newbcast:13 row_mask:0xf bank_mask:0xf
	v_fmac_f32_dpp v196, v224, v56 row_newbcast:14 row_mask:0xf bank_mask:0xf
	v_fmac_f32_dpp v197, v225, v57 row_newbcast:14 row_mask:0xf bank_mask:0xf
	v_fmac_f32_dpp v198, v226, v58 row_newbcast:14 row_mask:0xf bank_mask:0xf
	v_fmac_f32_dpp v199, v227, v59 row_newbcast:14 row_mask:0xf bank_mask:0xf
	v_fmac_f32_dpp v196, v224, v60 row_newbcast:15 row_mask:0xf bank_mask:0xf
	v_fmac_f32_dpp v197, v225, v61 row_newbcast:15 row_mask:0xf bank_mask:0xf
	v_fmac_f32_dpp v198, v226, v62 row_newbcast:15 row_mask:0xf bank_mask:0xf
	v_fmac_f32_dpp v199, v227, v63 row_newbcast:15 row_mask:0xf bank_mask:0xf
	v_add_f32_e32 v196, v196, v197
	v_add_f32_e32 v198, v198, v199
	v_sub_f32_e64 v202, -v196, v198
	s_waitcnt lgkmcnt(0)
; #define SB __builtin_amdgcn_sched_barrier(0)
; #define ST2(set, s) { DERIVE_BK(set); float sd[4]; ScanK<0>::dot(S, set.a, sd); float y0 = set.yo, y1 = 0.f; ScanK<0>::upd(S, set, -((sd[0] + sd[1]) + (sd[2] + sd[3])), __uint_as_float(set.v << 16), y0, y1); __builtin_amdgcn_raw_buffer_store_b32(__float_as_uint(y0 + y1), rY, lo4b, ob4 + (unsigned)((int)(s) * (int)stp * 4), 0); }
;     static __device__ __forceinline__ void upd(float (&S)[64], const In2& in, float sa, float vv, float& y0, float& y1) {
;         float t0, t1, t2, t3;
;         asm volatile("v_mul_f32_dpp %0, %10, %27 row_newbcast:%28" DPPM "v_mul_f32_dpp %1, %11, %27 row_newbcast:%28" DPPM "v_mul_f32_dpp %2, %12, %27 row_newbcast:%28" DPPM "v_mul_f32_dpp %3, %13, %27 row_newbcast:%28" DPPM
;                      "v_fmac_f32_dpp %0, %14, %6 row_newbcast:%28" DPPM "v_fmac_f32_dpp %1, %15, %7 row_newbcast:%28" DPPM "v_fmac_f32_dpp %2, %16, %8 row_newbcast:%28" DPPM "v_fmac_f32_dpp %3, %17, %9 row_newbcast:%28" DPPM
;                      "v_fmac_f32_dpp %0, %18, %26 row_newbcast:%28" DPPM "v_fmac_f32_dpp %1, %19, %26 row_newbcast:%28" DPPM "v_fmac_f32_dpp %2, %20, %26 row_newbcast:%28" DPPM "v_fmac_f32_dpp %3, %21, %26 row_newbcast:%28" DPPM
;                      "v_fmac_f32_dpp %4, %22, %0 row_newbcast:%28" DPPM "v_fmac_f32_dpp %5, %23, %1 row_newbcast:%28" DPPM "v_fmac_f32_dpp %4, %24, %2 row_newbcast:%28" DPPM "v_fmac_f32_dpp %5, %25, %3 row_newbcast:%28" DPPM
;                      : "=&v"(t0), "=&v"(t1), "=&v"(t2), "=&v"(t3), "+v"(y0), "+v"(y1)
;                      : "v"(S[K]), "v"(S[K + 1]), "v"(S[K + 2]), "v"(S[K + 3]), "v"(in.kd[0]), "v"(in.kd[1]), "v"(in.kd[2]), "v"(in.kd[3]), "v"(in.w[0]), "v"(in.w[1]), "v"(in.w[2]), "v"(in.w[3]),
;                        "v"(in.b[0]), "v"(in.b[1]), "v"(in.b[2]), "v"(in.b[3]), "v"(in.r[0]), "v"(in.r[1]), "v"(in.r[2]), "v"(in.r[3]), "v"(sa), "v"(vv), "n"(N0));
;         S[K] = t0; S[K + 1] = t1; S[K + 2] = t2; S[K + 3] = t3;
;         if constexpr (K + 4 < 64) ScanK<K + 4>::upd(S, in, sa, vv, y0, y1);
;     }
; __device__ __forceinline__ void scan_pass2(const Params& p, int d) {
;     ...
; #pragma unroll 1
;         for (int s = 0; s < LC; s += 2) { TOUCH2(i0); SB; LD2(i1, s + 1); SB; ST2(i0, s); TOUCH2(i1); SB; LD2(i0, s + 2); SB; ST2(i1, s + 1); }
	s_nop 1
	v_mfma_f32_4x4x1_16b_f32 v[0:3], v64, v202, v[0:3]
	v_mfma_f32_4x4x1_16b_f32 v[4:7], v65, v202, v[4:7]
	v_mfma_f32_4x4x1_16b_f32 v[8:11], v66, v202, v[8:11]
	v_mfma_f32_4x4x1_16b_f32 v[12:15], v67, v202, v[12:15]
	v_mfma_f32_4x4x1_16b_f32 v[16:19], v68, v202, v[16:19]
	v_mfma_f32_4x4x1_16b_f32 v[20:23], v69, v202, v[20:23]
	v_mfma_f32_4x4x1_16b_f32 v[24:27], v70, v202, v[24:27]
	v_mfma_f32_4x4x1_16b_f32 v[28:31], v71, v202, v[28:31]
	v_mfma_f32_4x4x1_16b_f32 v[32:35], v72, v202, v[32:35]
	v_mfma_f32_4x4x1_16b_f32 v[36:39], v73, v202, v[36:39]
	v_mfma_f32_4x4x1_16b_f32 v[40:43], v74, v202, v[40:43]
	v_mfma_f32_4x4x1_16b_f32 v[44:47], v75, v202, v[44:47]
	v_mfma_f32_4x4x1_16b_f32 v[48:51], v76, v202, v[48:51]
	v_mfma_f32_4x4x1_16b_f32 v[52:55], v77, v202, v[52:55]
	v_mfma_f32_4x4x1_16b_f32 v[56:59], v78, v202, v[56:59]
	v_mfma_f32_4x4x1_16b_f32 v[60:63], v79, v202, v[60:63]
	v_mfma_f32_4x4x1_16b_f32 v[0:3], v80, v203, v[0:3]
	v_mfma_f32_4x4x1_16b_f32 v[4:7], v81, v203, v[4:7]
	v_mfma_f32_4x4x1_16b_f32 v[8:11], v82, v203, v[8:11]
	v_mfma_f32_4x4x1_16b_f32 v[12:15], v83, v203, v[12:15]
	v_mfma_f32_4x4x1_16b_f32 v[16:19], v84, v203, v[16:19]
	v_mfma_f32_4x4x1_16b_f32 v[20:23], v85, v203, v[20:23]
	v_mfma_f32_4x4x1_16b_f32 v[24:27], v86, v203, v[24:27]
	v_mfma_f32_4x4x1_16b_f32 v[28:31], v87, v203, v[28:31]
	v_mfma_f32_4x4x1_16b_f32 v[32:35], v88, v203, v[32:35]
	v_mfma_f32_4x4x1_16b_f32 v[36:39], v89, v203, v[36:39]
	v_mfma_f32_4x4x1_16b_f32 v[40:43], v90, v203, v[40:43]
	v_mfma_f32_4x4x1_16b_f32 v[44:47], v91, v203, v[44:47]
	v_mfma_f32_4x4x1_16b_f32 v[48:51], v92, v203, v[48:51]
	v_mfma_f32_4x4x1_16b_f32 v[52:55], v93, v203, v[52:55]
	v_mfma_f32_4x4x1_16b_f32 v[56:59], v94, v203, v[56:59]
	v_mfma_f32_4x4x1_16b_f32 v[60:63], v95, v203, v[60:63]
	v_fmac_f32_dpp v175, v228, v0 row_newbcast:0 row_mask:0xf bank_mask:0xf
	v_mul_f32_dpp v201, v229, v1 row_newbcast:0 row_mask:0xf bank_mask:0xf
	v_fmac_f32_dpp v175, v230, v2 row_newbcast:0 row_mask:0xf bank_mask:0xf
	v_fmac_f32_dpp v201, v231, v3 row_newbcast:0 row_mask:0xf bank_mask:0xf
	v_fmac_f32_dpp v175, v228, v4 row_newbcast:1 row_mask:0xf bank_mask:0xf
	v_fmac_f32_dpp v201, v229, v5 row_newbcast:1 row_mask:0xf bank_mask:0xf
	v_fmac_f32_dpp v175, v230, v6 row_newbcast:1 row_mask:0xf bank_mask:0xf
	v_fmac_f32_dpp v201, v231, v7 row_newbcast:1 row_mask:0xf bank_mask:0xf
	v_fmac_f32_dpp v175, v228, v8 row_newbcast:2 row_mask:0xf bank_mask:0xf
	v_fmac_f32_dpp v201, v229, v9 row_newbcast:2 row_mask:0xf bank_mask:0xf
	v_fmac_f32_dpp v175, v230, v10 row_newbcast:2 row_mask:0xf bank_mask:0xf
	v_fmac_f32_dpp v201, v231, v11 row_newbcast:2 row_mask:0xf bank_mask:0xf
	v_fmac_f32_dpp v175, v228, v12 row_newbcast:3 row_mask:0xf bank_mask:0xf
	v_fmac_f32_dpp v201, v229, v13 row_newbcast:3 row_mask:0xf bank_mask:0xf
	v_fmac_f32_dpp v175, v230, v14 row_newbcast:3 row_mask:0xf bank_mask:0xf
	v_fmac_f32_dpp v201, v231, v15 row_newbcast:3 row_mask:0xf bank_mask:0xf
	v_fmac_f32_dpp v175, v228, v16 row_newbcast:4 row_mask:0xf bank_mask:0xf
	v_fmac_f32_dpp v201, v229, v17 row_newbcast:4 row_mask:0xf bank_mask:0xf
	v_fmac_f32_dpp v175, v230, v18 row_newbcast:4 row_mask:0xf bank_mask:0xf
	v_fmac_f32_dpp v201, v231, v19 row_newbcast:4 row_mask:0xf bank_mask:0xf
	v_fmac_f32_dpp v175, v228, v20 row_newbcast:5 row_mask:0xf bank_mask:0xf
	v_fmac_f32_dpp v201, v229, v21 row_newbcast:5 row_mask:0xf bank_mask:0xf
	v_fmac_f32_dpp v175, v230, v22 row_newbcast:5 row_mask:0xf bank_mask:0xf
	v_fmac_f32_dpp v201, v231, v23 row_newbcast:5 row_mask:0xf bank_mask:0xf
	v_fmac_f32_dpp v175, v228, v24 row_newbcast:6 row_mask:0xf bank_mask:0xf
	v_fmac_f32_dpp v201, v229, v25 row_newbcast:6 row_mask:0xf bank_mask:0xf
	v_fmac_f32_dpp v175, v230, v26 row_newbcast:6 row_mask:0xf bank_mask:0xf
	v_fmac_f32_dpp v201, v231, v27 row_newbcast:6 row_mask:0xf bank_mask:0xf
	v_fmac_f32_dpp v175, v228, v28 row_newbcast:7 row_mask:0xf bank_mask:0xf
	v_fmac_f32_dpp v201, v229, v29 row_newbcast:7 row_mask:0xf bank_mask:0xf
	v_fmac_f32_dpp v175, v230, v30 row_newbcast:7 row_mask:0xf bank_mask:0xf
	v_fmac_f32_dpp v201, v231, v31 row_newbcast:7 row_mask:0xf bank_mask:0xf
	v_fmac_f32_dpp v175, v228, v32 row_newbcast:8 row_mask:0xf bank_mask:0xf
	v_fmac_f32_dpp v201, v229, v33 row_newbcast:8 row_mask:0xf bank_mask:0xf
	v_fmac_f32_dpp v175, v230, v34 row_newbcast:8 row_mask:0xf bank_mask:0xf
	v_fmac_f32_dpp v201, v231, v35 row_newbcast:8 row_mask:0xf bank_mask:0xf
	v_fmac_f32_dpp v175, v228, v36 row_newbcast:9 row_mask:0xf bank_mask:0xf
	v_fmac_f32_dpp v201, v229, v37 row_newbcast:9 row_mask:0xf bank_mask:0xf
	v_fmac_f32_dpp v175, v230, v38 row_newbcast:9 row_mask:0xf bank_mask:0xf
	v_fmac_f32_dpp v201, v231, v39 row_newbcast:9 row_mask:0xf bank_mask:0xf
	v_fmac_f32_dpp v175, v228, v40 row_newbcast:10 row_mask:0xf bank_mask:0xf
	v_fmac_f32_dpp v201, v229, v41 row_newbcast:10 row_mask:0xf bank_mask:0xf
	v_fmac_f32_dpp v175, v230, v42 row_newbcast:10 row_mask:0xf bank_mask:0xf
	v_fmac_f32_dpp v201, v231, v43 row_newbcast:10 row_mask:0xf bank_mask:0xf
	v_fmac_f32_dpp v175, v228, v44 row_newbcast:11 row_mask:0xf bank_mask:0xf
	v_fmac_f32_dpp v201, v229, v45 row_newbcast:11 row_mask:0xf bank_mask:0xf
	v_fmac_f32_dpp v175, v230, v46 row_newbcast:11 row_mask:0xf bank_mask:0xf
	v_fmac_f32_dpp v201, v231, v47 row_newbcast:11 row_mask:0xf bank_mask:0xf
	v_fmac_f32_dpp v175, v228, v48 row_newbcast:12 row_mask:0xf bank_mask:0xf
	v_fmac_f32_dpp v201, v229, v49 row_newbcast:12 row_mask:0xf bank_mask:0xf
	v_fmac_f32_dpp v175, v230, v50 row_newbcast:12 row_mask:0xf bank_mask:0xf
	v_fmac_f32_dpp v201, v231, v51 row_newbcast:12 row_mask:0xf bank_mask:0xf
	v_fmac_f32_dpp v175, v228, v52 row_newbcast:13 row_mask:0xf bank_mask:0xf
	v_fmac_f32_dpp v201, v229, v53 row_newbcast:13 row_mask:0xf bank_mask:0xf
	v_fmac_f32_dpp v175, v230, v54 row_newbcast:13 row_mask:0xf bank_mask:0xf
	v_fmac_f32_dpp v201, v231, v55 row_newbcast:13 row_mask:0xf bank_mask:0xf
	v_fmac_f32_dpp v175, v228, v56 row_newbcast:14 row_mask:0xf bank_mask:0xf
	v_fmac_f32_dpp v201, v229, v57 row_newbcast:14 row_mask:0xf bank_mask:0xf
	v_fmac_f32_dpp v175, v230, v58 row_newbcast:14 row_mask:0xf bank_mask:0xf
	v_fmac_f32_dpp v201, v231, v59 row_newbcast:14 row_mask:0xf bank_mask:0xf
	v_fmac_f32_dpp v175, v228, v60 row_newbcast:15 row_mask:0xf bank_mask:0xf
	v_fmac_f32_dpp v201, v229, v61 row_newbcast:15 row_mask:0xf bank_mask:0xf
	v_fmac_f32_dpp v175, v230, v62 row_newbcast:15 row_mask:0xf bank_mask:0xf
	v_fmac_f32_dpp v201, v231, v63 row_newbcast:15 row_mask:0xf bank_mask:0xf
	v_add_f32_e32 v200, v175, v201
	s_sub_u32 s83, s83, 1
	s_cmp_eq_u32 s83, 0
	s_cbranch_scc1 .Lmy_p2d1_ldone
	s_and_b32 s9, s83, 7
	s_cmp_eq_u32 s9, 0
	s_cbranch_scc1 .Lmy_p2d1_renorm
	s_branch .Lmy_p2d1_loop
